# GEMM K-loop load segments: merged vmcnt/lgkmcnt waits, address add used as the M0 wait state instead of s_nop (A/B on top of v33)
# speedup vs baseline: 1.0088x; 1.0002x over previous
; #define PG8_STAGE(bufoff, gbase, voff) do { _Pragma("unroll") for (int _i = 0; _i < 2; ++_i) \
;         __builtin_amdgcn_global_load_lds((const unsigned*)((const char*)(gbase) + (voff)[_i]), (LAS unsigned*)(lds + (bufoff) + ldsw + _i * 8192), 16, 0, 0); } while (0)
; #define PG8_LDA(dst, b, h) do { _Pragma("unroll") for (int m = 0; m < 4; ++m) _Pragma("unroll") for (int k = 0; k < 2; ++k) dst[m][k] = *(const LAS bf16x8*)(lds + PG8_SA(b, h) + aoff + m * 2048 + k * 1024); } while (0)
; #define PG8_LDB(dst, b, h) do { _Pragma("unroll") for (int n = 0; n < 2; ++n) _Pragma("unroll") for (int k = 0; k < 2; ++k) dst[n][k] = *(const LAS bf16x8*)(lds + PG8_SB(b, h) + boff + n * 2048 + k * 1024); } while (0)
; #define PG8_MMA(ai, bj, At, Bt) do { __builtin_amdgcn_s_setprio(1); _Pragma("unroll") for (int m = 0; m < 4; ++m) _Pragma("unroll") for (int n = 0; n < 2; ++n) _Pragma("unroll") for (int k = 0; k < 2; ++k) \
;         acc[ai][bj][m][n] = __builtin_amdgcn_mfma_f32_16x16x32_bf16(Bt[n][k], At[m][k], acc[ai][bj][m][n], 0, 0, 0); __builtin_amdgcn_s_setprio(0); } while (0)
; #define PG8_WAIT_V(n) asm volatile("s_waitcnt vmcnt(" #n ")" ::: "memory")
; #define PG8_WAIT_L(n) asm volatile("s_waitcnt lgkmcnt(" #n ")" ::: "memory")
; #define PG8_BAR __builtin_amdgcn_s_barrier()
; #define PG8_SCHED __builtin_amdgcn_sched_barrier(0)
; template <class Desc, class Epi>
; DI void gemm_phase(LAS unsigned char* lds, const Desc& D, const Epi& E, int wv) {
;     ...
;             PG8_LDB(B0, 0, 0); PG8_LDB(B1, 0, 1); PG8_SCHED; PG8_LDA(At, 0, 0); PG8_STAGE(PG8_SA(1, 1), a1 + hstepA, voffA);
;             PG8_WAIT_V(8); PG8_WAIT_L(0); PG8_BAR; PG8_MMA(0, 0, At, B0); PG8_MMA(0, 1, At, B1); PG8_BAR; PG8_SCHED;
;             PG8_LDA(At, 0, 1); PG8_STAGE(PG8_SB(0, 0), b2, voffB); PG8_STAGE(PG8_SB(0, 1), b2 + hstepB, voffB); PG8_STAGE(PG8_SA(0, 0), a2, voffA);
;             PG8_WAIT_V(8); PG8_WAIT_L(0); PG8_BAR; PG8_MMA(1, 0, At, B0); PG8_MMA(1, 1, At, B1); PG8_BAR; PG8_SCHED;
.LBB0_292:
	ds_read_b128 v[152:155], v149
	ds_read_b128 v[156:159], v149 offset:1024
	ds_read_b128 v[160:163], v149 offset:2048
	ds_read_b128 v[164:167], v149 offset:3072
	ds_read_b128 v[168:171], v150
	ds_read_b128 v[172:175], v150 offset:1024
	ds_read_b128 v[176:179], v150 offset:2048
	ds_read_b128 v[180:183], v150 offset:3072
	s_add_u32 s66, s64, 0xfff80080
	s_addc_u32 s67, s65, -1
	s_cmp_eq_u32 s63, 28
	s_cselect_b32 s69, s39, s67
	s_cselect_b32 s68, s38, s66
	s_cselect_b32 s67, s47, s61
	s_cselect_b32 s66, s46, s53
	v_lshl_add_u64 v[146:147], s[64:65], 0, v[138:139]
	s_add_i32 m0, s31, 0xc000
	ds_read_b128 v[184:187], v151
	ds_read_b128 v[188:191], v151 offset:1024
	ds_read_b128 v[192:195], v151 offset:2048
	ds_read_b128 v[196:199], v151 offset:3072
	ds_read_b128 v[200:203], v151 offset:4096
	ds_read_b128 v[204:207], v151 offset:5120
	ds_read_b128 v[208:211], v151 offset:6144
	ds_read_b128 v[212:215], v151 offset:7168
	global_load_lds_dwordx4 v[146:147], off
	s_add_i32 m0, s31, 0xe000
	v_lshl_add_u64 v[146:147], s[64:65], 0, v[140:141]
	global_load_lds_dwordx4 v[146:147], off
	s_waitcnt vmcnt(8) lgkmcnt(0)
	s_barrier
	s_setprio 1
	v_mfma_f32_16x16x32_bf16 v[124:127], v[152:155], v[184:187], v[124:127]
	v_mfma_f32_16x16x32_bf16 v[120:123], v[160:163], v[184:187], v[120:123]
	v_mfma_f32_16x16x32_bf16 v[108:111], v[152:155], v[192:195], v[108:111]
	v_mfma_f32_16x16x32_bf16 v[104:107], v[160:163], v[192:195], v[104:107]
	v_mfma_f32_16x16x32_bf16 v[92:95], v[152:155], v[200:203], v[92:95]
	v_mfma_f32_16x16x32_bf16 v[88:91], v[160:163], v[200:203], v[88:91]
	v_mfma_f32_16x16x32_bf16 v[76:79], v[152:155], v[208:211], v[76:79]
	v_mfma_f32_16x16x32_bf16 v[72:75], v[160:163], v[208:211], v[72:75]
	v_mfma_f32_16x16x32_bf16 v[124:127], v[156:159], v[188:191], v[124:127]
	v_mfma_f32_16x16x32_bf16 v[120:123], v[164:167], v[188:191], v[120:123]
	v_mfma_f32_16x16x32_bf16 v[108:111], v[156:159], v[196:199], v[108:111]
	v_mfma_f32_16x16x32_bf16 v[104:107], v[164:167], v[196:199], v[104:107]
	v_mfma_f32_16x16x32_bf16 v[92:95], v[156:159], v[204:207], v[92:95]
	v_mfma_f32_16x16x32_bf16 v[88:91], v[164:167], v[204:207], v[88:91]
	v_mfma_f32_16x16x32_bf16 v[76:79], v[156:159], v[212:215], v[76:79]
	v_mfma_f32_16x16x32_bf16 v[72:75], v[164:167], v[212:215], v[72:75]
	v_mfma_f32_16x16x32_bf16 v[116:119], v[168:171], v[184:187], v[116:119]
	v_mfma_f32_16x16x32_bf16 v[112:115], v[176:179], v[184:187], v[112:115]
	v_mfma_f32_16x16x32_bf16 v[100:103], v[168:171], v[192:195], v[100:103]
	v_mfma_f32_16x16x32_bf16 v[96:99], v[176:179], v[192:195], v[96:99]
	v_mfma_f32_16x16x32_bf16 v[84:87], v[168:171], v[200:203], v[84:87]
	v_mfma_f32_16x16x32_bf16 v[80:83], v[176:179], v[200:203], v[80:83]
	v_mfma_f32_16x16x32_bf16 v[68:71], v[168:171], v[208:211], v[68:71]
	v_mfma_f32_16x16x32_bf16 v[64:67], v[176:179], v[208:211], v[64:67]
	v_mfma_f32_16x16x32_bf16 v[116:119], v[172:175], v[188:191], v[116:119]
	v_mfma_f32_16x16x32_bf16 v[112:115], v[180:183], v[188:191], v[112:115]
	v_mfma_f32_16x16x32_bf16 v[100:103], v[172:175], v[196:199], v[100:103]
	v_mfma_f32_16x16x32_bf16 v[96:99], v[180:183], v[196:199], v[96:99]
	v_mfma_f32_16x16x32_bf16 v[84:87], v[172:175], v[204:207], v[84:87]
	v_mfma_f32_16x16x32_bf16 v[80:83], v[180:183], v[204:207], v[80:83]
	v_mfma_f32_16x16x32_bf16 v[68:71], v[172:175], v[212:215], v[68:71]
	v_mfma_f32_16x16x32_bf16 v[64:67], v[180:183], v[212:215], v[64:67]
	s_setprio 0
	s_barrier
	s_add_i32 s76, s51, s28
	v_lshl_add_u64 v[146:147], s[66:67], 0, v[132:133]
	s_mov_b32 m0, s76
	ds_read_b128 v[184:187], v151 offset:16384
	ds_read_b128 v[188:191], v151 offset:17408
	ds_read_b128 v[192:195], v151 offset:18432
	ds_read_b128 v[196:199], v151 offset:19456
	ds_read_b128 v[200:203], v151 offset:20480
	ds_read_b128 v[204:207], v151 offset:21504
	ds_read_b128 v[208:211], v151 offset:22528
	ds_read_b128 v[212:215], v151 offset:23552
	global_load_lds_dwordx4 v[146:147], off
	s_add_i32 m0, s76, 0x2000
	s_add_u32 s76, s66, 0x80000
	v_lshl_add_u64 v[216:217], s[66:67], 0, v[128:129]
	s_addc_u32 s77, s67, 0
	s_add_i32 s78, s70, s28
	global_load_lds_dwordx4 v[216:217], off
	v_lshl_add_u64 v[218:219], s[76:77], 0, v[132:133]
	s_mov_b32 m0, s78
	v_lshl_add_u64 v[220:221], s[68:69], 0, v[130:131]
	global_load_lds_dwordx4 v[218:219], off
	s_add_i32 m0, s78, 0x2000
	v_lshl_add_u64 v[218:219], s[76:77], 0, v[128:129]
	global_load_lds_dwordx4 v[218:219], off
	s_mov_b32 m0, s31
	v_lshl_add_u64 v[218:219], s[68:69], 0, v[134:135]
	global_load_lds_dwordx4 v[218:219], off
	s_mov_b32 m0, s34
	s_nop 0
	global_load_lds_dwordx4 v[220:221], off
	s_waitcnt vmcnt(8) lgkmcnt(0)
	s_barrier
; #define PG8_STAGE(bufoff, gbase, voff) do { _Pragma("unroll") for (int _i = 0; _i < 2; ++_i) \
;         __builtin_amdgcn_global_load_lds((const unsigned*)((const char*)(gbase) + (voff)[_i]), (LAS unsigned*)(lds + (bufoff) + ldsw + _i * 8192), 16, 0, 0); } while (0)
; #define PG8_LDA(dst, b, h) do { _Pragma("unroll") for (int m = 0; m < 4; ++m) _Pragma("unroll") for (int k = 0; k < 2; ++k) dst[m][k] = *(const LAS bf16x8*)(lds + PG8_SA(b, h) + aoff + m * 2048 + k * 1024); } while (0)
; #define PG8_LDB(dst, b, h) do { _Pragma("unroll") for (int n = 0; n < 2; ++n) _Pragma("unroll") for (int k = 0; k < 2; ++k) dst[n][k] = *(const LAS bf16x8*)(lds + PG8_SB(b, h) + boff + n * 2048 + k * 1024); } while (0)
; #define PG8_MMA(ai, bj, At, Bt) do { __builtin_amdgcn_s_setprio(1); _Pragma("unroll") for (int m = 0; m < 4; ++m) _Pragma("unroll") for (int n = 0; n < 2; ++n) _Pragma("unroll") for (int k = 0; k < 2; ++k) \
;         acc[ai][bj][m][n] = __builtin_amdgcn_mfma_f32_16x16x32_bf16(Bt[n][k], At[m][k], acc[ai][bj][m][n], 0, 0, 0); __builtin_amdgcn_s_setprio(0); } while (0)
; #define PG8_WAIT_V(n) asm volatile("s_waitcnt vmcnt(" #n ")" ::: "memory")
; #define PG8_WAIT_L(n) asm volatile("s_waitcnt lgkmcnt(" #n ")" ::: "memory")
; #define PG8_BAR __builtin_amdgcn_s_barrier()
; #define PG8_SCHED __builtin_amdgcn_sched_barrier(0)
; template <class Desc, class Epi>
; DI void gemm_phase(LAS unsigned char* lds, const Desc& D, const Epi& E, int wv) {
;     ...
;             PG8_WAIT_V(8); PG8_WAIT_L(0); PG8_BAR; PG8_MMA(1, 0, At, B0); PG8_MMA(1, 1, At, B1); PG8_BAR; PG8_SCHED;
;             PG8_LDB(B0, 1, 0); PG8_LDB(B1, 1, 1); PG8_SCHED; PG8_LDA(At, 1, 0); PG8_STAGE(PG8_SA(0, 1), a2 + hstepA, voffA);
;             PG8_WAIT_V(8); PG8_WAIT_L(0); PG8_BAR; PG8_MMA(0, 0, At, B0); PG8_MMA(0, 1, At, B1); PG8_BAR; PG8_SCHED;
	s_setprio 1
	v_mfma_f32_16x16x32_bf16 v[60:63], v[152:155], v[184:187], v[60:63]
	v_mfma_f32_16x16x32_bf16 v[56:59], v[160:163], v[184:187], v[56:59]
	v_mfma_f32_16x16x32_bf16 v[44:47], v[152:155], v[192:195], v[44:47]
	v_mfma_f32_16x16x32_bf16 v[40:43], v[160:163], v[192:195], v[40:43]
	v_mfma_f32_16x16x32_bf16 v[28:31], v[152:155], v[200:203], v[28:31]
	v_mfma_f32_16x16x32_bf16 v[24:27], v[160:163], v[200:203], v[24:27]
	v_mfma_f32_16x16x32_bf16 v[12:15], v[152:155], v[208:211], v[12:15]
	v_mfma_f32_16x16x32_bf16 v[8:11], v[160:163], v[208:211], v[8:11]
	v_mfma_f32_16x16x32_bf16 v[60:63], v[156:159], v[188:191], v[60:63]
	v_mfma_f32_16x16x32_bf16 v[56:59], v[164:167], v[188:191], v[56:59]
	v_mfma_f32_16x16x32_bf16 v[44:47], v[156:159], v[196:199], v[44:47]
	v_mfma_f32_16x16x32_bf16 v[40:43], v[164:167], v[196:199], v[40:43]
	v_mfma_f32_16x16x32_bf16 v[28:31], v[156:159], v[204:207], v[28:31]
	v_mfma_f32_16x16x32_bf16 v[24:27], v[164:167], v[204:207], v[24:27]
	v_mfma_f32_16x16x32_bf16 v[12:15], v[156:159], v[212:215], v[12:15]
	v_mfma_f32_16x16x32_bf16 v[8:11], v[164:167], v[212:215], v[8:11]
	v_mfma_f32_16x16x32_bf16 v[52:55], v[168:171], v[184:187], v[52:55]
	v_mfma_f32_16x16x32_bf16 v[48:51], v[176:179], v[184:187], v[48:51]
	v_mfma_f32_16x16x32_bf16 v[36:39], v[168:171], v[192:195], v[36:39]
	v_mfma_f32_16x16x32_bf16 v[32:35], v[176:179], v[192:195], v[32:35]
	v_mfma_f32_16x16x32_bf16 v[20:23], v[168:171], v[200:203], v[20:23]
	v_mfma_f32_16x16x32_bf16 v[16:19], v[176:179], v[200:203], v[16:19]
	v_mfma_f32_16x16x32_bf16 v[4:7], v[168:171], v[208:211], v[4:7]
	v_mfma_f32_16x16x32_bf16 v[0:3], v[176:179], v[208:211], v[0:3]
	v_mfma_f32_16x16x32_bf16 v[52:55], v[172:175], v[188:191], v[52:55]
	v_mfma_f32_16x16x32_bf16 v[48:51], v[180:183], v[188:191], v[48:51]
	v_mfma_f32_16x16x32_bf16 v[36:39], v[172:175], v[196:199], v[36:39]
	v_mfma_f32_16x16x32_bf16 v[32:35], v[180:183], v[196:199], v[32:35]
	v_mfma_f32_16x16x32_bf16 v[20:23], v[172:175], v[204:207], v[20:23]
	v_mfma_f32_16x16x32_bf16 v[16:19], v[180:183], v[204:207], v[16:19]
	v_mfma_f32_16x16x32_bf16 v[4:7], v[172:175], v[212:215], v[4:7]
	v_mfma_f32_16x16x32_bf16 v[0:3], v[180:183], v[212:215], v[0:3]
	s_setprio 0
	s_barrier
	s_add_i32 s76, 0, 0x18000
	v_add_u32_e32 v136, s76, v148
	s_add_i32 s77, 0, 0x1c000
	ds_read_b128 v[152:155], v136
	ds_read_b128 v[156:159], v136 offset:1024
	ds_read_b128 v[160:163], v136 offset:2048
	ds_read_b128 v[164:167], v136 offset:3072
	v_add_u32_e32 v136, s77, v148
	ds_read_b128 v[168:171], v136
	ds_read_b128 v[172:175], v136 offset:1024
	ds_read_b128 v[176:179], v136 offset:2048
	ds_read_b128 v[180:183], v136 offset:3072
	s_add_u32 s68, s68, 0x80000
	s_addc_u32 s69, s69, 0
	s_mov_b32 m0, s35
	v_lshl_add_u64 v[222:223], s[68:69], 0, v[134:135]
	ds_read_b128 v[184:187], v151 offset:32768
	ds_read_b128 v[188:191], v151 offset:33792
	ds_read_b128 v[192:195], v151 offset:34816
	ds_read_b128 v[196:199], v151 offset:35840
	ds_read_b128 v[200:203], v151 offset:36864
	ds_read_b128 v[204:207], v151 offset:37888
	ds_read_b128 v[208:211], v151 offset:38912
	ds_read_b128 v[212:215], v151 offset:39936
	global_load_lds_dwordx4 v[222:223], off
	s_mov_b32 m0, s40
	v_lshl_add_u64 v[222:223], s[68:69], 0, v[130:131]
	global_load_lds_dwordx4 v[222:223], off
	s_waitcnt vmcnt(8) lgkmcnt(0)
	s_barrier
	s_setprio 1
	v_mfma_f32_16x16x32_bf16 v[124:127], v[152:155], v[184:187], v[124:127]
	v_mfma_f32_16x16x32_bf16 v[120:123], v[160:163], v[184:187], v[120:123]
	v_mfma_f32_16x16x32_bf16 v[108:111], v[152:155], v[192:195], v[108:111]
	v_mfma_f32_16x16x32_bf16 v[104:107], v[160:163], v[192:195], v[104:107]
	v_mfma_f32_16x16x32_bf16 v[92:95], v[152:155], v[200:203], v[92:95]
	v_mfma_f32_16x16x32_bf16 v[88:91], v[160:163], v[200:203], v[88:91]
	v_mfma_f32_16x16x32_bf16 v[76:79], v[152:155], v[208:211], v[76:79]
	v_mfma_f32_16x16x32_bf16 v[72:75], v[160:163], v[208:211], v[72:75]
	v_mfma_f32_16x16x32_bf16 v[124:127], v[156:159], v[188:191], v[124:127]
	v_mfma_f32_16x16x32_bf16 v[120:123], v[164:167], v[188:191], v[120:123]
	v_mfma_f32_16x16x32_bf16 v[108:111], v[156:159], v[196:199], v[108:111]
	v_mfma_f32_16x16x32_bf16 v[104:107], v[164:167], v[196:199], v[104:107]
	v_mfma_f32_16x16x32_bf16 v[92:95], v[156:159], v[204:207], v[92:95]
	v_mfma_f32_16x16x32_bf16 v[88:91], v[164:167], v[204:207], v[88:91]
	v_mfma_f32_16x16x32_bf16 v[76:79], v[156:159], v[212:215], v[76:79]
	v_mfma_f32_16x16x32_bf16 v[72:75], v[164:167], v[212:215], v[72:75]
	v_mfma_f32_16x16x32_bf16 v[116:119], v[168:171], v[184:187], v[116:119]
	v_mfma_f32_16x16x32_bf16 v[112:115], v[176:179], v[184:187], v[112:115]
	v_mfma_f32_16x16x32_bf16 v[100:103], v[168:171], v[192:195], v[100:103]
	v_mfma_f32_16x16x32_bf16 v[96:99], v[176:179], v[192:195], v[96:99]
	v_mfma_f32_16x16x32_bf16 v[84:87], v[168:171], v[200:203], v[84:87]
	v_mfma_f32_16x16x32_bf16 v[80:83], v[176:179], v[200:203], v[80:83]
	v_mfma_f32_16x16x32_bf16 v[68:71], v[168:171], v[208:211], v[68:71]
	v_mfma_f32_16x16x32_bf16 v[64:67], v[176:179], v[208:211], v[64:67]
	v_mfma_f32_16x16x32_bf16 v[116:119], v[172:175], v[188:191], v[116:119]
	v_mfma_f32_16x16x32_bf16 v[112:115], v[180:183], v[188:191], v[112:115]
	v_mfma_f32_16x16x32_bf16 v[100:103], v[172:175], v[196:199], v[100:103]
	v_mfma_f32_16x16x32_bf16 v[96:99], v[180:183], v[196:199], v[96:99]
	v_mfma_f32_16x16x32_bf16 v[84:87], v[172:175], v[204:207], v[84:87]
	v_mfma_f32_16x16x32_bf16 v[80:83], v[180:183], v[204:207], v[80:83]
	v_mfma_f32_16x16x32_bf16 v[68:71], v[172:175], v[212:215], v[68:71]
	v_mfma_f32_16x16x32_bf16 v[64:67], v[180:183], v[212:215], v[64:67]
	s_setprio 0
	s_barrier
; #define PG8_STAGE(bufoff, gbase, voff) do { _Pragma("unroll") for (int _i = 0; _i < 2; ++_i) \
;         __builtin_amdgcn_global_load_lds((const unsigned*)((const char*)(gbase) + (voff)[_i]), (LAS unsigned*)(lds + (bufoff) + ldsw + _i * 8192), 16, 0, 0); } while (0)
; #define PG8_LDA(dst, b, h) do { _Pragma("unroll") for (int m = 0; m < 4; ++m) _Pragma("unroll") for (int k = 0; k < 2; ++k) dst[m][k] = *(const LAS bf16x8*)(lds + PG8_SA(b, h) + aoff + m * 2048 + k * 1024); } while (0)
; #define PG8_MMA(ai, bj, At, Bt) do { __builtin_amdgcn_s_setprio(1); _Pragma("unroll") for (int m = 0; m < 4; ++m) _Pragma("unroll") for (int n = 0; n < 2; ++n) _Pragma("unroll") for (int k = 0; k < 2; ++k) \
;         acc[ai][bj][m][n] = __builtin_amdgcn_mfma_f32_16x16x32_bf16(Bt[n][k], At[m][k], acc[ai][bj][m][n], 0, 0, 0); __builtin_amdgcn_s_setprio(0); } while (0)
; #define PG8_WAIT_V(n) asm volatile("s_waitcnt vmcnt(" #n ")" ::: "memory")
; #define PG8_WAIT_L(n) asm volatile("s_waitcnt lgkmcnt(" #n ")" ::: "memory")
; #define PG8_BAR __builtin_amdgcn_s_barrier()
; #define PG8_SCHED __builtin_amdgcn_sched_barrier(0)
; template <class Desc, class Epi>
; DI void gemm_phase(LAS unsigned char* lds, const Desc& D, const Epi& E, int wv) {
;     ...
;             PG8_LDA(At, 1, 1); PG8_STAGE(PG8_SB(1, 0), b3, voffB); PG8_STAGE(PG8_SB(1, 1), b3 + hstepB, voffB); PG8_STAGE(PG8_SA(1, 0), a3, voffA);
;             PG8_WAIT_V(8); PG8_WAIT_L(0); PG8_BAR; PG8_MMA(1, 0, At, B0); PG8_MMA(1, 1, At, B1); PG8_BAR; PG8_SCHED;
;         }
	s_add_i32 s68, s76, s28
	v_lshl_add_u64 v[146:147], v[146:147], 0, s[8:9]
	s_mov_b32 m0, s68
	ds_read_b128 v[184:187], v151 offset:49152
	ds_read_b128 v[188:191], v151 offset:50176
	ds_read_b128 v[192:195], v151 offset:51200
	ds_read_b128 v[196:199], v151 offset:52224
	ds_read_b128 v[200:203], v151 offset:53248
	ds_read_b128 v[204:207], v151 offset:54272
	ds_read_b128 v[208:211], v151 offset:55296
	ds_read_b128 v[212:215], v151 offset:56320
	global_load_lds_dwordx4 v[146:147], off
	s_add_i32 m0, s68, 0x2000
	s_add_u32 s66, s66, 0x80080
	v_lshl_add_u64 v[146:147], v[216:217], 0, s[8:9]
	s_addc_u32 s67, s67, 0
	s_add_i32 s68, s77, s28
	global_load_lds_dwordx4 v[146:147], off
	s_mov_b32 m0, s68
	v_lshl_add_u64 v[146:147], s[66:67], 0, v[132:133]
	global_load_lds_dwordx4 v[146:147], off
	s_add_i32 m0, s68, 0x2000
	v_lshl_add_u64 v[146:147], s[66:67], 0, v[128:129]
	global_load_lds_dwordx4 v[146:147], off
	s_mov_b32 m0, s48
	v_lshl_add_u64 v[146:147], v[218:219], 0, s[8:9]
	global_load_lds_dwordx4 v[146:147], off
	s_mov_b32 m0, s49
	v_lshl_add_u64 v[146:147], v[220:221], 0, s[8:9]
	global_load_lds_dwordx4 v[146:147], off
	s_waitcnt vmcnt(8) lgkmcnt(0)
	s_barrier
	s_setprio 1
	v_mfma_f32_16x16x32_bf16 v[60:63], v[152:155], v[184:187], v[60:63]
	v_mfma_f32_16x16x32_bf16 v[56:59], v[160:163], v[184:187], v[56:59]
	v_mfma_f32_16x16x32_bf16 v[44:47], v[152:155], v[192:195], v[44:47]
	v_mfma_f32_16x16x32_bf16 v[40:43], v[160:163], v[192:195], v[40:43]
	v_mfma_f32_16x16x32_bf16 v[28:31], v[152:155], v[200:203], v[28:31]
	v_mfma_f32_16x16x32_bf16 v[24:27], v[160:163], v[200:203], v[24:27]
	v_mfma_f32_16x16x32_bf16 v[12:15], v[152:155], v[208:211], v[12:15]
	v_mfma_f32_16x16x32_bf16 v[8:11], v[160:163], v[208:211], v[8:11]
	v_mfma_f32_16x16x32_bf16 v[60:63], v[156:159], v[188:191], v[60:63]
	v_mfma_f32_16x16x32_bf16 v[56:59], v[164:167], v[188:191], v[56:59]
	v_mfma_f32_16x16x32_bf16 v[44:47], v[156:159], v[196:199], v[44:47]
	v_mfma_f32_16x16x32_bf16 v[40:43], v[164:167], v[196:199], v[40:43]
	v_mfma_f32_16x16x32_bf16 v[28:31], v[156:159], v[204:207], v[28:31]
	v_mfma_f32_16x16x32_bf16 v[24:27], v[164:167], v[204:207], v[24:27]
	v_mfma_f32_16x16x32_bf16 v[12:15], v[156:159], v[212:215], v[12:15]
	v_mfma_f32_16x16x32_bf16 v[8:11], v[164:167], v[212:215], v[8:11]
	v_mfma_f32_16x16x32_bf16 v[52:55], v[168:171], v[184:187], v[52:55]
	v_mfma_f32_16x16x32_bf16 v[48:51], v[176:179], v[184:187], v[48:51]
	v_mfma_f32_16x16x32_bf16 v[36:39], v[168:171], v[192:195], v[36:39]
	v_mfma_f32_16x16x32_bf16 v[32:35], v[176:179], v[192:195], v[32:35]
	v_mfma_f32_16x16x32_bf16 v[20:23], v[168:171], v[200:203], v[20:23]
	v_mfma_f32_16x16x32_bf16 v[16:19], v[176:179], v[200:203], v[16:19]
	v_mfma_f32_16x16x32_bf16 v[4:7], v[168:171], v[208:211], v[4:7]
	v_mfma_f32_16x16x32_bf16 v[0:3], v[176:179], v[208:211], v[0:3]
	v_mfma_f32_16x16x32_bf16 v[52:55], v[172:175], v[188:191], v[52:55]
	v_mfma_f32_16x16x32_bf16 v[48:51], v[180:183], v[188:191], v[48:51]
	v_mfma_f32_16x16x32_bf16 v[36:39], v[172:175], v[196:199], v[36:39]
	v_mfma_f32_16x16x32_bf16 v[32:35], v[180:183], v[196:199], v[32:35]
	v_mfma_f32_16x16x32_bf16 v[20:23], v[172:175], v[204:207], v[20:23]
	v_mfma_f32_16x16x32_bf16 v[16:19], v[180:183], v[204:207], v[16:19]
	v_mfma_f32_16x16x32_bf16 v[4:7], v[172:175], v[212:215], v[4:7]
	v_mfma_f32_16x16x32_bf16 v[0:3], v[180:183], v[212:215], v[0:3]
	s_setprio 0
	s_barrier
	s_add_i32 s63, s63, 2
	s_add_u32 s64, s64, 0x100
	s_addc_u32 s65, s65, 0
	s_add_u32 s53, s53, 0x100
	s_addc_u32 s61, s61, 0
	s_cmp_gt_u32 s63, 29
	s_cbranch_scc0 .LBB0_292
	s_and_b64 vcc, exec, s[14:15]
	s_cbranch_vccz .LBB0_295
	s_barrier

; #define PG8_STAGE(bufoff, gbase, voff) do { _Pragma("unroll") for (int _i = 0; _i < 2; ++_i) \
;         __builtin_amdgcn_global_load_lds((const unsigned*)((const char*)(gbase) + (voff)[_i]), (LAS unsigned*)(lds + (bufoff) + ldsw + _i * 8192), 16, 0, 0); } while (0)
; #define PG8_LDA(dst, b, h) do { _Pragma("unroll") for (int m = 0; m < 4; ++m) _Pragma("unroll") for (int k = 0; k < 2; ++k) dst[m][k] = *(const LAS bf16x8*)(lds + PG8_SA(b, h) + aoff + m * 2048 + k * 1024); } while (0)
; #define PG8_LDB(dst, b, h) do { _Pragma("unroll") for (int n = 0; n < 2; ++n) _Pragma("unroll") for (int k = 0; k < 2; ++k) dst[n][k] = *(const LAS bf16x8*)(lds + PG8_SB(b, h) + boff + n * 2048 + k * 1024); } while (0)
; #define PG8_MMA(ai, bj, At, Bt) do { __builtin_amdgcn_s_setprio(1); _Pragma("unroll") for (int m = 0; m < 4; ++m) _Pragma("unroll") for (int n = 0; n < 2; ++n) _Pragma("unroll") for (int k = 0; k < 2; ++k) \
;         acc[ai][bj][m][n] = __builtin_amdgcn_mfma_f32_16x16x32_bf16(Bt[n][k], At[m][k], acc[ai][bj][m][n], 0, 0, 0); __builtin_amdgcn_s_setprio(0); } while (0)
; #define PG8_WAIT_V(n) asm volatile("s_waitcnt vmcnt(" #n ")" ::: "memory")
; #define PG8_WAIT_L(n) asm volatile("s_waitcnt lgkmcnt(" #n ")" ::: "memory")
; #define PG8_BAR __builtin_amdgcn_s_barrier()
; #define PG8_SCHED __builtin_amdgcn_sched_barrier(0)
; template <class Desc, class Epi>
; DI void gemm_phase(LAS unsigned char* lds, const Desc& D, const Epi& E, int wv) {
;     ...
;             PG8_LDB(B0, 0, 0); PG8_LDB(B1, 0, 1); PG8_SCHED; PG8_LDA(At, 0, 0); PG8_STAGE(PG8_SA(1, 1), a1 + hstepA, voffA);
;             PG8_WAIT_V(8); PG8_WAIT_L(0); PG8_BAR; PG8_MMA(0, 0, At, B0); PG8_MMA(0, 1, At, B1); PG8_BAR; PG8_SCHED;
;             PG8_LDA(At, 0, 1); PG8_STAGE(PG8_SB(0, 0), b2, voffB); PG8_STAGE(PG8_SB(0, 1), b2 + hstepB, voffB); PG8_STAGE(PG8_SA(0, 0), a2, voffA);
;             PG8_WAIT_V(8); PG8_WAIT_L(0); PG8_BAR; PG8_MMA(1, 0, At, B0); PG8_MMA(1, 1, At, B1); PG8_BAR; PG8_SCHED;
.LBB0_339:
	ds_read_b128 v[142:145], v151
	ds_read_b128 v[146:149], v151 offset:1024
	ds_read_b128 v[158:161], v151 offset:2048
	ds_read_b128 v[162:165], v151 offset:3072
	ds_read_b128 v[166:169], v152
	ds_read_b128 v[170:173], v152 offset:1024
	ds_read_b128 v[174:177], v152 offset:2048
	ds_read_b128 v[178:181], v152 offset:3072
	s_add_u32 s8, s6, 0xfffe0080
	s_addc_u32 s9, s7, -1
	s_cmp_eq_u32 s67, 4
	s_cselect_b32 s65, s61, s9
	s_cselect_b32 s64, s60, s8
	s_cselect_b32 s9, s63, s66
	s_cselect_b32 s8, s62, s53
	v_lshl_add_u64 v[214:215], s[6:7], 0, v[138:139]
	s_add_i32 m0, s3, 0xc000
	ds_read_b128 v[182:185], v153
	ds_read_b128 v[186:189], v153 offset:1024
	ds_read_b128 v[190:193], v153 offset:2048
	ds_read_b128 v[194:197], v153 offset:3072
	ds_read_b128 v[198:201], v153 offset:4096
	ds_read_b128 v[202:205], v153 offset:5120
	ds_read_b128 v[206:209], v153 offset:6144
	ds_read_b128 v[210:213], v153 offset:7168
	global_load_lds_dwordx4 v[214:215], off
	s_add_i32 m0, s3, 0xe000
	v_lshl_add_u64 v[214:215], s[6:7], 0, v[140:141]
	global_load_lds_dwordx4 v[214:215], off
	s_waitcnt vmcnt(8) lgkmcnt(0)
	s_barrier
	s_setprio 1
	v_mfma_f32_16x16x32_bf16 v[124:127], v[142:145], v[182:185], v[124:127]
	v_mfma_f32_16x16x32_bf16 v[120:123], v[158:161], v[182:185], v[120:123]
	v_mfma_f32_16x16x32_bf16 v[108:111], v[142:145], v[190:193], v[108:111]
	v_mfma_f32_16x16x32_bf16 v[104:107], v[158:161], v[190:193], v[104:107]
	v_mfma_f32_16x16x32_bf16 v[92:95], v[142:145], v[198:201], v[92:95]
	v_mfma_f32_16x16x32_bf16 v[88:91], v[158:161], v[198:201], v[88:91]
	v_mfma_f32_16x16x32_bf16 v[76:79], v[142:145], v[206:209], v[76:79]
	v_mfma_f32_16x16x32_bf16 v[72:75], v[158:161], v[206:209], v[72:75]
	v_mfma_f32_16x16x32_bf16 v[124:127], v[146:149], v[186:189], v[124:127]
	v_mfma_f32_16x16x32_bf16 v[120:123], v[162:165], v[186:189], v[120:123]
	v_mfma_f32_16x16x32_bf16 v[108:111], v[146:149], v[194:197], v[108:111]
	v_mfma_f32_16x16x32_bf16 v[104:107], v[162:165], v[194:197], v[104:107]
	v_mfma_f32_16x16x32_bf16 v[92:95], v[146:149], v[202:205], v[92:95]
	v_mfma_f32_16x16x32_bf16 v[88:91], v[162:165], v[202:205], v[88:91]
	v_mfma_f32_16x16x32_bf16 v[76:79], v[146:149], v[210:213], v[76:79]
	v_mfma_f32_16x16x32_bf16 v[72:75], v[162:165], v[210:213], v[72:75]
	v_mfma_f32_16x16x32_bf16 v[116:119], v[166:169], v[182:185], v[116:119]
	v_mfma_f32_16x16x32_bf16 v[112:115], v[174:177], v[182:185], v[112:115]
	v_mfma_f32_16x16x32_bf16 v[100:103], v[166:169], v[190:193], v[100:103]
	v_mfma_f32_16x16x32_bf16 v[96:99], v[174:177], v[190:193], v[96:99]
	v_mfma_f32_16x16x32_bf16 v[84:87], v[166:169], v[198:201], v[84:87]
	v_mfma_f32_16x16x32_bf16 v[80:83], v[174:177], v[198:201], v[80:83]
	v_mfma_f32_16x16x32_bf16 v[68:71], v[166:169], v[206:209], v[68:71]
	v_mfma_f32_16x16x32_bf16 v[64:67], v[174:177], v[206:209], v[64:67]
	v_mfma_f32_16x16x32_bf16 v[116:119], v[170:173], v[186:189], v[116:119]
	v_mfma_f32_16x16x32_bf16 v[112:115], v[178:181], v[186:189], v[112:115]
	v_mfma_f32_16x16x32_bf16 v[100:103], v[170:173], v[194:197], v[100:103]
	v_mfma_f32_16x16x32_bf16 v[96:99], v[178:181], v[194:197], v[96:99]
	v_mfma_f32_16x16x32_bf16 v[84:87], v[170:173], v[202:205], v[84:87]
	v_mfma_f32_16x16x32_bf16 v[80:83], v[178:181], v[202:205], v[80:83]
	v_mfma_f32_16x16x32_bf16 v[68:71], v[170:173], v[210:213], v[68:71]
	v_mfma_f32_16x16x32_bf16 v[64:67], v[178:181], v[210:213], v[64:67]
	s_setprio 0
	s_barrier
	s_add_i32 s68, s41, s2
	v_lshl_add_u64 v[214:215], s[8:9], 0, v[130:131]
	s_mov_b32 m0, s68
	ds_read_b128 v[182:185], v153 offset:16384
	ds_read_b128 v[186:189], v153 offset:17408
	ds_read_b128 v[190:193], v153 offset:18432
	ds_read_b128 v[194:197], v153 offset:19456
	ds_read_b128 v[198:201], v153 offset:20480
	ds_read_b128 v[202:205], v153 offset:21504
	ds_read_b128 v[206:209], v153 offset:22528
	ds_read_b128 v[210:213], v153 offset:23552
	global_load_lds_dwordx4 v[214:215], off
	s_add_i32 m0, s68, 0x2000
	s_add_u32 s68, s8, 0x80000
	v_lshl_add_u64 v[216:217], s[8:9], 0, v[134:135]
	s_addc_u32 s69, s9, 0
	s_add_i32 s70, s42, s2
	global_load_lds_dwordx4 v[216:217], off
	v_lshl_add_u64 v[218:219], s[68:69], 0, v[130:131]
	s_mov_b32 m0, s70
	v_lshl_add_u64 v[220:221], s[64:65], 0, v[132:133]
	global_load_lds_dwordx4 v[218:219], off
	s_add_i32 m0, s70, 0x2000
	v_lshl_add_u64 v[218:219], s[68:69], 0, v[134:135]
	global_load_lds_dwordx4 v[218:219], off
	s_mov_b32 m0, s3
	v_lshl_add_u64 v[218:219], s[64:65], 0, v[128:129]
	global_load_lds_dwordx4 v[218:219], off
	s_mov_b32 m0, s28
	s_nop 0
	global_load_lds_dwordx4 v[220:221], off
	s_waitcnt vmcnt(8) lgkmcnt(0)
	s_barrier
; #define PG8_STAGE(bufoff, gbase, voff) do { _Pragma("unroll") for (int _i = 0; _i < 2; ++_i) \
;         __builtin_amdgcn_global_load_lds((const unsigned*)((const char*)(gbase) + (voff)[_i]), (LAS unsigned*)(lds + (bufoff) + ldsw + _i * 8192), 16, 0, 0); } while (0)
; #define PG8_LDA(dst, b, h) do { _Pragma("unroll") for (int m = 0; m < 4; ++m) _Pragma("unroll") for (int k = 0; k < 2; ++k) dst[m][k] = *(const LAS bf16x8*)(lds + PG8_SA(b, h) + aoff + m * 2048 + k * 1024); } while (0)
; #define PG8_LDB(dst, b, h) do { _Pragma("unroll") for (int n = 0; n < 2; ++n) _Pragma("unroll") for (int k = 0; k < 2; ++k) dst[n][k] = *(const LAS bf16x8*)(lds + PG8_SB(b, h) + boff + n * 2048 + k * 1024); } while (0)
; #define PG8_MMA(ai, bj, At, Bt) do { __builtin_amdgcn_s_setprio(1); _Pragma("unroll") for (int m = 0; m < 4; ++m) _Pragma("unroll") for (int n = 0; n < 2; ++n) _Pragma("unroll") for (int k = 0; k < 2; ++k) \
;         acc[ai][bj][m][n] = __builtin_amdgcn_mfma_f32_16x16x32_bf16(Bt[n][k], At[m][k], acc[ai][bj][m][n], 0, 0, 0); __builtin_amdgcn_s_setprio(0); } while (0)
; #define PG8_WAIT_V(n) asm volatile("s_waitcnt vmcnt(" #n ")" ::: "memory")
; #define PG8_WAIT_L(n) asm volatile("s_waitcnt lgkmcnt(" #n ")" ::: "memory")
; #define PG8_BAR __builtin_amdgcn_s_barrier()
; #define PG8_SCHED __builtin_amdgcn_sched_barrier(0)
; template <class Desc, class Epi>
; DI void gemm_phase(LAS unsigned char* lds, const Desc& D, const Epi& E, int wv) {
;     ...
;             PG8_WAIT_V(8); PG8_WAIT_L(0); PG8_BAR; PG8_MMA(1, 0, At, B0); PG8_MMA(1, 1, At, B1); PG8_BAR; PG8_SCHED;
;             PG8_LDB(B0, 1, 0); PG8_LDB(B1, 1, 1); PG8_SCHED; PG8_LDA(At, 1, 0); PG8_STAGE(PG8_SA(0, 1), a2 + hstepA, voffA);
;             PG8_WAIT_V(8); PG8_WAIT_L(0); PG8_BAR; PG8_MMA(0, 0, At, B0); PG8_MMA(0, 1, At, B1); PG8_BAR; PG8_SCHED;
	s_setprio 1
	v_mfma_f32_16x16x32_bf16 v[60:63], v[142:145], v[182:185], v[60:63]
	v_mfma_f32_16x16x32_bf16 v[56:59], v[158:161], v[182:185], v[56:59]
	v_mfma_f32_16x16x32_bf16 v[44:47], v[142:145], v[190:193], v[44:47]
	v_mfma_f32_16x16x32_bf16 v[40:43], v[158:161], v[190:193], v[40:43]
	v_mfma_f32_16x16x32_bf16 v[28:31], v[142:145], v[198:201], v[28:31]
	v_mfma_f32_16x16x32_bf16 v[24:27], v[158:161], v[198:201], v[24:27]
	v_mfma_f32_16x16x32_bf16 v[12:15], v[142:145], v[206:209], v[12:15]
	v_mfma_f32_16x16x32_bf16 v[8:11], v[158:161], v[206:209], v[8:11]
	v_mfma_f32_16x16x32_bf16 v[60:63], v[146:149], v[186:189], v[60:63]
	v_mfma_f32_16x16x32_bf16 v[56:59], v[162:165], v[186:189], v[56:59]
	v_mfma_f32_16x16x32_bf16 v[44:47], v[146:149], v[194:197], v[44:47]
	v_mfma_f32_16x16x32_bf16 v[40:43], v[162:165], v[194:197], v[40:43]
	v_mfma_f32_16x16x32_bf16 v[28:31], v[146:149], v[202:205], v[28:31]
	v_mfma_f32_16x16x32_bf16 v[24:27], v[162:165], v[202:205], v[24:27]
	v_mfma_f32_16x16x32_bf16 v[12:15], v[146:149], v[210:213], v[12:15]
	v_mfma_f32_16x16x32_bf16 v[8:11], v[162:165], v[210:213], v[8:11]
	v_mfma_f32_16x16x32_bf16 v[52:55], v[166:169], v[182:185], v[52:55]
	v_mfma_f32_16x16x32_bf16 v[48:51], v[174:177], v[182:185], v[48:51]
	v_mfma_f32_16x16x32_bf16 v[36:39], v[166:169], v[190:193], v[36:39]
	v_mfma_f32_16x16x32_bf16 v[32:35], v[174:177], v[190:193], v[32:35]
	v_mfma_f32_16x16x32_bf16 v[20:23], v[166:169], v[198:201], v[20:23]
	v_mfma_f32_16x16x32_bf16 v[16:19], v[174:177], v[198:201], v[16:19]
	v_mfma_f32_16x16x32_bf16 v[4:7], v[166:169], v[206:209], v[4:7]
	v_mfma_f32_16x16x32_bf16 v[0:3], v[174:177], v[206:209], v[0:3]
	v_mfma_f32_16x16x32_bf16 v[52:55], v[170:173], v[186:189], v[52:55]
	v_mfma_f32_16x16x32_bf16 v[48:51], v[178:181], v[186:189], v[48:51]
	v_mfma_f32_16x16x32_bf16 v[36:39], v[170:173], v[194:197], v[36:39]
	v_mfma_f32_16x16x32_bf16 v[32:35], v[178:181], v[194:197], v[32:35]
	v_mfma_f32_16x16x32_bf16 v[20:23], v[170:173], v[202:205], v[20:23]
	v_mfma_f32_16x16x32_bf16 v[16:19], v[178:181], v[202:205], v[16:19]
	v_mfma_f32_16x16x32_bf16 v[4:7], v[170:173], v[210:213], v[4:7]
	v_mfma_f32_16x16x32_bf16 v[0:3], v[178:181], v[210:213], v[0:3]
	s_setprio 0
	s_barrier
	s_add_i32 s68, 0, 0x18000
	v_add_u32_e32 v136, s68, v150
	s_add_i32 s69, 0, 0x1c000
	ds_read_b128 v[142:145], v136
	ds_read_b128 v[146:149], v136 offset:1024
	ds_read_b128 v[158:161], v136 offset:2048
	ds_read_b128 v[162:165], v136 offset:3072
	v_add_u32_e32 v136, s69, v150
	ds_read_b128 v[166:169], v136
	ds_read_b128 v[170:173], v136 offset:1024
	ds_read_b128 v[174:177], v136 offset:2048
	ds_read_b128 v[178:181], v136 offset:3072
	s_add_u32 s64, s64, 0x20000
	s_addc_u32 s65, s65, 0
	s_mov_b32 m0, s29
	v_lshl_add_u64 v[222:223], s[64:65], 0, v[128:129]
	ds_read_b128 v[182:185], v153 offset:32768
	ds_read_b128 v[186:189], v153 offset:33792
	ds_read_b128 v[190:193], v153 offset:34816
	ds_read_b128 v[194:197], v153 offset:35840
	ds_read_b128 v[198:201], v153 offset:36864
	ds_read_b128 v[202:205], v153 offset:37888
	ds_read_b128 v[206:209], v153 offset:38912
	ds_read_b128 v[210:213], v153 offset:39936
	global_load_lds_dwordx4 v[222:223], off
	s_mov_b32 m0, s30
	v_lshl_add_u64 v[222:223], s[64:65], 0, v[132:133]
	global_load_lds_dwordx4 v[222:223], off
	s_waitcnt vmcnt(8) lgkmcnt(0)
	s_barrier
	s_setprio 1
	v_mfma_f32_16x16x32_bf16 v[124:127], v[142:145], v[182:185], v[124:127]
	v_mfma_f32_16x16x32_bf16 v[120:123], v[158:161], v[182:185], v[120:123]
	v_mfma_f32_16x16x32_bf16 v[108:111], v[142:145], v[190:193], v[108:111]
	v_mfma_f32_16x16x32_bf16 v[104:107], v[158:161], v[190:193], v[104:107]
	v_mfma_f32_16x16x32_bf16 v[92:95], v[142:145], v[198:201], v[92:95]
	v_mfma_f32_16x16x32_bf16 v[88:91], v[158:161], v[198:201], v[88:91]
	v_mfma_f32_16x16x32_bf16 v[76:79], v[142:145], v[206:209], v[76:79]
	v_mfma_f32_16x16x32_bf16 v[72:75], v[158:161], v[206:209], v[72:75]
	v_mfma_f32_16x16x32_bf16 v[124:127], v[146:149], v[186:189], v[124:127]
	v_mfma_f32_16x16x32_bf16 v[120:123], v[162:165], v[186:189], v[120:123]
	v_mfma_f32_16x16x32_bf16 v[108:111], v[146:149], v[194:197], v[108:111]
	v_mfma_f32_16x16x32_bf16 v[104:107], v[162:165], v[194:197], v[104:107]
	v_mfma_f32_16x16x32_bf16 v[92:95], v[146:149], v[202:205], v[92:95]
	v_mfma_f32_16x16x32_bf16 v[88:91], v[162:165], v[202:205], v[88:91]
	v_mfma_f32_16x16x32_bf16 v[76:79], v[146:149], v[210:213], v[76:79]
	v_mfma_f32_16x16x32_bf16 v[72:75], v[162:165], v[210:213], v[72:75]
	v_mfma_f32_16x16x32_bf16 v[116:119], v[166:169], v[182:185], v[116:119]
	v_mfma_f32_16x16x32_bf16 v[112:115], v[174:177], v[182:185], v[112:115]
	v_mfma_f32_16x16x32_bf16 v[100:103], v[166:169], v[190:193], v[100:103]
	v_mfma_f32_16x16x32_bf16 v[96:99], v[174:177], v[190:193], v[96:99]
	v_mfma_f32_16x16x32_bf16 v[84:87], v[166:169], v[198:201], v[84:87]
	v_mfma_f32_16x16x32_bf16 v[80:83], v[174:177], v[198:201], v[80:83]
	v_mfma_f32_16x16x32_bf16 v[68:71], v[166:169], v[206:209], v[68:71]
	v_mfma_f32_16x16x32_bf16 v[64:67], v[174:177], v[206:209], v[64:67]
	v_mfma_f32_16x16x32_bf16 v[116:119], v[170:173], v[186:189], v[116:119]
	v_mfma_f32_16x16x32_bf16 v[112:115], v[178:181], v[186:189], v[112:115]
	v_mfma_f32_16x16x32_bf16 v[100:103], v[170:173], v[194:197], v[100:103]
	v_mfma_f32_16x16x32_bf16 v[96:99], v[178:181], v[194:197], v[96:99]
	v_mfma_f32_16x16x32_bf16 v[84:87], v[170:173], v[202:205], v[84:87]
	v_mfma_f32_16x16x32_bf16 v[80:83], v[178:181], v[202:205], v[80:83]
	v_mfma_f32_16x16x32_bf16 v[68:71], v[170:173], v[210:213], v[68:71]
	v_mfma_f32_16x16x32_bf16 v[64:67], v[178:181], v[210:213], v[64:67]
	s_setprio 0
	s_barrier
; #define PG8_STAGE(bufoff, gbase, voff) do { _Pragma("unroll") for (int _i = 0; _i < 2; ++_i) \
;         __builtin_amdgcn_global_load_lds((const unsigned*)((const char*)(gbase) + (voff)[_i]), (LAS unsigned*)(lds + (bufoff) + ldsw + _i * 8192), 16, 0, 0); } while (0)
; #define PG8_LDA(dst, b, h) do { _Pragma("unroll") for (int m = 0; m < 4; ++m) _Pragma("unroll") for (int k = 0; k < 2; ++k) dst[m][k] = *(const LAS bf16x8*)(lds + PG8_SA(b, h) + aoff + m * 2048 + k * 1024); } while (0)
; #define PG8_MMA(ai, bj, At, Bt) do { __builtin_amdgcn_s_setprio(1); _Pragma("unroll") for (int m = 0; m < 4; ++m) _Pragma("unroll") for (int n = 0; n < 2; ++n) _Pragma("unroll") for (int k = 0; k < 2; ++k) \
;         acc[ai][bj][m][n] = __builtin_amdgcn_mfma_f32_16x16x32_bf16(Bt[n][k], At[m][k], acc[ai][bj][m][n], 0, 0, 0); __builtin_amdgcn_s_setprio(0); } while (0)
; #define PG8_WAIT_V(n) asm volatile("s_waitcnt vmcnt(" #n ")" ::: "memory")
; #define PG8_WAIT_L(n) asm volatile("s_waitcnt lgkmcnt(" #n ")" ::: "memory")
; #define PG8_BAR __builtin_amdgcn_s_barrier()
; #define PG8_SCHED __builtin_amdgcn_sched_barrier(0)
; template <class Desc, class Epi>
; DI void gemm_phase(LAS unsigned char* lds, const Desc& D, const Epi& E, int wv) {
;     ...
;             PG8_LDA(At, 1, 1); PG8_STAGE(PG8_SB(1, 0), b3, voffB); PG8_STAGE(PG8_SB(1, 1), b3 + hstepB, voffB); PG8_STAGE(PG8_SA(1, 0), a3, voffA);
;             PG8_WAIT_V(8); PG8_WAIT_L(0); PG8_BAR; PG8_MMA(1, 0, At, B0); PG8_MMA(1, 1, At, B1); PG8_BAR; PG8_SCHED;
;         }
	s_add_i32 s64, s68, s2
	v_lshl_add_u64 v[214:215], v[214:215], 0, s[20:21]
	s_mov_b32 m0, s64
	ds_read_b128 v[182:185], v153 offset:49152
	ds_read_b128 v[186:189], v153 offset:50176
	ds_read_b128 v[190:193], v153 offset:51200
	ds_read_b128 v[194:197], v153 offset:52224
	ds_read_b128 v[198:201], v153 offset:53248
	ds_read_b128 v[202:205], v153 offset:54272
	ds_read_b128 v[206:209], v153 offset:55296
	ds_read_b128 v[210:213], v153 offset:56320
	global_load_lds_dwordx4 v[214:215], off
	s_add_i32 m0, s64, 0x2000
	s_add_u32 s8, s8, 0x80080
	v_lshl_add_u64 v[214:215], v[216:217], 0, s[20:21]
	s_addc_u32 s9, s9, 0
	s_add_i32 s64, s69, s2
	global_load_lds_dwordx4 v[214:215], off
	s_mov_b32 m0, s64
	v_lshl_add_u64 v[214:215], s[8:9], 0, v[130:131]
	global_load_lds_dwordx4 v[214:215], off
	s_add_i32 m0, s64, 0x2000
	v_lshl_add_u64 v[214:215], s[8:9], 0, v[134:135]
	global_load_lds_dwordx4 v[214:215], off
	s_mov_b32 m0, s35
	v_lshl_add_u64 v[214:215], v[218:219], 0, s[20:21]
	global_load_lds_dwordx4 v[214:215], off
	s_mov_b32 m0, s40
	v_lshl_add_u64 v[214:215], v[220:221], 0, s[20:21]
	global_load_lds_dwordx4 v[214:215], off
	s_waitcnt vmcnt(8) lgkmcnt(0)
	s_barrier
	s_setprio 1
	v_mfma_f32_16x16x32_bf16 v[60:63], v[142:145], v[182:185], v[60:63]
	v_mfma_f32_16x16x32_bf16 v[56:59], v[158:161], v[182:185], v[56:59]
	v_mfma_f32_16x16x32_bf16 v[44:47], v[142:145], v[190:193], v[44:47]
	v_mfma_f32_16x16x32_bf16 v[40:43], v[158:161], v[190:193], v[40:43]
	v_mfma_f32_16x16x32_bf16 v[28:31], v[142:145], v[198:201], v[28:31]
	v_mfma_f32_16x16x32_bf16 v[24:27], v[158:161], v[198:201], v[24:27]
	v_mfma_f32_16x16x32_bf16 v[12:15], v[142:145], v[206:209], v[12:15]
	v_mfma_f32_16x16x32_bf16 v[8:11], v[158:161], v[206:209], v[8:11]
	v_mfma_f32_16x16x32_bf16 v[60:63], v[146:149], v[186:189], v[60:63]
	v_mfma_f32_16x16x32_bf16 v[56:59], v[162:165], v[186:189], v[56:59]
	v_mfma_f32_16x16x32_bf16 v[44:47], v[146:149], v[194:197], v[44:47]
	v_mfma_f32_16x16x32_bf16 v[40:43], v[162:165], v[194:197], v[40:43]
	v_mfma_f32_16x16x32_bf16 v[28:31], v[146:149], v[202:205], v[28:31]
	v_mfma_f32_16x16x32_bf16 v[24:27], v[162:165], v[202:205], v[24:27]
	v_mfma_f32_16x16x32_bf16 v[12:15], v[146:149], v[210:213], v[12:15]
	v_mfma_f32_16x16x32_bf16 v[8:11], v[162:165], v[210:213], v[8:11]
	v_mfma_f32_16x16x32_bf16 v[52:55], v[166:169], v[182:185], v[52:55]
	v_mfma_f32_16x16x32_bf16 v[48:51], v[174:177], v[182:185], v[48:51]
	v_mfma_f32_16x16x32_bf16 v[36:39], v[166:169], v[190:193], v[36:39]
	v_mfma_f32_16x16x32_bf16 v[32:35], v[174:177], v[190:193], v[32:35]
	v_mfma_f32_16x16x32_bf16 v[20:23], v[166:169], v[198:201], v[20:23]
	v_mfma_f32_16x16x32_bf16 v[16:19], v[174:177], v[198:201], v[16:19]
	v_mfma_f32_16x16x32_bf16 v[4:7], v[166:169], v[206:209], v[4:7]
	v_mfma_f32_16x16x32_bf16 v[0:3], v[174:177], v[206:209], v[0:3]
	v_mfma_f32_16x16x32_bf16 v[52:55], v[170:173], v[186:189], v[52:55]
	v_mfma_f32_16x16x32_bf16 v[48:51], v[178:181], v[186:189], v[48:51]
	v_mfma_f32_16x16x32_bf16 v[36:39], v[170:173], v[194:197], v[36:39]
	v_mfma_f32_16x16x32_bf16 v[32:35], v[178:181], v[194:197], v[32:35]
	v_mfma_f32_16x16x32_bf16 v[20:23], v[170:173], v[202:205], v[20:23]
	v_mfma_f32_16x16x32_bf16 v[16:19], v[178:181], v[202:205], v[16:19]
	v_mfma_f32_16x16x32_bf16 v[4:7], v[170:173], v[210:213], v[4:7]
	v_mfma_f32_16x16x32_bf16 v[0:3], v[178:181], v[210:213], v[0:3]
	s_setprio 0
	s_barrier
	s_add_i32 s67, s67, 2
	s_add_u32 s6, s6, 0x100
	s_addc_u32 s7, s7, 0
	s_add_u32 s53, s53, 0x100
	s_addc_u32 s66, s66, 0
	s_cmp_gt_u32 s67, 5
	s_cbranch_scc0 .LBB0_339
	s_and_b64 vcc, exec, s[22:23]
	s_cbranch_vccz .LBB0_342
	s_barrier

; #define PG8_STAGE(bufoff, gbase, voff) do { _Pragma("unroll") for (int _i = 0; _i < 2; ++_i) \
;         __builtin_amdgcn_global_load_lds((const unsigned*)((const char*)(gbase) + (voff)[_i]), (LAS unsigned*)(lds + (bufoff) + ldsw + _i * 8192), 16, 0, 0); } while (0)
; #define PG8_LDA(dst, b, h) do { _Pragma("unroll") for (int m = 0; m < 4; ++m) _Pragma("unroll") for (int k = 0; k < 2; ++k) dst[m][k] = *(const LAS bf16x8*)(lds + PG8_SA(b, h) + aoff + m * 2048 + k * 1024); } while (0)
; #define PG8_LDB(dst, b, h) do { _Pragma("unroll") for (int n = 0; n < 2; ++n) _Pragma("unroll") for (int k = 0; k < 2; ++k) dst[n][k] = *(const LAS bf16x8*)(lds + PG8_SB(b, h) + boff + n * 2048 + k * 1024); } while (0)
; #define PG8_MMA(ai, bj, At, Bt) do { __builtin_amdgcn_s_setprio(1); _Pragma("unroll") for (int m = 0; m < 4; ++m) _Pragma("unroll") for (int n = 0; n < 2; ++n) _Pragma("unroll") for (int k = 0; k < 2; ++k) \
;         acc[ai][bj][m][n] = __builtin_amdgcn_mfma_f32_16x16x32_bf16(Bt[n][k], At[m][k], acc[ai][bj][m][n], 0, 0, 0); __builtin_amdgcn_s_setprio(0); } while (0)
; #define PG8_WAIT_V(n) asm volatile("s_waitcnt vmcnt(" #n ")" ::: "memory")
; #define PG8_WAIT_L(n) asm volatile("s_waitcnt lgkmcnt(" #n ")" ::: "memory")
; #define PG8_BAR __builtin_amdgcn_s_barrier()
; #define PG8_SCHED __builtin_amdgcn_sched_barrier(0)
; template <class Desc, class Epi>
; DI void gemm_phase(LAS unsigned char* lds, const Desc& D, const Epi& E, int wv) {
;     ...
;             PG8_LDB(B0, 0, 0); PG8_LDB(B1, 0, 1); PG8_SCHED; PG8_LDA(At, 0, 0); PG8_STAGE(PG8_SA(1, 1), a1 + hstepA, voffA);
;             PG8_WAIT_V(8); PG8_WAIT_L(0); PG8_BAR; PG8_MMA(0, 0, At, B0); PG8_MMA(0, 1, At, B1); PG8_BAR; PG8_SCHED;
;             PG8_LDA(At, 0, 1); PG8_STAGE(PG8_SB(0, 0), b2, voffB); PG8_STAGE(PG8_SB(0, 1), b2 + hstepB, voffB); PG8_STAGE(PG8_SA(0, 0), a2, voffA);
;             PG8_WAIT_V(8); PG8_WAIT_L(0); PG8_BAR; PG8_MMA(1, 0, At, B0); PG8_MMA(1, 1, At, B1); PG8_BAR; PG8_SCHED;
.LBB0_581:
	ds_read_b128 v[128:131], v185
	ds_read_b128 v[132:135], v185 offset:1024
	ds_read_b128 v[150:153], v185 offset:2048
	ds_read_b128 v[154:157], v185 offset:3072
	ds_read_b128 v[158:161], v186
	ds_read_b128 v[162:165], v186 offset:1024
	ds_read_b128 v[166:169], v186 offset:2048
	ds_read_b128 v[170:173], v186 offset:3072
	s_add_u32 s49, s66, 0xfff00080
	s_addc_u32 s50, s67, -1
	s_cmp_eq_u32 s48, 28
	s_cselect_b32 s71, s19, s50
	s_cselect_b32 s70, s18, s49
	s_cselect_b32 s69, s21, s47
	s_cselect_b32 s68, s20, s1
	v_lshl_add_u64 v[182:183], s[66:67], 0, v[146:147]
	s_add_i32 m0, s3, 0xc000
	ds_read_b128 v[174:177], v187
	ds_read_b128 v[178:181], v187 offset:1024
	ds_read_b128 v[190:193], v187 offset:2048
	ds_read_b128 v[194:197], v187 offset:3072
	ds_read_b128 v[198:201], v187 offset:4096
	ds_read_b128 v[202:205], v187 offset:5120
	ds_read_b128 v[206:209], v187 offset:6144
	ds_read_b128 v[210:213], v187 offset:7168
	global_load_lds_dwordx4 v[182:183], off
	s_add_i32 m0, s3, 0xe000
	v_lshl_add_u64 v[182:183], s[66:67], 0, v[148:149]
	global_load_lds_dwordx4 v[182:183], off
	s_waitcnt vmcnt(8) lgkmcnt(0)
	s_barrier
	s_setprio 1
	v_mfma_f32_16x16x32_bf16 v[124:127], v[128:131], v[174:177], v[124:127]
	v_mfma_f32_16x16x32_bf16 v[120:123], v[150:153], v[174:177], v[120:123]
	v_mfma_f32_16x16x32_bf16 v[108:111], v[128:131], v[190:193], v[108:111]
	v_mfma_f32_16x16x32_bf16 v[104:107], v[150:153], v[190:193], v[104:107]
	v_mfma_f32_16x16x32_bf16 v[92:95], v[128:131], v[198:201], v[92:95]
	v_mfma_f32_16x16x32_bf16 v[88:91], v[150:153], v[198:201], v[88:91]
	v_mfma_f32_16x16x32_bf16 v[76:79], v[128:131], v[206:209], v[76:79]
	v_mfma_f32_16x16x32_bf16 v[72:75], v[150:153], v[206:209], v[72:75]
	v_mfma_f32_16x16x32_bf16 v[124:127], v[132:135], v[178:181], v[124:127]
	v_mfma_f32_16x16x32_bf16 v[120:123], v[154:157], v[178:181], v[120:123]
	v_mfma_f32_16x16x32_bf16 v[108:111], v[132:135], v[194:197], v[108:111]
	v_mfma_f32_16x16x32_bf16 v[104:107], v[154:157], v[194:197], v[104:107]
	v_mfma_f32_16x16x32_bf16 v[92:95], v[132:135], v[202:205], v[92:95]
	v_mfma_f32_16x16x32_bf16 v[88:91], v[154:157], v[202:205], v[88:91]
	v_mfma_f32_16x16x32_bf16 v[76:79], v[132:135], v[210:213], v[76:79]
	v_mfma_f32_16x16x32_bf16 v[72:75], v[154:157], v[210:213], v[72:75]
	v_mfma_f32_16x16x32_bf16 v[116:119], v[158:161], v[174:177], v[116:119]
	v_mfma_f32_16x16x32_bf16 v[112:115], v[166:169], v[174:177], v[112:115]
	v_mfma_f32_16x16x32_bf16 v[100:103], v[158:161], v[190:193], v[100:103]
	v_mfma_f32_16x16x32_bf16 v[96:99], v[166:169], v[190:193], v[96:99]
	v_mfma_f32_16x16x32_bf16 v[84:87], v[158:161], v[198:201], v[84:87]
	v_mfma_f32_16x16x32_bf16 v[80:83], v[166:169], v[198:201], v[80:83]
	v_mfma_f32_16x16x32_bf16 v[68:71], v[158:161], v[206:209], v[68:71]
	v_mfma_f32_16x16x32_bf16 v[64:67], v[166:169], v[206:209], v[64:67]
	v_mfma_f32_16x16x32_bf16 v[116:119], v[162:165], v[178:181], v[116:119]
	v_mfma_f32_16x16x32_bf16 v[112:115], v[170:173], v[178:181], v[112:115]
	v_mfma_f32_16x16x32_bf16 v[100:103], v[162:165], v[194:197], v[100:103]
	v_mfma_f32_16x16x32_bf16 v[96:99], v[170:173], v[194:197], v[96:99]
	v_mfma_f32_16x16x32_bf16 v[84:87], v[162:165], v[202:205], v[84:87]
	v_mfma_f32_16x16x32_bf16 v[80:83], v[170:173], v[202:205], v[80:83]
	v_mfma_f32_16x16x32_bf16 v[68:71], v[162:165], v[210:213], v[68:71]
	v_mfma_f32_16x16x32_bf16 v[64:67], v[170:173], v[210:213], v[64:67]
	s_setprio 0
	s_barrier
	s_add_i32 s49, s42, s2
	v_lshl_add_u64 v[182:183], s[68:69], 0, v[140:141]
	s_mov_b32 m0, s49
	ds_read_b128 v[174:177], v187 offset:16384
	ds_read_b128 v[178:181], v187 offset:17408
	ds_read_b128 v[190:193], v187 offset:18432
	ds_read_b128 v[194:197], v187 offset:19456
	ds_read_b128 v[198:201], v187 offset:20480
	ds_read_b128 v[202:205], v187 offset:21504
	ds_read_b128 v[206:209], v187 offset:22528
	ds_read_b128 v[210:213], v187 offset:23552
	global_load_lds_dwordx4 v[182:183], off
	s_add_i32 m0, s49, 0x2000
	s_add_u32 s50, s68, 0x100000
	v_lshl_add_u64 v[214:215], s[68:69], 0, v[136:137]
	s_addc_u32 s51, s69, 0
	s_add_i32 s49, s43, s2
	global_load_lds_dwordx4 v[214:215], off
	v_lshl_add_u64 v[216:217], s[50:51], 0, v[140:141]
	s_mov_b32 m0, s49
	v_lshl_add_u64 v[218:219], s[70:71], 0, v[138:139]
	global_load_lds_dwordx4 v[216:217], off
	s_add_i32 m0, s49, 0x2000
	v_lshl_add_u64 v[216:217], s[50:51], 0, v[136:137]
	global_load_lds_dwordx4 v[216:217], off
	s_mov_b32 m0, s3
	v_lshl_add_u64 v[216:217], s[70:71], 0, v[142:143]
	global_load_lds_dwordx4 v[216:217], off
	s_mov_b32 m0, s28
	s_nop 0
	global_load_lds_dwordx4 v[218:219], off
	s_waitcnt vmcnt(8) lgkmcnt(0)
	s_barrier
; #define PG8_STAGE(bufoff, gbase, voff) do { _Pragma("unroll") for (int _i = 0; _i < 2; ++_i) \
;         __builtin_amdgcn_global_load_lds((const unsigned*)((const char*)(gbase) + (voff)[_i]), (LAS unsigned*)(lds + (bufoff) + ldsw + _i * 8192), 16, 0, 0); } while (0)
; #define PG8_LDA(dst, b, h) do { _Pragma("unroll") for (int m = 0; m < 4; ++m) _Pragma("unroll") for (int k = 0; k < 2; ++k) dst[m][k] = *(const LAS bf16x8*)(lds + PG8_SA(b, h) + aoff + m * 2048 + k * 1024); } while (0)
; #define PG8_LDB(dst, b, h) do { _Pragma("unroll") for (int n = 0; n < 2; ++n) _Pragma("unroll") for (int k = 0; k < 2; ++k) dst[n][k] = *(const LAS bf16x8*)(lds + PG8_SB(b, h) + boff + n * 2048 + k * 1024); } while (0)
; #define PG8_MMA(ai, bj, At, Bt) do { __builtin_amdgcn_s_setprio(1); _Pragma("unroll") for (int m = 0; m < 4; ++m) _Pragma("unroll") for (int n = 0; n < 2; ++n) _Pragma("unroll") for (int k = 0; k < 2; ++k) \
;         acc[ai][bj][m][n] = __builtin_amdgcn_mfma_f32_16x16x32_bf16(Bt[n][k], At[m][k], acc[ai][bj][m][n], 0, 0, 0); __builtin_amdgcn_s_setprio(0); } while (0)
; #define PG8_WAIT_V(n) asm volatile("s_waitcnt vmcnt(" #n ")" ::: "memory")
; #define PG8_WAIT_L(n) asm volatile("s_waitcnt lgkmcnt(" #n ")" ::: "memory")
; #define PG8_BAR __builtin_amdgcn_s_barrier()
; #define PG8_SCHED __builtin_amdgcn_sched_barrier(0)
; template <class Desc, class Epi>
; DI void gemm_phase(LAS unsigned char* lds, const Desc& D, const Epi& E, int wv) {
;     ...
;             PG8_WAIT_V(8); PG8_WAIT_L(0); PG8_BAR; PG8_MMA(1, 0, At, B0); PG8_MMA(1, 1, At, B1); PG8_BAR; PG8_SCHED;
;             PG8_LDB(B0, 1, 0); PG8_LDB(B1, 1, 1); PG8_SCHED; PG8_LDA(At, 1, 0); PG8_STAGE(PG8_SA(0, 1), a2 + hstepA, voffA);
;             PG8_WAIT_V(8); PG8_WAIT_L(0); PG8_BAR; PG8_MMA(0, 0, At, B0); PG8_MMA(0, 1, At, B1); PG8_BAR; PG8_SCHED;
	s_setprio 1
	v_mfma_f32_16x16x32_bf16 v[60:63], v[128:131], v[174:177], v[60:63]
	v_mfma_f32_16x16x32_bf16 v[56:59], v[150:153], v[174:177], v[56:59]
	v_mfma_f32_16x16x32_bf16 v[44:47], v[128:131], v[190:193], v[44:47]
	v_mfma_f32_16x16x32_bf16 v[40:43], v[150:153], v[190:193], v[40:43]
	v_mfma_f32_16x16x32_bf16 v[28:31], v[128:131], v[198:201], v[28:31]
	v_mfma_f32_16x16x32_bf16 v[24:27], v[150:153], v[198:201], v[24:27]
	v_mfma_f32_16x16x32_bf16 v[12:15], v[128:131], v[206:209], v[12:15]
	v_mfma_f32_16x16x32_bf16 v[8:11], v[150:153], v[206:209], v[8:11]
	v_mfma_f32_16x16x32_bf16 v[60:63], v[132:135], v[178:181], v[60:63]
	v_mfma_f32_16x16x32_bf16 v[56:59], v[154:157], v[178:181], v[56:59]
	v_mfma_f32_16x16x32_bf16 v[44:47], v[132:135], v[194:197], v[44:47]
	v_mfma_f32_16x16x32_bf16 v[40:43], v[154:157], v[194:197], v[40:43]
	v_mfma_f32_16x16x32_bf16 v[28:31], v[132:135], v[202:205], v[28:31]
	v_mfma_f32_16x16x32_bf16 v[24:27], v[154:157], v[202:205], v[24:27]
	v_mfma_f32_16x16x32_bf16 v[12:15], v[132:135], v[210:213], v[12:15]
	v_mfma_f32_16x16x32_bf16 v[8:11], v[154:157], v[210:213], v[8:11]
	v_mfma_f32_16x16x32_bf16 v[52:55], v[158:161], v[174:177], v[52:55]
	v_mfma_f32_16x16x32_bf16 v[48:51], v[166:169], v[174:177], v[48:51]
	v_mfma_f32_16x16x32_bf16 v[36:39], v[158:161], v[190:193], v[36:39]
	v_mfma_f32_16x16x32_bf16 v[32:35], v[166:169], v[190:193], v[32:35]
	v_mfma_f32_16x16x32_bf16 v[20:23], v[158:161], v[198:201], v[20:23]
	v_mfma_f32_16x16x32_bf16 v[16:19], v[166:169], v[198:201], v[16:19]
	v_mfma_f32_16x16x32_bf16 v[4:7], v[158:161], v[206:209], v[4:7]
	v_mfma_f32_16x16x32_bf16 v[0:3], v[166:169], v[206:209], v[0:3]
	v_mfma_f32_16x16x32_bf16 v[52:55], v[162:165], v[178:181], v[52:55]
	v_mfma_f32_16x16x32_bf16 v[48:51], v[170:173], v[178:181], v[48:51]
	v_mfma_f32_16x16x32_bf16 v[36:39], v[162:165], v[194:197], v[36:39]
	v_mfma_f32_16x16x32_bf16 v[32:35], v[170:173], v[194:197], v[32:35]
	v_mfma_f32_16x16x32_bf16 v[20:23], v[162:165], v[202:205], v[20:23]
	v_mfma_f32_16x16x32_bf16 v[16:19], v[170:173], v[202:205], v[16:19]
	v_mfma_f32_16x16x32_bf16 v[4:7], v[162:165], v[210:213], v[4:7]
	v_mfma_f32_16x16x32_bf16 v[0:3], v[170:173], v[210:213], v[0:3]
	s_setprio 0
	s_barrier
	s_add_i32 s49, 0, 0x18000
	v_add_u32_e32 v144, s49, v184
	s_add_i32 s52, 0, 0x1c000
	ds_read_b128 v[128:131], v144
	ds_read_b128 v[132:135], v144 offset:1024
	ds_read_b128 v[150:153], v144 offset:2048
	ds_read_b128 v[154:157], v144 offset:3072
	v_add_u32_e32 v144, s52, v184
	ds_read_b128 v[158:161], v144
	ds_read_b128 v[162:165], v144 offset:1024
	ds_read_b128 v[166:169], v144 offset:2048
	ds_read_b128 v[170:173], v144 offset:3072
	s_add_u32 s50, s70, 0x100000
	s_addc_u32 s51, s71, 0
	s_mov_b32 m0, s29
	v_lshl_add_u64 v[220:221], s[50:51], 0, v[142:143]
	ds_read_b128 v[174:177], v187 offset:32768
	ds_read_b128 v[178:181], v187 offset:33792
	ds_read_b128 v[190:193], v187 offset:34816
	ds_read_b128 v[194:197], v187 offset:35840
	ds_read_b128 v[198:201], v187 offset:36864
	ds_read_b128 v[202:205], v187 offset:37888
	ds_read_b128 v[206:209], v187 offset:38912
	ds_read_b128 v[210:213], v187 offset:39936
	global_load_lds_dwordx4 v[220:221], off
	s_mov_b32 m0, s30
	v_lshl_add_u64 v[220:221], s[50:51], 0, v[138:139]
	global_load_lds_dwordx4 v[220:221], off
	s_waitcnt vmcnt(8) lgkmcnt(0)
	s_barrier
	s_setprio 1
	v_mfma_f32_16x16x32_bf16 v[124:127], v[128:131], v[174:177], v[124:127]
	v_mfma_f32_16x16x32_bf16 v[120:123], v[150:153], v[174:177], v[120:123]
	v_mfma_f32_16x16x32_bf16 v[108:111], v[128:131], v[190:193], v[108:111]
	v_mfma_f32_16x16x32_bf16 v[104:107], v[150:153], v[190:193], v[104:107]
	v_mfma_f32_16x16x32_bf16 v[92:95], v[128:131], v[198:201], v[92:95]
	v_mfma_f32_16x16x32_bf16 v[88:91], v[150:153], v[198:201], v[88:91]
	v_mfma_f32_16x16x32_bf16 v[76:79], v[128:131], v[206:209], v[76:79]
	v_mfma_f32_16x16x32_bf16 v[72:75], v[150:153], v[206:209], v[72:75]
	v_mfma_f32_16x16x32_bf16 v[124:127], v[132:135], v[178:181], v[124:127]
	v_mfma_f32_16x16x32_bf16 v[120:123], v[154:157], v[178:181], v[120:123]
	v_mfma_f32_16x16x32_bf16 v[108:111], v[132:135], v[194:197], v[108:111]
	v_mfma_f32_16x16x32_bf16 v[104:107], v[154:157], v[194:197], v[104:107]
	v_mfma_f32_16x16x32_bf16 v[92:95], v[132:135], v[202:205], v[92:95]
	v_mfma_f32_16x16x32_bf16 v[88:91], v[154:157], v[202:205], v[88:91]
	v_mfma_f32_16x16x32_bf16 v[76:79], v[132:135], v[210:213], v[76:79]
	v_mfma_f32_16x16x32_bf16 v[72:75], v[154:157], v[210:213], v[72:75]
	v_mfma_f32_16x16x32_bf16 v[116:119], v[158:161], v[174:177], v[116:119]
	v_mfma_f32_16x16x32_bf16 v[112:115], v[166:169], v[174:177], v[112:115]
	v_mfma_f32_16x16x32_bf16 v[100:103], v[158:161], v[190:193], v[100:103]
	v_mfma_f32_16x16x32_bf16 v[96:99], v[166:169], v[190:193], v[96:99]
	v_mfma_f32_16x16x32_bf16 v[84:87], v[158:161], v[198:201], v[84:87]
	v_mfma_f32_16x16x32_bf16 v[80:83], v[166:169], v[198:201], v[80:83]
	v_mfma_f32_16x16x32_bf16 v[68:71], v[158:161], v[206:209], v[68:71]
	v_mfma_f32_16x16x32_bf16 v[64:67], v[166:169], v[206:209], v[64:67]
	v_mfma_f32_16x16x32_bf16 v[116:119], v[162:165], v[178:181], v[116:119]
	v_mfma_f32_16x16x32_bf16 v[112:115], v[170:173], v[178:181], v[112:115]
	v_mfma_f32_16x16x32_bf16 v[100:103], v[162:165], v[194:197], v[100:103]
	v_mfma_f32_16x16x32_bf16 v[96:99], v[170:173], v[194:197], v[96:99]
	v_mfma_f32_16x16x32_bf16 v[84:87], v[162:165], v[202:205], v[84:87]
	v_mfma_f32_16x16x32_bf16 v[80:83], v[170:173], v[202:205], v[80:83]
	v_mfma_f32_16x16x32_bf16 v[68:71], v[162:165], v[210:213], v[68:71]
	v_mfma_f32_16x16x32_bf16 v[64:67], v[170:173], v[210:213], v[64:67]
	s_setprio 0
	s_barrier
; #define PG8_STAGE(bufoff, gbase, voff) do { _Pragma("unroll") for (int _i = 0; _i < 2; ++_i) \
;         __builtin_amdgcn_global_load_lds((const unsigned*)((const char*)(gbase) + (voff)[_i]), (LAS unsigned*)(lds + (bufoff) + ldsw + _i * 8192), 16, 0, 0); } while (0)
; #define PG8_LDA(dst, b, h) do { _Pragma("unroll") for (int m = 0; m < 4; ++m) _Pragma("unroll") for (int k = 0; k < 2; ++k) dst[m][k] = *(const LAS bf16x8*)(lds + PG8_SA(b, h) + aoff + m * 2048 + k * 1024); } while (0)
; #define PG8_MMA(ai, bj, At, Bt) do { __builtin_amdgcn_s_setprio(1); _Pragma("unroll") for (int m = 0; m < 4; ++m) _Pragma("unroll") for (int n = 0; n < 2; ++n) _Pragma("unroll") for (int k = 0; k < 2; ++k) \
;         acc[ai][bj][m][n] = __builtin_amdgcn_mfma_f32_16x16x32_bf16(Bt[n][k], At[m][k], acc[ai][bj][m][n], 0, 0, 0); __builtin_amdgcn_s_setprio(0); } while (0)
; #define PG8_WAIT_V(n) asm volatile("s_waitcnt vmcnt(" #n ")" ::: "memory")
; #define PG8_WAIT_L(n) asm volatile("s_waitcnt lgkmcnt(" #n ")" ::: "memory")
; #define PG8_BAR __builtin_amdgcn_s_barrier()
; #define PG8_SCHED __builtin_amdgcn_sched_barrier(0)
; template <class Desc, class Epi>
; DI void gemm_phase(LAS unsigned char* lds, const Desc& D, const Epi& E, int wv) {
;     ...
;             PG8_LDA(At, 1, 1); PG8_STAGE(PG8_SB(1, 0), b3, voffB); PG8_STAGE(PG8_SB(1, 1), b3 + hstepB, voffB); PG8_STAGE(PG8_SA(1, 0), a3, voffA);
;             PG8_WAIT_V(8); PG8_WAIT_L(0); PG8_BAR; PG8_MMA(1, 0, At, B0); PG8_MMA(1, 1, At, B1); PG8_BAR; PG8_SCHED;
;         }
	s_add_i32 s49, s49, s2
	v_lshl_add_u64 v[182:183], v[182:183], 0, s[8:9]
	s_mov_b32 m0, s49
	ds_read_b128 v[174:177], v187 offset:49152
	ds_read_b128 v[178:181], v187 offset:50176
	ds_read_b128 v[190:193], v187 offset:51200
	ds_read_b128 v[194:197], v187 offset:52224
	ds_read_b128 v[198:201], v187 offset:53248
	ds_read_b128 v[202:205], v187 offset:54272
	ds_read_b128 v[206:209], v187 offset:55296
	ds_read_b128 v[210:213], v187 offset:56320
	global_load_lds_dwordx4 v[182:183], off
	s_add_i32 m0, s49, 0x2000
	s_add_u32 s50, s68, 0x100080
	v_lshl_add_u64 v[182:183], v[214:215], 0, s[8:9]
	s_addc_u32 s51, s69, 0
	s_add_i32 s49, s52, s2
	global_load_lds_dwordx4 v[182:183], off
	s_mov_b32 m0, s49
	v_lshl_add_u64 v[182:183], s[50:51], 0, v[140:141]
	global_load_lds_dwordx4 v[182:183], off
	s_add_i32 m0, s49, 0x2000
	v_lshl_add_u64 v[182:183], s[50:51], 0, v[136:137]
	global_load_lds_dwordx4 v[182:183], off
	s_mov_b32 m0, s35
	v_lshl_add_u64 v[182:183], v[216:217], 0, s[8:9]
	global_load_lds_dwordx4 v[182:183], off
	s_mov_b32 m0, s40
	v_lshl_add_u64 v[182:183], v[218:219], 0, s[8:9]
	global_load_lds_dwordx4 v[182:183], off
	s_waitcnt vmcnt(8) lgkmcnt(0)
	s_barrier
	s_setprio 1
	v_mfma_f32_16x16x32_bf16 v[60:63], v[128:131], v[174:177], v[60:63]
	v_mfma_f32_16x16x32_bf16 v[56:59], v[150:153], v[174:177], v[56:59]
	v_mfma_f32_16x16x32_bf16 v[44:47], v[128:131], v[190:193], v[44:47]
	v_mfma_f32_16x16x32_bf16 v[40:43], v[150:153], v[190:193], v[40:43]
	v_mfma_f32_16x16x32_bf16 v[28:31], v[128:131], v[198:201], v[28:31]
	v_mfma_f32_16x16x32_bf16 v[24:27], v[150:153], v[198:201], v[24:27]
	v_mfma_f32_16x16x32_bf16 v[12:15], v[128:131], v[206:209], v[12:15]
	v_mfma_f32_16x16x32_bf16 v[8:11], v[150:153], v[206:209], v[8:11]
	v_mfma_f32_16x16x32_bf16 v[60:63], v[132:135], v[178:181], v[60:63]
	v_mfma_f32_16x16x32_bf16 v[56:59], v[154:157], v[178:181], v[56:59]
	v_mfma_f32_16x16x32_bf16 v[44:47], v[132:135], v[194:197], v[44:47]
	v_mfma_f32_16x16x32_bf16 v[40:43], v[154:157], v[194:197], v[40:43]
	v_mfma_f32_16x16x32_bf16 v[28:31], v[132:135], v[202:205], v[28:31]
	v_mfma_f32_16x16x32_bf16 v[24:27], v[154:157], v[202:205], v[24:27]
	v_mfma_f32_16x16x32_bf16 v[12:15], v[132:135], v[210:213], v[12:15]
	v_mfma_f32_16x16x32_bf16 v[8:11], v[154:157], v[210:213], v[8:11]
	v_mfma_f32_16x16x32_bf16 v[52:55], v[158:161], v[174:177], v[52:55]
	v_mfma_f32_16x16x32_bf16 v[48:51], v[166:169], v[174:177], v[48:51]
	v_mfma_f32_16x16x32_bf16 v[36:39], v[158:161], v[190:193], v[36:39]
	v_mfma_f32_16x16x32_bf16 v[32:35], v[166:169], v[190:193], v[32:35]
	v_mfma_f32_16x16x32_bf16 v[20:23], v[158:161], v[198:201], v[20:23]
	v_mfma_f32_16x16x32_bf16 v[16:19], v[166:169], v[198:201], v[16:19]
	v_mfma_f32_16x16x32_bf16 v[4:7], v[158:161], v[206:209], v[4:7]
	v_mfma_f32_16x16x32_bf16 v[0:3], v[166:169], v[206:209], v[0:3]
	v_mfma_f32_16x16x32_bf16 v[52:55], v[162:165], v[178:181], v[52:55]
	v_mfma_f32_16x16x32_bf16 v[48:51], v[170:173], v[178:181], v[48:51]
	v_mfma_f32_16x16x32_bf16 v[36:39], v[162:165], v[194:197], v[36:39]
	v_mfma_f32_16x16x32_bf16 v[32:35], v[170:173], v[194:197], v[32:35]
	v_mfma_f32_16x16x32_bf16 v[20:23], v[162:165], v[202:205], v[20:23]
	v_mfma_f32_16x16x32_bf16 v[16:19], v[170:173], v[202:205], v[16:19]
	v_mfma_f32_16x16x32_bf16 v[4:7], v[162:165], v[210:213], v[4:7]
	v_mfma_f32_16x16x32_bf16 v[0:3], v[170:173], v[210:213], v[0:3]
	s_setprio 0
	s_barrier
	s_add_i32 s48, s48, 2
	s_add_u32 s66, s66, 0x100
	s_addc_u32 s67, s67, 0
	s_add_u32 s1, s1, 0x100
	s_addc_u32 s47, s47, 0
	s_cmp_gt_u32 s48, 29
	s_cbranch_scc0 .LBB0_581
	s_and_b64 vcc, exec, s[14:15]
	s_cbranch_vccz .LBB0_584
	s_barrier

; #define PG8_STAGE(bufoff, gbase, voff) do { _Pragma("unroll") for (int _i = 0; _i < 2; ++_i) \
;         __builtin_amdgcn_global_load_lds((const unsigned*)((const char*)(gbase) + (voff)[_i]), (LAS unsigned*)(lds + (bufoff) + ldsw + _i * 8192), 16, 0, 0); } while (0)
; #define PG8_LDA(dst, b, h) do { _Pragma("unroll") for (int m = 0; m < 4; ++m) _Pragma("unroll") for (int k = 0; k < 2; ++k) dst[m][k] = *(const LAS bf16x8*)(lds + PG8_SA(b, h) + aoff + m * 2048 + k * 1024); } while (0)
; #define PG8_LDB(dst, b, h) do { _Pragma("unroll") for (int n = 0; n < 2; ++n) _Pragma("unroll") for (int k = 0; k < 2; ++k) dst[n][k] = *(const LAS bf16x8*)(lds + PG8_SB(b, h) + boff + n * 2048 + k * 1024); } while (0)
; #define PG8_MMA(ai, bj, At, Bt) do { __builtin_amdgcn_s_setprio(1); _Pragma("unroll") for (int m = 0; m < 4; ++m) _Pragma("unroll") for (int n = 0; n < 2; ++n) _Pragma("unroll") for (int k = 0; k < 2; ++k) \
;         acc[ai][bj][m][n] = __builtin_amdgcn_mfma_f32_16x16x32_bf16(Bt[n][k], At[m][k], acc[ai][bj][m][n], 0, 0, 0); __builtin_amdgcn_s_setprio(0); } while (0)
; #define PG8_WAIT_V(n) asm volatile("s_waitcnt vmcnt(" #n ")" ::: "memory")
; #define PG8_WAIT_L(n) asm volatile("s_waitcnt lgkmcnt(" #n ")" ::: "memory")
; #define PG8_BAR __builtin_amdgcn_s_barrier()
; #define PG8_SCHED __builtin_amdgcn_sched_barrier(0)
; template <class Desc, class Epi>
; DI void gemm_phase(LAS unsigned char* lds, const Desc& D, const Epi& E, int wv) {
;     ...
;             PG8_LDB(B0, 0, 0); PG8_LDB(B1, 0, 1); PG8_SCHED; PG8_LDA(At, 0, 0); PG8_STAGE(PG8_SA(1, 1), a1 + hstepA, voffA);
;             PG8_WAIT_V(8); PG8_WAIT_L(0); PG8_BAR; PG8_MMA(0, 0, At, B0); PG8_MMA(0, 1, At, B1); PG8_BAR; PG8_SCHED;
;             PG8_LDA(At, 0, 1); PG8_STAGE(PG8_SB(0, 0), b2, voffB); PG8_STAGE(PG8_SB(0, 1), b2 + hstepB, voffB); PG8_STAGE(PG8_SA(0, 0), a2, voffA);
;             PG8_WAIT_V(8); PG8_WAIT_L(0); PG8_BAR; PG8_MMA(1, 0, At, B0); PG8_MMA(1, 1, At, B1); PG8_BAR; PG8_SCHED;
.LBB0_763:
	ds_read_b128 v[150:153], v147
	ds_read_b128 v[154:157], v147 offset:1024
	ds_read_b128 v[158:161], v147 offset:2048
	ds_read_b128 v[162:165], v147 offset:3072
	ds_read_b128 v[166:169], v148
	ds_read_b128 v[170:173], v148 offset:1024
	ds_read_b128 v[174:177], v148 offset:2048
	ds_read_b128 v[178:181], v148 offset:3072
	s_add_u32 s64, s62, 0x100
	s_addc_u32 s65, s63, 0
	s_add_u32 s50, s21, s62
	s_addc_u32 s51, s23, s63
	s_cmp_eq_u32 s49, 4
	s_cselect_b32 s53, 0, s64
	s_cselect_b32 s52, 0, s65
	s_cselect_b32 s66, s18, s50
	s_cselect_b32 s67, s19, s51
	s_add_u32 s68, s4, s53
	s_addc_u32 s69, s5, s52
	v_lshl_add_u64 v[144:145], v[136:137], 0, s[62:63]
	s_add_i32 m0, s3, 0xc000
	ds_read_b128 v[182:185], v149
	ds_read_b128 v[186:189], v149 offset:1024
	ds_read_b128 v[190:193], v149 offset:2048
	ds_read_b128 v[194:197], v149 offset:3072
	ds_read_b128 v[198:201], v149 offset:4096
	ds_read_b128 v[202:205], v149 offset:5120
	ds_read_b128 v[206:209], v149 offset:6144
	ds_read_b128 v[210:213], v149 offset:7168
	global_load_lds_dwordx4 v[144:145], off
	s_add_i32 m0, s3, 0xe000
	v_lshl_add_u64 v[144:145], v[138:139], 0, s[62:63]
	global_load_lds_dwordx4 v[144:145], off
	s_waitcnt vmcnt(8) lgkmcnt(0)
	s_barrier
	s_setprio 1
	v_mfma_f32_16x16x32_bf16 v[124:127], v[150:153], v[182:185], v[124:127]
	v_mfma_f32_16x16x32_bf16 v[120:123], v[158:161], v[182:185], v[120:123]
	v_mfma_f32_16x16x32_bf16 v[108:111], v[150:153], v[190:193], v[108:111]
	v_mfma_f32_16x16x32_bf16 v[104:107], v[158:161], v[190:193], v[104:107]
	v_mfma_f32_16x16x32_bf16 v[92:95], v[150:153], v[198:201], v[92:95]
	v_mfma_f32_16x16x32_bf16 v[88:91], v[158:161], v[198:201], v[88:91]
	v_mfma_f32_16x16x32_bf16 v[76:79], v[150:153], v[206:209], v[76:79]
	v_mfma_f32_16x16x32_bf16 v[72:75], v[158:161], v[206:209], v[72:75]
	v_mfma_f32_16x16x32_bf16 v[124:127], v[154:157], v[186:189], v[124:127]
	v_mfma_f32_16x16x32_bf16 v[120:123], v[162:165], v[186:189], v[120:123]
	v_mfma_f32_16x16x32_bf16 v[108:111], v[154:157], v[194:197], v[108:111]
	v_mfma_f32_16x16x32_bf16 v[104:107], v[162:165], v[194:197], v[104:107]
	v_mfma_f32_16x16x32_bf16 v[92:95], v[154:157], v[202:205], v[92:95]
	v_mfma_f32_16x16x32_bf16 v[88:91], v[162:165], v[202:205], v[88:91]
	v_mfma_f32_16x16x32_bf16 v[76:79], v[154:157], v[210:213], v[76:79]
	v_mfma_f32_16x16x32_bf16 v[72:75], v[162:165], v[210:213], v[72:75]
	v_mfma_f32_16x16x32_bf16 v[116:119], v[166:169], v[182:185], v[116:119]
	v_mfma_f32_16x16x32_bf16 v[112:115], v[174:177], v[182:185], v[112:115]
	v_mfma_f32_16x16x32_bf16 v[100:103], v[166:169], v[190:193], v[100:103]
	v_mfma_f32_16x16x32_bf16 v[96:99], v[174:177], v[190:193], v[96:99]
	v_mfma_f32_16x16x32_bf16 v[84:87], v[166:169], v[198:201], v[84:87]
	v_mfma_f32_16x16x32_bf16 v[80:83], v[174:177], v[198:201], v[80:83]
	v_mfma_f32_16x16x32_bf16 v[68:71], v[166:169], v[206:209], v[68:71]
	v_mfma_f32_16x16x32_bf16 v[64:67], v[174:177], v[206:209], v[64:67]
	v_mfma_f32_16x16x32_bf16 v[116:119], v[170:173], v[186:189], v[116:119]
	v_mfma_f32_16x16x32_bf16 v[112:115], v[178:181], v[186:189], v[112:115]
	v_mfma_f32_16x16x32_bf16 v[100:103], v[170:173], v[194:197], v[100:103]
	v_mfma_f32_16x16x32_bf16 v[96:99], v[178:181], v[194:197], v[96:99]
	v_mfma_f32_16x16x32_bf16 v[84:87], v[170:173], v[202:205], v[84:87]
	v_mfma_f32_16x16x32_bf16 v[80:83], v[178:181], v[202:205], v[80:83]
	v_mfma_f32_16x16x32_bf16 v[68:71], v[170:173], v[210:213], v[68:71]
	v_mfma_f32_16x16x32_bf16 v[64:67], v[178:181], v[210:213], v[64:67]
	s_setprio 0
	s_barrier
	s_add_i32 s50, s43, s2
	v_lshl_add_u64 v[144:145], s[66:67], 0, v[130:131]
	s_mov_b32 m0, s50
	ds_read_b128 v[182:185], v149 offset:16384
	ds_read_b128 v[186:189], v149 offset:17408
	ds_read_b128 v[190:193], v149 offset:18432
	ds_read_b128 v[194:197], v149 offset:19456
	ds_read_b128 v[198:201], v149 offset:20480
	ds_read_b128 v[202:205], v149 offset:21504
	ds_read_b128 v[206:209], v149 offset:22528
	ds_read_b128 v[210:213], v149 offset:23552
	global_load_lds_dwordx4 v[144:145], off
	s_add_i32 m0, s50, 0x2000
	s_add_u32 s50, s66, 0x20000
	v_lshl_add_u64 v[214:215], s[66:67], 0, v[134:135]
	s_addc_u32 s51, s67, 0
	s_add_i32 s52, s46, s2
	global_load_lds_dwordx4 v[214:215], off
	v_lshl_add_u64 v[216:217], s[50:51], 0, v[130:131]
	s_mov_b32 m0, s52
	v_lshl_add_u64 v[218:219], s[68:69], 0, v[132:133]
	global_load_lds_dwordx4 v[216:217], off
	s_add_i32 m0, s52, 0x2000
	v_lshl_add_u64 v[216:217], s[50:51], 0, v[134:135]
	global_load_lds_dwordx4 v[216:217], off
	s_mov_b32 m0, s3
	v_lshl_add_u64 v[216:217], s[68:69], 0, v[128:129]
	global_load_lds_dwordx4 v[216:217], off
	s_mov_b32 m0, s28
	s_nop 0
	global_load_lds_dwordx4 v[218:219], off
	s_waitcnt vmcnt(8) lgkmcnt(0)
	s_barrier
; #define PG8_STAGE(bufoff, gbase, voff) do { _Pragma("unroll") for (int _i = 0; _i < 2; ++_i) \
;         __builtin_amdgcn_global_load_lds((const unsigned*)((const char*)(gbase) + (voff)[_i]), (LAS unsigned*)(lds + (bufoff) + ldsw + _i * 8192), 16, 0, 0); } while (0)
; #define PG8_LDA(dst, b, h) do { _Pragma("unroll") for (int m = 0; m < 4; ++m) _Pragma("unroll") for (int k = 0; k < 2; ++k) dst[m][k] = *(const LAS bf16x8*)(lds + PG8_SA(b, h) + aoff + m * 2048 + k * 1024); } while (0)
; #define PG8_LDB(dst, b, h) do { _Pragma("unroll") for (int n = 0; n < 2; ++n) _Pragma("unroll") for (int k = 0; k < 2; ++k) dst[n][k] = *(const LAS bf16x8*)(lds + PG8_SB(b, h) + boff + n * 2048 + k * 1024); } while (0)
; #define PG8_MMA(ai, bj, At, Bt) do { __builtin_amdgcn_s_setprio(1); _Pragma("unroll") for (int m = 0; m < 4; ++m) _Pragma("unroll") for (int n = 0; n < 2; ++n) _Pragma("unroll") for (int k = 0; k < 2; ++k) \
;         acc[ai][bj][m][n] = __builtin_amdgcn_mfma_f32_16x16x32_bf16(Bt[n][k], At[m][k], acc[ai][bj][m][n], 0, 0, 0); __builtin_amdgcn_s_setprio(0); } while (0)
; #define PG8_WAIT_V(n) asm volatile("s_waitcnt vmcnt(" #n ")" ::: "memory")
; #define PG8_WAIT_L(n) asm volatile("s_waitcnt lgkmcnt(" #n ")" ::: "memory")
; #define PG8_BAR __builtin_amdgcn_s_barrier()
; #define PG8_SCHED __builtin_amdgcn_sched_barrier(0)
; template <class Desc, class Epi>
; DI void gemm_phase(LAS unsigned char* lds, const Desc& D, const Epi& E, int wv) {
;     ...
;             PG8_WAIT_V(8); PG8_WAIT_L(0); PG8_BAR; PG8_MMA(1, 0, At, B0); PG8_MMA(1, 1, At, B1); PG8_BAR; PG8_SCHED;
;             PG8_LDB(B0, 1, 0); PG8_LDB(B1, 1, 1); PG8_SCHED; PG8_LDA(At, 1, 0); PG8_STAGE(PG8_SA(0, 1), a2 + hstepA, voffA);
;             PG8_WAIT_V(8); PG8_WAIT_L(0); PG8_BAR; PG8_MMA(0, 0, At, B0); PG8_MMA(0, 1, At, B1); PG8_BAR; PG8_SCHED;
	s_setprio 1
	v_mfma_f32_16x16x32_bf16 v[60:63], v[150:153], v[182:185], v[60:63]
	v_mfma_f32_16x16x32_bf16 v[56:59], v[158:161], v[182:185], v[56:59]
	v_mfma_f32_16x16x32_bf16 v[44:47], v[150:153], v[190:193], v[44:47]
	v_mfma_f32_16x16x32_bf16 v[40:43], v[158:161], v[190:193], v[40:43]
	v_mfma_f32_16x16x32_bf16 v[28:31], v[150:153], v[198:201], v[28:31]
	v_mfma_f32_16x16x32_bf16 v[24:27], v[158:161], v[198:201], v[24:27]
	v_mfma_f32_16x16x32_bf16 v[12:15], v[150:153], v[206:209], v[12:15]
	v_mfma_f32_16x16x32_bf16 v[8:11], v[158:161], v[206:209], v[8:11]
	v_mfma_f32_16x16x32_bf16 v[60:63], v[154:157], v[186:189], v[60:63]
	v_mfma_f32_16x16x32_bf16 v[56:59], v[162:165], v[186:189], v[56:59]
	v_mfma_f32_16x16x32_bf16 v[44:47], v[154:157], v[194:197], v[44:47]
	v_mfma_f32_16x16x32_bf16 v[40:43], v[162:165], v[194:197], v[40:43]
	v_mfma_f32_16x16x32_bf16 v[28:31], v[154:157], v[202:205], v[28:31]
	v_mfma_f32_16x16x32_bf16 v[24:27], v[162:165], v[202:205], v[24:27]
	v_mfma_f32_16x16x32_bf16 v[12:15], v[154:157], v[210:213], v[12:15]
	v_mfma_f32_16x16x32_bf16 v[8:11], v[162:165], v[210:213], v[8:11]
	v_mfma_f32_16x16x32_bf16 v[52:55], v[166:169], v[182:185], v[52:55]
	v_mfma_f32_16x16x32_bf16 v[48:51], v[174:177], v[182:185], v[48:51]
	v_mfma_f32_16x16x32_bf16 v[36:39], v[166:169], v[190:193], v[36:39]
	v_mfma_f32_16x16x32_bf16 v[32:35], v[174:177], v[190:193], v[32:35]
	v_mfma_f32_16x16x32_bf16 v[20:23], v[166:169], v[198:201], v[20:23]
	v_mfma_f32_16x16x32_bf16 v[16:19], v[174:177], v[198:201], v[16:19]
	v_mfma_f32_16x16x32_bf16 v[4:7], v[166:169], v[206:209], v[4:7]
	v_mfma_f32_16x16x32_bf16 v[0:3], v[174:177], v[206:209], v[0:3]
	v_mfma_f32_16x16x32_bf16 v[52:55], v[170:173], v[186:189], v[52:55]
	v_mfma_f32_16x16x32_bf16 v[48:51], v[178:181], v[186:189], v[48:51]
	v_mfma_f32_16x16x32_bf16 v[36:39], v[170:173], v[194:197], v[36:39]
	v_mfma_f32_16x16x32_bf16 v[32:35], v[178:181], v[194:197], v[32:35]
	v_mfma_f32_16x16x32_bf16 v[20:23], v[170:173], v[202:205], v[20:23]
	v_mfma_f32_16x16x32_bf16 v[16:19], v[178:181], v[202:205], v[16:19]
	v_mfma_f32_16x16x32_bf16 v[4:7], v[170:173], v[210:213], v[4:7]
	v_mfma_f32_16x16x32_bf16 v[0:3], v[178:181], v[210:213], v[0:3]
	s_setprio 0
	s_barrier
	s_add_i32 s52, 0, 0x18000
	s_add_i32 s53, 0, 0x1c000
	v_add_u32_e32 v162, s52, v146
	v_add_u32_e32 v178, s53, v146
	ds_read_b128 v[150:153], v162
	ds_read_b128 v[154:157], v162 offset:1024
	ds_read_b128 v[158:161], v162 offset:2048
	ds_read_b128 v[162:165], v162 offset:3072
	ds_read_b128 v[166:169], v178
	ds_read_b128 v[170:173], v178 offset:1024
	ds_read_b128 v[174:177], v178 offset:2048
	ds_read_b128 v[178:181], v178 offset:3072
	s_add_u32 s50, s68, 0x20000
	s_addc_u32 s51, s69, 0
	s_mov_b32 m0, s29
	v_lshl_add_u64 v[220:221], s[50:51], 0, v[128:129]
	ds_read_b128 v[182:185], v149 offset:32768
	ds_read_b128 v[186:189], v149 offset:33792
	ds_read_b128 v[190:193], v149 offset:34816
	ds_read_b128 v[194:197], v149 offset:35840
	ds_read_b128 v[198:201], v149 offset:36864
	ds_read_b128 v[202:205], v149 offset:37888
	ds_read_b128 v[206:209], v149 offset:38912
	ds_read_b128 v[210:213], v149 offset:39936
	global_load_lds_dwordx4 v[220:221], off
	s_mov_b32 m0, s30
	v_lshl_add_u64 v[220:221], s[50:51], 0, v[132:133]
	global_load_lds_dwordx4 v[220:221], off
	s_waitcnt vmcnt(8) lgkmcnt(0)
	s_barrier
	s_setprio 1
	v_mfma_f32_16x16x32_bf16 v[124:127], v[150:153], v[182:185], v[124:127]
	v_mfma_f32_16x16x32_bf16 v[120:123], v[158:161], v[182:185], v[120:123]
	v_mfma_f32_16x16x32_bf16 v[108:111], v[150:153], v[190:193], v[108:111]
	v_mfma_f32_16x16x32_bf16 v[104:107], v[158:161], v[190:193], v[104:107]
	v_mfma_f32_16x16x32_bf16 v[92:95], v[150:153], v[198:201], v[92:95]
	v_mfma_f32_16x16x32_bf16 v[88:91], v[158:161], v[198:201], v[88:91]
	v_mfma_f32_16x16x32_bf16 v[76:79], v[150:153], v[206:209], v[76:79]
	v_mfma_f32_16x16x32_bf16 v[72:75], v[158:161], v[206:209], v[72:75]
	v_mfma_f32_16x16x32_bf16 v[124:127], v[154:157], v[186:189], v[124:127]
	v_mfma_f32_16x16x32_bf16 v[120:123], v[162:165], v[186:189], v[120:123]
	v_mfma_f32_16x16x32_bf16 v[108:111], v[154:157], v[194:197], v[108:111]
	v_mfma_f32_16x16x32_bf16 v[104:107], v[162:165], v[194:197], v[104:107]
	v_mfma_f32_16x16x32_bf16 v[92:95], v[154:157], v[202:205], v[92:95]
	v_mfma_f32_16x16x32_bf16 v[88:91], v[162:165], v[202:205], v[88:91]
	v_mfma_f32_16x16x32_bf16 v[76:79], v[154:157], v[210:213], v[76:79]
	v_mfma_f32_16x16x32_bf16 v[72:75], v[162:165], v[210:213], v[72:75]
	v_mfma_f32_16x16x32_bf16 v[116:119], v[166:169], v[182:185], v[116:119]
	v_mfma_f32_16x16x32_bf16 v[112:115], v[174:177], v[182:185], v[112:115]
	v_mfma_f32_16x16x32_bf16 v[100:103], v[166:169], v[190:193], v[100:103]
	v_mfma_f32_16x16x32_bf16 v[96:99], v[174:177], v[190:193], v[96:99]
	v_mfma_f32_16x16x32_bf16 v[84:87], v[166:169], v[198:201], v[84:87]
	v_mfma_f32_16x16x32_bf16 v[80:83], v[174:177], v[198:201], v[80:83]
	v_mfma_f32_16x16x32_bf16 v[68:71], v[166:169], v[206:209], v[68:71]
	v_mfma_f32_16x16x32_bf16 v[64:67], v[174:177], v[206:209], v[64:67]
	v_mfma_f32_16x16x32_bf16 v[116:119], v[170:173], v[186:189], v[116:119]
	v_mfma_f32_16x16x32_bf16 v[112:115], v[178:181], v[186:189], v[112:115]
	v_mfma_f32_16x16x32_bf16 v[100:103], v[170:173], v[194:197], v[100:103]
	v_mfma_f32_16x16x32_bf16 v[96:99], v[178:181], v[194:197], v[96:99]
	v_mfma_f32_16x16x32_bf16 v[84:87], v[170:173], v[202:205], v[84:87]
	v_mfma_f32_16x16x32_bf16 v[80:83], v[178:181], v[202:205], v[80:83]
	v_mfma_f32_16x16x32_bf16 v[68:71], v[170:173], v[210:213], v[68:71]
	v_mfma_f32_16x16x32_bf16 v[64:67], v[178:181], v[210:213], v[64:67]
	s_setprio 0
	s_barrier
; #define PG8_STAGE(bufoff, gbase, voff) do { _Pragma("unroll") for (int _i = 0; _i < 2; ++_i) \
;         __builtin_amdgcn_global_load_lds((const unsigned*)((const char*)(gbase) + (voff)[_i]), (LAS unsigned*)(lds + (bufoff) + ldsw + _i * 8192), 16, 0, 0); } while (0)
; #define PG8_LDA(dst, b, h) do { _Pragma("unroll") for (int m = 0; m < 4; ++m) _Pragma("unroll") for (int k = 0; k < 2; ++k) dst[m][k] = *(const LAS bf16x8*)(lds + PG8_SA(b, h) + aoff + m * 2048 + k * 1024); } while (0)
; #define PG8_MMA(ai, bj, At, Bt) do { __builtin_amdgcn_s_setprio(1); _Pragma("unroll") for (int m = 0; m < 4; ++m) _Pragma("unroll") for (int n = 0; n < 2; ++n) _Pragma("unroll") for (int k = 0; k < 2; ++k) \
;         acc[ai][bj][m][n] = __builtin_amdgcn_mfma_f32_16x16x32_bf16(Bt[n][k], At[m][k], acc[ai][bj][m][n], 0, 0, 0); __builtin_amdgcn_s_setprio(0); } while (0)
; #define PG8_WAIT_V(n) asm volatile("s_waitcnt vmcnt(" #n ")" ::: "memory")
; #define PG8_WAIT_L(n) asm volatile("s_waitcnt lgkmcnt(" #n ")" ::: "memory")
; #define PG8_BAR __builtin_amdgcn_s_barrier()
; #define PG8_SCHED __builtin_amdgcn_sched_barrier(0)
; template <class Desc, class Epi>
; DI void gemm_phase(LAS unsigned char* lds, const Desc& D, const Epi& E, int wv) {
;     ...
;             PG8_LDA(At, 1, 1); PG8_STAGE(PG8_SB(1, 0), b3, voffB); PG8_STAGE(PG8_SB(1, 1), b3 + hstepB, voffB); PG8_STAGE(PG8_SA(1, 0), a3, voffA);
;             PG8_WAIT_V(8); PG8_WAIT_L(0); PG8_BAR; PG8_MMA(1, 0, At, B0); PG8_MMA(1, 1, At, B1); PG8_BAR; PG8_SCHED;
;         }
	s_add_i32 s50, s52, s2
	v_lshl_add_u64 v[144:145], v[144:145], 0, s[8:9]
	s_mov_b32 m0, s50
	ds_read_b128 v[182:185], v149 offset:49152
	ds_read_b128 v[186:189], v149 offset:50176
	ds_read_b128 v[190:193], v149 offset:51200
	ds_read_b128 v[194:197], v149 offset:52224
	ds_read_b128 v[198:201], v149 offset:53248
	ds_read_b128 v[202:205], v149 offset:54272
	ds_read_b128 v[206:209], v149 offset:55296
	ds_read_b128 v[210:213], v149 offset:56320
	global_load_lds_dwordx4 v[144:145], off
	s_add_i32 m0, s50, 0x2000
	s_add_u32 s50, s66, 0x20080
	v_lshl_add_u64 v[144:145], v[214:215], 0, s[8:9]
	s_addc_u32 s51, s67, 0
	s_add_i32 s52, s53, s2
	global_load_lds_dwordx4 v[144:145], off
	s_mov_b32 m0, s52
	v_lshl_add_u64 v[144:145], s[50:51], 0, v[130:131]
	global_load_lds_dwordx4 v[144:145], off
	s_add_i32 m0, s52, 0x2000
	v_lshl_add_u64 v[144:145], s[50:51], 0, v[134:135]
	global_load_lds_dwordx4 v[144:145], off
	s_mov_b32 m0, s40
	v_lshl_add_u64 v[144:145], v[216:217], 0, s[8:9]
	global_load_lds_dwordx4 v[144:145], off
	s_mov_b32 m0, s41
	v_lshl_add_u64 v[144:145], v[218:219], 0, s[8:9]
	global_load_lds_dwordx4 v[144:145], off
	s_waitcnt vmcnt(8) lgkmcnt(0)
	s_barrier
	s_setprio 1
	v_mfma_f32_16x16x32_bf16 v[60:63], v[150:153], v[182:185], v[60:63]
	v_mfma_f32_16x16x32_bf16 v[56:59], v[158:161], v[182:185], v[56:59]
	v_mfma_f32_16x16x32_bf16 v[44:47], v[150:153], v[190:193], v[44:47]
	v_mfma_f32_16x16x32_bf16 v[40:43], v[158:161], v[190:193], v[40:43]
	v_mfma_f32_16x16x32_bf16 v[28:31], v[150:153], v[198:201], v[28:31]
	v_mfma_f32_16x16x32_bf16 v[24:27], v[158:161], v[198:201], v[24:27]
	v_mfma_f32_16x16x32_bf16 v[12:15], v[150:153], v[206:209], v[12:15]
	v_mfma_f32_16x16x32_bf16 v[8:11], v[158:161], v[206:209], v[8:11]
	v_mfma_f32_16x16x32_bf16 v[60:63], v[154:157], v[186:189], v[60:63]
	v_mfma_f32_16x16x32_bf16 v[56:59], v[162:165], v[186:189], v[56:59]
	v_mfma_f32_16x16x32_bf16 v[44:47], v[154:157], v[194:197], v[44:47]
	v_mfma_f32_16x16x32_bf16 v[40:43], v[162:165], v[194:197], v[40:43]
	v_mfma_f32_16x16x32_bf16 v[28:31], v[154:157], v[202:205], v[28:31]
	v_mfma_f32_16x16x32_bf16 v[24:27], v[162:165], v[202:205], v[24:27]
	v_mfma_f32_16x16x32_bf16 v[12:15], v[154:157], v[210:213], v[12:15]
	v_mfma_f32_16x16x32_bf16 v[8:11], v[162:165], v[210:213], v[8:11]
	v_mfma_f32_16x16x32_bf16 v[52:55], v[166:169], v[182:185], v[52:55]
	v_mfma_f32_16x16x32_bf16 v[48:51], v[174:177], v[182:185], v[48:51]
	v_mfma_f32_16x16x32_bf16 v[36:39], v[166:169], v[190:193], v[36:39]
	v_mfma_f32_16x16x32_bf16 v[32:35], v[174:177], v[190:193], v[32:35]
	v_mfma_f32_16x16x32_bf16 v[20:23], v[166:169], v[198:201], v[20:23]
	v_mfma_f32_16x16x32_bf16 v[16:19], v[174:177], v[198:201], v[16:19]
	v_mfma_f32_16x16x32_bf16 v[4:7], v[166:169], v[206:209], v[4:7]
	v_mfma_f32_16x16x32_bf16 v[0:3], v[174:177], v[206:209], v[0:3]
	v_mfma_f32_16x16x32_bf16 v[52:55], v[170:173], v[186:189], v[52:55]
	v_mfma_f32_16x16x32_bf16 v[48:51], v[178:181], v[186:189], v[48:51]
	v_mfma_f32_16x16x32_bf16 v[36:39], v[170:173], v[194:197], v[36:39]
	v_mfma_f32_16x16x32_bf16 v[32:35], v[178:181], v[194:197], v[32:35]
	v_mfma_f32_16x16x32_bf16 v[20:23], v[170:173], v[202:205], v[20:23]
	v_mfma_f32_16x16x32_bf16 v[16:19], v[178:181], v[202:205], v[16:19]
	v_mfma_f32_16x16x32_bf16 v[4:7], v[170:173], v[210:213], v[4:7]
	v_mfma_f32_16x16x32_bf16 v[0:3], v[178:181], v[210:213], v[0:3]
	s_setprio 0
	s_barrier
	s_add_i32 s49, s49, 2
	s_cmp_gt_u32 s49, 5
	s_mov_b64 s[62:63], s[64:65]
	s_cbranch_scc0 .LBB0_763
	s_and_b64 vcc, exec, s[14:15]
	s_cbranch_vccz .LBB0_766
	s_barrier

; #define PG8_STAGE(bufoff, gbase, voff) do { _Pragma("unroll") for (int _i = 0; _i < 2; ++_i) \
;         __builtin_amdgcn_global_load_lds((const unsigned*)((const char*)(gbase) + (voff)[_i]), (LAS unsigned*)(lds + (bufoff) + ldsw + _i * 8192), 16, 0, 0); } while (0)
; #define PG8_LDA(dst, b, h) do { _Pragma("unroll") for (int m = 0; m < 4; ++m) _Pragma("unroll") for (int k = 0; k < 2; ++k) dst[m][k] = *(const LAS bf16x8*)(lds + PG8_SA(b, h) + aoff + m * 2048 + k * 1024); } while (0)
; #define PG8_LDB(dst, b, h) do { _Pragma("unroll") for (int n = 0; n < 2; ++n) _Pragma("unroll") for (int k = 0; k < 2; ++k) dst[n][k] = *(const LAS bf16x8*)(lds + PG8_SB(b, h) + boff + n * 2048 + k * 1024); } while (0)
; #define PG8_MMA(ai, bj, At, Bt) do { __builtin_amdgcn_s_setprio(1); _Pragma("unroll") for (int m = 0; m < 4; ++m) _Pragma("unroll") for (int n = 0; n < 2; ++n) _Pragma("unroll") for (int k = 0; k < 2; ++k) \
;         acc[ai][bj][m][n] = __builtin_amdgcn_mfma_f32_16x16x32_bf16(Bt[n][k], At[m][k], acc[ai][bj][m][n], 0, 0, 0); __builtin_amdgcn_s_setprio(0); } while (0)
; #define PG8_WAIT_V(n) asm volatile("s_waitcnt vmcnt(" #n ")" ::: "memory")
; #define PG8_WAIT_L(n) asm volatile("s_waitcnt lgkmcnt(" #n ")" ::: "memory")
; #define PG8_BAR __builtin_amdgcn_s_barrier()
; #define PG8_SCHED __builtin_amdgcn_sched_barrier(0)
; template <class Desc, class Epi>
; DI void gemm_phase(LAS unsigned char* lds, const Desc& D, const Epi& E, int wv) {
;     ...
;             PG8_LDB(B0, 0, 0); PG8_LDB(B1, 0, 1); PG8_SCHED; PG8_LDA(At, 0, 0); PG8_STAGE(PG8_SA(1, 1), a1 + hstepA, voffA);
;             PG8_WAIT_V(8); PG8_WAIT_L(0); PG8_BAR; PG8_MMA(0, 0, At, B0); PG8_MMA(0, 1, At, B1); PG8_BAR; PG8_SCHED;
;             PG8_LDA(At, 0, 1); PG8_STAGE(PG8_SB(0, 0), b2, voffB); PG8_STAGE(PG8_SB(0, 1), b2 + hstepB, voffB); PG8_STAGE(PG8_SA(0, 0), a2, voffA);
;             PG8_WAIT_V(8); PG8_WAIT_L(0); PG8_BAR; PG8_MMA(1, 0, At, B0); PG8_MMA(1, 1, At, B1); PG8_BAR; PG8_SCHED;
.LBB0_831:
	ds_read_b128 v[128:131], v169
	ds_read_b128 v[132:135], v169 offset:1024
	ds_read_b128 v[136:139], v169 offset:2048
	ds_read_b128 v[140:143], v169 offset:3072
	ds_read_b128 v[160:163], v170
	ds_read_b128 v[164:167], v170 offset:1024
	ds_read_b128 v[172:175], v170 offset:2048
	ds_read_b128 v[176:179], v170 offset:3072
	s_add_u32 s51, s6, 0xfff80080
	s_addc_u32 s52, s7, -1
	s_cmp_eq_u32 s50, 28
	s_cselect_b32 s69, s19, s52
	s_cselect_b32 s68, s18, s51
	s_cselect_b32 s67, s21, s49
	s_cselect_b32 s66, s20, s23
	v_lshl_add_u64 v[212:213], s[6:7], 0, v[152:153]
	s_add_i32 m0, s28, 0xc000
	ds_read_b128 v[180:183], v171
	ds_read_b128 v[184:187], v171 offset:1024
	ds_read_b128 v[188:191], v171 offset:2048
	ds_read_b128 v[192:195], v171 offset:3072
	ds_read_b128 v[196:199], v171 offset:4096
	ds_read_b128 v[200:203], v171 offset:5120
	ds_read_b128 v[204:207], v171 offset:6144
	ds_read_b128 v[208:211], v171 offset:7168
	global_load_lds_dwordx4 v[212:213], off
	s_add_i32 m0, s28, 0xe000
	v_lshl_add_u64 v[212:213], s[6:7], 0, v[154:155]
	global_load_lds_dwordx4 v[212:213], off
	s_waitcnt vmcnt(8) lgkmcnt(0)
	s_barrier
	s_setprio 1
	v_mfma_f32_16x16x32_bf16 v[124:127], v[128:131], v[180:183], v[124:127]
	v_mfma_f32_16x16x32_bf16 v[120:123], v[136:139], v[180:183], v[120:123]
	v_mfma_f32_16x16x32_bf16 v[112:115], v[128:131], v[188:191], v[112:115]
	v_mfma_f32_16x16x32_bf16 v[108:111], v[136:139], v[188:191], v[108:111]
	v_mfma_f32_16x16x32_bf16 v[100:103], v[128:131], v[196:199], v[100:103]
	v_mfma_f32_16x16x32_bf16 v[92:95], v[136:139], v[196:199], v[92:95]
	v_mfma_f32_16x16x32_bf16 v[84:87], v[128:131], v[204:207], v[84:87]
	v_mfma_f32_16x16x32_bf16 v[76:79], v[136:139], v[204:207], v[76:79]
	v_mfma_f32_16x16x32_bf16 v[124:127], v[132:135], v[184:187], v[124:127]
	v_mfma_f32_16x16x32_bf16 v[120:123], v[140:143], v[184:187], v[120:123]
	v_mfma_f32_16x16x32_bf16 v[112:115], v[132:135], v[192:195], v[112:115]
	v_mfma_f32_16x16x32_bf16 v[108:111], v[140:143], v[192:195], v[108:111]
	v_mfma_f32_16x16x32_bf16 v[100:103], v[132:135], v[200:203], v[100:103]
	v_mfma_f32_16x16x32_bf16 v[92:95], v[140:143], v[200:203], v[92:95]
	v_mfma_f32_16x16x32_bf16 v[84:87], v[132:135], v[208:211], v[84:87]
	v_mfma_f32_16x16x32_bf16 v[76:79], v[140:143], v[208:211], v[76:79]
	v_mfma_f32_16x16x32_bf16 v[116:119], v[160:163], v[180:183], v[116:119]
	v_mfma_f32_16x16x32_bf16 v[104:107], v[172:175], v[180:183], v[104:107]
	v_mfma_f32_16x16x32_bf16 v[96:99], v[160:163], v[188:191], v[96:99]
	v_mfma_f32_16x16x32_bf16 v[88:91], v[172:175], v[188:191], v[88:91]
	v_mfma_f32_16x16x32_bf16 v[80:83], v[160:163], v[196:199], v[80:83]
	v_mfma_f32_16x16x32_bf16 v[72:75], v[172:175], v[196:199], v[72:75]
	v_mfma_f32_16x16x32_bf16 v[68:71], v[160:163], v[204:207], v[68:71]
	v_mfma_f32_16x16x32_bf16 v[64:67], v[172:175], v[204:207], v[64:67]
	v_mfma_f32_16x16x32_bf16 v[116:119], v[164:167], v[184:187], v[116:119]
	v_mfma_f32_16x16x32_bf16 v[104:107], v[176:179], v[184:187], v[104:107]
	v_mfma_f32_16x16x32_bf16 v[96:99], v[164:167], v[192:195], v[96:99]
	v_mfma_f32_16x16x32_bf16 v[88:91], v[176:179], v[192:195], v[88:91]
	v_mfma_f32_16x16x32_bf16 v[80:83], v[164:167], v[200:203], v[80:83]
	v_mfma_f32_16x16x32_bf16 v[72:75], v[176:179], v[200:203], v[72:75]
	v_mfma_f32_16x16x32_bf16 v[68:71], v[164:167], v[208:211], v[68:71]
	v_mfma_f32_16x16x32_bf16 v[64:67], v[176:179], v[208:211], v[64:67]
	s_setprio 0
	s_barrier
	s_add_i32 s51, s46, s2
	v_lshl_add_u64 v[212:213], s[66:67], 0, v[148:149]
	s_mov_b32 m0, s51
	ds_read_b128 v[180:183], v171 offset:16384
	ds_read_b128 v[184:187], v171 offset:17408
	ds_read_b128 v[188:191], v171 offset:18432
	ds_read_b128 v[192:195], v171 offset:19456
	ds_read_b128 v[196:199], v171 offset:20480
	ds_read_b128 v[200:203], v171 offset:21504
	ds_read_b128 v[204:207], v171 offset:22528
	ds_read_b128 v[208:211], v171 offset:23552
	global_load_lds_dwordx4 v[212:213], off
	s_add_i32 m0, s51, 0x2000
	s_add_u32 s52, s66, 0x80000
	v_lshl_add_u64 v[214:215], s[66:67], 0, v[144:145]
	s_addc_u32 s53, s67, 0
	s_add_i32 s51, s47, s2
	global_load_lds_dwordx4 v[214:215], off
	v_lshl_add_u64 v[216:217], s[52:53], 0, v[148:149]
	s_mov_b32 m0, s51
	v_lshl_add_u64 v[218:219], s[68:69], 0, v[146:147]
	global_load_lds_dwordx4 v[216:217], off
	s_add_i32 m0, s51, 0x2000
	v_lshl_add_u64 v[216:217], s[52:53], 0, v[144:145]
	global_load_lds_dwordx4 v[216:217], off
	s_mov_b32 m0, s28
	v_lshl_add_u64 v[216:217], s[68:69], 0, v[150:151]
	global_load_lds_dwordx4 v[216:217], off
	s_mov_b32 m0, s29
	s_nop 0
	global_load_lds_dwordx4 v[218:219], off
	s_waitcnt vmcnt(8) lgkmcnt(0)
	s_barrier
; #define PG8_STAGE(bufoff, gbase, voff) do { _Pragma("unroll") for (int _i = 0; _i < 2; ++_i) \
;         __builtin_amdgcn_global_load_lds((const unsigned*)((const char*)(gbase) + (voff)[_i]), (LAS unsigned*)(lds + (bufoff) + ldsw + _i * 8192), 16, 0, 0); } while (0)
; #define PG8_LDA(dst, b, h) do { _Pragma("unroll") for (int m = 0; m < 4; ++m) _Pragma("unroll") for (int k = 0; k < 2; ++k) dst[m][k] = *(const LAS bf16x8*)(lds + PG8_SA(b, h) + aoff + m * 2048 + k * 1024); } while (0)
; #define PG8_LDB(dst, b, h) do { _Pragma("unroll") for (int n = 0; n < 2; ++n) _Pragma("unroll") for (int k = 0; k < 2; ++k) dst[n][k] = *(const LAS bf16x8*)(lds + PG8_SB(b, h) + boff + n * 2048 + k * 1024); } while (0)
; #define PG8_MMA(ai, bj, At, Bt) do { __builtin_amdgcn_s_setprio(1); _Pragma("unroll") for (int m = 0; m < 4; ++m) _Pragma("unroll") for (int n = 0; n < 2; ++n) _Pragma("unroll") for (int k = 0; k < 2; ++k) \
;         acc[ai][bj][m][n] = __builtin_amdgcn_mfma_f32_16x16x32_bf16(Bt[n][k], At[m][k], acc[ai][bj][m][n], 0, 0, 0); __builtin_amdgcn_s_setprio(0); } while (0)
; #define PG8_WAIT_V(n) asm volatile("s_waitcnt vmcnt(" #n ")" ::: "memory")
; #define PG8_WAIT_L(n) asm volatile("s_waitcnt lgkmcnt(" #n ")" ::: "memory")
; #define PG8_BAR __builtin_amdgcn_s_barrier()
; #define PG8_SCHED __builtin_amdgcn_sched_barrier(0)
; template <class Desc, class Epi>
; DI void gemm_phase(LAS unsigned char* lds, const Desc& D, const Epi& E, int wv) {
;     ...
;             PG8_WAIT_V(8); PG8_WAIT_L(0); PG8_BAR; PG8_MMA(1, 0, At, B0); PG8_MMA(1, 1, At, B1); PG8_BAR; PG8_SCHED;
;             PG8_LDB(B0, 1, 0); PG8_LDB(B1, 1, 1); PG8_SCHED; PG8_LDA(At, 1, 0); PG8_STAGE(PG8_SA(0, 1), a2 + hstepA, voffA);
;             PG8_WAIT_V(8); PG8_WAIT_L(0); PG8_BAR; PG8_MMA(0, 0, At, B0); PG8_MMA(0, 1, At, B1); PG8_BAR; PG8_SCHED;
	s_setprio 1
	v_mfma_f32_16x16x32_bf16 v[60:63], v[128:131], v[180:183], v[60:63]
	v_mfma_f32_16x16x32_bf16 v[56:59], v[136:139], v[180:183], v[56:59]
	v_mfma_f32_16x16x32_bf16 v[52:55], v[128:131], v[188:191], v[52:55]
	v_mfma_f32_16x16x32_bf16 v[44:47], v[136:139], v[188:191], v[44:47]
	v_mfma_f32_16x16x32_bf16 v[36:39], v[128:131], v[196:199], v[36:39]
	v_mfma_f32_16x16x32_bf16 v[28:31], v[136:139], v[196:199], v[28:31]
	v_mfma_f32_16x16x32_bf16 v[20:23], v[128:131], v[204:207], v[20:23]
	v_mfma_f32_16x16x32_bf16 v[12:15], v[136:139], v[204:207], v[12:15]
	v_mfma_f32_16x16x32_bf16 v[60:63], v[132:135], v[184:187], v[60:63]
	v_mfma_f32_16x16x32_bf16 v[56:59], v[140:143], v[184:187], v[56:59]
	v_mfma_f32_16x16x32_bf16 v[52:55], v[132:135], v[192:195], v[52:55]
	v_mfma_f32_16x16x32_bf16 v[44:47], v[140:143], v[192:195], v[44:47]
	v_mfma_f32_16x16x32_bf16 v[36:39], v[132:135], v[200:203], v[36:39]
	v_mfma_f32_16x16x32_bf16 v[28:31], v[140:143], v[200:203], v[28:31]
	v_mfma_f32_16x16x32_bf16 v[20:23], v[132:135], v[208:211], v[20:23]
	v_mfma_f32_16x16x32_bf16 v[12:15], v[140:143], v[208:211], v[12:15]
	v_mfma_f32_16x16x32_bf16 v[48:51], v[160:163], v[180:183], v[48:51]
	v_mfma_f32_16x16x32_bf16 v[40:43], v[172:175], v[180:183], v[40:43]
	v_mfma_f32_16x16x32_bf16 v[32:35], v[160:163], v[188:191], v[32:35]
	v_mfma_f32_16x16x32_bf16 v[24:27], v[172:175], v[188:191], v[24:27]
	v_mfma_f32_16x16x32_bf16 v[16:19], v[160:163], v[196:199], v[16:19]
	v_mfma_f32_16x16x32_bf16 v[8:11], v[172:175], v[196:199], v[8:11]
	v_mfma_f32_16x16x32_bf16 v[4:7], v[160:163], v[204:207], v[4:7]
	v_mfma_f32_16x16x32_bf16 v[0:3], v[172:175], v[204:207], v[0:3]
	v_mfma_f32_16x16x32_bf16 v[48:51], v[164:167], v[184:187], v[48:51]
	v_mfma_f32_16x16x32_bf16 v[40:43], v[176:179], v[184:187], v[40:43]
	v_mfma_f32_16x16x32_bf16 v[32:35], v[164:167], v[192:195], v[32:35]
	v_mfma_f32_16x16x32_bf16 v[24:27], v[176:179], v[192:195], v[24:27]
	v_mfma_f32_16x16x32_bf16 v[16:19], v[164:167], v[200:203], v[16:19]
	v_mfma_f32_16x16x32_bf16 v[8:11], v[176:179], v[200:203], v[8:11]
	v_mfma_f32_16x16x32_bf16 v[4:7], v[164:167], v[208:211], v[4:7]
	v_mfma_f32_16x16x32_bf16 v[0:3], v[176:179], v[208:211], v[0:3]
	s_setprio 0
	s_barrier
	s_add_i32 s51, 0, 0x18000
	s_add_i32 s60, 0, 0x1c000
	v_add_u32_e32 v140, s51, v168
	v_add_u32_e32 v176, s60, v168
	ds_read_b128 v[128:131], v140
	ds_read_b128 v[132:135], v140 offset:1024
	ds_read_b128 v[136:139], v140 offset:2048
	ds_read_b128 v[140:143], v140 offset:3072
	ds_read_b128 v[160:163], v176
	ds_read_b128 v[164:167], v176 offset:1024
	ds_read_b128 v[172:175], v176 offset:2048
	ds_read_b128 v[176:179], v176 offset:3072
	s_add_u32 s52, s68, 0x80000
	s_addc_u32 s53, s69, 0
	s_mov_b32 m0, s30
	v_lshl_add_u64 v[220:221], s[52:53], 0, v[150:151]
	ds_read_b128 v[180:183], v171 offset:32768
	ds_read_b128 v[184:187], v171 offset:33792
	ds_read_b128 v[188:191], v171 offset:34816
	ds_read_b128 v[192:195], v171 offset:35840
	ds_read_b128 v[196:199], v171 offset:36864
	ds_read_b128 v[200:203], v171 offset:37888
	ds_read_b128 v[204:207], v171 offset:38912
	ds_read_b128 v[208:211], v171 offset:39936
	global_load_lds_dwordx4 v[220:221], off
	s_mov_b32 m0, s31
	v_lshl_add_u64 v[220:221], s[52:53], 0, v[146:147]
	global_load_lds_dwordx4 v[220:221], off
	s_waitcnt vmcnt(8) lgkmcnt(0)
	s_barrier
	s_setprio 1
	v_mfma_f32_16x16x32_bf16 v[124:127], v[128:131], v[180:183], v[124:127]
	v_mfma_f32_16x16x32_bf16 v[120:123], v[136:139], v[180:183], v[120:123]
	v_mfma_f32_16x16x32_bf16 v[112:115], v[128:131], v[188:191], v[112:115]
	v_mfma_f32_16x16x32_bf16 v[108:111], v[136:139], v[188:191], v[108:111]
	v_mfma_f32_16x16x32_bf16 v[100:103], v[128:131], v[196:199], v[100:103]
	v_mfma_f32_16x16x32_bf16 v[92:95], v[136:139], v[196:199], v[92:95]
	v_mfma_f32_16x16x32_bf16 v[84:87], v[128:131], v[204:207], v[84:87]
	v_mfma_f32_16x16x32_bf16 v[76:79], v[136:139], v[204:207], v[76:79]
	v_mfma_f32_16x16x32_bf16 v[124:127], v[132:135], v[184:187], v[124:127]
	v_mfma_f32_16x16x32_bf16 v[120:123], v[140:143], v[184:187], v[120:123]
	v_mfma_f32_16x16x32_bf16 v[112:115], v[132:135], v[192:195], v[112:115]
	v_mfma_f32_16x16x32_bf16 v[108:111], v[140:143], v[192:195], v[108:111]
	v_mfma_f32_16x16x32_bf16 v[100:103], v[132:135], v[200:203], v[100:103]
	v_mfma_f32_16x16x32_bf16 v[92:95], v[140:143], v[200:203], v[92:95]
	v_mfma_f32_16x16x32_bf16 v[84:87], v[132:135], v[208:211], v[84:87]
	v_mfma_f32_16x16x32_bf16 v[76:79], v[140:143], v[208:211], v[76:79]
	v_mfma_f32_16x16x32_bf16 v[116:119], v[160:163], v[180:183], v[116:119]
	v_mfma_f32_16x16x32_bf16 v[104:107], v[172:175], v[180:183], v[104:107]
	v_mfma_f32_16x16x32_bf16 v[96:99], v[160:163], v[188:191], v[96:99]
	v_mfma_f32_16x16x32_bf16 v[88:91], v[172:175], v[188:191], v[88:91]
	v_mfma_f32_16x16x32_bf16 v[80:83], v[160:163], v[196:199], v[80:83]
	v_mfma_f32_16x16x32_bf16 v[72:75], v[172:175], v[196:199], v[72:75]
	v_mfma_f32_16x16x32_bf16 v[68:71], v[160:163], v[204:207], v[68:71]
	v_mfma_f32_16x16x32_bf16 v[64:67], v[172:175], v[204:207], v[64:67]
	v_mfma_f32_16x16x32_bf16 v[116:119], v[164:167], v[184:187], v[116:119]
	v_mfma_f32_16x16x32_bf16 v[104:107], v[176:179], v[184:187], v[104:107]
	v_mfma_f32_16x16x32_bf16 v[96:99], v[164:167], v[192:195], v[96:99]
	v_mfma_f32_16x16x32_bf16 v[88:91], v[176:179], v[192:195], v[88:91]
	v_mfma_f32_16x16x32_bf16 v[80:83], v[164:167], v[200:203], v[80:83]
	v_mfma_f32_16x16x32_bf16 v[72:75], v[176:179], v[200:203], v[72:75]
	v_mfma_f32_16x16x32_bf16 v[68:71], v[164:167], v[208:211], v[68:71]
	v_mfma_f32_16x16x32_bf16 v[64:67], v[176:179], v[208:211], v[64:67]
	s_setprio 0
	s_barrier
; #define PG8_STAGE(bufoff, gbase, voff) do { _Pragma("unroll") for (int _i = 0; _i < 2; ++_i) \
;         __builtin_amdgcn_global_load_lds((const unsigned*)((const char*)(gbase) + (voff)[_i]), (LAS unsigned*)(lds + (bufoff) + ldsw + _i * 8192), 16, 0, 0); } while (0)
; #define PG8_LDA(dst, b, h) do { _Pragma("unroll") for (int m = 0; m < 4; ++m) _Pragma("unroll") for (int k = 0; k < 2; ++k) dst[m][k] = *(const LAS bf16x8*)(lds + PG8_SA(b, h) + aoff + m * 2048 + k * 1024); } while (0)
; #define PG8_MMA(ai, bj, At, Bt) do { __builtin_amdgcn_s_setprio(1); _Pragma("unroll") for (int m = 0; m < 4; ++m) _Pragma("unroll") for (int n = 0; n < 2; ++n) _Pragma("unroll") for (int k = 0; k < 2; ++k) \
;         acc[ai][bj][m][n] = __builtin_amdgcn_mfma_f32_16x16x32_bf16(Bt[n][k], At[m][k], acc[ai][bj][m][n], 0, 0, 0); __builtin_amdgcn_s_setprio(0); } while (0)
; #define PG8_WAIT_V(n) asm volatile("s_waitcnt vmcnt(" #n ")" ::: "memory")
; #define PG8_WAIT_L(n) asm volatile("s_waitcnt lgkmcnt(" #n ")" ::: "memory")
; #define PG8_BAR __builtin_amdgcn_s_barrier()
; #define PG8_SCHED __builtin_amdgcn_sched_barrier(0)
; template <class Desc, class Epi>
; DI void gemm_phase(LAS unsigned char* lds, const Desc& D, const Epi& E, int wv) {
;     ...
;             PG8_LDA(At, 1, 1); PG8_STAGE(PG8_SB(1, 0), b3, voffB); PG8_STAGE(PG8_SB(1, 1), b3 + hstepB, voffB); PG8_STAGE(PG8_SA(1, 0), a3, voffA);
;             PG8_WAIT_V(8); PG8_WAIT_L(0); PG8_BAR; PG8_MMA(1, 0, At, B0); PG8_MMA(1, 1, At, B1); PG8_BAR; PG8_SCHED;
;         }
	s_add_i32 s51, s51, s2
	v_lshl_add_u64 v[212:213], v[212:213], 0, s[10:11]
	s_mov_b32 m0, s51
	ds_read_b128 v[180:183], v171 offset:49152
	ds_read_b128 v[184:187], v171 offset:50176
	ds_read_b128 v[188:191], v171 offset:51200
	ds_read_b128 v[192:195], v171 offset:52224
	ds_read_b128 v[196:199], v171 offset:53248
	ds_read_b128 v[200:203], v171 offset:54272
	ds_read_b128 v[204:207], v171 offset:55296
	ds_read_b128 v[208:211], v171 offset:56320
	global_load_lds_dwordx4 v[212:213], off
	s_add_i32 m0, s51, 0x2000
	s_add_u32 s52, s66, 0x80080
	v_lshl_add_u64 v[212:213], v[214:215], 0, s[10:11]
	s_addc_u32 s53, s67, 0
	s_add_i32 s51, s60, s2
	global_load_lds_dwordx4 v[212:213], off
	s_mov_b32 m0, s51
	v_lshl_add_u64 v[212:213], s[52:53], 0, v[148:149]
	global_load_lds_dwordx4 v[212:213], off
	s_add_i32 m0, s51, 0x2000
	v_lshl_add_u64 v[212:213], s[52:53], 0, v[144:145]
	global_load_lds_dwordx4 v[212:213], off
	s_mov_b32 m0, s41
	v_lshl_add_u64 v[212:213], v[216:217], 0, s[10:11]
	global_load_lds_dwordx4 v[212:213], off
	s_mov_b32 m0, s42
	v_lshl_add_u64 v[212:213], v[218:219], 0, s[10:11]
	global_load_lds_dwordx4 v[212:213], off
	s_waitcnt vmcnt(8) lgkmcnt(0)
	s_barrier
	s_setprio 1
	v_mfma_f32_16x16x32_bf16 v[60:63], v[128:131], v[180:183], v[60:63]
	v_mfma_f32_16x16x32_bf16 v[56:59], v[136:139], v[180:183], v[56:59]
	v_mfma_f32_16x16x32_bf16 v[52:55], v[128:131], v[188:191], v[52:55]
	v_mfma_f32_16x16x32_bf16 v[44:47], v[136:139], v[188:191], v[44:47]
	v_mfma_f32_16x16x32_bf16 v[36:39], v[128:131], v[196:199], v[36:39]
	v_mfma_f32_16x16x32_bf16 v[28:31], v[136:139], v[196:199], v[28:31]
	v_mfma_f32_16x16x32_bf16 v[20:23], v[128:131], v[204:207], v[20:23]
	v_mfma_f32_16x16x32_bf16 v[12:15], v[136:139], v[204:207], v[12:15]
	v_mfma_f32_16x16x32_bf16 v[60:63], v[132:135], v[184:187], v[60:63]
	v_mfma_f32_16x16x32_bf16 v[56:59], v[140:143], v[184:187], v[56:59]
	v_mfma_f32_16x16x32_bf16 v[52:55], v[132:135], v[192:195], v[52:55]
	v_mfma_f32_16x16x32_bf16 v[44:47], v[140:143], v[192:195], v[44:47]
	v_mfma_f32_16x16x32_bf16 v[36:39], v[132:135], v[200:203], v[36:39]
	v_mfma_f32_16x16x32_bf16 v[28:31], v[140:143], v[200:203], v[28:31]
	v_mfma_f32_16x16x32_bf16 v[20:23], v[132:135], v[208:211], v[20:23]
	v_mfma_f32_16x16x32_bf16 v[12:15], v[140:143], v[208:211], v[12:15]
	v_mfma_f32_16x16x32_bf16 v[48:51], v[160:163], v[180:183], v[48:51]
	v_mfma_f32_16x16x32_bf16 v[40:43], v[172:175], v[180:183], v[40:43]
	v_mfma_f32_16x16x32_bf16 v[32:35], v[160:163], v[188:191], v[32:35]
	v_mfma_f32_16x16x32_bf16 v[24:27], v[172:175], v[188:191], v[24:27]
	v_mfma_f32_16x16x32_bf16 v[16:19], v[160:163], v[196:199], v[16:19]
	v_mfma_f32_16x16x32_bf16 v[8:11], v[172:175], v[196:199], v[8:11]
	v_mfma_f32_16x16x32_bf16 v[4:7], v[160:163], v[204:207], v[4:7]
	v_mfma_f32_16x16x32_bf16 v[0:3], v[172:175], v[204:207], v[0:3]
	v_mfma_f32_16x16x32_bf16 v[48:51], v[164:167], v[184:187], v[48:51]
	v_mfma_f32_16x16x32_bf16 v[40:43], v[176:179], v[184:187], v[40:43]
	v_mfma_f32_16x16x32_bf16 v[32:35], v[164:167], v[192:195], v[32:35]
	v_mfma_f32_16x16x32_bf16 v[24:27], v[176:179], v[192:195], v[24:27]
	v_mfma_f32_16x16x32_bf16 v[16:19], v[164:167], v[200:203], v[16:19]
	v_mfma_f32_16x16x32_bf16 v[8:11], v[176:179], v[200:203], v[8:11]
	v_mfma_f32_16x16x32_bf16 v[4:7], v[164:167], v[208:211], v[4:7]
	v_mfma_f32_16x16x32_bf16 v[0:3], v[176:179], v[208:211], v[0:3]
	s_setprio 0
	s_barrier
	s_add_i32 s50, s50, 2
	s_add_u32 s6, s6, 0x100
	s_addc_u32 s7, s7, 0
	s_add_u32 s23, s23, 0x100
	s_addc_u32 s49, s49, 0
	s_cmp_gt_u32 s50, 29
	s_cbranch_scc0 .LBB0_831
	s_and_b64 vcc, exec, s[14:15]
	s_cbranch_vccz .LBB0_834
	s_barrier

; #define PG8_STAGE(bufoff, gbase, voff) do { _Pragma("unroll") for (int _i = 0; _i < 2; ++_i) \
;         __builtin_amdgcn_global_load_lds((const unsigned*)((const char*)(gbase) + (voff)[_i]), (LAS unsigned*)(lds + (bufoff) + ldsw + _i * 8192), 16, 0, 0); } while (0)
; #define PG8_LDA(dst, b, h) do { _Pragma("unroll") for (int m = 0; m < 4; ++m) _Pragma("unroll") for (int k = 0; k < 2; ++k) dst[m][k] = *(const LAS bf16x8*)(lds + PG8_SA(b, h) + aoff + m * 2048 + k * 1024); } while (0)
; #define PG8_LDB(dst, b, h) do { _Pragma("unroll") for (int n = 0; n < 2; ++n) _Pragma("unroll") for (int k = 0; k < 2; ++k) dst[n][k] = *(const LAS bf16x8*)(lds + PG8_SB(b, h) + boff + n * 2048 + k * 1024); } while (0)
; #define PG8_MMA(ai, bj, At, Bt) do { __builtin_amdgcn_s_setprio(1); _Pragma("unroll") for (int m = 0; m < 4; ++m) _Pragma("unroll") for (int n = 0; n < 2; ++n) _Pragma("unroll") for (int k = 0; k < 2; ++k) \
;         acc[ai][bj][m][n] = __builtin_amdgcn_mfma_f32_16x16x32_bf16(Bt[n][k], At[m][k], acc[ai][bj][m][n], 0, 0, 0); __builtin_amdgcn_s_setprio(0); } while (0)
; #define PG8_WAIT_V(n) asm volatile("s_waitcnt vmcnt(" #n ")" ::: "memory")
; #define PG8_WAIT_L(n) asm volatile("s_waitcnt lgkmcnt(" #n ")" ::: "memory")
; #define PG8_BAR __builtin_amdgcn_s_barrier()
; #define PG8_SCHED __builtin_amdgcn_sched_barrier(0)
; template <class Desc, class Epi>
; DI void gemm_phase(LAS unsigned char* lds, const Desc& D, const Epi& E, int wv) {
;     ...
;             PG8_LDB(B0, 0, 0); PG8_LDB(B1, 0, 1); PG8_SCHED; PG8_LDA(At, 0, 0); PG8_STAGE(PG8_SA(1, 1), a1 + hstepA, voffA);
;             PG8_WAIT_V(8); PG8_WAIT_L(0); PG8_BAR; PG8_MMA(0, 0, At, B0); PG8_MMA(0, 1, At, B1); PG8_BAR; PG8_SCHED;
;             PG8_LDA(At, 0, 1); PG8_STAGE(PG8_SB(0, 0), b2, voffB); PG8_STAGE(PG8_SB(0, 1), b2 + hstepB, voffB); PG8_STAGE(PG8_SA(0, 0), a2, voffA);
;             PG8_WAIT_V(8); PG8_WAIT_L(0); PG8_BAR; PG8_MMA(1, 0, At, B0); PG8_MMA(1, 1, At, B1); PG8_BAR; PG8_SCHED;
.LBB0_962:
	ds_read_b128 v[146:149], v157
	ds_read_b128 v[150:153], v157 offset:1024
	ds_read_b128 v[160:163], v157 offset:2048
	ds_read_b128 v[164:167], v157 offset:3072
	ds_read_b128 v[168:171], v158
	ds_read_b128 v[172:175], v158 offset:1024
	ds_read_b128 v[176:179], v158 offset:2048
	ds_read_b128 v[180:183], v158 offset:3072
	s_add_u32 s60, s70, 0xfff80080
	s_addc_u32 s63, s71, -1
	s_cmp_eq_u32 s53, 28
	s_cselect_b32 s75, s65, s63
	s_cselect_b32 s74, s64, s60
	s_cselect_b32 s73, s69, s10
	s_cselect_b32 s72, s68, s9
	v_lshl_add_u64 v[154:155], s[70:71], 0, v[138:139]
	s_add_i32 m0, s3, 0xc000
	ds_read_b128 v[184:187], v159
	ds_read_b128 v[188:191], v159 offset:1024
	ds_read_b128 v[192:195], v159 offset:2048
	ds_read_b128 v[196:199], v159 offset:3072
	ds_read_b128 v[200:203], v159 offset:4096
	ds_read_b128 v[204:207], v159 offset:5120
	ds_read_b128 v[208:211], v159 offset:6144
	ds_read_b128 v[212:215], v159 offset:7168
	global_load_lds_dwordx4 v[154:155], off
	s_add_i32 m0, s3, 0xe000
	v_lshl_add_u64 v[154:155], s[70:71], 0, v[140:141]
	global_load_lds_dwordx4 v[154:155], off
	s_waitcnt vmcnt(8) lgkmcnt(0)
	s_barrier
	s_setprio 1
	v_mfma_f32_16x16x32_bf16 v[124:127], v[146:149], v[184:187], v[124:127]
	v_mfma_f32_16x16x32_bf16 v[120:123], v[160:163], v[184:187], v[120:123]
	v_mfma_f32_16x16x32_bf16 v[108:111], v[146:149], v[192:195], v[108:111]
	v_mfma_f32_16x16x32_bf16 v[104:107], v[160:163], v[192:195], v[104:107]
	v_mfma_f32_16x16x32_bf16 v[92:95], v[146:149], v[200:203], v[92:95]
	v_mfma_f32_16x16x32_bf16 v[88:91], v[160:163], v[200:203], v[88:91]
	v_mfma_f32_16x16x32_bf16 v[76:79], v[146:149], v[208:211], v[76:79]
	v_mfma_f32_16x16x32_bf16 v[72:75], v[160:163], v[208:211], v[72:75]
	v_mfma_f32_16x16x32_bf16 v[124:127], v[150:153], v[188:191], v[124:127]
	v_mfma_f32_16x16x32_bf16 v[120:123], v[164:167], v[188:191], v[120:123]
	v_mfma_f32_16x16x32_bf16 v[108:111], v[150:153], v[196:199], v[108:111]
	v_mfma_f32_16x16x32_bf16 v[104:107], v[164:167], v[196:199], v[104:107]
	v_mfma_f32_16x16x32_bf16 v[92:95], v[150:153], v[204:207], v[92:95]
	v_mfma_f32_16x16x32_bf16 v[88:91], v[164:167], v[204:207], v[88:91]
	v_mfma_f32_16x16x32_bf16 v[76:79], v[150:153], v[212:215], v[76:79]
	v_mfma_f32_16x16x32_bf16 v[72:75], v[164:167], v[212:215], v[72:75]
	v_mfma_f32_16x16x32_bf16 v[116:119], v[168:171], v[184:187], v[116:119]
	v_mfma_f32_16x16x32_bf16 v[112:115], v[176:179], v[184:187], v[112:115]
	v_mfma_f32_16x16x32_bf16 v[100:103], v[168:171], v[192:195], v[100:103]
	v_mfma_f32_16x16x32_bf16 v[96:99], v[176:179], v[192:195], v[96:99]
	v_mfma_f32_16x16x32_bf16 v[84:87], v[168:171], v[200:203], v[84:87]
	v_mfma_f32_16x16x32_bf16 v[80:83], v[176:179], v[200:203], v[80:83]
	v_mfma_f32_16x16x32_bf16 v[68:71], v[168:171], v[208:211], v[68:71]
	v_mfma_f32_16x16x32_bf16 v[64:67], v[176:179], v[208:211], v[64:67]
	v_mfma_f32_16x16x32_bf16 v[116:119], v[172:175], v[188:191], v[116:119]
	v_mfma_f32_16x16x32_bf16 v[112:115], v[180:183], v[188:191], v[112:115]
	v_mfma_f32_16x16x32_bf16 v[100:103], v[172:175], v[196:199], v[100:103]
	v_mfma_f32_16x16x32_bf16 v[96:99], v[180:183], v[196:199], v[96:99]
	v_mfma_f32_16x16x32_bf16 v[84:87], v[172:175], v[204:207], v[84:87]
	v_mfma_f32_16x16x32_bf16 v[80:83], v[180:183], v[204:207], v[80:83]
	v_mfma_f32_16x16x32_bf16 v[68:71], v[172:175], v[212:215], v[68:71]
	v_mfma_f32_16x16x32_bf16 v[64:67], v[180:183], v[212:215], v[64:67]
	s_setprio 0
	s_barrier
	s_add_i32 s60, s46, s2
	v_lshl_add_u64 v[154:155], s[72:73], 0, v[130:131]
	s_mov_b32 m0, s60
	ds_read_b128 v[184:187], v159 offset:16384
	ds_read_b128 v[188:191], v159 offset:17408
	ds_read_b128 v[192:195], v159 offset:18432
	ds_read_b128 v[196:199], v159 offset:19456
	ds_read_b128 v[200:203], v159 offset:20480
	ds_read_b128 v[204:207], v159 offset:21504
	ds_read_b128 v[208:211], v159 offset:22528
	ds_read_b128 v[212:215], v159 offset:23552
	global_load_lds_dwordx4 v[154:155], off
	s_add_i32 m0, s60, 0x2000
	s_add_u32 s76, s72, 0x80000
	v_lshl_add_u64 v[216:217], s[72:73], 0, v[134:135]
	s_addc_u32 s77, s73, 0
	s_add_i32 s60, s47, s2
	global_load_lds_dwordx4 v[216:217], off
	v_lshl_add_u64 v[218:219], s[76:77], 0, v[130:131]
	s_mov_b32 m0, s60
	v_lshl_add_u64 v[220:221], s[74:75], 0, v[132:133]
	global_load_lds_dwordx4 v[218:219], off
	s_add_i32 m0, s60, 0x2000
	v_lshl_add_u64 v[218:219], s[76:77], 0, v[134:135]
	global_load_lds_dwordx4 v[218:219], off
	s_mov_b32 m0, s3
	v_lshl_add_u64 v[218:219], s[74:75], 0, v[128:129]
	global_load_lds_dwordx4 v[218:219], off
	s_mov_b32 m0, s28
	s_nop 0
	global_load_lds_dwordx4 v[220:221], off
	s_waitcnt vmcnt(8) lgkmcnt(0)
	s_barrier
; #define PG8_STAGE(bufoff, gbase, voff) do { _Pragma("unroll") for (int _i = 0; _i < 2; ++_i) \
;         __builtin_amdgcn_global_load_lds((const unsigned*)((const char*)(gbase) + (voff)[_i]), (LAS unsigned*)(lds + (bufoff) + ldsw + _i * 8192), 16, 0, 0); } while (0)
; #define PG8_LDA(dst, b, h) do { _Pragma("unroll") for (int m = 0; m < 4; ++m) _Pragma("unroll") for (int k = 0; k < 2; ++k) dst[m][k] = *(const LAS bf16x8*)(lds + PG8_SA(b, h) + aoff + m * 2048 + k * 1024); } while (0)
; #define PG8_LDB(dst, b, h) do { _Pragma("unroll") for (int n = 0; n < 2; ++n) _Pragma("unroll") for (int k = 0; k < 2; ++k) dst[n][k] = *(const LAS bf16x8*)(lds + PG8_SB(b, h) + boff + n * 2048 + k * 1024); } while (0)
; #define PG8_MMA(ai, bj, At, Bt) do { __builtin_amdgcn_s_setprio(1); _Pragma("unroll") for (int m = 0; m < 4; ++m) _Pragma("unroll") for (int n = 0; n < 2; ++n) _Pragma("unroll") for (int k = 0; k < 2; ++k) \
;         acc[ai][bj][m][n] = __builtin_amdgcn_mfma_f32_16x16x32_bf16(Bt[n][k], At[m][k], acc[ai][bj][m][n], 0, 0, 0); __builtin_amdgcn_s_setprio(0); } while (0)
; #define PG8_WAIT_V(n) asm volatile("s_waitcnt vmcnt(" #n ")" ::: "memory")
; #define PG8_WAIT_L(n) asm volatile("s_waitcnt lgkmcnt(" #n ")" ::: "memory")
; #define PG8_BAR __builtin_amdgcn_s_barrier()
; #define PG8_SCHED __builtin_amdgcn_sched_barrier(0)
; template <class Desc, class Epi>
; DI void gemm_phase(LAS unsigned char* lds, const Desc& D, const Epi& E, int wv) {
;     ...
;             PG8_WAIT_V(8); PG8_WAIT_L(0); PG8_BAR; PG8_MMA(1, 0, At, B0); PG8_MMA(1, 1, At, B1); PG8_BAR; PG8_SCHED;
;             PG8_LDB(B0, 1, 0); PG8_LDB(B1, 1, 1); PG8_SCHED; PG8_LDA(At, 1, 0); PG8_STAGE(PG8_SA(0, 1), a2 + hstepA, voffA);
;             PG8_WAIT_V(8); PG8_WAIT_L(0); PG8_BAR; PG8_MMA(0, 0, At, B0); PG8_MMA(0, 1, At, B1); PG8_BAR; PG8_SCHED;
	s_setprio 1
	v_mfma_f32_16x16x32_bf16 v[60:63], v[146:149], v[184:187], v[60:63]
	v_mfma_f32_16x16x32_bf16 v[56:59], v[160:163], v[184:187], v[56:59]
	v_mfma_f32_16x16x32_bf16 v[44:47], v[146:149], v[192:195], v[44:47]
	v_mfma_f32_16x16x32_bf16 v[40:43], v[160:163], v[192:195], v[40:43]
	v_mfma_f32_16x16x32_bf16 v[28:31], v[146:149], v[200:203], v[28:31]
	v_mfma_f32_16x16x32_bf16 v[24:27], v[160:163], v[200:203], v[24:27]
	v_mfma_f32_16x16x32_bf16 v[12:15], v[146:149], v[208:211], v[12:15]
	v_mfma_f32_16x16x32_bf16 v[8:11], v[160:163], v[208:211], v[8:11]
	v_mfma_f32_16x16x32_bf16 v[60:63], v[150:153], v[188:191], v[60:63]
	v_mfma_f32_16x16x32_bf16 v[56:59], v[164:167], v[188:191], v[56:59]
	v_mfma_f32_16x16x32_bf16 v[44:47], v[150:153], v[196:199], v[44:47]
	v_mfma_f32_16x16x32_bf16 v[40:43], v[164:167], v[196:199], v[40:43]
	v_mfma_f32_16x16x32_bf16 v[28:31], v[150:153], v[204:207], v[28:31]
	v_mfma_f32_16x16x32_bf16 v[24:27], v[164:167], v[204:207], v[24:27]
	v_mfma_f32_16x16x32_bf16 v[12:15], v[150:153], v[212:215], v[12:15]
	v_mfma_f32_16x16x32_bf16 v[8:11], v[164:167], v[212:215], v[8:11]
	v_mfma_f32_16x16x32_bf16 v[52:55], v[168:171], v[184:187], v[52:55]
	v_mfma_f32_16x16x32_bf16 v[48:51], v[176:179], v[184:187], v[48:51]
	v_mfma_f32_16x16x32_bf16 v[36:39], v[168:171], v[192:195], v[36:39]
	v_mfma_f32_16x16x32_bf16 v[32:35], v[176:179], v[192:195], v[32:35]
	v_mfma_f32_16x16x32_bf16 v[20:23], v[168:171], v[200:203], v[20:23]
	v_mfma_f32_16x16x32_bf16 v[16:19], v[176:179], v[200:203], v[16:19]
	v_mfma_f32_16x16x32_bf16 v[4:7], v[168:171], v[208:211], v[4:7]
	v_mfma_f32_16x16x32_bf16 v[0:3], v[176:179], v[208:211], v[0:3]
	v_mfma_f32_16x16x32_bf16 v[52:55], v[172:175], v[188:191], v[52:55]
	v_mfma_f32_16x16x32_bf16 v[48:51], v[180:183], v[188:191], v[48:51]
	v_mfma_f32_16x16x32_bf16 v[36:39], v[172:175], v[196:199], v[36:39]
	v_mfma_f32_16x16x32_bf16 v[32:35], v[180:183], v[196:199], v[32:35]
	v_mfma_f32_16x16x32_bf16 v[20:23], v[172:175], v[204:207], v[20:23]
	v_mfma_f32_16x16x32_bf16 v[16:19], v[180:183], v[204:207], v[16:19]
	v_mfma_f32_16x16x32_bf16 v[4:7], v[172:175], v[212:215], v[4:7]
	v_mfma_f32_16x16x32_bf16 v[0:3], v[180:183], v[212:215], v[0:3]
	s_setprio 0
	s_barrier
	s_add_i32 s60, 0, 0x18000
	v_add_u32_e32 v136, s60, v156
	s_add_i32 s63, 0, 0x1c000
	ds_read_b128 v[146:149], v136
	ds_read_b128 v[150:153], v136 offset:1024
	ds_read_b128 v[160:163], v136 offset:2048
	ds_read_b128 v[164:167], v136 offset:3072
	v_add_u32_e32 v136, s63, v156
	ds_read_b128 v[168:171], v136
	ds_read_b128 v[172:175], v136 offset:1024
	ds_read_b128 v[176:179], v136 offset:2048
	ds_read_b128 v[180:183], v136 offset:3072
	s_add_u32 s74, s74, 0x80000
	s_addc_u32 s75, s75, 0
	s_mov_b32 m0, s29
	v_lshl_add_u64 v[222:223], s[74:75], 0, v[128:129]
	ds_read_b128 v[184:187], v159 offset:32768
	ds_read_b128 v[188:191], v159 offset:33792
	ds_read_b128 v[192:195], v159 offset:34816
	ds_read_b128 v[196:199], v159 offset:35840
	ds_read_b128 v[200:203], v159 offset:36864
	ds_read_b128 v[204:207], v159 offset:37888
	ds_read_b128 v[208:211], v159 offset:38912
	ds_read_b128 v[212:215], v159 offset:39936
	global_load_lds_dwordx4 v[222:223], off
	s_mov_b32 m0, s30
	v_lshl_add_u64 v[222:223], s[74:75], 0, v[132:133]
	global_load_lds_dwordx4 v[222:223], off
	s_waitcnt vmcnt(8) lgkmcnt(0)
	s_barrier
	s_setprio 1
	v_mfma_f32_16x16x32_bf16 v[124:127], v[146:149], v[184:187], v[124:127]
	v_mfma_f32_16x16x32_bf16 v[120:123], v[160:163], v[184:187], v[120:123]
	v_mfma_f32_16x16x32_bf16 v[108:111], v[146:149], v[192:195], v[108:111]
	v_mfma_f32_16x16x32_bf16 v[104:107], v[160:163], v[192:195], v[104:107]
	v_mfma_f32_16x16x32_bf16 v[92:95], v[146:149], v[200:203], v[92:95]
	v_mfma_f32_16x16x32_bf16 v[88:91], v[160:163], v[200:203], v[88:91]
	v_mfma_f32_16x16x32_bf16 v[76:79], v[146:149], v[208:211], v[76:79]
	v_mfma_f32_16x16x32_bf16 v[72:75], v[160:163], v[208:211], v[72:75]
	v_mfma_f32_16x16x32_bf16 v[124:127], v[150:153], v[188:191], v[124:127]
	v_mfma_f32_16x16x32_bf16 v[120:123], v[164:167], v[188:191], v[120:123]
	v_mfma_f32_16x16x32_bf16 v[108:111], v[150:153], v[196:199], v[108:111]
	v_mfma_f32_16x16x32_bf16 v[104:107], v[164:167], v[196:199], v[104:107]
	v_mfma_f32_16x16x32_bf16 v[92:95], v[150:153], v[204:207], v[92:95]
	v_mfma_f32_16x16x32_bf16 v[88:91], v[164:167], v[204:207], v[88:91]
	v_mfma_f32_16x16x32_bf16 v[76:79], v[150:153], v[212:215], v[76:79]
	v_mfma_f32_16x16x32_bf16 v[72:75], v[164:167], v[212:215], v[72:75]
	v_mfma_f32_16x16x32_bf16 v[116:119], v[168:171], v[184:187], v[116:119]
	v_mfma_f32_16x16x32_bf16 v[112:115], v[176:179], v[184:187], v[112:115]
	v_mfma_f32_16x16x32_bf16 v[100:103], v[168:171], v[192:195], v[100:103]
	v_mfma_f32_16x16x32_bf16 v[96:99], v[176:179], v[192:195], v[96:99]
	v_mfma_f32_16x16x32_bf16 v[84:87], v[168:171], v[200:203], v[84:87]
	v_mfma_f32_16x16x32_bf16 v[80:83], v[176:179], v[200:203], v[80:83]
	v_mfma_f32_16x16x32_bf16 v[68:71], v[168:171], v[208:211], v[68:71]
	v_mfma_f32_16x16x32_bf16 v[64:67], v[176:179], v[208:211], v[64:67]
	v_mfma_f32_16x16x32_bf16 v[116:119], v[172:175], v[188:191], v[116:119]
	v_mfma_f32_16x16x32_bf16 v[112:115], v[180:183], v[188:191], v[112:115]
	v_mfma_f32_16x16x32_bf16 v[100:103], v[172:175], v[196:199], v[100:103]
	v_mfma_f32_16x16x32_bf16 v[96:99], v[180:183], v[196:199], v[96:99]
	v_mfma_f32_16x16x32_bf16 v[84:87], v[172:175], v[204:207], v[84:87]
	v_mfma_f32_16x16x32_bf16 v[80:83], v[180:183], v[204:207], v[80:83]
	v_mfma_f32_16x16x32_bf16 v[68:71], v[172:175], v[212:215], v[68:71]
	v_mfma_f32_16x16x32_bf16 v[64:67], v[180:183], v[212:215], v[64:67]
	s_setprio 0
	s_barrier
; #define PG8_STAGE(bufoff, gbase, voff) do { _Pragma("unroll") for (int _i = 0; _i < 2; ++_i) \
;         __builtin_amdgcn_global_load_lds((const unsigned*)((const char*)(gbase) + (voff)[_i]), (LAS unsigned*)(lds + (bufoff) + ldsw + _i * 8192), 16, 0, 0); } while (0)
; #define PG8_LDA(dst, b, h) do { _Pragma("unroll") for (int m = 0; m < 4; ++m) _Pragma("unroll") for (int k = 0; k < 2; ++k) dst[m][k] = *(const LAS bf16x8*)(lds + PG8_SA(b, h) + aoff + m * 2048 + k * 1024); } while (0)
; #define PG8_MMA(ai, bj, At, Bt) do { __builtin_amdgcn_s_setprio(1); _Pragma("unroll") for (int m = 0; m < 4; ++m) _Pragma("unroll") for (int n = 0; n < 2; ++n) _Pragma("unroll") for (int k = 0; k < 2; ++k) \
;         acc[ai][bj][m][n] = __builtin_amdgcn_mfma_f32_16x16x32_bf16(Bt[n][k], At[m][k], acc[ai][bj][m][n], 0, 0, 0); __builtin_amdgcn_s_setprio(0); } while (0)
; #define PG8_WAIT_V(n) asm volatile("s_waitcnt vmcnt(" #n ")" ::: "memory")
; #define PG8_WAIT_L(n) asm volatile("s_waitcnt lgkmcnt(" #n ")" ::: "memory")
; #define PG8_BAR __builtin_amdgcn_s_barrier()
; #define PG8_SCHED __builtin_amdgcn_sched_barrier(0)
; template <class Desc, class Epi>
; DI void gemm_phase(LAS unsigned char* lds, const Desc& D, const Epi& E, int wv) {
;     ...
;             PG8_LDA(At, 1, 1); PG8_STAGE(PG8_SB(1, 0), b3, voffB); PG8_STAGE(PG8_SB(1, 1), b3 + hstepB, voffB); PG8_STAGE(PG8_SA(1, 0), a3, voffA);
;             PG8_WAIT_V(8); PG8_WAIT_L(0); PG8_BAR; PG8_MMA(1, 0, At, B0); PG8_MMA(1, 1, At, B1); PG8_BAR; PG8_SCHED;
;         }
	s_add_i32 s60, s60, s2
	v_lshl_add_u64 v[154:155], v[154:155], 0, s[14:15]
	s_mov_b32 m0, s60
	ds_read_b128 v[184:187], v159 offset:49152
	ds_read_b128 v[188:191], v159 offset:50176
	ds_read_b128 v[192:195], v159 offset:51200
	ds_read_b128 v[196:199], v159 offset:52224
	ds_read_b128 v[200:203], v159 offset:53248
	ds_read_b128 v[204:207], v159 offset:54272
	ds_read_b128 v[208:211], v159 offset:55296
	ds_read_b128 v[212:215], v159 offset:56320
	global_load_lds_dwordx4 v[154:155], off
	s_add_i32 m0, s60, 0x2000
	s_add_u32 s72, s72, 0x80080
	v_lshl_add_u64 v[154:155], v[216:217], 0, s[14:15]
	s_addc_u32 s73, s73, 0
	s_add_i32 s60, s63, s2
	global_load_lds_dwordx4 v[154:155], off
	s_mov_b32 m0, s60
	v_lshl_add_u64 v[154:155], s[72:73], 0, v[130:131]
	global_load_lds_dwordx4 v[154:155], off
	s_add_i32 m0, s60, 0x2000
	v_lshl_add_u64 v[154:155], s[72:73], 0, v[134:135]
	global_load_lds_dwordx4 v[154:155], off
	s_mov_b32 m0, s41
	v_lshl_add_u64 v[154:155], v[218:219], 0, s[14:15]
	global_load_lds_dwordx4 v[154:155], off
	s_mov_b32 m0, s42
	v_lshl_add_u64 v[154:155], v[220:221], 0, s[14:15]
	global_load_lds_dwordx4 v[154:155], off
	s_waitcnt vmcnt(8) lgkmcnt(0)
	s_barrier
	s_setprio 1
	v_mfma_f32_16x16x32_bf16 v[60:63], v[146:149], v[184:187], v[60:63]
	v_mfma_f32_16x16x32_bf16 v[56:59], v[160:163], v[184:187], v[56:59]
	v_mfma_f32_16x16x32_bf16 v[44:47], v[146:149], v[192:195], v[44:47]
	v_mfma_f32_16x16x32_bf16 v[40:43], v[160:163], v[192:195], v[40:43]
	v_mfma_f32_16x16x32_bf16 v[28:31], v[146:149], v[200:203], v[28:31]
	v_mfma_f32_16x16x32_bf16 v[24:27], v[160:163], v[200:203], v[24:27]
	v_mfma_f32_16x16x32_bf16 v[12:15], v[146:149], v[208:211], v[12:15]
	v_mfma_f32_16x16x32_bf16 v[8:11], v[160:163], v[208:211], v[8:11]
	v_mfma_f32_16x16x32_bf16 v[60:63], v[150:153], v[188:191], v[60:63]
	v_mfma_f32_16x16x32_bf16 v[56:59], v[164:167], v[188:191], v[56:59]
	v_mfma_f32_16x16x32_bf16 v[44:47], v[150:153], v[196:199], v[44:47]
	v_mfma_f32_16x16x32_bf16 v[40:43], v[164:167], v[196:199], v[40:43]
	v_mfma_f32_16x16x32_bf16 v[28:31], v[150:153], v[204:207], v[28:31]
	v_mfma_f32_16x16x32_bf16 v[24:27], v[164:167], v[204:207], v[24:27]
	v_mfma_f32_16x16x32_bf16 v[12:15], v[150:153], v[212:215], v[12:15]
	v_mfma_f32_16x16x32_bf16 v[8:11], v[164:167], v[212:215], v[8:11]
	v_mfma_f32_16x16x32_bf16 v[52:55], v[168:171], v[184:187], v[52:55]
	v_mfma_f32_16x16x32_bf16 v[48:51], v[176:179], v[184:187], v[48:51]
	v_mfma_f32_16x16x32_bf16 v[36:39], v[168:171], v[192:195], v[36:39]
	v_mfma_f32_16x16x32_bf16 v[32:35], v[176:179], v[192:195], v[32:35]
	v_mfma_f32_16x16x32_bf16 v[20:23], v[168:171], v[200:203], v[20:23]
	v_mfma_f32_16x16x32_bf16 v[16:19], v[176:179], v[200:203], v[16:19]
	v_mfma_f32_16x16x32_bf16 v[4:7], v[168:171], v[208:211], v[4:7]
	v_mfma_f32_16x16x32_bf16 v[0:3], v[176:179], v[208:211], v[0:3]
	v_mfma_f32_16x16x32_bf16 v[52:55], v[172:175], v[188:191], v[52:55]
	v_mfma_f32_16x16x32_bf16 v[48:51], v[180:183], v[188:191], v[48:51]
	v_mfma_f32_16x16x32_bf16 v[36:39], v[172:175], v[196:199], v[36:39]
	v_mfma_f32_16x16x32_bf16 v[32:35], v[180:183], v[196:199], v[32:35]
	v_mfma_f32_16x16x32_bf16 v[20:23], v[172:175], v[204:207], v[20:23]
	v_mfma_f32_16x16x32_bf16 v[16:19], v[180:183], v[204:207], v[16:19]
	v_mfma_f32_16x16x32_bf16 v[4:7], v[172:175], v[212:215], v[4:7]
	v_mfma_f32_16x16x32_bf16 v[0:3], v[180:183], v[212:215], v[0:3]
	s_setprio 0
	s_barrier
	s_add_i32 s53, s53, 2
	s_add_u32 s70, s70, 0x100
	s_addc_u32 s71, s71, 0
	s_add_u32 s9, s9, 0x100
	s_addc_u32 s10, s10, 0
	s_cmp_gt_u32 s53, 29
	s_cbranch_scc0 .LBB0_962
	s_and_b64 vcc, exec, s[20:21]
	s_cbranch_vccz .LBB0_965
	s_barrier

; #define PG8_STAGE(bufoff, gbase, voff) do { _Pragma("unroll") for (int _i = 0; _i < 2; ++_i) \
;         __builtin_amdgcn_global_load_lds((const unsigned*)((const char*)(gbase) + (voff)[_i]), (LAS unsigned*)(lds + (bufoff) + ldsw + _i * 8192), 16, 0, 0); } while (0)
; #define PG8_LDA(dst, b, h) do { _Pragma("unroll") for (int m = 0; m < 4; ++m) _Pragma("unroll") for (int k = 0; k < 2; ++k) dst[m][k] = *(const LAS bf16x8*)(lds + PG8_SA(b, h) + aoff + m * 2048 + k * 1024); } while (0)
; #define PG8_LDB(dst, b, h) do { _Pragma("unroll") for (int n = 0; n < 2; ++n) _Pragma("unroll") for (int k = 0; k < 2; ++k) dst[n][k] = *(const LAS bf16x8*)(lds + PG8_SB(b, h) + boff + n * 2048 + k * 1024); } while (0)
; #define PG8_MMA(ai, bj, At, Bt) do { __builtin_amdgcn_s_setprio(1); _Pragma("unroll") for (int m = 0; m < 4; ++m) _Pragma("unroll") for (int n = 0; n < 2; ++n) _Pragma("unroll") for (int k = 0; k < 2; ++k) \
;         acc[ai][bj][m][n] = __builtin_amdgcn_mfma_f32_16x16x32_bf16(Bt[n][k], At[m][k], acc[ai][bj][m][n], 0, 0, 0); __builtin_amdgcn_s_setprio(0); } while (0)
; #define PG8_WAIT_V(n) asm volatile("s_waitcnt vmcnt(" #n ")" ::: "memory")
; #define PG8_WAIT_L(n) asm volatile("s_waitcnt lgkmcnt(" #n ")" ::: "memory")
; #define PG8_BAR __builtin_amdgcn_s_barrier()
; #define PG8_SCHED __builtin_amdgcn_sched_barrier(0)
; template <class Desc, class Epi>
; DI void gemm_phase(LAS unsigned char* lds, const Desc& D, const Epi& E, int wv) {
;     ...
;             PG8_LDB(B0, 0, 0); PG8_LDB(B1, 0, 1); PG8_SCHED; PG8_LDA(At, 0, 0); PG8_STAGE(PG8_SA(1, 1), a1 + hstepA, voffA);
;             PG8_WAIT_V(8); PG8_WAIT_L(0); PG8_BAR; PG8_MMA(0, 0, At, B0); PG8_MMA(0, 1, At, B1); PG8_BAR; PG8_SCHED;
;             PG8_LDA(At, 0, 1); PG8_STAGE(PG8_SB(0, 0), b2, voffB); PG8_STAGE(PG8_SB(0, 1), b2 + hstepB, voffB); PG8_STAGE(PG8_SA(0, 0), a2, voffA);
;             PG8_WAIT_V(8); PG8_WAIT_L(0); PG8_BAR; PG8_MMA(1, 0, At, B0); PG8_MMA(1, 1, At, B1); PG8_BAR; PG8_SCHED;
.LBB0_1313:
	ds_read_b128 v[146:149], v157
	ds_read_b128 v[150:153], v157 offset:1024
	ds_read_b128 v[160:163], v157 offset:2048
	ds_read_b128 v[164:167], v157 offset:3072
	ds_read_b128 v[168:171], v158
	ds_read_b128 v[172:175], v158 offset:1024
	ds_read_b128 v[176:179], v158 offset:2048
	ds_read_b128 v[180:183], v158 offset:3072
	s_add_u32 s40, s22, 0xfff80080
	s_addc_u32 s41, s23, -1
	s_cmp_eq_u32 s50, 28
	s_cselect_b32 s63, s15, s41
	s_cselect_b32 s62, s14, s40
	s_cselect_b32 s41, s17, s21
	s_cselect_b32 s40, s16, s19
	v_lshl_add_u64 v[154:155], s[22:23], 0, v[138:139]
	s_add_i32 m0, s28, 0xc000
	ds_read_b128 v[184:187], v159
	ds_read_b128 v[188:191], v159 offset:1024
	ds_read_b128 v[192:195], v159 offset:2048
	ds_read_b128 v[196:199], v159 offset:3072
	ds_read_b128 v[200:203], v159 offset:4096
	ds_read_b128 v[204:207], v159 offset:5120
	ds_read_b128 v[208:211], v159 offset:6144
	ds_read_b128 v[212:215], v159 offset:7168
	global_load_lds_dwordx4 v[154:155], off
	s_add_i32 m0, s28, 0xe000
	v_lshl_add_u64 v[154:155], s[22:23], 0, v[140:141]
	global_load_lds_dwordx4 v[154:155], off
	s_waitcnt vmcnt(8) lgkmcnt(0)
	s_barrier
	s_setprio 1
	v_mfma_f32_16x16x32_bf16 v[124:127], v[146:149], v[184:187], v[124:127]
	v_mfma_f32_16x16x32_bf16 v[120:123], v[160:163], v[184:187], v[120:123]
	v_mfma_f32_16x16x32_bf16 v[108:111], v[146:149], v[192:195], v[108:111]
	v_mfma_f32_16x16x32_bf16 v[104:107], v[160:163], v[192:195], v[104:107]
	v_mfma_f32_16x16x32_bf16 v[92:95], v[146:149], v[200:203], v[92:95]
	v_mfma_f32_16x16x32_bf16 v[88:91], v[160:163], v[200:203], v[88:91]
	v_mfma_f32_16x16x32_bf16 v[76:79], v[146:149], v[208:211], v[76:79]
	v_mfma_f32_16x16x32_bf16 v[72:75], v[160:163], v[208:211], v[72:75]
	v_mfma_f32_16x16x32_bf16 v[124:127], v[150:153], v[188:191], v[124:127]
	v_mfma_f32_16x16x32_bf16 v[120:123], v[164:167], v[188:191], v[120:123]
	v_mfma_f32_16x16x32_bf16 v[108:111], v[150:153], v[196:199], v[108:111]
	v_mfma_f32_16x16x32_bf16 v[104:107], v[164:167], v[196:199], v[104:107]
	v_mfma_f32_16x16x32_bf16 v[92:95], v[150:153], v[204:207], v[92:95]
	v_mfma_f32_16x16x32_bf16 v[88:91], v[164:167], v[204:207], v[88:91]
	v_mfma_f32_16x16x32_bf16 v[76:79], v[150:153], v[212:215], v[76:79]
	v_mfma_f32_16x16x32_bf16 v[72:75], v[164:167], v[212:215], v[72:75]
	v_mfma_f32_16x16x32_bf16 v[116:119], v[168:171], v[184:187], v[116:119]
	v_mfma_f32_16x16x32_bf16 v[112:115], v[176:179], v[184:187], v[112:115]
	v_mfma_f32_16x16x32_bf16 v[100:103], v[168:171], v[192:195], v[100:103]
	v_mfma_f32_16x16x32_bf16 v[96:99], v[176:179], v[192:195], v[96:99]
	v_mfma_f32_16x16x32_bf16 v[84:87], v[168:171], v[200:203], v[84:87]
	v_mfma_f32_16x16x32_bf16 v[80:83], v[176:179], v[200:203], v[80:83]
	v_mfma_f32_16x16x32_bf16 v[68:71], v[168:171], v[208:211], v[68:71]
	v_mfma_f32_16x16x32_bf16 v[64:67], v[176:179], v[208:211], v[64:67]
	v_mfma_f32_16x16x32_bf16 v[116:119], v[172:175], v[188:191], v[116:119]
	v_mfma_f32_16x16x32_bf16 v[112:115], v[180:183], v[188:191], v[112:115]
	v_mfma_f32_16x16x32_bf16 v[100:103], v[172:175], v[196:199], v[100:103]
	v_mfma_f32_16x16x32_bf16 v[96:99], v[180:183], v[196:199], v[96:99]
	v_mfma_f32_16x16x32_bf16 v[84:87], v[172:175], v[204:207], v[84:87]
	v_mfma_f32_16x16x32_bf16 v[80:83], v[180:183], v[204:207], v[80:83]
	v_mfma_f32_16x16x32_bf16 v[68:71], v[172:175], v[212:215], v[68:71]
	v_mfma_f32_16x16x32_bf16 v[64:67], v[180:183], v[212:215], v[64:67]
	s_setprio 0
	s_barrier
	s_add_i32 s51, s48, s2
	v_lshl_add_u64 v[154:155], s[40:41], 0, v[132:133]
	s_mov_b32 m0, s51
	ds_read_b128 v[184:187], v159 offset:16384
	ds_read_b128 v[188:191], v159 offset:17408
	ds_read_b128 v[192:195], v159 offset:18432
	ds_read_b128 v[196:199], v159 offset:19456
	ds_read_b128 v[200:203], v159 offset:20480
	ds_read_b128 v[204:207], v159 offset:21504
	ds_read_b128 v[208:211], v159 offset:22528
	ds_read_b128 v[212:215], v159 offset:23552
	global_load_lds_dwordx4 v[154:155], off
	s_add_i32 m0, s51, 0x2000
	s_add_u32 s52, s40, 0x80000
	v_lshl_add_u64 v[216:217], s[40:41], 0, v[128:129]
	s_addc_u32 s53, s41, 0
	s_add_i32 s51, s49, s2
	global_load_lds_dwordx4 v[216:217], off
	v_lshl_add_u64 v[218:219], s[52:53], 0, v[132:133]
	s_mov_b32 m0, s51
	v_lshl_add_u64 v[220:221], s[62:63], 0, v[130:131]
	global_load_lds_dwordx4 v[218:219], off
	s_add_i32 m0, s51, 0x2000
	v_lshl_add_u64 v[218:219], s[52:53], 0, v[128:129]
	global_load_lds_dwordx4 v[218:219], off
	s_mov_b32 m0, s28
	v_lshl_add_u64 v[218:219], s[62:63], 0, v[134:135]
	global_load_lds_dwordx4 v[218:219], off
	s_mov_b32 m0, s29
	s_nop 0
	global_load_lds_dwordx4 v[220:221], off
	s_waitcnt vmcnt(8) lgkmcnt(0)
	s_barrier
; #define PG8_STAGE(bufoff, gbase, voff) do { _Pragma("unroll") for (int _i = 0; _i < 2; ++_i) \
;         __builtin_amdgcn_global_load_lds((const unsigned*)((const char*)(gbase) + (voff)[_i]), (LAS unsigned*)(lds + (bufoff) + ldsw + _i * 8192), 16, 0, 0); } while (0)
; #define PG8_LDA(dst, b, h) do { _Pragma("unroll") for (int m = 0; m < 4; ++m) _Pragma("unroll") for (int k = 0; k < 2; ++k) dst[m][k] = *(const LAS bf16x8*)(lds + PG8_SA(b, h) + aoff + m * 2048 + k * 1024); } while (0)
; #define PG8_LDB(dst, b, h) do { _Pragma("unroll") for (int n = 0; n < 2; ++n) _Pragma("unroll") for (int k = 0; k < 2; ++k) dst[n][k] = *(const LAS bf16x8*)(lds + PG8_SB(b, h) + boff + n * 2048 + k * 1024); } while (0)
; #define PG8_MMA(ai, bj, At, Bt) do { __builtin_amdgcn_s_setprio(1); _Pragma("unroll") for (int m = 0; m < 4; ++m) _Pragma("unroll") for (int n = 0; n < 2; ++n) _Pragma("unroll") for (int k = 0; k < 2; ++k) \
;         acc[ai][bj][m][n] = __builtin_amdgcn_mfma_f32_16x16x32_bf16(Bt[n][k], At[m][k], acc[ai][bj][m][n], 0, 0, 0); __builtin_amdgcn_s_setprio(0); } while (0)
; #define PG8_WAIT_V(n) asm volatile("s_waitcnt vmcnt(" #n ")" ::: "memory")
; #define PG8_WAIT_L(n) asm volatile("s_waitcnt lgkmcnt(" #n ")" ::: "memory")
; #define PG8_BAR __builtin_amdgcn_s_barrier()
; #define PG8_SCHED __builtin_amdgcn_sched_barrier(0)
; template <class Desc, class Epi>
; DI void gemm_phase(LAS unsigned char* lds, const Desc& D, const Epi& E, int wv) {
;     ...
;             PG8_WAIT_V(8); PG8_WAIT_L(0); PG8_BAR; PG8_MMA(1, 0, At, B0); PG8_MMA(1, 1, At, B1); PG8_BAR; PG8_SCHED;
;             PG8_LDB(B0, 1, 0); PG8_LDB(B1, 1, 1); PG8_SCHED; PG8_LDA(At, 1, 0); PG8_STAGE(PG8_SA(0, 1), a2 + hstepA, voffA);
;             PG8_WAIT_V(8); PG8_WAIT_L(0); PG8_BAR; PG8_MMA(0, 0, At, B0); PG8_MMA(0, 1, At, B1); PG8_BAR; PG8_SCHED;
	s_setprio 1
	v_mfma_f32_16x16x32_bf16 v[60:63], v[146:149], v[184:187], v[60:63]
	v_mfma_f32_16x16x32_bf16 v[56:59], v[160:163], v[184:187], v[56:59]
	v_mfma_f32_16x16x32_bf16 v[44:47], v[146:149], v[192:195], v[44:47]
	v_mfma_f32_16x16x32_bf16 v[40:43], v[160:163], v[192:195], v[40:43]
	v_mfma_f32_16x16x32_bf16 v[28:31], v[146:149], v[200:203], v[28:31]
	v_mfma_f32_16x16x32_bf16 v[24:27], v[160:163], v[200:203], v[24:27]
	v_mfma_f32_16x16x32_bf16 v[12:15], v[146:149], v[208:211], v[12:15]
	v_mfma_f32_16x16x32_bf16 v[8:11], v[160:163], v[208:211], v[8:11]
	v_mfma_f32_16x16x32_bf16 v[60:63], v[150:153], v[188:191], v[60:63]
	v_mfma_f32_16x16x32_bf16 v[56:59], v[164:167], v[188:191], v[56:59]
	v_mfma_f32_16x16x32_bf16 v[44:47], v[150:153], v[196:199], v[44:47]
	v_mfma_f32_16x16x32_bf16 v[40:43], v[164:167], v[196:199], v[40:43]
	v_mfma_f32_16x16x32_bf16 v[28:31], v[150:153], v[204:207], v[28:31]
	v_mfma_f32_16x16x32_bf16 v[24:27], v[164:167], v[204:207], v[24:27]
	v_mfma_f32_16x16x32_bf16 v[12:15], v[150:153], v[212:215], v[12:15]
	v_mfma_f32_16x16x32_bf16 v[8:11], v[164:167], v[212:215], v[8:11]
	v_mfma_f32_16x16x32_bf16 v[52:55], v[168:171], v[184:187], v[52:55]
	v_mfma_f32_16x16x32_bf16 v[48:51], v[176:179], v[184:187], v[48:51]
	v_mfma_f32_16x16x32_bf16 v[36:39], v[168:171], v[192:195], v[36:39]
	v_mfma_f32_16x16x32_bf16 v[32:35], v[176:179], v[192:195], v[32:35]
	v_mfma_f32_16x16x32_bf16 v[20:23], v[168:171], v[200:203], v[20:23]
	v_mfma_f32_16x16x32_bf16 v[16:19], v[176:179], v[200:203], v[16:19]
	v_mfma_f32_16x16x32_bf16 v[4:7], v[168:171], v[208:211], v[4:7]
	v_mfma_f32_16x16x32_bf16 v[0:3], v[176:179], v[208:211], v[0:3]
	v_mfma_f32_16x16x32_bf16 v[52:55], v[172:175], v[188:191], v[52:55]
	v_mfma_f32_16x16x32_bf16 v[48:51], v[180:183], v[188:191], v[48:51]
	v_mfma_f32_16x16x32_bf16 v[36:39], v[172:175], v[196:199], v[36:39]
	v_mfma_f32_16x16x32_bf16 v[32:35], v[180:183], v[196:199], v[32:35]
	v_mfma_f32_16x16x32_bf16 v[20:23], v[172:175], v[204:207], v[20:23]
	v_mfma_f32_16x16x32_bf16 v[16:19], v[180:183], v[204:207], v[16:19]
	v_mfma_f32_16x16x32_bf16 v[4:7], v[172:175], v[212:215], v[4:7]
	v_mfma_f32_16x16x32_bf16 v[0:3], v[180:183], v[212:215], v[0:3]
	s_setprio 0
	s_barrier
	s_add_i32 s51, 0, 0x18000
	v_add_u32_e32 v136, s51, v156
	s_add_i32 s60, 0, 0x1c000
	ds_read_b128 v[146:149], v136
	ds_read_b128 v[150:153], v136 offset:1024
	ds_read_b128 v[160:163], v136 offset:2048
	ds_read_b128 v[164:167], v136 offset:3072
	v_add_u32_e32 v136, s60, v156
	ds_read_b128 v[168:171], v136
	ds_read_b128 v[172:175], v136 offset:1024
	ds_read_b128 v[176:179], v136 offset:2048
	ds_read_b128 v[180:183], v136 offset:3072
	s_add_u32 s52, s62, 0x80000
	s_addc_u32 s53, s63, 0
	s_mov_b32 m0, s30
	v_lshl_add_u64 v[222:223], s[52:53], 0, v[134:135]
	ds_read_b128 v[184:187], v159 offset:32768
	ds_read_b128 v[188:191], v159 offset:33792
	ds_read_b128 v[192:195], v159 offset:34816
	ds_read_b128 v[196:199], v159 offset:35840
	ds_read_b128 v[200:203], v159 offset:36864
	ds_read_b128 v[204:207], v159 offset:37888
	ds_read_b128 v[208:211], v159 offset:38912
	ds_read_b128 v[212:215], v159 offset:39936
	global_load_lds_dwordx4 v[222:223], off
	s_mov_b32 m0, s31
	v_lshl_add_u64 v[222:223], s[52:53], 0, v[130:131]
	global_load_lds_dwordx4 v[222:223], off
	s_waitcnt vmcnt(8) lgkmcnt(0)
	s_barrier
	s_setprio 1
	v_mfma_f32_16x16x32_bf16 v[124:127], v[146:149], v[184:187], v[124:127]
	v_mfma_f32_16x16x32_bf16 v[120:123], v[160:163], v[184:187], v[120:123]
	v_mfma_f32_16x16x32_bf16 v[108:111], v[146:149], v[192:195], v[108:111]
	v_mfma_f32_16x16x32_bf16 v[104:107], v[160:163], v[192:195], v[104:107]
	v_mfma_f32_16x16x32_bf16 v[92:95], v[146:149], v[200:203], v[92:95]
	v_mfma_f32_16x16x32_bf16 v[88:91], v[160:163], v[200:203], v[88:91]
	v_mfma_f32_16x16x32_bf16 v[76:79], v[146:149], v[208:211], v[76:79]
	v_mfma_f32_16x16x32_bf16 v[72:75], v[160:163], v[208:211], v[72:75]
	v_mfma_f32_16x16x32_bf16 v[124:127], v[150:153], v[188:191], v[124:127]
	v_mfma_f32_16x16x32_bf16 v[120:123], v[164:167], v[188:191], v[120:123]
	v_mfma_f32_16x16x32_bf16 v[108:111], v[150:153], v[196:199], v[108:111]
	v_mfma_f32_16x16x32_bf16 v[104:107], v[164:167], v[196:199], v[104:107]
	v_mfma_f32_16x16x32_bf16 v[92:95], v[150:153], v[204:207], v[92:95]
	v_mfma_f32_16x16x32_bf16 v[88:91], v[164:167], v[204:207], v[88:91]
	v_mfma_f32_16x16x32_bf16 v[76:79], v[150:153], v[212:215], v[76:79]
	v_mfma_f32_16x16x32_bf16 v[72:75], v[164:167], v[212:215], v[72:75]
	v_mfma_f32_16x16x32_bf16 v[116:119], v[168:171], v[184:187], v[116:119]
	v_mfma_f32_16x16x32_bf16 v[112:115], v[176:179], v[184:187], v[112:115]
	v_mfma_f32_16x16x32_bf16 v[100:103], v[168:171], v[192:195], v[100:103]
	v_mfma_f32_16x16x32_bf16 v[96:99], v[176:179], v[192:195], v[96:99]
	v_mfma_f32_16x16x32_bf16 v[84:87], v[168:171], v[200:203], v[84:87]
	v_mfma_f32_16x16x32_bf16 v[80:83], v[176:179], v[200:203], v[80:83]
	v_mfma_f32_16x16x32_bf16 v[68:71], v[168:171], v[208:211], v[68:71]
	v_mfma_f32_16x16x32_bf16 v[64:67], v[176:179], v[208:211], v[64:67]
	v_mfma_f32_16x16x32_bf16 v[116:119], v[172:175], v[188:191], v[116:119]
	v_mfma_f32_16x16x32_bf16 v[112:115], v[180:183], v[188:191], v[112:115]
	v_mfma_f32_16x16x32_bf16 v[100:103], v[172:175], v[196:199], v[100:103]
	v_mfma_f32_16x16x32_bf16 v[96:99], v[180:183], v[196:199], v[96:99]
	v_mfma_f32_16x16x32_bf16 v[84:87], v[172:175], v[204:207], v[84:87]
	v_mfma_f32_16x16x32_bf16 v[80:83], v[180:183], v[204:207], v[80:83]
	v_mfma_f32_16x16x32_bf16 v[68:71], v[172:175], v[212:215], v[68:71]
	v_mfma_f32_16x16x32_bf16 v[64:67], v[180:183], v[212:215], v[64:67]
	s_setprio 0
	s_barrier
; #define PG8_STAGE(bufoff, gbase, voff) do { _Pragma("unroll") for (int _i = 0; _i < 2; ++_i) \
;         __builtin_amdgcn_global_load_lds((const unsigned*)((const char*)(gbase) + (voff)[_i]), (LAS unsigned*)(lds + (bufoff) + ldsw + _i * 8192), 16, 0, 0); } while (0)
; #define PG8_LDA(dst, b, h) do { _Pragma("unroll") for (int m = 0; m < 4; ++m) _Pragma("unroll") for (int k = 0; k < 2; ++k) dst[m][k] = *(const LAS bf16x8*)(lds + PG8_SA(b, h) + aoff + m * 2048 + k * 1024); } while (0)
; #define PG8_MMA(ai, bj, At, Bt) do { __builtin_amdgcn_s_setprio(1); _Pragma("unroll") for (int m = 0; m < 4; ++m) _Pragma("unroll") for (int n = 0; n < 2; ++n) _Pragma("unroll") for (int k = 0; k < 2; ++k) \
;         acc[ai][bj][m][n] = __builtin_amdgcn_mfma_f32_16x16x32_bf16(Bt[n][k], At[m][k], acc[ai][bj][m][n], 0, 0, 0); __builtin_amdgcn_s_setprio(0); } while (0)
; #define PG8_WAIT_V(n) asm volatile("s_waitcnt vmcnt(" #n ")" ::: "memory")
; #define PG8_WAIT_L(n) asm volatile("s_waitcnt lgkmcnt(" #n ")" ::: "memory")
; #define PG8_BAR __builtin_amdgcn_s_barrier()
; #define PG8_SCHED __builtin_amdgcn_sched_barrier(0)
; template <class Desc, class Epi>
; DI void gemm_phase(LAS unsigned char* lds, const Desc& D, const Epi& E, int wv) {
;     ...
;             PG8_LDA(At, 1, 1); PG8_STAGE(PG8_SB(1, 0), b3, voffB); PG8_STAGE(PG8_SB(1, 1), b3 + hstepB, voffB); PG8_STAGE(PG8_SA(1, 0), a3, voffA);
;             PG8_WAIT_V(8); PG8_WAIT_L(0); PG8_BAR; PG8_MMA(1, 0, At, B0); PG8_MMA(1, 1, At, B1); PG8_BAR; PG8_SCHED;
;         }
	s_add_i32 s51, s51, s2
	v_lshl_add_u64 v[154:155], v[154:155], 0, s[10:11]
	s_mov_b32 m0, s51
	ds_read_b128 v[184:187], v159 offset:49152
	ds_read_b128 v[188:191], v159 offset:50176
	ds_read_b128 v[192:195], v159 offset:51200
	ds_read_b128 v[196:199], v159 offset:52224
	ds_read_b128 v[200:203], v159 offset:53248
	ds_read_b128 v[204:207], v159 offset:54272
	ds_read_b128 v[208:211], v159 offset:55296
	ds_read_b128 v[212:215], v159 offset:56320
	global_load_lds_dwordx4 v[154:155], off
	s_add_i32 m0, s51, 0x2000
	s_add_u32 s40, s40, 0x80080
	v_lshl_add_u64 v[154:155], v[216:217], 0, s[10:11]
	s_addc_u32 s41, s41, 0
	s_add_i32 s51, s60, s2
	global_load_lds_dwordx4 v[154:155], off
	s_mov_b32 m0, s51
	v_lshl_add_u64 v[154:155], s[40:41], 0, v[132:133]
	global_load_lds_dwordx4 v[154:155], off
	s_add_i32 m0, s51, 0x2000
	v_lshl_add_u64 v[154:155], s[40:41], 0, v[128:129]
	global_load_lds_dwordx4 v[154:155], off
	s_mov_b32 m0, s43
	v_lshl_add_u64 v[154:155], v[218:219], 0, s[10:11]
	global_load_lds_dwordx4 v[154:155], off
	s_mov_b32 m0, s46
	v_lshl_add_u64 v[154:155], v[220:221], 0, s[10:11]
	global_load_lds_dwordx4 v[154:155], off
	s_waitcnt vmcnt(8) lgkmcnt(0)
	s_barrier
	s_setprio 1
	v_mfma_f32_16x16x32_bf16 v[60:63], v[146:149], v[184:187], v[60:63]
	v_mfma_f32_16x16x32_bf16 v[56:59], v[160:163], v[184:187], v[56:59]
	v_mfma_f32_16x16x32_bf16 v[44:47], v[146:149], v[192:195], v[44:47]
	v_mfma_f32_16x16x32_bf16 v[40:43], v[160:163], v[192:195], v[40:43]
	v_mfma_f32_16x16x32_bf16 v[28:31], v[146:149], v[200:203], v[28:31]
	v_mfma_f32_16x16x32_bf16 v[24:27], v[160:163], v[200:203], v[24:27]
	v_mfma_f32_16x16x32_bf16 v[12:15], v[146:149], v[208:211], v[12:15]
	v_mfma_f32_16x16x32_bf16 v[8:11], v[160:163], v[208:211], v[8:11]
	v_mfma_f32_16x16x32_bf16 v[60:63], v[150:153], v[188:191], v[60:63]
	v_mfma_f32_16x16x32_bf16 v[56:59], v[164:167], v[188:191], v[56:59]
	v_mfma_f32_16x16x32_bf16 v[44:47], v[150:153], v[196:199], v[44:47]
	v_mfma_f32_16x16x32_bf16 v[40:43], v[164:167], v[196:199], v[40:43]
	v_mfma_f32_16x16x32_bf16 v[28:31], v[150:153], v[204:207], v[28:31]
	v_mfma_f32_16x16x32_bf16 v[24:27], v[164:167], v[204:207], v[24:27]
	v_mfma_f32_16x16x32_bf16 v[12:15], v[150:153], v[212:215], v[12:15]
	v_mfma_f32_16x16x32_bf16 v[8:11], v[164:167], v[212:215], v[8:11]
	v_mfma_f32_16x16x32_bf16 v[52:55], v[168:171], v[184:187], v[52:55]
	v_mfma_f32_16x16x32_bf16 v[48:51], v[176:179], v[184:187], v[48:51]
	v_mfma_f32_16x16x32_bf16 v[36:39], v[168:171], v[192:195], v[36:39]
	v_mfma_f32_16x16x32_bf16 v[32:35], v[176:179], v[192:195], v[32:35]
	v_mfma_f32_16x16x32_bf16 v[20:23], v[168:171], v[200:203], v[20:23]
	v_mfma_f32_16x16x32_bf16 v[16:19], v[176:179], v[200:203], v[16:19]
	v_mfma_f32_16x16x32_bf16 v[4:7], v[168:171], v[208:211], v[4:7]
	v_mfma_f32_16x16x32_bf16 v[0:3], v[176:179], v[208:211], v[0:3]
	v_mfma_f32_16x16x32_bf16 v[52:55], v[172:175], v[188:191], v[52:55]
	v_mfma_f32_16x16x32_bf16 v[48:51], v[180:183], v[188:191], v[48:51]
	v_mfma_f32_16x16x32_bf16 v[36:39], v[172:175], v[196:199], v[36:39]
	v_mfma_f32_16x16x32_bf16 v[32:35], v[180:183], v[196:199], v[32:35]
	v_mfma_f32_16x16x32_bf16 v[20:23], v[172:175], v[204:207], v[20:23]
	v_mfma_f32_16x16x32_bf16 v[16:19], v[180:183], v[204:207], v[16:19]
	v_mfma_f32_16x16x32_bf16 v[4:7], v[172:175], v[212:215], v[4:7]
	v_mfma_f32_16x16x32_bf16 v[0:3], v[180:183], v[212:215], v[0:3]
	s_setprio 0
	s_barrier
	s_add_i32 s50, s50, 2
	s_add_u32 s22, s22, 0x100
	s_addc_u32 s23, s23, 0
	s_add_u32 s19, s19, 0x100
	s_addc_u32 s21, s21, 0
	s_cmp_gt_u32 s50, 29
	s_cbranch_scc0 .LBB0_1313
	s_and_b64 vcc, exec, s[12:13]
	s_cbranch_vccz .LBB0_1316
	s_barrier

; #define PG8_STAGE(bufoff, gbase, voff) do { _Pragma("unroll") for (int _i = 0; _i < 2; ++_i) \
;         __builtin_amdgcn_global_load_lds((const unsigned*)((const char*)(gbase) + (voff)[_i]), (LAS unsigned*)(lds + (bufoff) + ldsw + _i * 8192), 16, 0, 0); } while (0)
; #define PG8_LDA(dst, b, h) do { _Pragma("unroll") for (int m = 0; m < 4; ++m) _Pragma("unroll") for (int k = 0; k < 2; ++k) dst[m][k] = *(const LAS bf16x8*)(lds + PG8_SA(b, h) + aoff + m * 2048 + k * 1024); } while (0)
; #define PG8_LDB(dst, b, h) do { _Pragma("unroll") for (int n = 0; n < 2; ++n) _Pragma("unroll") for (int k = 0; k < 2; ++k) dst[n][k] = *(const LAS bf16x8*)(lds + PG8_SB(b, h) + boff + n * 2048 + k * 1024); } while (0)
; #define PG8_MMA(ai, bj, At, Bt) do { __builtin_amdgcn_s_setprio(1); _Pragma("unroll") for (int m = 0; m < 4; ++m) _Pragma("unroll") for (int n = 0; n < 2; ++n) _Pragma("unroll") for (int k = 0; k < 2; ++k) \
;         acc[ai][bj][m][n] = __builtin_amdgcn_mfma_f32_16x16x32_bf16(Bt[n][k], At[m][k], acc[ai][bj][m][n], 0, 0, 0); __builtin_amdgcn_s_setprio(0); } while (0)
; #define PG8_WAIT_V(n) asm volatile("s_waitcnt vmcnt(" #n ")" ::: "memory")
; #define PG8_WAIT_L(n) asm volatile("s_waitcnt lgkmcnt(" #n ")" ::: "memory")
; #define PG8_BAR __builtin_amdgcn_s_barrier()
; #define PG8_SCHED __builtin_amdgcn_sched_barrier(0)
; template <class Desc, class Epi>
; DI void gemm_phase(LAS unsigned char* lds, const Desc& D, const Epi& E, int wv) {
;     ...
;             PG8_LDB(B0, 0, 0); PG8_LDB(B1, 0, 1); PG8_SCHED; PG8_LDA(At, 0, 0); PG8_STAGE(PG8_SA(1, 1), a1 + hstepA, voffA);
;             PG8_WAIT_V(8); PG8_WAIT_L(0); PG8_BAR; PG8_MMA(0, 0, At, B0); PG8_MMA(0, 1, At, B1); PG8_BAR; PG8_SCHED;
;             PG8_LDA(At, 0, 1); PG8_STAGE(PG8_SB(0, 0), b2, voffB); PG8_STAGE(PG8_SB(0, 1), b2 + hstepB, voffB); PG8_STAGE(PG8_SA(0, 0), a2, voffA);
;             PG8_WAIT_V(8); PG8_WAIT_L(0); PG8_BAR; PG8_MMA(1, 0, At, B0); PG8_MMA(1, 1, At, B1); PG8_BAR; PG8_SCHED;
.LBB0_1501:
	ds_read_b128 v[128:131], v230
	ds_read_b128 v[132:135], v230 offset:1024
	ds_read_b128 v[136:139], v230 offset:2048
	ds_read_b128 v[140:143], v230 offset:3072
	ds_read_b128 v[144:147], v231
	ds_read_b128 v[148:151], v231 offset:1024
	ds_read_b128 v[152:155], v231 offset:2048
	ds_read_b128 v[156:159], v231 offset:3072
	s_add_u32 s22, s20, 0xfff80080
	s_addc_u32 s23, s21, -1
	s_cmp_eq_u32 s64, 28
	s_cselect_b32 s41, s11, s23
	s_cselect_b32 s40, s10, s22
	s_cselect_b32 s23, s13, s17
	s_cselect_b32 s22, s12, s15
	v_lshl_add_u64 v[192:193], s[20:21], 0, v[216:217]
	s_add_i32 m0, s30, 0xc000
	ds_read_b128 v[160:163], v232
	ds_read_b128 v[164:167], v232 offset:1024
	ds_read_b128 v[168:171], v232 offset:2048
	ds_read_b128 v[172:175], v232 offset:3072
	ds_read_b128 v[176:179], v232 offset:4096
	ds_read_b128 v[180:183], v232 offset:5120
	ds_read_b128 v[184:187], v232 offset:6144
	ds_read_b128 v[188:191], v232 offset:7168
	global_load_lds_dwordx4 v[192:193], off
	s_add_i32 m0, s30, 0xe000
	v_lshl_add_u64 v[192:193], s[20:21], 0, v[218:219]
	global_load_lds_dwordx4 v[192:193], off
	s_waitcnt vmcnt(8) lgkmcnt(0)
	s_barrier
	s_setprio 1
	v_mfma_f32_16x16x32_bf16 v[124:127], v[128:131], v[160:163], v[124:127]
	v_mfma_f32_16x16x32_bf16 v[120:123], v[136:139], v[160:163], v[120:123]
	v_mfma_f32_16x16x32_bf16 v[112:115], v[128:131], v[168:171], v[112:115]
	v_mfma_f32_16x16x32_bf16 v[104:107], v[136:139], v[168:171], v[104:107]
	v_mfma_f32_16x16x32_bf16 v[96:99], v[128:131], v[176:179], v[96:99]
	v_mfma_f32_16x16x32_bf16 v[88:91], v[136:139], v[176:179], v[88:91]
	v_mfma_f32_16x16x32_bf16 v[80:83], v[128:131], v[184:187], v[80:83]
	v_mfma_f32_16x16x32_bf16 v[72:75], v[136:139], v[184:187], v[72:75]
	v_mfma_f32_16x16x32_bf16 v[124:127], v[132:135], v[164:167], v[124:127]
	v_mfma_f32_16x16x32_bf16 v[120:123], v[140:143], v[164:167], v[120:123]
	v_mfma_f32_16x16x32_bf16 v[112:115], v[132:135], v[172:175], v[112:115]
	v_mfma_f32_16x16x32_bf16 v[104:107], v[140:143], v[172:175], v[104:107]
	v_mfma_f32_16x16x32_bf16 v[96:99], v[132:135], v[180:183], v[96:99]
	v_mfma_f32_16x16x32_bf16 v[88:91], v[140:143], v[180:183], v[88:91]
	v_mfma_f32_16x16x32_bf16 v[80:83], v[132:135], v[188:191], v[80:83]
	v_mfma_f32_16x16x32_bf16 v[72:75], v[140:143], v[188:191], v[72:75]
	v_mfma_f32_16x16x32_bf16 v[116:119], v[144:147], v[160:163], v[116:119]
	v_mfma_f32_16x16x32_bf16 v[108:111], v[152:155], v[160:163], v[108:111]
	v_mfma_f32_16x16x32_bf16 v[100:103], v[144:147], v[168:171], v[100:103]
	v_mfma_f32_16x16x32_bf16 v[92:95], v[152:155], v[168:171], v[92:95]
	v_mfma_f32_16x16x32_bf16 v[84:87], v[144:147], v[176:179], v[84:87]
	v_mfma_f32_16x16x32_bf16 v[76:79], v[152:155], v[176:179], v[76:79]
	v_mfma_f32_16x16x32_bf16 v[68:71], v[144:147], v[184:187], v[68:71]
	v_mfma_f32_16x16x32_bf16 v[64:67], v[152:155], v[184:187], v[64:67]
	v_mfma_f32_16x16x32_bf16 v[116:119], v[148:151], v[164:167], v[116:119]
	v_mfma_f32_16x16x32_bf16 v[108:111], v[156:159], v[164:167], v[108:111]
	v_mfma_f32_16x16x32_bf16 v[100:103], v[148:151], v[172:175], v[100:103]
	v_mfma_f32_16x16x32_bf16 v[92:95], v[156:159], v[172:175], v[92:95]
	v_mfma_f32_16x16x32_bf16 v[84:87], v[148:151], v[180:183], v[84:87]
	v_mfma_f32_16x16x32_bf16 v[76:79], v[156:159], v[180:183], v[76:79]
	v_mfma_f32_16x16x32_bf16 v[68:71], v[148:151], v[188:191], v[68:71]
	v_mfma_f32_16x16x32_bf16 v[64:67], v[156:159], v[188:191], v[64:67]
	s_setprio 0
	s_barrier
	s_add_i32 s65, s51, s28
	v_lshl_add_u64 v[192:193], s[22:23], 0, v[212:213]
	s_mov_b32 m0, s65
	ds_read_b128 v[160:163], v232 offset:16384
	ds_read_b128 v[164:167], v232 offset:17408
	ds_read_b128 v[168:171], v232 offset:18432
	ds_read_b128 v[172:175], v232 offset:19456
	ds_read_b128 v[176:179], v232 offset:20480
	ds_read_b128 v[180:183], v232 offset:21504
	ds_read_b128 v[184:187], v232 offset:22528
	ds_read_b128 v[188:191], v232 offset:23552
	global_load_lds_dwordx4 v[192:193], off
	s_add_i32 m0, s65, 0x2000
	s_add_u32 s66, s22, 0x80000
	v_lshl_add_u64 v[194:195], s[22:23], 0, v[208:209]
	s_addc_u32 s67, s23, 0
	s_add_i32 s65, s52, s28
	global_load_lds_dwordx4 v[194:195], off
	v_lshl_add_u64 v[196:197], s[66:67], 0, v[212:213]
	s_mov_b32 m0, s65
	v_lshl_add_u64 v[198:199], s[40:41], 0, v[210:211]
	global_load_lds_dwordx4 v[196:197], off
	s_add_i32 m0, s65, 0x2000
	v_lshl_add_u64 v[196:197], s[66:67], 0, v[208:209]
	global_load_lds_dwordx4 v[196:197], off
	s_mov_b32 m0, s30
	v_lshl_add_u64 v[196:197], s[40:41], 0, v[214:215]
	global_load_lds_dwordx4 v[196:197], off
	s_mov_b32 m0, s31
	s_nop 0
	global_load_lds_dwordx4 v[198:199], off
	s_waitcnt vmcnt(8) lgkmcnt(0)
	s_barrier
; #define PG8_STAGE(bufoff, gbase, voff) do { _Pragma("unroll") for (int _i = 0; _i < 2; ++_i) \
;         __builtin_amdgcn_global_load_lds((const unsigned*)((const char*)(gbase) + (voff)[_i]), (LAS unsigned*)(lds + (bufoff) + ldsw + _i * 8192), 16, 0, 0); } while (0)
; #define PG8_LDA(dst, b, h) do { _Pragma("unroll") for (int m = 0; m < 4; ++m) _Pragma("unroll") for (int k = 0; k < 2; ++k) dst[m][k] = *(const LAS bf16x8*)(lds + PG8_SA(b, h) + aoff + m * 2048 + k * 1024); } while (0)
; #define PG8_LDB(dst, b, h) do { _Pragma("unroll") for (int n = 0; n < 2; ++n) _Pragma("unroll") for (int k = 0; k < 2; ++k) dst[n][k] = *(const LAS bf16x8*)(lds + PG8_SB(b, h) + boff + n * 2048 + k * 1024); } while (0)
; #define PG8_MMA(ai, bj, At, Bt) do { __builtin_amdgcn_s_setprio(1); _Pragma("unroll") for (int m = 0; m < 4; ++m) _Pragma("unroll") for (int n = 0; n < 2; ++n) _Pragma("unroll") for (int k = 0; k < 2; ++k) \
;         acc[ai][bj][m][n] = __builtin_amdgcn_mfma_f32_16x16x32_bf16(Bt[n][k], At[m][k], acc[ai][bj][m][n], 0, 0, 0); __builtin_amdgcn_s_setprio(0); } while (0)
; #define PG8_WAIT_V(n) asm volatile("s_waitcnt vmcnt(" #n ")" ::: "memory")
; #define PG8_WAIT_L(n) asm volatile("s_waitcnt lgkmcnt(" #n ")" ::: "memory")
; #define PG8_BAR __builtin_amdgcn_s_barrier()
; #define PG8_SCHED __builtin_amdgcn_sched_barrier(0)
; template <class Desc, class Epi>
; DI void gemm_phase(LAS unsigned char* lds, const Desc& D, const Epi& E, int wv) {
;     ...
;             PG8_WAIT_V(8); PG8_WAIT_L(0); PG8_BAR; PG8_MMA(1, 0, At, B0); PG8_MMA(1, 1, At, B1); PG8_BAR; PG8_SCHED;
;             PG8_LDB(B0, 1, 0); PG8_LDB(B1, 1, 1); PG8_SCHED; PG8_LDA(At, 1, 0); PG8_STAGE(PG8_SA(0, 1), a2 + hstepA, voffA);
;             PG8_WAIT_V(8); PG8_WAIT_L(0); PG8_BAR; PG8_MMA(0, 0, At, B0); PG8_MMA(0, 1, At, B1); PG8_BAR; PG8_SCHED;
	s_setprio 1
	v_mfma_f32_16x16x32_bf16 v[60:63], v[128:131], v[160:163], v[60:63]
	v_mfma_f32_16x16x32_bf16 v[56:59], v[136:139], v[160:163], v[56:59]
	v_mfma_f32_16x16x32_bf16 v[48:51], v[128:131], v[168:171], v[48:51]
	v_mfma_f32_16x16x32_bf16 v[40:43], v[136:139], v[168:171], v[40:43]
	v_mfma_f32_16x16x32_bf16 v[32:35], v[128:131], v[176:179], v[32:35]
	v_mfma_f32_16x16x32_bf16 v[24:27], v[136:139], v[176:179], v[24:27]
	v_mfma_f32_16x16x32_bf16 v[16:19], v[128:131], v[184:187], v[16:19]
	v_mfma_f32_16x16x32_bf16 v[8:11], v[136:139], v[184:187], v[8:11]
	v_mfma_f32_16x16x32_bf16 v[60:63], v[132:135], v[164:167], v[60:63]
	v_mfma_f32_16x16x32_bf16 v[56:59], v[140:143], v[164:167], v[56:59]
	v_mfma_f32_16x16x32_bf16 v[48:51], v[132:135], v[172:175], v[48:51]
	v_mfma_f32_16x16x32_bf16 v[40:43], v[140:143], v[172:175], v[40:43]
	v_mfma_f32_16x16x32_bf16 v[32:35], v[132:135], v[180:183], v[32:35]
	v_mfma_f32_16x16x32_bf16 v[24:27], v[140:143], v[180:183], v[24:27]
	v_mfma_f32_16x16x32_bf16 v[16:19], v[132:135], v[188:191], v[16:19]
	v_mfma_f32_16x16x32_bf16 v[8:11], v[140:143], v[188:191], v[8:11]
	v_mfma_f32_16x16x32_bf16 v[52:55], v[144:147], v[160:163], v[52:55]
	v_mfma_f32_16x16x32_bf16 v[44:47], v[152:155], v[160:163], v[44:47]
	v_mfma_f32_16x16x32_bf16 v[36:39], v[144:147], v[168:171], v[36:39]
	v_mfma_f32_16x16x32_bf16 v[28:31], v[152:155], v[168:171], v[28:31]
	v_mfma_f32_16x16x32_bf16 v[20:23], v[144:147], v[176:179], v[20:23]
	v_mfma_f32_16x16x32_bf16 v[12:15], v[152:155], v[176:179], v[12:15]
	v_mfma_f32_16x16x32_bf16 v[4:7], v[144:147], v[184:187], v[4:7]
	v_mfma_f32_16x16x32_bf16 v[0:3], v[152:155], v[184:187], v[0:3]
	v_mfma_f32_16x16x32_bf16 v[52:55], v[148:151], v[164:167], v[52:55]
	v_mfma_f32_16x16x32_bf16 v[44:47], v[156:159], v[164:167], v[44:47]
	v_mfma_f32_16x16x32_bf16 v[36:39], v[148:151], v[172:175], v[36:39]
	v_mfma_f32_16x16x32_bf16 v[28:31], v[156:159], v[172:175], v[28:31]
	v_mfma_f32_16x16x32_bf16 v[20:23], v[148:151], v[180:183], v[20:23]
	v_mfma_f32_16x16x32_bf16 v[12:15], v[156:159], v[180:183], v[12:15]
	v_mfma_f32_16x16x32_bf16 v[4:7], v[148:151], v[188:191], v[4:7]
	v_mfma_f32_16x16x32_bf16 v[0:3], v[156:159], v[188:191], v[0:3]
	s_setprio 0
	s_barrier
	s_add_i32 s65, 0, 0x18000
	s_add_i32 s66, 0, 0x1c000
	v_add_u32_e32 v140, s65, v229
	v_add_u32_e32 v156, s66, v229
	ds_read_b128 v[128:131], v140
	ds_read_b128 v[132:135], v140 offset:1024
	ds_read_b128 v[136:139], v140 offset:2048
	ds_read_b128 v[140:143], v140 offset:3072
	ds_read_b128 v[144:147], v156
	ds_read_b128 v[148:151], v156 offset:1024
	ds_read_b128 v[152:155], v156 offset:2048
	ds_read_b128 v[156:159], v156 offset:3072
	s_add_u32 s40, s40, 0x80000
	s_addc_u32 s41, s41, 0
	s_mov_b32 m0, s34
	v_lshl_add_u64 v[200:201], s[40:41], 0, v[214:215]
	ds_read_b128 v[160:163], v232 offset:32768
	ds_read_b128 v[164:167], v232 offset:33792
	ds_read_b128 v[168:171], v232 offset:34816
	ds_read_b128 v[172:175], v232 offset:35840
	ds_read_b128 v[176:179], v232 offset:36864
	ds_read_b128 v[180:183], v232 offset:37888
	ds_read_b128 v[184:187], v232 offset:38912
	ds_read_b128 v[188:191], v232 offset:39936
	global_load_lds_dwordx4 v[200:201], off
	s_mov_b32 m0, s35
	v_lshl_add_u64 v[200:201], s[40:41], 0, v[210:211]
	global_load_lds_dwordx4 v[200:201], off
	s_waitcnt vmcnt(8) lgkmcnt(0)
	s_barrier
	s_setprio 1
	v_mfma_f32_16x16x32_bf16 v[124:127], v[128:131], v[160:163], v[124:127]
	v_mfma_f32_16x16x32_bf16 v[120:123], v[136:139], v[160:163], v[120:123]
	v_mfma_f32_16x16x32_bf16 v[112:115], v[128:131], v[168:171], v[112:115]
	v_mfma_f32_16x16x32_bf16 v[104:107], v[136:139], v[168:171], v[104:107]
	v_mfma_f32_16x16x32_bf16 v[96:99], v[128:131], v[176:179], v[96:99]
	v_mfma_f32_16x16x32_bf16 v[88:91], v[136:139], v[176:179], v[88:91]
	v_mfma_f32_16x16x32_bf16 v[80:83], v[128:131], v[184:187], v[80:83]
	v_mfma_f32_16x16x32_bf16 v[72:75], v[136:139], v[184:187], v[72:75]
	v_mfma_f32_16x16x32_bf16 v[124:127], v[132:135], v[164:167], v[124:127]
	v_mfma_f32_16x16x32_bf16 v[120:123], v[140:143], v[164:167], v[120:123]
	v_mfma_f32_16x16x32_bf16 v[112:115], v[132:135], v[172:175], v[112:115]
	v_mfma_f32_16x16x32_bf16 v[104:107], v[140:143], v[172:175], v[104:107]
	v_mfma_f32_16x16x32_bf16 v[96:99], v[132:135], v[180:183], v[96:99]
	v_mfma_f32_16x16x32_bf16 v[88:91], v[140:143], v[180:183], v[88:91]
	v_mfma_f32_16x16x32_bf16 v[80:83], v[132:135], v[188:191], v[80:83]
	v_mfma_f32_16x16x32_bf16 v[72:75], v[140:143], v[188:191], v[72:75]
	v_mfma_f32_16x16x32_bf16 v[116:119], v[144:147], v[160:163], v[116:119]
	v_mfma_f32_16x16x32_bf16 v[108:111], v[152:155], v[160:163], v[108:111]
	v_mfma_f32_16x16x32_bf16 v[100:103], v[144:147], v[168:171], v[100:103]
	v_mfma_f32_16x16x32_bf16 v[92:95], v[152:155], v[168:171], v[92:95]
	v_mfma_f32_16x16x32_bf16 v[84:87], v[144:147], v[176:179], v[84:87]
	v_mfma_f32_16x16x32_bf16 v[76:79], v[152:155], v[176:179], v[76:79]
	v_mfma_f32_16x16x32_bf16 v[68:71], v[144:147], v[184:187], v[68:71]
	v_mfma_f32_16x16x32_bf16 v[64:67], v[152:155], v[184:187], v[64:67]
	v_mfma_f32_16x16x32_bf16 v[116:119], v[148:151], v[164:167], v[116:119]
	v_mfma_f32_16x16x32_bf16 v[108:111], v[156:159], v[164:167], v[108:111]
	v_mfma_f32_16x16x32_bf16 v[100:103], v[148:151], v[172:175], v[100:103]
	v_mfma_f32_16x16x32_bf16 v[92:95], v[156:159], v[172:175], v[92:95]
	v_mfma_f32_16x16x32_bf16 v[84:87], v[148:151], v[180:183], v[84:87]
	v_mfma_f32_16x16x32_bf16 v[76:79], v[156:159], v[180:183], v[76:79]
	v_mfma_f32_16x16x32_bf16 v[68:71], v[148:151], v[188:191], v[68:71]
	v_mfma_f32_16x16x32_bf16 v[64:67], v[156:159], v[188:191], v[64:67]
	s_setprio 0
	s_barrier
; #define PG8_STAGE(bufoff, gbase, voff) do { _Pragma("unroll") for (int _i = 0; _i < 2; ++_i) \
;         __builtin_amdgcn_global_load_lds((const unsigned*)((const char*)(gbase) + (voff)[_i]), (LAS unsigned*)(lds + (bufoff) + ldsw + _i * 8192), 16, 0, 0); } while (0)
; #define PG8_LDA(dst, b, h) do { _Pragma("unroll") for (int m = 0; m < 4; ++m) _Pragma("unroll") for (int k = 0; k < 2; ++k) dst[m][k] = *(const LAS bf16x8*)(lds + PG8_SA(b, h) + aoff + m * 2048 + k * 1024); } while (0)
; #define PG8_MMA(ai, bj, At, Bt) do { __builtin_amdgcn_s_setprio(1); _Pragma("unroll") for (int m = 0; m < 4; ++m) _Pragma("unroll") for (int n = 0; n < 2; ++n) _Pragma("unroll") for (int k = 0; k < 2; ++k) \
;         acc[ai][bj][m][n] = __builtin_amdgcn_mfma_f32_16x16x32_bf16(Bt[n][k], At[m][k], acc[ai][bj][m][n], 0, 0, 0); __builtin_amdgcn_s_setprio(0); } while (0)
; #define PG8_WAIT_V(n) asm volatile("s_waitcnt vmcnt(" #n ")" ::: "memory")
; #define PG8_WAIT_L(n) asm volatile("s_waitcnt lgkmcnt(" #n ")" ::: "memory")
; #define PG8_BAR __builtin_amdgcn_s_barrier()
; #define PG8_SCHED __builtin_amdgcn_sched_barrier(0)
; template <class Desc, class Epi>
; DI void gemm_phase(LAS unsigned char* lds, const Desc& D, const Epi& E, int wv) {
;     ...
;             PG8_LDA(At, 1, 1); PG8_STAGE(PG8_SB(1, 0), b3, voffB); PG8_STAGE(PG8_SB(1, 1), b3 + hstepB, voffB); PG8_STAGE(PG8_SA(1, 0), a3, voffA);
;             PG8_WAIT_V(8); PG8_WAIT_L(0); PG8_BAR; PG8_MMA(1, 0, At, B0); PG8_MMA(1, 1, At, B1); PG8_BAR; PG8_SCHED;
;         }
;         if (wr == 0) PG8_BAR;
	s_add_i32 s40, s65, s28
	v_lshl_add_u64 v[192:193], v[192:193], 0, s[6:7]
	s_mov_b32 m0, s40
	ds_read_b128 v[160:163], v232 offset:49152
	ds_read_b128 v[164:167], v232 offset:50176
	ds_read_b128 v[168:171], v232 offset:51200
	ds_read_b128 v[172:175], v232 offset:52224
	ds_read_b128 v[176:179], v232 offset:53248
	ds_read_b128 v[180:183], v232 offset:54272
	ds_read_b128 v[184:187], v232 offset:55296
	ds_read_b128 v[188:191], v232 offset:56320
	global_load_lds_dwordx4 v[192:193], off
	s_add_i32 m0, s40, 0x2000
	s_add_u32 s22, s22, 0x80080
	v_lshl_add_u64 v[192:193], v[194:195], 0, s[6:7]
	s_addc_u32 s23, s23, 0
	s_add_i32 s40, s66, s28
	global_load_lds_dwordx4 v[192:193], off
	s_mov_b32 m0, s40
	v_lshl_add_u64 v[192:193], s[22:23], 0, v[212:213]
	global_load_lds_dwordx4 v[192:193], off
	s_add_i32 m0, s40, 0x2000
	v_lshl_add_u64 v[192:193], s[22:23], 0, v[208:209]
	global_load_lds_dwordx4 v[192:193], off
	s_mov_b32 m0, s47
	v_lshl_add_u64 v[192:193], v[196:197], 0, s[6:7]
	global_load_lds_dwordx4 v[192:193], off
	s_mov_b32 m0, s48
	v_lshl_add_u64 v[192:193], v[198:199], 0, s[6:7]
	global_load_lds_dwordx4 v[192:193], off
	s_waitcnt vmcnt(8) lgkmcnt(0)
	s_barrier
	s_setprio 1
	v_mfma_f32_16x16x32_bf16 v[60:63], v[128:131], v[160:163], v[60:63]
	v_mfma_f32_16x16x32_bf16 v[56:59], v[136:139], v[160:163], v[56:59]
	v_mfma_f32_16x16x32_bf16 v[48:51], v[128:131], v[168:171], v[48:51]
	v_mfma_f32_16x16x32_bf16 v[40:43], v[136:139], v[168:171], v[40:43]
	v_mfma_f32_16x16x32_bf16 v[32:35], v[128:131], v[176:179], v[32:35]
	v_mfma_f32_16x16x32_bf16 v[24:27], v[136:139], v[176:179], v[24:27]
	v_mfma_f32_16x16x32_bf16 v[16:19], v[128:131], v[184:187], v[16:19]
	v_mfma_f32_16x16x32_bf16 v[8:11], v[136:139], v[184:187], v[8:11]
	v_mfma_f32_16x16x32_bf16 v[60:63], v[132:135], v[164:167], v[60:63]
	v_mfma_f32_16x16x32_bf16 v[56:59], v[140:143], v[164:167], v[56:59]
	v_mfma_f32_16x16x32_bf16 v[48:51], v[132:135], v[172:175], v[48:51]
	v_mfma_f32_16x16x32_bf16 v[40:43], v[140:143], v[172:175], v[40:43]
	v_mfma_f32_16x16x32_bf16 v[32:35], v[132:135], v[180:183], v[32:35]
	v_mfma_f32_16x16x32_bf16 v[24:27], v[140:143], v[180:183], v[24:27]
	v_mfma_f32_16x16x32_bf16 v[16:19], v[132:135], v[188:191], v[16:19]
	v_mfma_f32_16x16x32_bf16 v[8:11], v[140:143], v[188:191], v[8:11]
	v_mfma_f32_16x16x32_bf16 v[52:55], v[144:147], v[160:163], v[52:55]
	v_mfma_f32_16x16x32_bf16 v[44:47], v[152:155], v[160:163], v[44:47]
	v_mfma_f32_16x16x32_bf16 v[36:39], v[144:147], v[168:171], v[36:39]
	v_mfma_f32_16x16x32_bf16 v[28:31], v[152:155], v[168:171], v[28:31]
	v_mfma_f32_16x16x32_bf16 v[20:23], v[144:147], v[176:179], v[20:23]
	v_mfma_f32_16x16x32_bf16 v[12:15], v[152:155], v[176:179], v[12:15]
	v_mfma_f32_16x16x32_bf16 v[4:7], v[144:147], v[184:187], v[4:7]
	v_mfma_f32_16x16x32_bf16 v[0:3], v[152:155], v[184:187], v[0:3]
	v_mfma_f32_16x16x32_bf16 v[52:55], v[148:151], v[164:167], v[52:55]
	v_mfma_f32_16x16x32_bf16 v[44:47], v[156:159], v[164:167], v[44:47]
	v_mfma_f32_16x16x32_bf16 v[36:39], v[148:151], v[172:175], v[36:39]
	v_mfma_f32_16x16x32_bf16 v[28:31], v[156:159], v[172:175], v[28:31]
	v_mfma_f32_16x16x32_bf16 v[20:23], v[148:151], v[180:183], v[20:23]
	v_mfma_f32_16x16x32_bf16 v[12:15], v[156:159], v[180:183], v[12:15]
	v_mfma_f32_16x16x32_bf16 v[4:7], v[148:151], v[188:191], v[4:7]
	v_mfma_f32_16x16x32_bf16 v[0:3], v[156:159], v[188:191], v[0:3]
	s_setprio 0
	s_barrier
	s_add_i32 s64, s64, 2
	s_add_u32 s20, s20, 0x100
	s_addc_u32 s21, s21, 0
	s_add_u32 s15, s15, 0x100
	s_addc_u32 s17, s17, 0
	s_cmp_gt_u32 s64, 29
	s_cbranch_scc0 .LBB0_1501
	s_and_b64 vcc, exec, s[8:9]
	s_cbranch_vccz .LBB0_1504
	s_barrier

; #define PG8_STAGE(bufoff, gbase, voff) do { _Pragma("unroll") for (int _i = 0; _i < 2; ++_i) \
;         __builtin_amdgcn_global_load_lds((const unsigned*)((const char*)(gbase) + (voff)[_i]), (LAS unsigned*)(lds + (bufoff) + ldsw + _i * 8192), 16, 0, 0); } while (0)
; #define PG8_LDA(dst, b, h) do { _Pragma("unroll") for (int m = 0; m < 4; ++m) _Pragma("unroll") for (int k = 0; k < 2; ++k) dst[m][k] = *(const LAS bf16x8*)(lds + PG8_SA(b, h) + aoff + m * 2048 + k * 1024); } while (0)
; #define PG8_LDB(dst, b, h) do { _Pragma("unroll") for (int n = 0; n < 2; ++n) _Pragma("unroll") for (int k = 0; k < 2; ++k) dst[n][k] = *(const LAS bf16x8*)(lds + PG8_SB(b, h) + boff + n * 2048 + k * 1024); } while (0)
; #define PG8_MMA(ai, bj, At, Bt) do { __builtin_amdgcn_s_setprio(1); _Pragma("unroll") for (int m = 0; m < 4; ++m) _Pragma("unroll") for (int n = 0; n < 2; ++n) _Pragma("unroll") for (int k = 0; k < 2; ++k) \
;         acc[ai][bj][m][n] = __builtin_amdgcn_mfma_f32_16x16x32_bf16(Bt[n][k], At[m][k], acc[ai][bj][m][n], 0, 0, 0); __builtin_amdgcn_s_setprio(0); } while (0)
; #define PG8_WAIT_V(n) asm volatile("s_waitcnt vmcnt(" #n ")" ::: "memory")
; #define PG8_WAIT_L(n) asm volatile("s_waitcnt lgkmcnt(" #n ")" ::: "memory")
; #define PG8_BAR __builtin_amdgcn_s_barrier()
; #define PG8_SCHED __builtin_amdgcn_sched_barrier(0)
; template <class Desc, class Epi>
; DI void gemm_phase(LAS unsigned char* lds, const Desc& D, const Epi& E, int wv) {
;     ...
;         for (int t = 0; t < nt; t += 2) {
;             const bool last = (t == nt - 2);
;             const char* a1 = cA + (size_t)(t + 1) * kstep;
;             const char* a2 = last ? nA : cA + (size_t)(t + 2) * kstep; const char* b2 = last ? nB : cB + (size_t)(t + 2) * kstep;
;             const char* a3 = a2 + kstep; const char* b3 = b2 + kstep;
;             PG8_LDB(B0, 0, 0); PG8_LDB(B1, 0, 1); PG8_SCHED; PG8_LDA(At, 0, 0); PG8_STAGE(PG8_SA(1, 1), a1 + hstepA, voffA);
;             PG8_WAIT_V(8); PG8_WAIT_L(0); PG8_BAR; PG8_MMA(0, 0, At, B0); PG8_MMA(0, 1, At, B1); PG8_BAR; PG8_SCHED;
;             PG8_LDA(At, 0, 1); PG8_STAGE(PG8_SB(0, 0), b2, voffB); PG8_STAGE(PG8_SB(0, 1), b2 + hstepB, voffB); PG8_STAGE(PG8_SA(0, 0), a2, voffA);
;             PG8_WAIT_V(8); PG8_WAIT_L(0); PG8_BAR; PG8_MMA(1, 0, At, B0); PG8_MMA(1, 1, At, B1); PG8_BAR; PG8_SCHED;
.LBB0_1632:
	ds_read_b128 v[146:149], v155
	ds_read_b128 v[150:153], v155 offset:1024
	ds_read_b128 v[158:161], v155 offset:2048
	ds_read_b128 v[162:165], v155 offset:3072
	ds_read_b128 v[166:169], v156
	ds_read_b128 v[170:173], v156 offset:1024
	ds_read_b128 v[174:177], v156 offset:2048
	ds_read_b128 v[178:181], v156 offset:3072
	s_add_u32 s17, s62, 0xfff80080
	s_addc_u32 s19, s63, -1
	s_cmp_eq_u32 s8, 28
	s_cselect_b32 s67, s21, s19
	s_cselect_b32 s66, s20, s17
	s_cselect_b32 s65, s23, s7
	s_cselect_b32 s64, s22, s5
	v_lshl_add_u64 v[214:215], s[62:63], 0, v[138:139]
	s_add_i32 m0, s29, 0xc000
	ds_read_b128 v[182:185], v157
	ds_read_b128 v[186:189], v157 offset:1024
	ds_read_b128 v[190:193], v157 offset:2048
	ds_read_b128 v[194:197], v157 offset:3072
	ds_read_b128 v[198:201], v157 offset:4096
	ds_read_b128 v[202:205], v157 offset:5120
	ds_read_b128 v[206:209], v157 offset:6144
	ds_read_b128 v[210:213], v157 offset:7168
	global_load_lds_dwordx4 v[214:215], off
	s_add_i32 m0, s29, 0xe000
	v_lshl_add_u64 v[214:215], s[62:63], 0, v[140:141]
	global_load_lds_dwordx4 v[214:215], off
	s_waitcnt vmcnt(8) lgkmcnt(0)
	s_barrier
	s_setprio 1
	v_mfma_f32_16x16x32_bf16 v[124:127], v[146:149], v[182:185], v[124:127]
	v_mfma_f32_16x16x32_bf16 v[120:123], v[158:161], v[182:185], v[120:123]
	v_mfma_f32_16x16x32_bf16 v[108:111], v[146:149], v[190:193], v[108:111]
	v_mfma_f32_16x16x32_bf16 v[104:107], v[158:161], v[190:193], v[104:107]
	v_mfma_f32_16x16x32_bf16 v[92:95], v[146:149], v[198:201], v[92:95]
	v_mfma_f32_16x16x32_bf16 v[88:91], v[158:161], v[198:201], v[88:91]
	v_mfma_f32_16x16x32_bf16 v[76:79], v[146:149], v[206:209], v[76:79]
	v_mfma_f32_16x16x32_bf16 v[72:75], v[158:161], v[206:209], v[72:75]
	v_mfma_f32_16x16x32_bf16 v[124:127], v[150:153], v[186:189], v[124:127]
	v_mfma_f32_16x16x32_bf16 v[120:123], v[162:165], v[186:189], v[120:123]
	v_mfma_f32_16x16x32_bf16 v[108:111], v[150:153], v[194:197], v[108:111]
	v_mfma_f32_16x16x32_bf16 v[104:107], v[162:165], v[194:197], v[104:107]
	v_mfma_f32_16x16x32_bf16 v[92:95], v[150:153], v[202:205], v[92:95]
	v_mfma_f32_16x16x32_bf16 v[88:91], v[162:165], v[202:205], v[88:91]
	v_mfma_f32_16x16x32_bf16 v[76:79], v[150:153], v[210:213], v[76:79]
	v_mfma_f32_16x16x32_bf16 v[72:75], v[162:165], v[210:213], v[72:75]
	v_mfma_f32_16x16x32_bf16 v[116:119], v[166:169], v[182:185], v[116:119]
	v_mfma_f32_16x16x32_bf16 v[112:115], v[174:177], v[182:185], v[112:115]
	v_mfma_f32_16x16x32_bf16 v[100:103], v[166:169], v[190:193], v[100:103]
	v_mfma_f32_16x16x32_bf16 v[96:99], v[174:177], v[190:193], v[96:99]
	v_mfma_f32_16x16x32_bf16 v[84:87], v[166:169], v[198:201], v[84:87]
	v_mfma_f32_16x16x32_bf16 v[80:83], v[174:177], v[198:201], v[80:83]
	v_mfma_f32_16x16x32_bf16 v[68:71], v[166:169], v[206:209], v[68:71]
	v_mfma_f32_16x16x32_bf16 v[64:67], v[174:177], v[206:209], v[64:67]
	v_mfma_f32_16x16x32_bf16 v[116:119], v[170:173], v[186:189], v[116:119]
	v_mfma_f32_16x16x32_bf16 v[112:115], v[178:181], v[186:189], v[112:115]
	v_mfma_f32_16x16x32_bf16 v[100:103], v[170:173], v[194:197], v[100:103]
	v_mfma_f32_16x16x32_bf16 v[96:99], v[178:181], v[194:197], v[96:99]
	v_mfma_f32_16x16x32_bf16 v[84:87], v[170:173], v[202:205], v[84:87]
	v_mfma_f32_16x16x32_bf16 v[80:83], v[178:181], v[202:205], v[80:83]
	v_mfma_f32_16x16x32_bf16 v[68:71], v[170:173], v[210:213], v[68:71]
	v_mfma_f32_16x16x32_bf16 v[64:67], v[178:181], v[210:213], v[64:67]
	s_setprio 0
	s_barrier
	s_add_i32 s17, s50, s28
	v_lshl_add_u64 v[214:215], s[64:65], 0, v[130:131]
	s_mov_b32 m0, s17
	ds_read_b128 v[182:185], v157 offset:16384
	ds_read_b128 v[186:189], v157 offset:17408
	ds_read_b128 v[190:193], v157 offset:18432
	ds_read_b128 v[194:197], v157 offset:19456
	ds_read_b128 v[198:201], v157 offset:20480
	ds_read_b128 v[202:205], v157 offset:21504
	ds_read_b128 v[206:209], v157 offset:22528
	ds_read_b128 v[210:213], v157 offset:23552
	global_load_lds_dwordx4 v[214:215], off
	s_add_i32 m0, s17, 0x2000
	s_add_u32 s68, s64, 0x80000
	v_lshl_add_u64 v[216:217], s[64:65], 0, v[134:135]
	s_addc_u32 s69, s65, 0
	s_add_i32 s17, s51, s28
	global_load_lds_dwordx4 v[216:217], off
	v_lshl_add_u64 v[218:219], s[68:69], 0, v[130:131]
	s_mov_b32 m0, s17
	v_lshl_add_u64 v[220:221], s[66:67], 0, v[132:133]
	global_load_lds_dwordx4 v[218:219], off
	s_add_i32 m0, s17, 0x2000
	v_lshl_add_u64 v[218:219], s[68:69], 0, v[134:135]
	global_load_lds_dwordx4 v[218:219], off
	s_mov_b32 m0, s29
	v_lshl_add_u64 v[218:219], s[66:67], 0, v[128:129]
	global_load_lds_dwordx4 v[218:219], off
	s_mov_b32 m0, s30
	s_nop 0
	global_load_lds_dwordx4 v[220:221], off
	s_waitcnt vmcnt(8) lgkmcnt(0)
	s_barrier
; #define PG8_STAGE(bufoff, gbase, voff) do { _Pragma("unroll") for (int _i = 0; _i < 2; ++_i) \
;         __builtin_amdgcn_global_load_lds((const unsigned*)((const char*)(gbase) + (voff)[_i]), (LAS unsigned*)(lds + (bufoff) + ldsw + _i * 8192), 16, 0, 0); } while (0)
; #define PG8_LDA(dst, b, h) do { _Pragma("unroll") for (int m = 0; m < 4; ++m) _Pragma("unroll") for (int k = 0; k < 2; ++k) dst[m][k] = *(const LAS bf16x8*)(lds + PG8_SA(b, h) + aoff + m * 2048 + k * 1024); } while (0)
; #define PG8_LDB(dst, b, h) do { _Pragma("unroll") for (int n = 0; n < 2; ++n) _Pragma("unroll") for (int k = 0; k < 2; ++k) dst[n][k] = *(const LAS bf16x8*)(lds + PG8_SB(b, h) + boff + n * 2048 + k * 1024); } while (0)
; #define PG8_MMA(ai, bj, At, Bt) do { __builtin_amdgcn_s_setprio(1); _Pragma("unroll") for (int m = 0; m < 4; ++m) _Pragma("unroll") for (int n = 0; n < 2; ++n) _Pragma("unroll") for (int k = 0; k < 2; ++k) \
;         acc[ai][bj][m][n] = __builtin_amdgcn_mfma_f32_16x16x32_bf16(Bt[n][k], At[m][k], acc[ai][bj][m][n], 0, 0, 0); __builtin_amdgcn_s_setprio(0); } while (0)
; #define PG8_WAIT_V(n) asm volatile("s_waitcnt vmcnt(" #n ")" ::: "memory")
; #define PG8_WAIT_L(n) asm volatile("s_waitcnt lgkmcnt(" #n ")" ::: "memory")
; #define PG8_BAR __builtin_amdgcn_s_barrier()
; #define PG8_SCHED __builtin_amdgcn_sched_barrier(0)
; template <class Desc, class Epi>
; DI void gemm_phase(LAS unsigned char* lds, const Desc& D, const Epi& E, int wv) {
;     ...
;             PG8_WAIT_V(8); PG8_WAIT_L(0); PG8_BAR; PG8_MMA(1, 0, At, B0); PG8_MMA(1, 1, At, B1); PG8_BAR; PG8_SCHED;
;             PG8_LDB(B0, 1, 0); PG8_LDB(B1, 1, 1); PG8_SCHED; PG8_LDA(At, 1, 0); PG8_STAGE(PG8_SA(0, 1), a2 + hstepA, voffA);
;             PG8_WAIT_V(8); PG8_WAIT_L(0); PG8_BAR; PG8_MMA(0, 0, At, B0); PG8_MMA(0, 1, At, B1); PG8_BAR; PG8_SCHED;
	s_setprio 1
	v_mfma_f32_16x16x32_bf16 v[60:63], v[146:149], v[182:185], v[60:63]
	v_mfma_f32_16x16x32_bf16 v[56:59], v[158:161], v[182:185], v[56:59]
	v_mfma_f32_16x16x32_bf16 v[44:47], v[146:149], v[190:193], v[44:47]
	v_mfma_f32_16x16x32_bf16 v[40:43], v[158:161], v[190:193], v[40:43]
	v_mfma_f32_16x16x32_bf16 v[28:31], v[146:149], v[198:201], v[28:31]
	v_mfma_f32_16x16x32_bf16 v[24:27], v[158:161], v[198:201], v[24:27]
	v_mfma_f32_16x16x32_bf16 v[12:15], v[146:149], v[206:209], v[12:15]
	v_mfma_f32_16x16x32_bf16 v[8:11], v[158:161], v[206:209], v[8:11]
	v_mfma_f32_16x16x32_bf16 v[60:63], v[150:153], v[186:189], v[60:63]
	v_mfma_f32_16x16x32_bf16 v[56:59], v[162:165], v[186:189], v[56:59]
	v_mfma_f32_16x16x32_bf16 v[44:47], v[150:153], v[194:197], v[44:47]
	v_mfma_f32_16x16x32_bf16 v[40:43], v[162:165], v[194:197], v[40:43]
	v_mfma_f32_16x16x32_bf16 v[28:31], v[150:153], v[202:205], v[28:31]
	v_mfma_f32_16x16x32_bf16 v[24:27], v[162:165], v[202:205], v[24:27]
	v_mfma_f32_16x16x32_bf16 v[12:15], v[150:153], v[210:213], v[12:15]
	v_mfma_f32_16x16x32_bf16 v[8:11], v[162:165], v[210:213], v[8:11]
	v_mfma_f32_16x16x32_bf16 v[52:55], v[166:169], v[182:185], v[52:55]
	v_mfma_f32_16x16x32_bf16 v[48:51], v[174:177], v[182:185], v[48:51]
	v_mfma_f32_16x16x32_bf16 v[36:39], v[166:169], v[190:193], v[36:39]
	v_mfma_f32_16x16x32_bf16 v[32:35], v[174:177], v[190:193], v[32:35]
	v_mfma_f32_16x16x32_bf16 v[20:23], v[166:169], v[198:201], v[20:23]
	v_mfma_f32_16x16x32_bf16 v[16:19], v[174:177], v[198:201], v[16:19]
	v_mfma_f32_16x16x32_bf16 v[4:7], v[166:169], v[206:209], v[4:7]
	v_mfma_f32_16x16x32_bf16 v[0:3], v[174:177], v[206:209], v[0:3]
	v_mfma_f32_16x16x32_bf16 v[52:55], v[170:173], v[186:189], v[52:55]
	v_mfma_f32_16x16x32_bf16 v[48:51], v[178:181], v[186:189], v[48:51]
	v_mfma_f32_16x16x32_bf16 v[36:39], v[170:173], v[194:197], v[36:39]
	v_mfma_f32_16x16x32_bf16 v[32:35], v[178:181], v[194:197], v[32:35]
	v_mfma_f32_16x16x32_bf16 v[20:23], v[170:173], v[202:205], v[20:23]
	v_mfma_f32_16x16x32_bf16 v[16:19], v[178:181], v[202:205], v[16:19]
	v_mfma_f32_16x16x32_bf16 v[4:7], v[170:173], v[210:213], v[4:7]
	v_mfma_f32_16x16x32_bf16 v[0:3], v[178:181], v[210:213], v[0:3]
	s_setprio 0
	s_barrier
	s_add_i32 s17, 0, 0x18000
	v_add_u32_e32 v136, s17, v154
	s_add_i32 s19, 0, 0x1c000
	ds_read_b128 v[146:149], v136
	ds_read_b128 v[150:153], v136 offset:1024
	ds_read_b128 v[158:161], v136 offset:2048
	ds_read_b128 v[162:165], v136 offset:3072
	v_add_u32_e32 v136, s19, v154
	ds_read_b128 v[166:169], v136
	ds_read_b128 v[170:173], v136 offset:1024
	ds_read_b128 v[174:177], v136 offset:2048
	ds_read_b128 v[178:181], v136 offset:3072
	s_add_u32 s66, s66, 0x80000
	s_addc_u32 s67, s67, 0
	s_mov_b32 m0, s31
	v_lshl_add_u64 v[222:223], s[66:67], 0, v[128:129]
	ds_read_b128 v[182:185], v157 offset:32768
	ds_read_b128 v[186:189], v157 offset:33792
	ds_read_b128 v[190:193], v157 offset:34816
	ds_read_b128 v[194:197], v157 offset:35840
	ds_read_b128 v[198:201], v157 offset:36864
	ds_read_b128 v[202:205], v157 offset:37888
	ds_read_b128 v[206:209], v157 offset:38912
	ds_read_b128 v[210:213], v157 offset:39936
	global_load_lds_dwordx4 v[222:223], off
	s_mov_b32 m0, s34
	v_lshl_add_u64 v[222:223], s[66:67], 0, v[132:133]
	global_load_lds_dwordx4 v[222:223], off
	s_waitcnt vmcnt(8) lgkmcnt(0)
	s_barrier
	s_setprio 1
	v_mfma_f32_16x16x32_bf16 v[124:127], v[146:149], v[182:185], v[124:127]
	v_mfma_f32_16x16x32_bf16 v[120:123], v[158:161], v[182:185], v[120:123]
	v_mfma_f32_16x16x32_bf16 v[108:111], v[146:149], v[190:193], v[108:111]
	v_mfma_f32_16x16x32_bf16 v[104:107], v[158:161], v[190:193], v[104:107]
	v_mfma_f32_16x16x32_bf16 v[92:95], v[146:149], v[198:201], v[92:95]
	v_mfma_f32_16x16x32_bf16 v[88:91], v[158:161], v[198:201], v[88:91]
	v_mfma_f32_16x16x32_bf16 v[76:79], v[146:149], v[206:209], v[76:79]
	v_mfma_f32_16x16x32_bf16 v[72:75], v[158:161], v[206:209], v[72:75]
	v_mfma_f32_16x16x32_bf16 v[124:127], v[150:153], v[186:189], v[124:127]
	v_mfma_f32_16x16x32_bf16 v[120:123], v[162:165], v[186:189], v[120:123]
	v_mfma_f32_16x16x32_bf16 v[108:111], v[150:153], v[194:197], v[108:111]
	v_mfma_f32_16x16x32_bf16 v[104:107], v[162:165], v[194:197], v[104:107]
	v_mfma_f32_16x16x32_bf16 v[92:95], v[150:153], v[202:205], v[92:95]
	v_mfma_f32_16x16x32_bf16 v[88:91], v[162:165], v[202:205], v[88:91]
	v_mfma_f32_16x16x32_bf16 v[76:79], v[150:153], v[210:213], v[76:79]
	v_mfma_f32_16x16x32_bf16 v[72:75], v[162:165], v[210:213], v[72:75]
	v_mfma_f32_16x16x32_bf16 v[116:119], v[166:169], v[182:185], v[116:119]
	v_mfma_f32_16x16x32_bf16 v[112:115], v[174:177], v[182:185], v[112:115]
	v_mfma_f32_16x16x32_bf16 v[100:103], v[166:169], v[190:193], v[100:103]
	v_mfma_f32_16x16x32_bf16 v[96:99], v[174:177], v[190:193], v[96:99]
	v_mfma_f32_16x16x32_bf16 v[84:87], v[166:169], v[198:201], v[84:87]
	v_mfma_f32_16x16x32_bf16 v[80:83], v[174:177], v[198:201], v[80:83]
	v_mfma_f32_16x16x32_bf16 v[68:71], v[166:169], v[206:209], v[68:71]
	v_mfma_f32_16x16x32_bf16 v[64:67], v[174:177], v[206:209], v[64:67]
	v_mfma_f32_16x16x32_bf16 v[116:119], v[170:173], v[186:189], v[116:119]
	v_mfma_f32_16x16x32_bf16 v[112:115], v[178:181], v[186:189], v[112:115]
	v_mfma_f32_16x16x32_bf16 v[100:103], v[170:173], v[194:197], v[100:103]
	v_mfma_f32_16x16x32_bf16 v[96:99], v[178:181], v[194:197], v[96:99]
	v_mfma_f32_16x16x32_bf16 v[84:87], v[170:173], v[202:205], v[84:87]
	v_mfma_f32_16x16x32_bf16 v[80:83], v[178:181], v[202:205], v[80:83]
	v_mfma_f32_16x16x32_bf16 v[68:71], v[170:173], v[210:213], v[68:71]
	v_mfma_f32_16x16x32_bf16 v[64:67], v[178:181], v[210:213], v[64:67]
	s_setprio 0
	s_barrier
; #define PG8_STAGE(bufoff, gbase, voff) do { _Pragma("unroll") for (int _i = 0; _i < 2; ++_i) \
;         __builtin_amdgcn_global_load_lds((const unsigned*)((const char*)(gbase) + (voff)[_i]), (LAS unsigned*)(lds + (bufoff) + ldsw + _i * 8192), 16, 0, 0); } while (0)
; #define PG8_LDA(dst, b, h) do { _Pragma("unroll") for (int m = 0; m < 4; ++m) _Pragma("unroll") for (int k = 0; k < 2; ++k) dst[m][k] = *(const LAS bf16x8*)(lds + PG8_SA(b, h) + aoff + m * 2048 + k * 1024); } while (0)
; #define PG8_MMA(ai, bj, At, Bt) do { __builtin_amdgcn_s_setprio(1); _Pragma("unroll") for (int m = 0; m < 4; ++m) _Pragma("unroll") for (int n = 0; n < 2; ++n) _Pragma("unroll") for (int k = 0; k < 2; ++k) \
;         acc[ai][bj][m][n] = __builtin_amdgcn_mfma_f32_16x16x32_bf16(Bt[n][k], At[m][k], acc[ai][bj][m][n], 0, 0, 0); __builtin_amdgcn_s_setprio(0); } while (0)
; #define PG8_WAIT_V(n) asm volatile("s_waitcnt vmcnt(" #n ")" ::: "memory")
; #define PG8_WAIT_L(n) asm volatile("s_waitcnt lgkmcnt(" #n ")" ::: "memory")
; #define PG8_BAR __builtin_amdgcn_s_barrier()
; #define PG8_SCHED __builtin_amdgcn_sched_barrier(0)
; template <class Desc, class Epi>
; DI void gemm_phase(LAS unsigned char* lds, const Desc& D, const Epi& E, int wv) {
;     ...
;             PG8_LDA(At, 1, 1); PG8_STAGE(PG8_SB(1, 0), b3, voffB); PG8_STAGE(PG8_SB(1, 1), b3 + hstepB, voffB); PG8_STAGE(PG8_SA(1, 0), a3, voffA);
;             PG8_WAIT_V(8); PG8_WAIT_L(0); PG8_BAR; PG8_MMA(1, 0, At, B0); PG8_MMA(1, 1, At, B1); PG8_BAR; PG8_SCHED;
;         }
;         if (wr == 0) PG8_BAR;
	s_add_i32 s17, s17, s28
	v_lshl_add_u64 v[214:215], v[214:215], 0, s[12:13]
	s_mov_b32 m0, s17
	ds_read_b128 v[182:185], v157 offset:49152
	ds_read_b128 v[186:189], v157 offset:50176
	ds_read_b128 v[190:193], v157 offset:51200
	ds_read_b128 v[194:197], v157 offset:52224
	ds_read_b128 v[198:201], v157 offset:53248
	ds_read_b128 v[202:205], v157 offset:54272
	ds_read_b128 v[206:209], v157 offset:55296
	ds_read_b128 v[210:213], v157 offset:56320
	global_load_lds_dwordx4 v[214:215], off
	s_add_i32 m0, s17, 0x2000
	s_add_u32 s64, s64, 0x80080
	v_lshl_add_u64 v[214:215], v[216:217], 0, s[12:13]
	s_addc_u32 s65, s65, 0
	s_add_i32 s17, s19, s28
	global_load_lds_dwordx4 v[214:215], off
	s_mov_b32 m0, s17
	v_lshl_add_u64 v[214:215], s[64:65], 0, v[130:131]
	global_load_lds_dwordx4 v[214:215], off
	s_add_i32 m0, s17, 0x2000
	v_lshl_add_u64 v[214:215], s[64:65], 0, v[134:135]
	global_load_lds_dwordx4 v[214:215], off
	s_mov_b32 m0, s47
	v_lshl_add_u64 v[214:215], v[218:219], 0, s[12:13]
	global_load_lds_dwordx4 v[214:215], off
	s_mov_b32 m0, s48
	v_lshl_add_u64 v[214:215], v[220:221], 0, s[12:13]
	global_load_lds_dwordx4 v[214:215], off
	s_waitcnt vmcnt(8) lgkmcnt(0)
	s_barrier
	s_setprio 1
	v_mfma_f32_16x16x32_bf16 v[60:63], v[146:149], v[182:185], v[60:63]
	v_mfma_f32_16x16x32_bf16 v[56:59], v[158:161], v[182:185], v[56:59]
	v_mfma_f32_16x16x32_bf16 v[44:47], v[146:149], v[190:193], v[44:47]
	v_mfma_f32_16x16x32_bf16 v[40:43], v[158:161], v[190:193], v[40:43]
	v_mfma_f32_16x16x32_bf16 v[28:31], v[146:149], v[198:201], v[28:31]
	v_mfma_f32_16x16x32_bf16 v[24:27], v[158:161], v[198:201], v[24:27]
	v_mfma_f32_16x16x32_bf16 v[12:15], v[146:149], v[206:209], v[12:15]
	v_mfma_f32_16x16x32_bf16 v[8:11], v[158:161], v[206:209], v[8:11]
	v_mfma_f32_16x16x32_bf16 v[60:63], v[150:153], v[186:189], v[60:63]
	v_mfma_f32_16x16x32_bf16 v[56:59], v[162:165], v[186:189], v[56:59]
	v_mfma_f32_16x16x32_bf16 v[44:47], v[150:153], v[194:197], v[44:47]
	v_mfma_f32_16x16x32_bf16 v[40:43], v[162:165], v[194:197], v[40:43]
	v_mfma_f32_16x16x32_bf16 v[28:31], v[150:153], v[202:205], v[28:31]
	v_mfma_f32_16x16x32_bf16 v[24:27], v[162:165], v[202:205], v[24:27]
	v_mfma_f32_16x16x32_bf16 v[12:15], v[150:153], v[210:213], v[12:15]
	v_mfma_f32_16x16x32_bf16 v[8:11], v[162:165], v[210:213], v[8:11]
	v_mfma_f32_16x16x32_bf16 v[52:55], v[166:169], v[182:185], v[52:55]
	v_mfma_f32_16x16x32_bf16 v[48:51], v[174:177], v[182:185], v[48:51]
	v_mfma_f32_16x16x32_bf16 v[36:39], v[166:169], v[190:193], v[36:39]
	v_mfma_f32_16x16x32_bf16 v[32:35], v[174:177], v[190:193], v[32:35]
	v_mfma_f32_16x16x32_bf16 v[20:23], v[166:169], v[198:201], v[20:23]
	v_mfma_f32_16x16x32_bf16 v[16:19], v[174:177], v[198:201], v[16:19]
	v_mfma_f32_16x16x32_bf16 v[4:7], v[166:169], v[206:209], v[4:7]
	v_mfma_f32_16x16x32_bf16 v[0:3], v[174:177], v[206:209], v[0:3]
	v_mfma_f32_16x16x32_bf16 v[52:55], v[170:173], v[186:189], v[52:55]
	v_mfma_f32_16x16x32_bf16 v[48:51], v[178:181], v[186:189], v[48:51]
	v_mfma_f32_16x16x32_bf16 v[36:39], v[170:173], v[194:197], v[36:39]
	v_mfma_f32_16x16x32_bf16 v[32:35], v[178:181], v[194:197], v[32:35]
	v_mfma_f32_16x16x32_bf16 v[20:23], v[170:173], v[202:205], v[20:23]
	v_mfma_f32_16x16x32_bf16 v[16:19], v[178:181], v[202:205], v[16:19]
	v_mfma_f32_16x16x32_bf16 v[4:7], v[170:173], v[210:213], v[4:7]
	v_mfma_f32_16x16x32_bf16 v[0:3], v[178:181], v[210:213], v[0:3]
	s_setprio 0
	s_barrier
	s_add_i32 s8, s8, 2
	s_add_u32 s62, s62, 0x100
	s_addc_u32 s63, s63, 0
	s_add_u32 s5, s5, 0x100
	s_addc_u32 s7, s7, 0
	s_cmp_gt_u32 s8, 29
	s_cbranch_scc0 .LBB0_1632
	s_and_b64 vcc, exec, s[14:15]
	s_cbranch_vccz .LBB0_1635
	s_barrier

; #define PG8_STAGE(bufoff, gbase, voff) do { _Pragma("unroll") for (int _i = 0; _i < 2; ++_i) \
;         __builtin_amdgcn_global_load_lds((const unsigned*)((const char*)(gbase) + (voff)[_i]), (LAS unsigned*)(lds + (bufoff) + ldsw + _i * 8192), 16, 0, 0); } while (0)
; #define PG8_LDA(dst, b, h) do { _Pragma("unroll") for (int m = 0; m < 4; ++m) _Pragma("unroll") for (int k = 0; k < 2; ++k) dst[m][k] = *(const LAS bf16x8*)(lds + PG8_SA(b, h) + aoff + m * 2048 + k * 1024); } while (0)
; #define PG8_LDB(dst, b, h) do { _Pragma("unroll") for (int n = 0; n < 2; ++n) _Pragma("unroll") for (int k = 0; k < 2; ++k) dst[n][k] = *(const LAS bf16x8*)(lds + PG8_SB(b, h) + boff + n * 2048 + k * 1024); } while (0)
; #define PG8_MMA(ai, bj, At, Bt) do { __builtin_amdgcn_s_setprio(1); _Pragma("unroll") for (int m = 0; m < 4; ++m) _Pragma("unroll") for (int n = 0; n < 2; ++n) _Pragma("unroll") for (int k = 0; k < 2; ++k) \
;         acc[ai][bj][m][n] = __builtin_amdgcn_mfma_f32_16x16x32_bf16(Bt[n][k], At[m][k], acc[ai][bj][m][n], 0, 0, 0); __builtin_amdgcn_s_setprio(0); } while (0)
; #define PG8_WAIT_V(n) asm volatile("s_waitcnt vmcnt(" #n ")" ::: "memory")
; #define PG8_WAIT_L(n) asm volatile("s_waitcnt lgkmcnt(" #n ")" ::: "memory")
; #define PG8_BAR __builtin_amdgcn_s_barrier()
; #define PG8_SCHED __builtin_amdgcn_sched_barrier(0)
; template <class Desc, class Epi>
; DI void gemm_phase(LAS unsigned char* lds, const Desc& D, const Epi& E, int wv) {
;     ...
;         for (int t = 0; t < nt; t += 2) {
;             const bool last = (t == nt - 2);
;             const char* a1 = cA + (size_t)(t + 1) * kstep;
;             const char* a2 = last ? nA : cA + (size_t)(t + 2) * kstep; const char* b2 = last ? nB : cB + (size_t)(t + 2) * kstep;
;             const char* a3 = a2 + kstep; const char* b3 = b2 + kstep;
;             PG8_LDB(B0, 0, 0); PG8_LDB(B1, 0, 1); PG8_SCHED; PG8_LDA(At, 0, 0); PG8_STAGE(PG8_SA(1, 1), a1 + hstepA, voffA);
;             PG8_WAIT_V(8); PG8_WAIT_L(0); PG8_BAR; PG8_MMA(0, 0, At, B0); PG8_MMA(0, 1, At, B1); PG8_BAR; PG8_SCHED;
;             PG8_LDA(At, 0, 1); PG8_STAGE(PG8_SB(0, 0), b2, voffB); PG8_STAGE(PG8_SB(0, 1), b2 + hstepB, voffB); PG8_STAGE(PG8_SA(0, 0), a2, voffA);
;             PG8_WAIT_V(8); PG8_WAIT_L(0); PG8_BAR; PG8_MMA(1, 0, At, B0); PG8_MMA(1, 1, At, B1); PG8_BAR; PG8_SCHED;
.LBB0_2088:
	ds_read_b128 v[128:131], v221
	ds_read_b128 v[132:135], v221 offset:1024
	ds_read_b128 v[136:139], v221 offset:2048
	ds_read_b128 v[140:143], v221 offset:3072
	ds_read_b128 v[144:147], v222
	ds_read_b128 v[148:151], v222 offset:1024
	ds_read_b128 v[152:155], v222 offset:2048
	ds_read_b128 v[156:159], v222 offset:3072
	s_add_u32 s42, s40, 0xfff80080
	s_addc_u32 s43, s41, -1
	s_cmp_eq_u32 s66, 28
	s_cselect_b32 s49, s15, s43
	s_cselect_b32 s48, s14, s42
	s_cselect_b32 s43, s17, s21
	s_cselect_b32 s42, s16, s19
	v_lshl_add_u64 v[192:193], s[40:41], 0, v[208:209]
	s_add_i32 m0, s29, 0xc000
	ds_read_b128 v[160:163], v223
	ds_read_b128 v[164:167], v223 offset:1024
	ds_read_b128 v[168:171], v223 offset:2048
	ds_read_b128 v[172:175], v223 offset:3072
	ds_read_b128 v[176:179], v223 offset:4096
	ds_read_b128 v[180:183], v223 offset:5120
	ds_read_b128 v[184:187], v223 offset:6144
	ds_read_b128 v[188:191], v223 offset:7168
	global_load_lds_dwordx4 v[192:193], off
	s_add_i32 m0, s29, 0xe000
	v_lshl_add_u64 v[192:193], s[40:41], 0, v[210:211]
	global_load_lds_dwordx4 v[192:193], off
	s_waitcnt vmcnt(8) lgkmcnt(0)
	s_barrier
	s_setprio 1
	v_mfma_f32_16x16x32_bf16 v[124:127], v[128:131], v[160:163], v[124:127]
	v_mfma_f32_16x16x32_bf16 v[120:123], v[136:139], v[160:163], v[120:123]
	v_mfma_f32_16x16x32_bf16 v[112:115], v[128:131], v[168:171], v[112:115]
	v_mfma_f32_16x16x32_bf16 v[104:107], v[136:139], v[168:171], v[104:107]
	v_mfma_f32_16x16x32_bf16 v[96:99], v[128:131], v[176:179], v[96:99]
	v_mfma_f32_16x16x32_bf16 v[88:91], v[136:139], v[176:179], v[88:91]
	v_mfma_f32_16x16x32_bf16 v[80:83], v[128:131], v[184:187], v[80:83]
	v_mfma_f32_16x16x32_bf16 v[72:75], v[136:139], v[184:187], v[72:75]
	v_mfma_f32_16x16x32_bf16 v[124:127], v[132:135], v[164:167], v[124:127]
	v_mfma_f32_16x16x32_bf16 v[120:123], v[140:143], v[164:167], v[120:123]
	v_mfma_f32_16x16x32_bf16 v[112:115], v[132:135], v[172:175], v[112:115]
	v_mfma_f32_16x16x32_bf16 v[104:107], v[140:143], v[172:175], v[104:107]
	v_mfma_f32_16x16x32_bf16 v[96:99], v[132:135], v[180:183], v[96:99]
	v_mfma_f32_16x16x32_bf16 v[88:91], v[140:143], v[180:183], v[88:91]
	v_mfma_f32_16x16x32_bf16 v[80:83], v[132:135], v[188:191], v[80:83]
	v_mfma_f32_16x16x32_bf16 v[72:75], v[140:143], v[188:191], v[72:75]
	v_mfma_f32_16x16x32_bf16 v[116:119], v[144:147], v[160:163], v[116:119]
	v_mfma_f32_16x16x32_bf16 v[108:111], v[152:155], v[160:163], v[108:111]
	v_mfma_f32_16x16x32_bf16 v[100:103], v[144:147], v[168:171], v[100:103]
	v_mfma_f32_16x16x32_bf16 v[92:95], v[152:155], v[168:171], v[92:95]
	v_mfma_f32_16x16x32_bf16 v[84:87], v[144:147], v[176:179], v[84:87]
	v_mfma_f32_16x16x32_bf16 v[76:79], v[152:155], v[176:179], v[76:79]
	v_mfma_f32_16x16x32_bf16 v[68:71], v[144:147], v[184:187], v[68:71]
	v_mfma_f32_16x16x32_bf16 v[64:67], v[152:155], v[184:187], v[64:67]
	v_mfma_f32_16x16x32_bf16 v[116:119], v[148:151], v[164:167], v[116:119]
	v_mfma_f32_16x16x32_bf16 v[108:111], v[156:159], v[164:167], v[108:111]
	v_mfma_f32_16x16x32_bf16 v[100:103], v[148:151], v[172:175], v[100:103]
	v_mfma_f32_16x16x32_bf16 v[92:95], v[156:159], v[172:175], v[92:95]
	v_mfma_f32_16x16x32_bf16 v[84:87], v[148:151], v[180:183], v[84:87]
	v_mfma_f32_16x16x32_bf16 v[76:79], v[156:159], v[180:183], v[76:79]
	v_mfma_f32_16x16x32_bf16 v[68:71], v[148:151], v[188:191], v[68:71]
	v_mfma_f32_16x16x32_bf16 v[64:67], v[156:159], v[188:191], v[64:67]
	s_setprio 0
	s_barrier
	s_add_i32 s67, s53, s28
	v_lshl_add_u64 v[192:193], s[42:43], 0, v[202:203]
	s_mov_b32 m0, s67
	ds_read_b128 v[160:163], v223 offset:16384
	ds_read_b128 v[164:167], v223 offset:17408
	ds_read_b128 v[168:171], v223 offset:18432
	ds_read_b128 v[172:175], v223 offset:19456
	ds_read_b128 v[176:179], v223 offset:20480
	ds_read_b128 v[180:183], v223 offset:21504
	ds_read_b128 v[184:187], v223 offset:22528
	ds_read_b128 v[188:191], v223 offset:23552
	global_load_lds_dwordx4 v[192:193], off
	s_add_i32 m0, s67, 0x2000
	s_add_u32 s68, s42, 0x80000
	v_lshl_add_u64 v[194:195], s[42:43], 0, v[206:207]
	s_addc_u32 s69, s43, 0
	s_add_i32 s67, s60, s28
	global_load_lds_dwordx4 v[194:195], off
	v_lshl_add_u64 v[196:197], s[68:69], 0, v[202:203]
	s_mov_b32 m0, s67
	v_lshl_add_u64 v[198:199], s[48:49], 0, v[204:205]
	global_load_lds_dwordx4 v[196:197], off
	s_add_i32 m0, s67, 0x2000
	v_lshl_add_u64 v[196:197], s[68:69], 0, v[206:207]
	global_load_lds_dwordx4 v[196:197], off
	s_mov_b32 m0, s29
	v_lshl_add_u64 v[196:197], s[48:49], 0, v[200:201]
	global_load_lds_dwordx4 v[196:197], off
	s_mov_b32 m0, s30
	s_nop 0
	global_load_lds_dwordx4 v[198:199], off
	s_waitcnt vmcnt(8) lgkmcnt(0)
	s_barrier
; #define PG8_STAGE(bufoff, gbase, voff) do { _Pragma("unroll") for (int _i = 0; _i < 2; ++_i) \
;         __builtin_amdgcn_global_load_lds((const unsigned*)((const char*)(gbase) + (voff)[_i]), (LAS unsigned*)(lds + (bufoff) + ldsw + _i * 8192), 16, 0, 0); } while (0)
; #define PG8_LDA(dst, b, h) do { _Pragma("unroll") for (int m = 0; m < 4; ++m) _Pragma("unroll") for (int k = 0; k < 2; ++k) dst[m][k] = *(const LAS bf16x8*)(lds + PG8_SA(b, h) + aoff + m * 2048 + k * 1024); } while (0)
; #define PG8_LDB(dst, b, h) do { _Pragma("unroll") for (int n = 0; n < 2; ++n) _Pragma("unroll") for (int k = 0; k < 2; ++k) dst[n][k] = *(const LAS bf16x8*)(lds + PG8_SB(b, h) + boff + n * 2048 + k * 1024); } while (0)
; #define PG8_MMA(ai, bj, At, Bt) do { __builtin_amdgcn_s_setprio(1); _Pragma("unroll") for (int m = 0; m < 4; ++m) _Pragma("unroll") for (int n = 0; n < 2; ++n) _Pragma("unroll") for (int k = 0; k < 2; ++k) \
;         acc[ai][bj][m][n] = __builtin_amdgcn_mfma_f32_16x16x32_bf16(Bt[n][k], At[m][k], acc[ai][bj][m][n], 0, 0, 0); __builtin_amdgcn_s_setprio(0); } while (0)
; #define PG8_WAIT_V(n) asm volatile("s_waitcnt vmcnt(" #n ")" ::: "memory")
; #define PG8_WAIT_L(n) asm volatile("s_waitcnt lgkmcnt(" #n ")" ::: "memory")
; #define PG8_BAR __builtin_amdgcn_s_barrier()
; #define PG8_SCHED __builtin_amdgcn_sched_barrier(0)
; template <class Desc, class Epi>
; DI void gemm_phase(LAS unsigned char* lds, const Desc& D, const Epi& E, int wv) {
;     ...
;             PG8_WAIT_V(8); PG8_WAIT_L(0); PG8_BAR; PG8_MMA(1, 0, At, B0); PG8_MMA(1, 1, At, B1); PG8_BAR; PG8_SCHED;
;             PG8_LDB(B0, 1, 0); PG8_LDB(B1, 1, 1); PG8_SCHED; PG8_LDA(At, 1, 0); PG8_STAGE(PG8_SA(0, 1), a2 + hstepA, voffA);
;             PG8_WAIT_V(8); PG8_WAIT_L(0); PG8_BAR; PG8_MMA(0, 0, At, B0); PG8_MMA(0, 1, At, B1); PG8_BAR; PG8_SCHED;
	s_setprio 1
	v_mfma_f32_16x16x32_bf16 v[60:63], v[128:131], v[160:163], v[60:63]
	v_mfma_f32_16x16x32_bf16 v[56:59], v[136:139], v[160:163], v[56:59]
	v_mfma_f32_16x16x32_bf16 v[48:51], v[128:131], v[168:171], v[48:51]
	v_mfma_f32_16x16x32_bf16 v[40:43], v[136:139], v[168:171], v[40:43]
	v_mfma_f32_16x16x32_bf16 v[32:35], v[128:131], v[176:179], v[32:35]
	v_mfma_f32_16x16x32_bf16 v[24:27], v[136:139], v[176:179], v[24:27]
	v_mfma_f32_16x16x32_bf16 v[16:19], v[128:131], v[184:187], v[16:19]
	v_mfma_f32_16x16x32_bf16 v[8:11], v[136:139], v[184:187], v[8:11]
	v_mfma_f32_16x16x32_bf16 v[60:63], v[132:135], v[164:167], v[60:63]
	v_mfma_f32_16x16x32_bf16 v[56:59], v[140:143], v[164:167], v[56:59]
	v_mfma_f32_16x16x32_bf16 v[48:51], v[132:135], v[172:175], v[48:51]
	v_mfma_f32_16x16x32_bf16 v[40:43], v[140:143], v[172:175], v[40:43]
	v_mfma_f32_16x16x32_bf16 v[32:35], v[132:135], v[180:183], v[32:35]
	v_mfma_f32_16x16x32_bf16 v[24:27], v[140:143], v[180:183], v[24:27]
	v_mfma_f32_16x16x32_bf16 v[16:19], v[132:135], v[188:191], v[16:19]
	v_mfma_f32_16x16x32_bf16 v[8:11], v[140:143], v[188:191], v[8:11]
	v_mfma_f32_16x16x32_bf16 v[52:55], v[144:147], v[160:163], v[52:55]
	v_mfma_f32_16x16x32_bf16 v[44:47], v[152:155], v[160:163], v[44:47]
	v_mfma_f32_16x16x32_bf16 v[36:39], v[144:147], v[168:171], v[36:39]
	v_mfma_f32_16x16x32_bf16 v[28:31], v[152:155], v[168:171], v[28:31]
	v_mfma_f32_16x16x32_bf16 v[20:23], v[144:147], v[176:179], v[20:23]
	v_mfma_f32_16x16x32_bf16 v[12:15], v[152:155], v[176:179], v[12:15]
	v_mfma_f32_16x16x32_bf16 v[4:7], v[144:147], v[184:187], v[4:7]
	v_mfma_f32_16x16x32_bf16 v[0:3], v[152:155], v[184:187], v[0:3]
	v_mfma_f32_16x16x32_bf16 v[52:55], v[148:151], v[164:167], v[52:55]
	v_mfma_f32_16x16x32_bf16 v[44:47], v[156:159], v[164:167], v[44:47]
	v_mfma_f32_16x16x32_bf16 v[36:39], v[148:151], v[172:175], v[36:39]
	v_mfma_f32_16x16x32_bf16 v[28:31], v[156:159], v[172:175], v[28:31]
	v_mfma_f32_16x16x32_bf16 v[20:23], v[148:151], v[180:183], v[20:23]
	v_mfma_f32_16x16x32_bf16 v[12:15], v[156:159], v[180:183], v[12:15]
	v_mfma_f32_16x16x32_bf16 v[4:7], v[148:151], v[188:191], v[4:7]
	v_mfma_f32_16x16x32_bf16 v[0:3], v[156:159], v[188:191], v[0:3]
	s_setprio 0
	s_barrier
	s_add_i32 s67, 0, 0x18000
	s_add_i32 s68, 0, 0x1c000
	v_add_u32_e32 v140, s67, v220
	v_add_u32_e32 v156, s68, v220
	ds_read_b128 v[128:131], v140
	ds_read_b128 v[132:135], v140 offset:1024
	ds_read_b128 v[136:139], v140 offset:2048
	ds_read_b128 v[140:143], v140 offset:3072
	ds_read_b128 v[144:147], v156
	ds_read_b128 v[148:151], v156 offset:1024
	ds_read_b128 v[152:155], v156 offset:2048
	ds_read_b128 v[156:159], v156 offset:3072
	s_add_u32 s48, s48, 0x80000
	s_addc_u32 s49, s49, 0
	s_mov_b32 m0, s31
	v_lshl_add_u64 v[216:217], s[48:49], 0, v[200:201]
	ds_read_b128 v[160:163], v223 offset:32768
	ds_read_b128 v[164:167], v223 offset:33792
	ds_read_b128 v[168:171], v223 offset:34816
	ds_read_b128 v[172:175], v223 offset:35840
	ds_read_b128 v[176:179], v223 offset:36864
	ds_read_b128 v[180:183], v223 offset:37888
	ds_read_b128 v[184:187], v223 offset:38912
	ds_read_b128 v[188:191], v223 offset:39936
	global_load_lds_dwordx4 v[216:217], off
	s_mov_b32 m0, s34
	v_lshl_add_u64 v[216:217], s[48:49], 0, v[204:205]
	global_load_lds_dwordx4 v[216:217], off
	s_waitcnt vmcnt(8) lgkmcnt(0)
	s_barrier
	s_setprio 1
	v_mfma_f32_16x16x32_bf16 v[124:127], v[128:131], v[160:163], v[124:127]
	v_mfma_f32_16x16x32_bf16 v[120:123], v[136:139], v[160:163], v[120:123]
	v_mfma_f32_16x16x32_bf16 v[112:115], v[128:131], v[168:171], v[112:115]
	v_mfma_f32_16x16x32_bf16 v[104:107], v[136:139], v[168:171], v[104:107]
	v_mfma_f32_16x16x32_bf16 v[96:99], v[128:131], v[176:179], v[96:99]
	v_mfma_f32_16x16x32_bf16 v[88:91], v[136:139], v[176:179], v[88:91]
	v_mfma_f32_16x16x32_bf16 v[80:83], v[128:131], v[184:187], v[80:83]
	v_mfma_f32_16x16x32_bf16 v[72:75], v[136:139], v[184:187], v[72:75]
	v_mfma_f32_16x16x32_bf16 v[124:127], v[132:135], v[164:167], v[124:127]
	v_mfma_f32_16x16x32_bf16 v[120:123], v[140:143], v[164:167], v[120:123]
	v_mfma_f32_16x16x32_bf16 v[112:115], v[132:135], v[172:175], v[112:115]
	v_mfma_f32_16x16x32_bf16 v[104:107], v[140:143], v[172:175], v[104:107]
	v_mfma_f32_16x16x32_bf16 v[96:99], v[132:135], v[180:183], v[96:99]
	v_mfma_f32_16x16x32_bf16 v[88:91], v[140:143], v[180:183], v[88:91]
	v_mfma_f32_16x16x32_bf16 v[80:83], v[132:135], v[188:191], v[80:83]
	v_mfma_f32_16x16x32_bf16 v[72:75], v[140:143], v[188:191], v[72:75]
	v_mfma_f32_16x16x32_bf16 v[116:119], v[144:147], v[160:163], v[116:119]
	v_mfma_f32_16x16x32_bf16 v[108:111], v[152:155], v[160:163], v[108:111]
	v_mfma_f32_16x16x32_bf16 v[100:103], v[144:147], v[168:171], v[100:103]
	v_mfma_f32_16x16x32_bf16 v[92:95], v[152:155], v[168:171], v[92:95]
	v_mfma_f32_16x16x32_bf16 v[84:87], v[144:147], v[176:179], v[84:87]
	v_mfma_f32_16x16x32_bf16 v[76:79], v[152:155], v[176:179], v[76:79]
	v_mfma_f32_16x16x32_bf16 v[68:71], v[144:147], v[184:187], v[68:71]
	v_mfma_f32_16x16x32_bf16 v[64:67], v[152:155], v[184:187], v[64:67]
	v_mfma_f32_16x16x32_bf16 v[116:119], v[148:151], v[164:167], v[116:119]
	v_mfma_f32_16x16x32_bf16 v[108:111], v[156:159], v[164:167], v[108:111]
	v_mfma_f32_16x16x32_bf16 v[100:103], v[148:151], v[172:175], v[100:103]
	v_mfma_f32_16x16x32_bf16 v[92:95], v[156:159], v[172:175], v[92:95]
	v_mfma_f32_16x16x32_bf16 v[84:87], v[148:151], v[180:183], v[84:87]
	v_mfma_f32_16x16x32_bf16 v[76:79], v[156:159], v[180:183], v[76:79]
	v_mfma_f32_16x16x32_bf16 v[68:71], v[148:151], v[188:191], v[68:71]
	v_mfma_f32_16x16x32_bf16 v[64:67], v[156:159], v[188:191], v[64:67]
	s_setprio 0
	s_barrier
; #define PG8_STAGE(bufoff, gbase, voff) do { _Pragma("unroll") for (int _i = 0; _i < 2; ++_i) \
;         __builtin_amdgcn_global_load_lds((const unsigned*)((const char*)(gbase) + (voff)[_i]), (LAS unsigned*)(lds + (bufoff) + ldsw + _i * 8192), 16, 0, 0); } while (0)
; #define PG8_LDA(dst, b, h) do { _Pragma("unroll") for (int m = 0; m < 4; ++m) _Pragma("unroll") for (int k = 0; k < 2; ++k) dst[m][k] = *(const LAS bf16x8*)(lds + PG8_SA(b, h) + aoff + m * 2048 + k * 1024); } while (0)
; #define PG8_MMA(ai, bj, At, Bt) do { __builtin_amdgcn_s_setprio(1); _Pragma("unroll") for (int m = 0; m < 4; ++m) _Pragma("unroll") for (int n = 0; n < 2; ++n) _Pragma("unroll") for (int k = 0; k < 2; ++k) \
;         acc[ai][bj][m][n] = __builtin_amdgcn_mfma_f32_16x16x32_bf16(Bt[n][k], At[m][k], acc[ai][bj][m][n], 0, 0, 0); __builtin_amdgcn_s_setprio(0); } while (0)
; #define PG8_WAIT_V(n) asm volatile("s_waitcnt vmcnt(" #n ")" ::: "memory")
; #define PG8_WAIT_L(n) asm volatile("s_waitcnt lgkmcnt(" #n ")" ::: "memory")
; #define PG8_BAR __builtin_amdgcn_s_barrier()
; #define PG8_SCHED __builtin_amdgcn_sched_barrier(0)
; template <class Desc, class Epi>
; DI void gemm_phase(LAS unsigned char* lds, const Desc& D, const Epi& E, int wv) {
;     ...
;             PG8_LDA(At, 1, 1); PG8_STAGE(PG8_SB(1, 0), b3, voffB); PG8_STAGE(PG8_SB(1, 1), b3 + hstepB, voffB); PG8_STAGE(PG8_SA(1, 0), a3, voffA);
;             PG8_WAIT_V(8); PG8_WAIT_L(0); PG8_BAR; PG8_MMA(1, 0, At, B0); PG8_MMA(1, 1, At, B1); PG8_BAR; PG8_SCHED;
;         }
;         if (wr == 0) PG8_BAR;
	s_add_i32 s48, s67, s28
	v_lshl_add_u64 v[192:193], v[192:193], 0, s[8:9]
	s_mov_b32 m0, s48
	ds_read_b128 v[160:163], v223 offset:49152
	ds_read_b128 v[164:167], v223 offset:50176
	ds_read_b128 v[168:171], v223 offset:51200
	ds_read_b128 v[172:175], v223 offset:52224
	ds_read_b128 v[176:179], v223 offset:53248
	ds_read_b128 v[180:183], v223 offset:54272
	ds_read_b128 v[184:187], v223 offset:55296
	ds_read_b128 v[188:191], v223 offset:56320
	global_load_lds_dwordx4 v[192:193], off
	s_add_i32 m0, s48, 0x2000
	s_add_u32 s42, s42, 0x80080
	v_lshl_add_u64 v[192:193], v[194:195], 0, s[8:9]
	s_addc_u32 s43, s43, 0
	s_add_i32 s48, s68, s28
	global_load_lds_dwordx4 v[192:193], off
	s_mov_b32 m0, s48
	v_lshl_add_u64 v[192:193], s[42:43], 0, v[202:203]
	global_load_lds_dwordx4 v[192:193], off
	s_add_i32 m0, s48, 0x2000
	v_lshl_add_u64 v[192:193], s[42:43], 0, v[206:207]
	global_load_lds_dwordx4 v[192:193], off
	s_mov_b32 m0, s50
	v_lshl_add_u64 v[192:193], v[196:197], 0, s[8:9]
	global_load_lds_dwordx4 v[192:193], off
	s_mov_b32 m0, s51
	v_lshl_add_u64 v[192:193], v[198:199], 0, s[8:9]
	global_load_lds_dwordx4 v[192:193], off
	s_waitcnt vmcnt(8) lgkmcnt(0)
	s_barrier
	s_setprio 1
	v_mfma_f32_16x16x32_bf16 v[60:63], v[128:131], v[160:163], v[60:63]
	v_mfma_f32_16x16x32_bf16 v[56:59], v[136:139], v[160:163], v[56:59]
	v_mfma_f32_16x16x32_bf16 v[48:51], v[128:131], v[168:171], v[48:51]
	v_mfma_f32_16x16x32_bf16 v[40:43], v[136:139], v[168:171], v[40:43]
	v_mfma_f32_16x16x32_bf16 v[32:35], v[128:131], v[176:179], v[32:35]
	v_mfma_f32_16x16x32_bf16 v[24:27], v[136:139], v[176:179], v[24:27]
	v_mfma_f32_16x16x32_bf16 v[16:19], v[128:131], v[184:187], v[16:19]
	v_mfma_f32_16x16x32_bf16 v[8:11], v[136:139], v[184:187], v[8:11]
	v_mfma_f32_16x16x32_bf16 v[60:63], v[132:135], v[164:167], v[60:63]
	v_mfma_f32_16x16x32_bf16 v[56:59], v[140:143], v[164:167], v[56:59]
	v_mfma_f32_16x16x32_bf16 v[48:51], v[132:135], v[172:175], v[48:51]
	v_mfma_f32_16x16x32_bf16 v[40:43], v[140:143], v[172:175], v[40:43]
	v_mfma_f32_16x16x32_bf16 v[32:35], v[132:135], v[180:183], v[32:35]
	v_mfma_f32_16x16x32_bf16 v[24:27], v[140:143], v[180:183], v[24:27]
	v_mfma_f32_16x16x32_bf16 v[16:19], v[132:135], v[188:191], v[16:19]
	v_mfma_f32_16x16x32_bf16 v[8:11], v[140:143], v[188:191], v[8:11]
	v_mfma_f32_16x16x32_bf16 v[52:55], v[144:147], v[160:163], v[52:55]
	v_mfma_f32_16x16x32_bf16 v[44:47], v[152:155], v[160:163], v[44:47]
	v_mfma_f32_16x16x32_bf16 v[36:39], v[144:147], v[168:171], v[36:39]
	v_mfma_f32_16x16x32_bf16 v[28:31], v[152:155], v[168:171], v[28:31]
	v_mfma_f32_16x16x32_bf16 v[20:23], v[144:147], v[176:179], v[20:23]
	v_mfma_f32_16x16x32_bf16 v[12:15], v[152:155], v[176:179], v[12:15]
	v_mfma_f32_16x16x32_bf16 v[4:7], v[144:147], v[184:187], v[4:7]
	v_mfma_f32_16x16x32_bf16 v[0:3], v[152:155], v[184:187], v[0:3]
	v_mfma_f32_16x16x32_bf16 v[52:55], v[148:151], v[164:167], v[52:55]
	v_mfma_f32_16x16x32_bf16 v[44:47], v[156:159], v[164:167], v[44:47]
	v_mfma_f32_16x16x32_bf16 v[36:39], v[148:151], v[172:175], v[36:39]
	v_mfma_f32_16x16x32_bf16 v[28:31], v[156:159], v[172:175], v[28:31]
	v_mfma_f32_16x16x32_bf16 v[20:23], v[148:151], v[180:183], v[20:23]
	v_mfma_f32_16x16x32_bf16 v[12:15], v[156:159], v[180:183], v[12:15]
	v_mfma_f32_16x16x32_bf16 v[4:7], v[148:151], v[188:191], v[4:7]
	v_mfma_f32_16x16x32_bf16 v[0:3], v[156:159], v[188:191], v[0:3]
	s_setprio 0
	s_barrier
	s_add_i32 s66, s66, 2
	s_add_u32 s40, s40, 0x100
	s_addc_u32 s41, s41, 0
	s_add_u32 s19, s19, 0x100
	s_addc_u32 s21, s21, 0
	s_cmp_gt_u32 s66, 29
	s_cbranch_scc0 .LBB0_2088
	s_and_b64 vcc, exec, s[10:11]
	s_cbranch_vccz .LBB0_2091
	s_barrier

; #define PG8_STAGE(bufoff, gbase, voff) do { _Pragma("unroll") for (int _i = 0; _i < 2; ++_i) \
;         __builtin_amdgcn_global_load_lds((const unsigned*)((const char*)(gbase) + (voff)[_i]), (LAS unsigned*)(lds + (bufoff) + ldsw + _i * 8192), 16, 0, 0); } while (0)
; #define PG8_LDA(dst, b, h) do { _Pragma("unroll") for (int m = 0; m < 4; ++m) _Pragma("unroll") for (int k = 0; k < 2; ++k) dst[m][k] = *(const LAS bf16x8*)(lds + PG8_SA(b, h) + aoff + m * 2048 + k * 1024); } while (0)
; #define PG8_LDB(dst, b, h) do { _Pragma("unroll") for (int n = 0; n < 2; ++n) _Pragma("unroll") for (int k = 0; k < 2; ++k) dst[n][k] = *(const LAS bf16x8*)(lds + PG8_SB(b, h) + boff + n * 2048 + k * 1024); } while (0)
; #define PG8_MMA(ai, bj, At, Bt) do { __builtin_amdgcn_s_setprio(1); _Pragma("unroll") for (int m = 0; m < 4; ++m) _Pragma("unroll") for (int n = 0; n < 2; ++n) _Pragma("unroll") for (int k = 0; k < 2; ++k) \
;         acc[ai][bj][m][n] = __builtin_amdgcn_mfma_f32_16x16x32_bf16(Bt[n][k], At[m][k], acc[ai][bj][m][n], 0, 0, 0); __builtin_amdgcn_s_setprio(0); } while (0)
; #define PG8_WAIT_V(n) asm volatile("s_waitcnt vmcnt(" #n ")" ::: "memory")
; #define PG8_WAIT_L(n) asm volatile("s_waitcnt lgkmcnt(" #n ")" ::: "memory")
; #define PG8_BAR __builtin_amdgcn_s_barrier()
; #define PG8_SCHED __builtin_amdgcn_sched_barrier(0)
; template <class Desc, class Epi>
; DI void gemm_phase(LAS unsigned char* lds, const Desc& D, const Epi& E, int wv) {
;     ...
;         for (int t = 0; t < nt; t += 2) {
;             const bool last = (t == nt - 2);
;             const char* a1 = cA + (size_t)(t + 1) * kstep;
;             const char* a2 = last ? nA : cA + (size_t)(t + 2) * kstep; const char* b2 = last ? nB : cB + (size_t)(t + 2) * kstep;
;             const char* a3 = a2 + kstep; const char* b3 = b2 + kstep;
;             PG8_LDB(B0, 0, 0); PG8_LDB(B1, 0, 1); PG8_SCHED; PG8_LDA(At, 0, 0); PG8_STAGE(PG8_SA(1, 1), a1 + hstepA, voffA);
;             PG8_WAIT_V(8); PG8_WAIT_L(0); PG8_BAR; PG8_MMA(0, 0, At, B0); PG8_MMA(0, 1, At, B1); PG8_BAR; PG8_SCHED;
;             PG8_LDA(At, 0, 1); PG8_STAGE(PG8_SB(0, 0), b2, voffB); PG8_STAGE(PG8_SB(0, 1), b2 + hstepB, voffB); PG8_STAGE(PG8_SA(0, 0), a2, voffA);
;             PG8_WAIT_V(8); PG8_WAIT_L(0); PG8_BAR; PG8_MMA(1, 0, At, B0); PG8_MMA(1, 1, At, B1); PG8_BAR; PG8_SCHED;
.LBB0_2213:
	ds_read_b128 v[152:155], v149
	ds_read_b128 v[156:159], v149 offset:1024
	ds_read_b128 v[160:163], v149 offset:2048
	ds_read_b128 v[164:167], v149 offset:3072
	ds_read_b128 v[168:171], v150
	ds_read_b128 v[172:175], v150 offset:1024
	ds_read_b128 v[176:179], v150 offset:2048
	ds_read_b128 v[180:183], v150 offset:3072
	s_add_u32 s48, s42, 0xfff80080
	s_addc_u32 s49, s43, -1
	s_cmp_eq_u32 s41, 28
	s_cselect_b32 s51, s19, s49
	s_cselect_b32 s50, s18, s48
	s_cselect_b32 s49, s21, s25
	s_cselect_b32 s48, s20, s23
	v_lshl_add_u64 v[146:147], s[42:43], 0, v[138:139]
	s_add_i32 m0, s30, 0xc000
	ds_read_b128 v[184:187], v151
	ds_read_b128 v[188:191], v151 offset:1024
	ds_read_b128 v[192:195], v151 offset:2048
	ds_read_b128 v[196:199], v151 offset:3072
	ds_read_b128 v[200:203], v151 offset:4096
	ds_read_b128 v[204:207], v151 offset:5120
	ds_read_b128 v[208:211], v151 offset:6144
	ds_read_b128 v[212:215], v151 offset:7168
	global_load_lds_dwordx4 v[146:147], off
	s_add_i32 m0, s30, 0xe000
	v_lshl_add_u64 v[146:147], s[42:43], 0, v[140:141]
	global_load_lds_dwordx4 v[146:147], off
	s_waitcnt vmcnt(8) lgkmcnt(0)
	s_barrier
	s_setprio 1
	v_mfma_f32_16x16x32_bf16 v[124:127], v[152:155], v[184:187], v[124:127]
	v_mfma_f32_16x16x32_bf16 v[120:123], v[160:163], v[184:187], v[120:123]
	v_mfma_f32_16x16x32_bf16 v[108:111], v[152:155], v[192:195], v[108:111]
	v_mfma_f32_16x16x32_bf16 v[104:107], v[160:163], v[192:195], v[104:107]
	v_mfma_f32_16x16x32_bf16 v[92:95], v[152:155], v[200:203], v[92:95]
	v_mfma_f32_16x16x32_bf16 v[88:91], v[160:163], v[200:203], v[88:91]
	v_mfma_f32_16x16x32_bf16 v[76:79], v[152:155], v[208:211], v[76:79]
	v_mfma_f32_16x16x32_bf16 v[72:75], v[160:163], v[208:211], v[72:75]
	v_mfma_f32_16x16x32_bf16 v[124:127], v[156:159], v[188:191], v[124:127]
	v_mfma_f32_16x16x32_bf16 v[120:123], v[164:167], v[188:191], v[120:123]
	v_mfma_f32_16x16x32_bf16 v[108:111], v[156:159], v[196:199], v[108:111]
	v_mfma_f32_16x16x32_bf16 v[104:107], v[164:167], v[196:199], v[104:107]
	v_mfma_f32_16x16x32_bf16 v[92:95], v[156:159], v[204:207], v[92:95]
	v_mfma_f32_16x16x32_bf16 v[88:91], v[164:167], v[204:207], v[88:91]
	v_mfma_f32_16x16x32_bf16 v[76:79], v[156:159], v[212:215], v[76:79]
	v_mfma_f32_16x16x32_bf16 v[72:75], v[164:167], v[212:215], v[72:75]
	v_mfma_f32_16x16x32_bf16 v[116:119], v[168:171], v[184:187], v[116:119]
	v_mfma_f32_16x16x32_bf16 v[112:115], v[176:179], v[184:187], v[112:115]
	v_mfma_f32_16x16x32_bf16 v[100:103], v[168:171], v[192:195], v[100:103]
	v_mfma_f32_16x16x32_bf16 v[96:99], v[176:179], v[192:195], v[96:99]
	v_mfma_f32_16x16x32_bf16 v[84:87], v[168:171], v[200:203], v[84:87]
	v_mfma_f32_16x16x32_bf16 v[80:83], v[176:179], v[200:203], v[80:83]
	v_mfma_f32_16x16x32_bf16 v[68:71], v[168:171], v[208:211], v[68:71]
	v_mfma_f32_16x16x32_bf16 v[64:67], v[176:179], v[208:211], v[64:67]
	v_mfma_f32_16x16x32_bf16 v[116:119], v[172:175], v[188:191], v[116:119]
	v_mfma_f32_16x16x32_bf16 v[112:115], v[180:183], v[188:191], v[112:115]
	v_mfma_f32_16x16x32_bf16 v[100:103], v[172:175], v[196:199], v[100:103]
	v_mfma_f32_16x16x32_bf16 v[96:99], v[180:183], v[196:199], v[96:99]
	v_mfma_f32_16x16x32_bf16 v[84:87], v[172:175], v[204:207], v[84:87]
	v_mfma_f32_16x16x32_bf16 v[80:83], v[180:183], v[204:207], v[80:83]
	v_mfma_f32_16x16x32_bf16 v[68:71], v[172:175], v[212:215], v[68:71]
	v_mfma_f32_16x16x32_bf16 v[64:67], v[180:183], v[212:215], v[64:67]
	s_setprio 0
	s_barrier
	s_add_i32 s67, s62, s28
	v_lshl_add_u64 v[146:147], s[48:49], 0, v[132:133]
	s_mov_b32 m0, s67
	ds_read_b128 v[184:187], v151 offset:16384
	ds_read_b128 v[188:191], v151 offset:17408
	ds_read_b128 v[192:195], v151 offset:18432
	ds_read_b128 v[196:199], v151 offset:19456
	ds_read_b128 v[200:203], v151 offset:20480
	ds_read_b128 v[204:207], v151 offset:21504
	ds_read_b128 v[208:211], v151 offset:22528
	ds_read_b128 v[212:215], v151 offset:23552
	global_load_lds_dwordx4 v[146:147], off
	s_add_i32 m0, s67, 0x2000
	s_add_u32 s68, s48, 0x80000
	v_lshl_add_u64 v[216:217], s[48:49], 0, v[128:129]
	s_addc_u32 s69, s49, 0
	s_add_i32 s67, s63, s28
	global_load_lds_dwordx4 v[216:217], off
	v_lshl_add_u64 v[218:219], s[68:69], 0, v[132:133]
	s_mov_b32 m0, s67
	v_lshl_add_u64 v[220:221], s[50:51], 0, v[130:131]
	global_load_lds_dwordx4 v[218:219], off
	s_add_i32 m0, s67, 0x2000
	v_lshl_add_u64 v[218:219], s[68:69], 0, v[128:129]
	global_load_lds_dwordx4 v[218:219], off
	s_mov_b32 m0, s30
	v_lshl_add_u64 v[218:219], s[50:51], 0, v[134:135]
	global_load_lds_dwordx4 v[218:219], off
	s_mov_b32 m0, s31
	s_nop 0
	global_load_lds_dwordx4 v[220:221], off
	s_waitcnt vmcnt(8) lgkmcnt(0)
	s_barrier
; #define PG8_STAGE(bufoff, gbase, voff) do { _Pragma("unroll") for (int _i = 0; _i < 2; ++_i) \
;         __builtin_amdgcn_global_load_lds((const unsigned*)((const char*)(gbase) + (voff)[_i]), (LAS unsigned*)(lds + (bufoff) + ldsw + _i * 8192), 16, 0, 0); } while (0)
; #define PG8_LDA(dst, b, h) do { _Pragma("unroll") for (int m = 0; m < 4; ++m) _Pragma("unroll") for (int k = 0; k < 2; ++k) dst[m][k] = *(const LAS bf16x8*)(lds + PG8_SA(b, h) + aoff + m * 2048 + k * 1024); } while (0)
; #define PG8_LDB(dst, b, h) do { _Pragma("unroll") for (int n = 0; n < 2; ++n) _Pragma("unroll") for (int k = 0; k < 2; ++k) dst[n][k] = *(const LAS bf16x8*)(lds + PG8_SB(b, h) + boff + n * 2048 + k * 1024); } while (0)
; #define PG8_MMA(ai, bj, At, Bt) do { __builtin_amdgcn_s_setprio(1); _Pragma("unroll") for (int m = 0; m < 4; ++m) _Pragma("unroll") for (int n = 0; n < 2; ++n) _Pragma("unroll") for (int k = 0; k < 2; ++k) \
;         acc[ai][bj][m][n] = __builtin_amdgcn_mfma_f32_16x16x32_bf16(Bt[n][k], At[m][k], acc[ai][bj][m][n], 0, 0, 0); __builtin_amdgcn_s_setprio(0); } while (0)
; #define PG8_WAIT_V(n) asm volatile("s_waitcnt vmcnt(" #n ")" ::: "memory")
; #define PG8_WAIT_L(n) asm volatile("s_waitcnt lgkmcnt(" #n ")" ::: "memory")
; #define PG8_BAR __builtin_amdgcn_s_barrier()
; #define PG8_SCHED __builtin_amdgcn_sched_barrier(0)
; template <class Desc, class Epi>
; DI void gemm_phase(LAS unsigned char* lds, const Desc& D, const Epi& E, int wv) {
;     ...
;             PG8_WAIT_V(8); PG8_WAIT_L(0); PG8_BAR; PG8_MMA(1, 0, At, B0); PG8_MMA(1, 1, At, B1); PG8_BAR; PG8_SCHED;
;             PG8_LDB(B0, 1, 0); PG8_LDB(B1, 1, 1); PG8_SCHED; PG8_LDA(At, 1, 0); PG8_STAGE(PG8_SA(0, 1), a2 + hstepA, voffA);
;             PG8_WAIT_V(8); PG8_WAIT_L(0); PG8_BAR; PG8_MMA(0, 0, At, B0); PG8_MMA(0, 1, At, B1); PG8_BAR; PG8_SCHED;
	s_setprio 1
	v_mfma_f32_16x16x32_bf16 v[60:63], v[152:155], v[184:187], v[60:63]
	v_mfma_f32_16x16x32_bf16 v[56:59], v[160:163], v[184:187], v[56:59]
	v_mfma_f32_16x16x32_bf16 v[44:47], v[152:155], v[192:195], v[44:47]
	v_mfma_f32_16x16x32_bf16 v[40:43], v[160:163], v[192:195], v[40:43]
	v_mfma_f32_16x16x32_bf16 v[28:31], v[152:155], v[200:203], v[28:31]
	v_mfma_f32_16x16x32_bf16 v[24:27], v[160:163], v[200:203], v[24:27]
	v_mfma_f32_16x16x32_bf16 v[12:15], v[152:155], v[208:211], v[12:15]
	v_mfma_f32_16x16x32_bf16 v[8:11], v[160:163], v[208:211], v[8:11]
	v_mfma_f32_16x16x32_bf16 v[60:63], v[156:159], v[188:191], v[60:63]
	v_mfma_f32_16x16x32_bf16 v[56:59], v[164:167], v[188:191], v[56:59]
	v_mfma_f32_16x16x32_bf16 v[44:47], v[156:159], v[196:199], v[44:47]
	v_mfma_f32_16x16x32_bf16 v[40:43], v[164:167], v[196:199], v[40:43]
	v_mfma_f32_16x16x32_bf16 v[28:31], v[156:159], v[204:207], v[28:31]
	v_mfma_f32_16x16x32_bf16 v[24:27], v[164:167], v[204:207], v[24:27]
	v_mfma_f32_16x16x32_bf16 v[12:15], v[156:159], v[212:215], v[12:15]
	v_mfma_f32_16x16x32_bf16 v[8:11], v[164:167], v[212:215], v[8:11]
	v_mfma_f32_16x16x32_bf16 v[52:55], v[168:171], v[184:187], v[52:55]
	v_mfma_f32_16x16x32_bf16 v[48:51], v[176:179], v[184:187], v[48:51]
	v_mfma_f32_16x16x32_bf16 v[36:39], v[168:171], v[192:195], v[36:39]
	v_mfma_f32_16x16x32_bf16 v[32:35], v[176:179], v[192:195], v[32:35]
	v_mfma_f32_16x16x32_bf16 v[20:23], v[168:171], v[200:203], v[20:23]
	v_mfma_f32_16x16x32_bf16 v[16:19], v[176:179], v[200:203], v[16:19]
	v_mfma_f32_16x16x32_bf16 v[4:7], v[168:171], v[208:211], v[4:7]
	v_mfma_f32_16x16x32_bf16 v[0:3], v[176:179], v[208:211], v[0:3]
	v_mfma_f32_16x16x32_bf16 v[52:55], v[172:175], v[188:191], v[52:55]
	v_mfma_f32_16x16x32_bf16 v[48:51], v[180:183], v[188:191], v[48:51]
	v_mfma_f32_16x16x32_bf16 v[36:39], v[172:175], v[196:199], v[36:39]
	v_mfma_f32_16x16x32_bf16 v[32:35], v[180:183], v[196:199], v[32:35]
	v_mfma_f32_16x16x32_bf16 v[20:23], v[172:175], v[204:207], v[20:23]
	v_mfma_f32_16x16x32_bf16 v[16:19], v[180:183], v[204:207], v[16:19]
	v_mfma_f32_16x16x32_bf16 v[4:7], v[172:175], v[212:215], v[4:7]
	v_mfma_f32_16x16x32_bf16 v[0:3], v[180:183], v[212:215], v[0:3]
	s_setprio 0
	s_barrier
	s_add_i32 s67, 0, 0x18000
	v_add_u32_e32 v136, s67, v148
	s_add_i32 s68, 0, 0x1c000
	ds_read_b128 v[152:155], v136
	ds_read_b128 v[156:159], v136 offset:1024
	ds_read_b128 v[160:163], v136 offset:2048
	ds_read_b128 v[164:167], v136 offset:3072
	v_add_u32_e32 v136, s68, v148
	ds_read_b128 v[168:171], v136
	ds_read_b128 v[172:175], v136 offset:1024
	ds_read_b128 v[176:179], v136 offset:2048
	ds_read_b128 v[180:183], v136 offset:3072
	s_add_u32 s50, s50, 0x80000
	s_addc_u32 s51, s51, 0
	s_mov_b32 m0, s34
	v_lshl_add_u64 v[222:223], s[50:51], 0, v[134:135]
	ds_read_b128 v[184:187], v151 offset:32768
	ds_read_b128 v[188:191], v151 offset:33792
	ds_read_b128 v[192:195], v151 offset:34816
	ds_read_b128 v[196:199], v151 offset:35840
	ds_read_b128 v[200:203], v151 offset:36864
	ds_read_b128 v[204:207], v151 offset:37888
	ds_read_b128 v[208:211], v151 offset:38912
	ds_read_b128 v[212:215], v151 offset:39936
	global_load_lds_dwordx4 v[222:223], off
	s_mov_b32 m0, s35
	v_lshl_add_u64 v[222:223], s[50:51], 0, v[130:131]
	global_load_lds_dwordx4 v[222:223], off
	s_waitcnt vmcnt(8) lgkmcnt(0)
	s_barrier
	s_setprio 1
	v_mfma_f32_16x16x32_bf16 v[124:127], v[152:155], v[184:187], v[124:127]
	v_mfma_f32_16x16x32_bf16 v[120:123], v[160:163], v[184:187], v[120:123]
	v_mfma_f32_16x16x32_bf16 v[108:111], v[152:155], v[192:195], v[108:111]
	v_mfma_f32_16x16x32_bf16 v[104:107], v[160:163], v[192:195], v[104:107]
	v_mfma_f32_16x16x32_bf16 v[92:95], v[152:155], v[200:203], v[92:95]
	v_mfma_f32_16x16x32_bf16 v[88:91], v[160:163], v[200:203], v[88:91]
	v_mfma_f32_16x16x32_bf16 v[76:79], v[152:155], v[208:211], v[76:79]
	v_mfma_f32_16x16x32_bf16 v[72:75], v[160:163], v[208:211], v[72:75]
	v_mfma_f32_16x16x32_bf16 v[124:127], v[156:159], v[188:191], v[124:127]
	v_mfma_f32_16x16x32_bf16 v[120:123], v[164:167], v[188:191], v[120:123]
	v_mfma_f32_16x16x32_bf16 v[108:111], v[156:159], v[196:199], v[108:111]
	v_mfma_f32_16x16x32_bf16 v[104:107], v[164:167], v[196:199], v[104:107]
	v_mfma_f32_16x16x32_bf16 v[92:95], v[156:159], v[204:207], v[92:95]
	v_mfma_f32_16x16x32_bf16 v[88:91], v[164:167], v[204:207], v[88:91]
	v_mfma_f32_16x16x32_bf16 v[76:79], v[156:159], v[212:215], v[76:79]
	v_mfma_f32_16x16x32_bf16 v[72:75], v[164:167], v[212:215], v[72:75]
	v_mfma_f32_16x16x32_bf16 v[116:119], v[168:171], v[184:187], v[116:119]
	v_mfma_f32_16x16x32_bf16 v[112:115], v[176:179], v[184:187], v[112:115]
	v_mfma_f32_16x16x32_bf16 v[100:103], v[168:171], v[192:195], v[100:103]
	v_mfma_f32_16x16x32_bf16 v[96:99], v[176:179], v[192:195], v[96:99]
	v_mfma_f32_16x16x32_bf16 v[84:87], v[168:171], v[200:203], v[84:87]
	v_mfma_f32_16x16x32_bf16 v[80:83], v[176:179], v[200:203], v[80:83]
	v_mfma_f32_16x16x32_bf16 v[68:71], v[168:171], v[208:211], v[68:71]
	v_mfma_f32_16x16x32_bf16 v[64:67], v[176:179], v[208:211], v[64:67]
	v_mfma_f32_16x16x32_bf16 v[116:119], v[172:175], v[188:191], v[116:119]
	v_mfma_f32_16x16x32_bf16 v[112:115], v[180:183], v[188:191], v[112:115]
	v_mfma_f32_16x16x32_bf16 v[100:103], v[172:175], v[196:199], v[100:103]
	v_mfma_f32_16x16x32_bf16 v[96:99], v[180:183], v[196:199], v[96:99]
	v_mfma_f32_16x16x32_bf16 v[84:87], v[172:175], v[204:207], v[84:87]
	v_mfma_f32_16x16x32_bf16 v[80:83], v[180:183], v[204:207], v[80:83]
	v_mfma_f32_16x16x32_bf16 v[68:71], v[172:175], v[212:215], v[68:71]
	v_mfma_f32_16x16x32_bf16 v[64:67], v[180:183], v[212:215], v[64:67]
	s_setprio 0
	s_barrier
; #define PG8_STAGE(bufoff, gbase, voff) do { _Pragma("unroll") for (int _i = 0; _i < 2; ++_i) \
;         __builtin_amdgcn_global_load_lds((const unsigned*)((const char*)(gbase) + (voff)[_i]), (LAS unsigned*)(lds + (bufoff) + ldsw + _i * 8192), 16, 0, 0); } while (0)
; #define PG8_LDA(dst, b, h) do { _Pragma("unroll") for (int m = 0; m < 4; ++m) _Pragma("unroll") for (int k = 0; k < 2; ++k) dst[m][k] = *(const LAS bf16x8*)(lds + PG8_SA(b, h) + aoff + m * 2048 + k * 1024); } while (0)
; #define PG8_MMA(ai, bj, At, Bt) do { __builtin_amdgcn_s_setprio(1); _Pragma("unroll") for (int m = 0; m < 4; ++m) _Pragma("unroll") for (int n = 0; n < 2; ++n) _Pragma("unroll") for (int k = 0; k < 2; ++k) \
;         acc[ai][bj][m][n] = __builtin_amdgcn_mfma_f32_16x16x32_bf16(Bt[n][k], At[m][k], acc[ai][bj][m][n], 0, 0, 0); __builtin_amdgcn_s_setprio(0); } while (0)
; #define PG8_WAIT_V(n) asm volatile("s_waitcnt vmcnt(" #n ")" ::: "memory")
; #define PG8_WAIT_L(n) asm volatile("s_waitcnt lgkmcnt(" #n ")" ::: "memory")
; #define PG8_BAR __builtin_amdgcn_s_barrier()
; #define PG8_SCHED __builtin_amdgcn_sched_barrier(0)
; template <class Desc, class Epi>
; DI void gemm_phase(LAS unsigned char* lds, const Desc& D, const Epi& E, int wv) {
;     ...
;             PG8_LDA(At, 1, 1); PG8_STAGE(PG8_SB(1, 0), b3, voffB); PG8_STAGE(PG8_SB(1, 1), b3 + hstepB, voffB); PG8_STAGE(PG8_SA(1, 0), a3, voffA);
;             PG8_WAIT_V(8); PG8_WAIT_L(0); PG8_BAR; PG8_MMA(1, 0, At, B0); PG8_MMA(1, 1, At, B1); PG8_BAR; PG8_SCHED;
;         }
;         if (wr == 0) PG8_BAR;
	s_add_i32 s50, s67, s28
	v_lshl_add_u64 v[146:147], v[146:147], 0, s[8:9]
	s_mov_b32 m0, s50
	ds_read_b128 v[184:187], v151 offset:49152
	ds_read_b128 v[188:191], v151 offset:50176
	ds_read_b128 v[192:195], v151 offset:51200
	ds_read_b128 v[196:199], v151 offset:52224
	ds_read_b128 v[200:203], v151 offset:53248
	ds_read_b128 v[204:207], v151 offset:54272
	ds_read_b128 v[208:211], v151 offset:55296
	ds_read_b128 v[212:215], v151 offset:56320
	global_load_lds_dwordx4 v[146:147], off
	s_add_i32 m0, s50, 0x2000
	s_add_u32 s48, s48, 0x80080
	v_lshl_add_u64 v[146:147], v[216:217], 0, s[8:9]
	s_addc_u32 s49, s49, 0
	s_add_i32 s50, s68, s28
	global_load_lds_dwordx4 v[146:147], off
	s_mov_b32 m0, s50
	v_lshl_add_u64 v[146:147], s[48:49], 0, v[132:133]
	global_load_lds_dwordx4 v[146:147], off
	s_add_i32 m0, s50, 0x2000
	v_lshl_add_u64 v[146:147], s[48:49], 0, v[128:129]
	global_load_lds_dwordx4 v[146:147], off
	s_mov_b32 m0, s53
	v_lshl_add_u64 v[146:147], v[218:219], 0, s[8:9]
	global_load_lds_dwordx4 v[146:147], off
	s_mov_b32 m0, s60
	v_lshl_add_u64 v[146:147], v[220:221], 0, s[8:9]
	global_load_lds_dwordx4 v[146:147], off
	s_waitcnt vmcnt(8) lgkmcnt(0)
	s_barrier
	s_setprio 1
	v_mfma_f32_16x16x32_bf16 v[60:63], v[152:155], v[184:187], v[60:63]
	v_mfma_f32_16x16x32_bf16 v[56:59], v[160:163], v[184:187], v[56:59]
	v_mfma_f32_16x16x32_bf16 v[44:47], v[152:155], v[192:195], v[44:47]
	v_mfma_f32_16x16x32_bf16 v[40:43], v[160:163], v[192:195], v[40:43]
	v_mfma_f32_16x16x32_bf16 v[28:31], v[152:155], v[200:203], v[28:31]
	v_mfma_f32_16x16x32_bf16 v[24:27], v[160:163], v[200:203], v[24:27]
	v_mfma_f32_16x16x32_bf16 v[12:15], v[152:155], v[208:211], v[12:15]
	v_mfma_f32_16x16x32_bf16 v[8:11], v[160:163], v[208:211], v[8:11]
	v_mfma_f32_16x16x32_bf16 v[60:63], v[156:159], v[188:191], v[60:63]
	v_mfma_f32_16x16x32_bf16 v[56:59], v[164:167], v[188:191], v[56:59]
	v_mfma_f32_16x16x32_bf16 v[44:47], v[156:159], v[196:199], v[44:47]
	v_mfma_f32_16x16x32_bf16 v[40:43], v[164:167], v[196:199], v[40:43]
	v_mfma_f32_16x16x32_bf16 v[28:31], v[156:159], v[204:207], v[28:31]
	v_mfma_f32_16x16x32_bf16 v[24:27], v[164:167], v[204:207], v[24:27]
	v_mfma_f32_16x16x32_bf16 v[12:15], v[156:159], v[212:215], v[12:15]
	v_mfma_f32_16x16x32_bf16 v[8:11], v[164:167], v[212:215], v[8:11]
	v_mfma_f32_16x16x32_bf16 v[52:55], v[168:171], v[184:187], v[52:55]
	v_mfma_f32_16x16x32_bf16 v[48:51], v[176:179], v[184:187], v[48:51]
	v_mfma_f32_16x16x32_bf16 v[36:39], v[168:171], v[192:195], v[36:39]
	v_mfma_f32_16x16x32_bf16 v[32:35], v[176:179], v[192:195], v[32:35]
	v_mfma_f32_16x16x32_bf16 v[20:23], v[168:171], v[200:203], v[20:23]
	v_mfma_f32_16x16x32_bf16 v[16:19], v[176:179], v[200:203], v[16:19]
	v_mfma_f32_16x16x32_bf16 v[4:7], v[168:171], v[208:211], v[4:7]
	v_mfma_f32_16x16x32_bf16 v[0:3], v[176:179], v[208:211], v[0:3]
	v_mfma_f32_16x16x32_bf16 v[52:55], v[172:175], v[188:191], v[52:55]
	v_mfma_f32_16x16x32_bf16 v[48:51], v[180:183], v[188:191], v[48:51]
	v_mfma_f32_16x16x32_bf16 v[36:39], v[172:175], v[196:199], v[36:39]
	v_mfma_f32_16x16x32_bf16 v[32:35], v[180:183], v[196:199], v[32:35]
	v_mfma_f32_16x16x32_bf16 v[20:23], v[172:175], v[204:207], v[20:23]
	v_mfma_f32_16x16x32_bf16 v[16:19], v[180:183], v[204:207], v[16:19]
	v_mfma_f32_16x16x32_bf16 v[4:7], v[172:175], v[212:215], v[4:7]
	v_mfma_f32_16x16x32_bf16 v[0:3], v[180:183], v[212:215], v[0:3]
	s_setprio 0
	s_barrier
	s_add_i32 s41, s41, 2
	s_add_u32 s42, s42, 0x100
	s_addc_u32 s43, s43, 0
	s_add_u32 s23, s23, 0x100
	s_addc_u32 s25, s25, 0
	s_cmp_gt_u32 s41, 29
	s_cbranch_scc0 .LBB0_2213
	s_and_b64 vcc, exec, s[12:13]
	s_cbranch_vccz .LBB0_2216
	s_barrier

; #define PG8_STAGE(bufoff, gbase, voff) do { _Pragma("unroll") for (int _i = 0; _i < 2; ++_i) \
;         __builtin_amdgcn_global_load_lds((const unsigned*)((const char*)(gbase) + (voff)[_i]), (LAS unsigned*)(lds + (bufoff) + ldsw + _i * 8192), 16, 0, 0); } while (0)
; #define PG8_LDA(dst, b, h) do { _Pragma("unroll") for (int m = 0; m < 4; ++m) _Pragma("unroll") for (int k = 0; k < 2; ++k) dst[m][k] = *(const LAS bf16x8*)(lds + PG8_SA(b, h) + aoff + m * 2048 + k * 1024); } while (0)
; #define PG8_LDB(dst, b, h) do { _Pragma("unroll") for (int n = 0; n < 2; ++n) _Pragma("unroll") for (int k = 0; k < 2; ++k) dst[n][k] = *(const LAS bf16x8*)(lds + PG8_SB(b, h) + boff + n * 2048 + k * 1024); } while (0)
; #define PG8_MMA(ai, bj, At, Bt) do { __builtin_amdgcn_s_setprio(1); _Pragma("unroll") for (int m = 0; m < 4; ++m) _Pragma("unroll") for (int n = 0; n < 2; ++n) _Pragma("unroll") for (int k = 0; k < 2; ++k) \
;         acc[ai][bj][m][n] = __builtin_amdgcn_mfma_f32_16x16x32_bf16(Bt[n][k], At[m][k], acc[ai][bj][m][n], 0, 0, 0); __builtin_amdgcn_s_setprio(0); } while (0)
; #define PG8_WAIT_V(n) asm volatile("s_waitcnt vmcnt(" #n ")" ::: "memory")
; #define PG8_WAIT_L(n) asm volatile("s_waitcnt lgkmcnt(" #n ")" ::: "memory")
; #define PG8_BAR __builtin_amdgcn_s_barrier()
; #define PG8_SCHED __builtin_amdgcn_sched_barrier(0)
; template <class Desc, class Epi>
; DI void gemm_phase(LAS unsigned char* lds, const Desc& D, const Epi& E, int wv) {
;     ...
;         for (int t = 0; t < nt; t += 2) {
;             const bool last = (t == nt - 2);
;             const char* a1 = cA + (size_t)(t + 1) * kstep;
;             const char* a2 = last ? nA : cA + (size_t)(t + 2) * kstep; const char* b2 = last ? nB : cB + (size_t)(t + 2) * kstep;
;             const char* a3 = a2 + kstep; const char* b3 = b2 + kstep;
;             PG8_LDB(B0, 0, 0); PG8_LDB(B1, 0, 1); PG8_SCHED; PG8_LDA(At, 0, 0); PG8_STAGE(PG8_SA(1, 1), a1 + hstepA, voffA);
;             PG8_WAIT_V(8); PG8_WAIT_L(0); PG8_BAR; PG8_MMA(0, 0, At, B0); PG8_MMA(0, 1, At, B1); PG8_BAR; PG8_SCHED;
;             PG8_LDA(At, 0, 1); PG8_STAGE(PG8_SB(0, 0), b2, voffB); PG8_STAGE(PG8_SB(0, 1), b2 + hstepB, voffB); PG8_STAGE(PG8_SA(0, 0), a2, voffA);
;             PG8_WAIT_V(8); PG8_WAIT_L(0); PG8_BAR; PG8_MMA(1, 0, At, B0); PG8_MMA(1, 1, At, B1); PG8_BAR; PG8_SCHED;
.LBB0_2239:
	ds_read_b128 v[142:145], v151
	ds_read_b128 v[146:149], v151 offset:1024
	ds_read_b128 v[158:161], v151 offset:2048
	ds_read_b128 v[162:165], v151 offset:3072
	ds_read_b128 v[166:169], v152
	ds_read_b128 v[170:173], v152 offset:1024
	ds_read_b128 v[174:177], v152 offset:2048
	ds_read_b128 v[178:181], v152 offset:3072
	s_add_u32 s8, s6, 0xfffe0080
	s_addc_u32 s9, s7, -1
	s_cmp_eq_u32 s50, 4
	s_cselect_b32 s43, s25, s9
	s_cselect_b32 s42, s24, s8
	s_cselect_b32 s9, s41, s49
	s_cselect_b32 s8, s40, s48
	v_lshl_add_u64 v[214:215], s[6:7], 0, v[138:139]
	s_add_i32 m0, s3, 0xc000
	ds_read_b128 v[182:185], v153
	ds_read_b128 v[186:189], v153 offset:1024
	ds_read_b128 v[190:193], v153 offset:2048
	ds_read_b128 v[194:197], v153 offset:3072
	ds_read_b128 v[198:201], v153 offset:4096
	ds_read_b128 v[202:205], v153 offset:5120
	ds_read_b128 v[206:209], v153 offset:6144
	ds_read_b128 v[210:213], v153 offset:7168
	global_load_lds_dwordx4 v[214:215], off
	s_add_i32 m0, s3, 0xe000
	v_lshl_add_u64 v[214:215], s[6:7], 0, v[140:141]
	global_load_lds_dwordx4 v[214:215], off
	s_waitcnt vmcnt(8) lgkmcnt(0)
	s_barrier
	s_setprio 1
	v_mfma_f32_16x16x32_bf16 v[124:127], v[142:145], v[182:185], v[124:127]
	v_mfma_f32_16x16x32_bf16 v[120:123], v[158:161], v[182:185], v[120:123]
	v_mfma_f32_16x16x32_bf16 v[108:111], v[142:145], v[190:193], v[108:111]
	v_mfma_f32_16x16x32_bf16 v[104:107], v[158:161], v[190:193], v[104:107]
	v_mfma_f32_16x16x32_bf16 v[92:95], v[142:145], v[198:201], v[92:95]
	v_mfma_f32_16x16x32_bf16 v[88:91], v[158:161], v[198:201], v[88:91]
	v_mfma_f32_16x16x32_bf16 v[76:79], v[142:145], v[206:209], v[76:79]
	v_mfma_f32_16x16x32_bf16 v[72:75], v[158:161], v[206:209], v[72:75]
	v_mfma_f32_16x16x32_bf16 v[124:127], v[146:149], v[186:189], v[124:127]
	v_mfma_f32_16x16x32_bf16 v[120:123], v[162:165], v[186:189], v[120:123]
	v_mfma_f32_16x16x32_bf16 v[108:111], v[146:149], v[194:197], v[108:111]
	v_mfma_f32_16x16x32_bf16 v[104:107], v[162:165], v[194:197], v[104:107]
	v_mfma_f32_16x16x32_bf16 v[92:95], v[146:149], v[202:205], v[92:95]
	v_mfma_f32_16x16x32_bf16 v[88:91], v[162:165], v[202:205], v[88:91]
	v_mfma_f32_16x16x32_bf16 v[76:79], v[146:149], v[210:213], v[76:79]
	v_mfma_f32_16x16x32_bf16 v[72:75], v[162:165], v[210:213], v[72:75]
	v_mfma_f32_16x16x32_bf16 v[116:119], v[166:169], v[182:185], v[116:119]
	v_mfma_f32_16x16x32_bf16 v[112:115], v[174:177], v[182:185], v[112:115]
	v_mfma_f32_16x16x32_bf16 v[100:103], v[166:169], v[190:193], v[100:103]
	v_mfma_f32_16x16x32_bf16 v[96:99], v[174:177], v[190:193], v[96:99]
	v_mfma_f32_16x16x32_bf16 v[84:87], v[166:169], v[198:201], v[84:87]
	v_mfma_f32_16x16x32_bf16 v[80:83], v[174:177], v[198:201], v[80:83]
	v_mfma_f32_16x16x32_bf16 v[68:71], v[166:169], v[206:209], v[68:71]
	v_mfma_f32_16x16x32_bf16 v[64:67], v[174:177], v[206:209], v[64:67]
	v_mfma_f32_16x16x32_bf16 v[116:119], v[170:173], v[186:189], v[116:119]
	v_mfma_f32_16x16x32_bf16 v[112:115], v[178:181], v[186:189], v[112:115]
	v_mfma_f32_16x16x32_bf16 v[100:103], v[170:173], v[194:197], v[100:103]
	v_mfma_f32_16x16x32_bf16 v[96:99], v[178:181], v[194:197], v[96:99]
	v_mfma_f32_16x16x32_bf16 v[84:87], v[170:173], v[202:205], v[84:87]
	v_mfma_f32_16x16x32_bf16 v[80:83], v[178:181], v[202:205], v[80:83]
	v_mfma_f32_16x16x32_bf16 v[68:71], v[170:173], v[210:213], v[68:71]
	v_mfma_f32_16x16x32_bf16 v[64:67], v[178:181], v[210:213], v[64:67]
	s_setprio 0
	s_barrier
	s_add_i32 s51, s47, s2
	v_lshl_add_u64 v[214:215], s[8:9], 0, v[130:131]
	s_mov_b32 m0, s51
	ds_read_b128 v[182:185], v153 offset:16384
	ds_read_b128 v[186:189], v153 offset:17408
	ds_read_b128 v[190:193], v153 offset:18432
	ds_read_b128 v[194:197], v153 offset:19456
	ds_read_b128 v[198:201], v153 offset:20480
	ds_read_b128 v[202:205], v153 offset:21504
	ds_read_b128 v[206:209], v153 offset:22528
	ds_read_b128 v[210:213], v153 offset:23552
	global_load_lds_dwordx4 v[214:215], off
	s_add_i32 m0, s51, 0x2000
	s_add_u32 s64, s8, 0x80000
	v_lshl_add_u64 v[216:217], s[8:9], 0, v[134:135]
	s_addc_u32 s65, s9, 0
	s_add_i32 s51, s52, s2
	global_load_lds_dwordx4 v[216:217], off
	v_lshl_add_u64 v[218:219], s[64:65], 0, v[130:131]
	s_mov_b32 m0, s51
	v_lshl_add_u64 v[220:221], s[42:43], 0, v[132:133]
	global_load_lds_dwordx4 v[218:219], off
	s_add_i32 m0, s51, 0x2000
	v_lshl_add_u64 v[218:219], s[64:65], 0, v[134:135]
	global_load_lds_dwordx4 v[218:219], off
	s_mov_b32 m0, s3
	v_lshl_add_u64 v[218:219], s[42:43], 0, v[128:129]
	global_load_lds_dwordx4 v[218:219], off
	s_mov_b32 m0, s28
	s_nop 0
	global_load_lds_dwordx4 v[220:221], off
	s_waitcnt vmcnt(8) lgkmcnt(0)
	s_barrier
; #define PG8_STAGE(bufoff, gbase, voff) do { _Pragma("unroll") for (int _i = 0; _i < 2; ++_i) \
;         __builtin_amdgcn_global_load_lds((const unsigned*)((const char*)(gbase) + (voff)[_i]), (LAS unsigned*)(lds + (bufoff) + ldsw + _i * 8192), 16, 0, 0); } while (0)
; #define PG8_LDA(dst, b, h) do { _Pragma("unroll") for (int m = 0; m < 4; ++m) _Pragma("unroll") for (int k = 0; k < 2; ++k) dst[m][k] = *(const LAS bf16x8*)(lds + PG8_SA(b, h) + aoff + m * 2048 + k * 1024); } while (0)
; #define PG8_LDB(dst, b, h) do { _Pragma("unroll") for (int n = 0; n < 2; ++n) _Pragma("unroll") for (int k = 0; k < 2; ++k) dst[n][k] = *(const LAS bf16x8*)(lds + PG8_SB(b, h) + boff + n * 2048 + k * 1024); } while (0)
; #define PG8_MMA(ai, bj, At, Bt) do { __builtin_amdgcn_s_setprio(1); _Pragma("unroll") for (int m = 0; m < 4; ++m) _Pragma("unroll") for (int n = 0; n < 2; ++n) _Pragma("unroll") for (int k = 0; k < 2; ++k) \
;         acc[ai][bj][m][n] = __builtin_amdgcn_mfma_f32_16x16x32_bf16(Bt[n][k], At[m][k], acc[ai][bj][m][n], 0, 0, 0); __builtin_amdgcn_s_setprio(0); } while (0)
; #define PG8_WAIT_V(n) asm volatile("s_waitcnt vmcnt(" #n ")" ::: "memory")
; #define PG8_WAIT_L(n) asm volatile("s_waitcnt lgkmcnt(" #n ")" ::: "memory")
; #define PG8_BAR __builtin_amdgcn_s_barrier()
; #define PG8_SCHED __builtin_amdgcn_sched_barrier(0)
; template <class Desc, class Epi>
; DI void gemm_phase(LAS unsigned char* lds, const Desc& D, const Epi& E, int wv) {
;     ...
;             PG8_WAIT_V(8); PG8_WAIT_L(0); PG8_BAR; PG8_MMA(1, 0, At, B0); PG8_MMA(1, 1, At, B1); PG8_BAR; PG8_SCHED;
;             PG8_LDB(B0, 1, 0); PG8_LDB(B1, 1, 1); PG8_SCHED; PG8_LDA(At, 1, 0); PG8_STAGE(PG8_SA(0, 1), a2 + hstepA, voffA);
;             PG8_WAIT_V(8); PG8_WAIT_L(0); PG8_BAR; PG8_MMA(0, 0, At, B0); PG8_MMA(0, 1, At, B1); PG8_BAR; PG8_SCHED;
	s_setprio 1
	v_mfma_f32_16x16x32_bf16 v[60:63], v[142:145], v[182:185], v[60:63]
	v_mfma_f32_16x16x32_bf16 v[56:59], v[158:161], v[182:185], v[56:59]
	v_mfma_f32_16x16x32_bf16 v[44:47], v[142:145], v[190:193], v[44:47]
	v_mfma_f32_16x16x32_bf16 v[40:43], v[158:161], v[190:193], v[40:43]
	v_mfma_f32_16x16x32_bf16 v[28:31], v[142:145], v[198:201], v[28:31]
	v_mfma_f32_16x16x32_bf16 v[24:27], v[158:161], v[198:201], v[24:27]
	v_mfma_f32_16x16x32_bf16 v[12:15], v[142:145], v[206:209], v[12:15]
	v_mfma_f32_16x16x32_bf16 v[8:11], v[158:161], v[206:209], v[8:11]
	v_mfma_f32_16x16x32_bf16 v[60:63], v[146:149], v[186:189], v[60:63]
	v_mfma_f32_16x16x32_bf16 v[56:59], v[162:165], v[186:189], v[56:59]
	v_mfma_f32_16x16x32_bf16 v[44:47], v[146:149], v[194:197], v[44:47]
	v_mfma_f32_16x16x32_bf16 v[40:43], v[162:165], v[194:197], v[40:43]
	v_mfma_f32_16x16x32_bf16 v[28:31], v[146:149], v[202:205], v[28:31]
	v_mfma_f32_16x16x32_bf16 v[24:27], v[162:165], v[202:205], v[24:27]
	v_mfma_f32_16x16x32_bf16 v[12:15], v[146:149], v[210:213], v[12:15]
	v_mfma_f32_16x16x32_bf16 v[8:11], v[162:165], v[210:213], v[8:11]
	v_mfma_f32_16x16x32_bf16 v[52:55], v[166:169], v[182:185], v[52:55]
	v_mfma_f32_16x16x32_bf16 v[48:51], v[174:177], v[182:185], v[48:51]
	v_mfma_f32_16x16x32_bf16 v[36:39], v[166:169], v[190:193], v[36:39]
	v_mfma_f32_16x16x32_bf16 v[32:35], v[174:177], v[190:193], v[32:35]
	v_mfma_f32_16x16x32_bf16 v[20:23], v[166:169], v[198:201], v[20:23]
	v_mfma_f32_16x16x32_bf16 v[16:19], v[174:177], v[198:201], v[16:19]
	v_mfma_f32_16x16x32_bf16 v[4:7], v[166:169], v[206:209], v[4:7]
	v_mfma_f32_16x16x32_bf16 v[0:3], v[174:177], v[206:209], v[0:3]
	v_mfma_f32_16x16x32_bf16 v[52:55], v[170:173], v[186:189], v[52:55]
	v_mfma_f32_16x16x32_bf16 v[48:51], v[178:181], v[186:189], v[48:51]
	v_mfma_f32_16x16x32_bf16 v[36:39], v[170:173], v[194:197], v[36:39]
	v_mfma_f32_16x16x32_bf16 v[32:35], v[178:181], v[194:197], v[32:35]
	v_mfma_f32_16x16x32_bf16 v[20:23], v[170:173], v[202:205], v[20:23]
	v_mfma_f32_16x16x32_bf16 v[16:19], v[178:181], v[202:205], v[16:19]
	v_mfma_f32_16x16x32_bf16 v[4:7], v[170:173], v[210:213], v[4:7]
	v_mfma_f32_16x16x32_bf16 v[0:3], v[178:181], v[210:213], v[0:3]
	s_setprio 0
	s_barrier
	s_add_i32 s51, 0, 0x18000
	v_add_u32_e32 v136, s51, v150
	s_add_i32 s64, 0, 0x1c000
	ds_read_b128 v[142:145], v136
	ds_read_b128 v[146:149], v136 offset:1024
	ds_read_b128 v[158:161], v136 offset:2048
	ds_read_b128 v[162:165], v136 offset:3072
	v_add_u32_e32 v136, s64, v150
	ds_read_b128 v[166:169], v136
	ds_read_b128 v[170:173], v136 offset:1024
	ds_read_b128 v[174:177], v136 offset:2048
	ds_read_b128 v[178:181], v136 offset:3072
	s_add_u32 s42, s42, 0x20000
	s_addc_u32 s43, s43, 0
	s_mov_b32 m0, s29
	v_lshl_add_u64 v[222:223], s[42:43], 0, v[128:129]
	ds_read_b128 v[182:185], v153 offset:32768
	ds_read_b128 v[186:189], v153 offset:33792
	ds_read_b128 v[190:193], v153 offset:34816
	ds_read_b128 v[194:197], v153 offset:35840
	ds_read_b128 v[198:201], v153 offset:36864
	ds_read_b128 v[202:205], v153 offset:37888
	ds_read_b128 v[206:209], v153 offset:38912
	ds_read_b128 v[210:213], v153 offset:39936
	global_load_lds_dwordx4 v[222:223], off
	s_mov_b32 m0, s30
	v_lshl_add_u64 v[222:223], s[42:43], 0, v[132:133]
	global_load_lds_dwordx4 v[222:223], off
	s_waitcnt vmcnt(8) lgkmcnt(0)
	s_barrier
	s_setprio 1
	v_mfma_f32_16x16x32_bf16 v[124:127], v[142:145], v[182:185], v[124:127]
	v_mfma_f32_16x16x32_bf16 v[120:123], v[158:161], v[182:185], v[120:123]
	v_mfma_f32_16x16x32_bf16 v[108:111], v[142:145], v[190:193], v[108:111]
	v_mfma_f32_16x16x32_bf16 v[104:107], v[158:161], v[190:193], v[104:107]
	v_mfma_f32_16x16x32_bf16 v[92:95], v[142:145], v[198:201], v[92:95]
	v_mfma_f32_16x16x32_bf16 v[88:91], v[158:161], v[198:201], v[88:91]
	v_mfma_f32_16x16x32_bf16 v[76:79], v[142:145], v[206:209], v[76:79]
	v_mfma_f32_16x16x32_bf16 v[72:75], v[158:161], v[206:209], v[72:75]
	v_mfma_f32_16x16x32_bf16 v[124:127], v[146:149], v[186:189], v[124:127]
	v_mfma_f32_16x16x32_bf16 v[120:123], v[162:165], v[186:189], v[120:123]
	v_mfma_f32_16x16x32_bf16 v[108:111], v[146:149], v[194:197], v[108:111]
	v_mfma_f32_16x16x32_bf16 v[104:107], v[162:165], v[194:197], v[104:107]
	v_mfma_f32_16x16x32_bf16 v[92:95], v[146:149], v[202:205], v[92:95]
	v_mfma_f32_16x16x32_bf16 v[88:91], v[162:165], v[202:205], v[88:91]
	v_mfma_f32_16x16x32_bf16 v[76:79], v[146:149], v[210:213], v[76:79]
	v_mfma_f32_16x16x32_bf16 v[72:75], v[162:165], v[210:213], v[72:75]
	v_mfma_f32_16x16x32_bf16 v[116:119], v[166:169], v[182:185], v[116:119]
	v_mfma_f32_16x16x32_bf16 v[112:115], v[174:177], v[182:185], v[112:115]
	v_mfma_f32_16x16x32_bf16 v[100:103], v[166:169], v[190:193], v[100:103]
	v_mfma_f32_16x16x32_bf16 v[96:99], v[174:177], v[190:193], v[96:99]
	v_mfma_f32_16x16x32_bf16 v[84:87], v[166:169], v[198:201], v[84:87]
	v_mfma_f32_16x16x32_bf16 v[80:83], v[174:177], v[198:201], v[80:83]
	v_mfma_f32_16x16x32_bf16 v[68:71], v[166:169], v[206:209], v[68:71]
	v_mfma_f32_16x16x32_bf16 v[64:67], v[174:177], v[206:209], v[64:67]
	v_mfma_f32_16x16x32_bf16 v[116:119], v[170:173], v[186:189], v[116:119]
	v_mfma_f32_16x16x32_bf16 v[112:115], v[178:181], v[186:189], v[112:115]
	v_mfma_f32_16x16x32_bf16 v[100:103], v[170:173], v[194:197], v[100:103]
	v_mfma_f32_16x16x32_bf16 v[96:99], v[178:181], v[194:197], v[96:99]
	v_mfma_f32_16x16x32_bf16 v[84:87], v[170:173], v[202:205], v[84:87]
	v_mfma_f32_16x16x32_bf16 v[80:83], v[178:181], v[202:205], v[80:83]
	v_mfma_f32_16x16x32_bf16 v[68:71], v[170:173], v[210:213], v[68:71]
	v_mfma_f32_16x16x32_bf16 v[64:67], v[178:181], v[210:213], v[64:67]
	s_setprio 0
	s_barrier
; #define PG8_STAGE(bufoff, gbase, voff) do { _Pragma("unroll") for (int _i = 0; _i < 2; ++_i) \
;         __builtin_amdgcn_global_load_lds((const unsigned*)((const char*)(gbase) + (voff)[_i]), (LAS unsigned*)(lds + (bufoff) + ldsw + _i * 8192), 16, 0, 0); } while (0)
; #define PG8_LDA(dst, b, h) do { _Pragma("unroll") for (int m = 0; m < 4; ++m) _Pragma("unroll") for (int k = 0; k < 2; ++k) dst[m][k] = *(const LAS bf16x8*)(lds + PG8_SA(b, h) + aoff + m * 2048 + k * 1024); } while (0)
; #define PG8_MMA(ai, bj, At, Bt) do { __builtin_amdgcn_s_setprio(1); _Pragma("unroll") for (int m = 0; m < 4; ++m) _Pragma("unroll") for (int n = 0; n < 2; ++n) _Pragma("unroll") for (int k = 0; k < 2; ++k) \
;         acc[ai][bj][m][n] = __builtin_amdgcn_mfma_f32_16x16x32_bf16(Bt[n][k], At[m][k], acc[ai][bj][m][n], 0, 0, 0); __builtin_amdgcn_s_setprio(0); } while (0)
; #define PG8_WAIT_V(n) asm volatile("s_waitcnt vmcnt(" #n ")" ::: "memory")
; #define PG8_WAIT_L(n) asm volatile("s_waitcnt lgkmcnt(" #n ")" ::: "memory")
; #define PG8_BAR __builtin_amdgcn_s_barrier()
; #define PG8_SCHED __builtin_amdgcn_sched_barrier(0)
; template <class Desc, class Epi>
; DI void gemm_phase(LAS unsigned char* lds, const Desc& D, const Epi& E, int wv) {
;     ...
;             PG8_LDA(At, 1, 1); PG8_STAGE(PG8_SB(1, 0), b3, voffB); PG8_STAGE(PG8_SB(1, 1), b3 + hstepB, voffB); PG8_STAGE(PG8_SA(1, 0), a3, voffA);
;             PG8_WAIT_V(8); PG8_WAIT_L(0); PG8_BAR; PG8_MMA(1, 0, At, B0); PG8_MMA(1, 1, At, B1); PG8_BAR; PG8_SCHED;
;         }
;         if (wr == 0) PG8_BAR;
	s_add_i32 s42, s51, s2
	v_lshl_add_u64 v[214:215], v[214:215], 0, s[14:15]
	s_mov_b32 m0, s42
	ds_read_b128 v[182:185], v153 offset:49152
	ds_read_b128 v[186:189], v153 offset:50176
	ds_read_b128 v[190:193], v153 offset:51200
	ds_read_b128 v[194:197], v153 offset:52224
	ds_read_b128 v[198:201], v153 offset:53248
	ds_read_b128 v[202:205], v153 offset:54272
	ds_read_b128 v[206:209], v153 offset:55296
	ds_read_b128 v[210:213], v153 offset:56320
	global_load_lds_dwordx4 v[214:215], off
	s_add_i32 m0, s42, 0x2000
	s_add_u32 s8, s8, 0x80080
	v_lshl_add_u64 v[214:215], v[216:217], 0, s[14:15]
	s_addc_u32 s9, s9, 0
	s_add_i32 s42, s64, s2
	global_load_lds_dwordx4 v[214:215], off
	s_mov_b32 m0, s42
	v_lshl_add_u64 v[214:215], s[8:9], 0, v[130:131]
	global_load_lds_dwordx4 v[214:215], off
	s_add_i32 m0, s42, 0x2000
	v_lshl_add_u64 v[214:215], s[8:9], 0, v[134:135]
	global_load_lds_dwordx4 v[214:215], off
	s_mov_b32 m0, s35
	v_lshl_add_u64 v[214:215], v[218:219], 0, s[14:15]
	global_load_lds_dwordx4 v[214:215], off
	s_mov_b32 m0, s46
	v_lshl_add_u64 v[214:215], v[220:221], 0, s[14:15]
	global_load_lds_dwordx4 v[214:215], off
	s_waitcnt vmcnt(8) lgkmcnt(0)
	s_barrier
	s_setprio 1
	v_mfma_f32_16x16x32_bf16 v[60:63], v[142:145], v[182:185], v[60:63]
	v_mfma_f32_16x16x32_bf16 v[56:59], v[158:161], v[182:185], v[56:59]
	v_mfma_f32_16x16x32_bf16 v[44:47], v[142:145], v[190:193], v[44:47]
	v_mfma_f32_16x16x32_bf16 v[40:43], v[158:161], v[190:193], v[40:43]
	v_mfma_f32_16x16x32_bf16 v[28:31], v[142:145], v[198:201], v[28:31]
	v_mfma_f32_16x16x32_bf16 v[24:27], v[158:161], v[198:201], v[24:27]
	v_mfma_f32_16x16x32_bf16 v[12:15], v[142:145], v[206:209], v[12:15]
	v_mfma_f32_16x16x32_bf16 v[8:11], v[158:161], v[206:209], v[8:11]
	v_mfma_f32_16x16x32_bf16 v[60:63], v[146:149], v[186:189], v[60:63]
	v_mfma_f32_16x16x32_bf16 v[56:59], v[162:165], v[186:189], v[56:59]
	v_mfma_f32_16x16x32_bf16 v[44:47], v[146:149], v[194:197], v[44:47]
	v_mfma_f32_16x16x32_bf16 v[40:43], v[162:165], v[194:197], v[40:43]
	v_mfma_f32_16x16x32_bf16 v[28:31], v[146:149], v[202:205], v[28:31]
	v_mfma_f32_16x16x32_bf16 v[24:27], v[162:165], v[202:205], v[24:27]
	v_mfma_f32_16x16x32_bf16 v[12:15], v[146:149], v[210:213], v[12:15]
	v_mfma_f32_16x16x32_bf16 v[8:11], v[162:165], v[210:213], v[8:11]
	v_mfma_f32_16x16x32_bf16 v[52:55], v[166:169], v[182:185], v[52:55]
	v_mfma_f32_16x16x32_bf16 v[48:51], v[174:177], v[182:185], v[48:51]
	v_mfma_f32_16x16x32_bf16 v[36:39], v[166:169], v[190:193], v[36:39]
	v_mfma_f32_16x16x32_bf16 v[32:35], v[174:177], v[190:193], v[32:35]
	v_mfma_f32_16x16x32_bf16 v[20:23], v[166:169], v[198:201], v[20:23]
	v_mfma_f32_16x16x32_bf16 v[16:19], v[174:177], v[198:201], v[16:19]
	v_mfma_f32_16x16x32_bf16 v[4:7], v[166:169], v[206:209], v[4:7]
	v_mfma_f32_16x16x32_bf16 v[0:3], v[174:177], v[206:209], v[0:3]
	v_mfma_f32_16x16x32_bf16 v[52:55], v[170:173], v[186:189], v[52:55]
	v_mfma_f32_16x16x32_bf16 v[48:51], v[178:181], v[186:189], v[48:51]
	v_mfma_f32_16x16x32_bf16 v[36:39], v[170:173], v[194:197], v[36:39]
	v_mfma_f32_16x16x32_bf16 v[32:35], v[178:181], v[194:197], v[32:35]
	v_mfma_f32_16x16x32_bf16 v[20:23], v[170:173], v[202:205], v[20:23]
	v_mfma_f32_16x16x32_bf16 v[16:19], v[178:181], v[202:205], v[16:19]
	v_mfma_f32_16x16x32_bf16 v[4:7], v[170:173], v[210:213], v[4:7]
	v_mfma_f32_16x16x32_bf16 v[0:3], v[178:181], v[210:213], v[0:3]
	s_setprio 0
	s_barrier
	s_add_i32 s50, s50, 2
	s_add_u32 s6, s6, 0x100
	s_addc_u32 s7, s7, 0
	s_add_u32 s48, s48, 0x100
	s_addc_u32 s49, s49, 0
	s_cmp_gt_u32 s50, 5
	s_cbranch_scc0 .LBB0_2239
	s_and_b64 vcc, exec, s[18:19]
	s_cbranch_vccz .LBB0_2242
	s_barrier

; #define PG8_STAGE(bufoff, gbase, voff) do { _Pragma("unroll") for (int _i = 0; _i < 2; ++_i) \
;         __builtin_amdgcn_global_load_lds((const unsigned*)((const char*)(gbase) + (voff)[_i]), (LAS unsigned*)(lds + (bufoff) + ldsw + _i * 8192), 16, 0, 0); } while (0)
; #define PG8_LDA(dst, b, h) do { _Pragma("unroll") for (int m = 0; m < 4; ++m) _Pragma("unroll") for (int k = 0; k < 2; ++k) dst[m][k] = *(const LAS bf16x8*)(lds + PG8_SA(b, h) + aoff + m * 2048 + k * 1024); } while (0)
; #define PG8_LDB(dst, b, h) do { _Pragma("unroll") for (int n = 0; n < 2; ++n) _Pragma("unroll") for (int k = 0; k < 2; ++k) dst[n][k] = *(const LAS bf16x8*)(lds + PG8_SB(b, h) + boff + n * 2048 + k * 1024); } while (0)
; #define PG8_MMA(ai, bj, At, Bt) do { __builtin_amdgcn_s_setprio(1); _Pragma("unroll") for (int m = 0; m < 4; ++m) _Pragma("unroll") for (int n = 0; n < 2; ++n) _Pragma("unroll") for (int k = 0; k < 2; ++k) \
;         acc[ai][bj][m][n] = __builtin_amdgcn_mfma_f32_16x16x32_bf16(Bt[n][k], At[m][k], acc[ai][bj][m][n], 0, 0, 0); __builtin_amdgcn_s_setprio(0); } while (0)
; #define PG8_WAIT_V(n) asm volatile("s_waitcnt vmcnt(" #n ")" ::: "memory")
; #define PG8_WAIT_L(n) asm volatile("s_waitcnt lgkmcnt(" #n ")" ::: "memory")
; #define PG8_BAR __builtin_amdgcn_s_barrier()
; #define PG8_SCHED __builtin_amdgcn_sched_barrier(0)
; template <class Desc, class Epi>
; DI void gemm_phase(LAS unsigned char* lds, const Desc& D, const Epi& E, int wv) {
;     ...
;         for (int t = 0; t < nt; t += 2) {
;             const bool last = (t == nt - 2);
;             const char* a1 = cA + (size_t)(t + 1) * kstep;
;             const char* a2 = last ? nA : cA + (size_t)(t + 2) * kstep; const char* b2 = last ? nB : cB + (size_t)(t + 2) * kstep;
;             const char* a3 = a2 + kstep; const char* b3 = b2 + kstep;
;             PG8_LDB(B0, 0, 0); PG8_LDB(B1, 0, 1); PG8_SCHED; PG8_LDA(At, 0, 0); PG8_STAGE(PG8_SA(1, 1), a1 + hstepA, voffA);
;             PG8_WAIT_V(8); PG8_WAIT_L(0); PG8_BAR; PG8_MMA(0, 0, At, B0); PG8_MMA(0, 1, At, B1); PG8_BAR; PG8_SCHED;
;             PG8_LDA(At, 0, 1); PG8_STAGE(PG8_SB(0, 0), b2, voffB); PG8_STAGE(PG8_SB(0, 1), b2 + hstepB, voffB); PG8_STAGE(PG8_SA(0, 0), a2, voffA);
;             PG8_WAIT_V(8); PG8_WAIT_L(0); PG8_BAR; PG8_MMA(1, 0, At, B0); PG8_MMA(1, 1, At, B1); PG8_BAR; PG8_SCHED;
.LBB0_2480:
	ds_read_b128 v[128:131], v185
	ds_read_b128 v[132:135], v185 offset:1024
	ds_read_b128 v[150:153], v185 offset:2048
	ds_read_b128 v[154:157], v185 offset:3072
	ds_read_b128 v[158:161], v186
	ds_read_b128 v[162:165], v186 offset:1024
	ds_read_b128 v[166:169], v186 offset:2048
	ds_read_b128 v[170:173], v186 offset:3072
	s_add_u32 s42, s40, 0xfff00080
	s_addc_u32 s43, s41, -1
	s_cmp_eq_u32 s48, 28
	s_cselect_b32 s47, s17, s43
	s_cselect_b32 s46, s16, s42
	s_cselect_b32 s43, s19, s23
	s_cselect_b32 s42, s18, s5
	v_lshl_add_u64 v[182:183], s[40:41], 0, v[146:147]
	s_add_i32 m0, s3, 0xc000
	ds_read_b128 v[174:177], v187
	ds_read_b128 v[178:181], v187 offset:1024
	ds_read_b128 v[190:193], v187 offset:2048
	ds_read_b128 v[194:197], v187 offset:3072
	ds_read_b128 v[198:201], v187 offset:4096
	ds_read_b128 v[202:205], v187 offset:5120
	ds_read_b128 v[206:209], v187 offset:6144
	ds_read_b128 v[210:213], v187 offset:7168
	global_load_lds_dwordx4 v[182:183], off
	s_add_i32 m0, s3, 0xe000
	v_lshl_add_u64 v[182:183], s[40:41], 0, v[148:149]
	global_load_lds_dwordx4 v[182:183], off
	s_waitcnt vmcnt(8) lgkmcnt(0)
	s_barrier
	s_setprio 1
	v_mfma_f32_16x16x32_bf16 v[124:127], v[128:131], v[174:177], v[124:127]
	v_mfma_f32_16x16x32_bf16 v[120:123], v[150:153], v[174:177], v[120:123]
	v_mfma_f32_16x16x32_bf16 v[108:111], v[128:131], v[190:193], v[108:111]
	v_mfma_f32_16x16x32_bf16 v[104:107], v[150:153], v[190:193], v[104:107]
	v_mfma_f32_16x16x32_bf16 v[92:95], v[128:131], v[198:201], v[92:95]
	v_mfma_f32_16x16x32_bf16 v[88:91], v[150:153], v[198:201], v[88:91]
	v_mfma_f32_16x16x32_bf16 v[76:79], v[128:131], v[206:209], v[76:79]
	v_mfma_f32_16x16x32_bf16 v[72:75], v[150:153], v[206:209], v[72:75]
	v_mfma_f32_16x16x32_bf16 v[124:127], v[132:135], v[178:181], v[124:127]
	v_mfma_f32_16x16x32_bf16 v[120:123], v[154:157], v[178:181], v[120:123]
	v_mfma_f32_16x16x32_bf16 v[108:111], v[132:135], v[194:197], v[108:111]
	v_mfma_f32_16x16x32_bf16 v[104:107], v[154:157], v[194:197], v[104:107]
	v_mfma_f32_16x16x32_bf16 v[92:95], v[132:135], v[202:205], v[92:95]
	v_mfma_f32_16x16x32_bf16 v[88:91], v[154:157], v[202:205], v[88:91]
	v_mfma_f32_16x16x32_bf16 v[76:79], v[132:135], v[210:213], v[76:79]
	v_mfma_f32_16x16x32_bf16 v[72:75], v[154:157], v[210:213], v[72:75]
	v_mfma_f32_16x16x32_bf16 v[116:119], v[158:161], v[174:177], v[116:119]
	v_mfma_f32_16x16x32_bf16 v[112:115], v[166:169], v[174:177], v[112:115]
	v_mfma_f32_16x16x32_bf16 v[100:103], v[158:161], v[190:193], v[100:103]
	v_mfma_f32_16x16x32_bf16 v[96:99], v[166:169], v[190:193], v[96:99]
	v_mfma_f32_16x16x32_bf16 v[84:87], v[158:161], v[198:201], v[84:87]
	v_mfma_f32_16x16x32_bf16 v[80:83], v[166:169], v[198:201], v[80:83]
	v_mfma_f32_16x16x32_bf16 v[68:71], v[158:161], v[206:209], v[68:71]
	v_mfma_f32_16x16x32_bf16 v[64:67], v[166:169], v[206:209], v[64:67]
	v_mfma_f32_16x16x32_bf16 v[116:119], v[162:165], v[178:181], v[116:119]
	v_mfma_f32_16x16x32_bf16 v[112:115], v[170:173], v[178:181], v[112:115]
	v_mfma_f32_16x16x32_bf16 v[100:103], v[162:165], v[194:197], v[100:103]
	v_mfma_f32_16x16x32_bf16 v[96:99], v[170:173], v[194:197], v[96:99]
	v_mfma_f32_16x16x32_bf16 v[84:87], v[162:165], v[202:205], v[84:87]
	v_mfma_f32_16x16x32_bf16 v[80:83], v[170:173], v[202:205], v[80:83]
	v_mfma_f32_16x16x32_bf16 v[68:71], v[162:165], v[210:213], v[68:71]
	v_mfma_f32_16x16x32_bf16 v[64:67], v[170:173], v[210:213], v[64:67]
	s_setprio 0
	s_barrier
	s_add_i32 s49, s52, s2
	v_lshl_add_u64 v[182:183], s[42:43], 0, v[140:141]
	s_mov_b32 m0, s49
	ds_read_b128 v[174:177], v187 offset:16384
	ds_read_b128 v[178:181], v187 offset:17408
	ds_read_b128 v[190:193], v187 offset:18432
	ds_read_b128 v[194:197], v187 offset:19456
	ds_read_b128 v[198:201], v187 offset:20480
	ds_read_b128 v[202:205], v187 offset:21504
	ds_read_b128 v[206:209], v187 offset:22528
	ds_read_b128 v[210:213], v187 offset:23552
	global_load_lds_dwordx4 v[182:183], off
	s_add_i32 m0, s49, 0x2000
	s_add_u32 s62, s42, 0x100000
	v_lshl_add_u64 v[214:215], s[42:43], 0, v[136:137]
	s_addc_u32 s63, s43, 0
	s_add_i32 s49, s53, s2
	global_load_lds_dwordx4 v[214:215], off
	v_lshl_add_u64 v[216:217], s[62:63], 0, v[140:141]
	s_mov_b32 m0, s49
	v_lshl_add_u64 v[218:219], s[46:47], 0, v[138:139]
	global_load_lds_dwordx4 v[216:217], off
	s_add_i32 m0, s49, 0x2000
	v_lshl_add_u64 v[216:217], s[62:63], 0, v[136:137]
	global_load_lds_dwordx4 v[216:217], off
	s_mov_b32 m0, s3
	v_lshl_add_u64 v[216:217], s[46:47], 0, v[142:143]
	global_load_lds_dwordx4 v[216:217], off
	s_mov_b32 m0, s28
	s_nop 0
	global_load_lds_dwordx4 v[218:219], off
	s_waitcnt vmcnt(8) lgkmcnt(0)
	s_barrier
; #define PG8_STAGE(bufoff, gbase, voff) do { _Pragma("unroll") for (int _i = 0; _i < 2; ++_i) \
;         __builtin_amdgcn_global_load_lds((const unsigned*)((const char*)(gbase) + (voff)[_i]), (LAS unsigned*)(lds + (bufoff) + ldsw + _i * 8192), 16, 0, 0); } while (0)
; #define PG8_LDA(dst, b, h) do { _Pragma("unroll") for (int m = 0; m < 4; ++m) _Pragma("unroll") for (int k = 0; k < 2; ++k) dst[m][k] = *(const LAS bf16x8*)(lds + PG8_SA(b, h) + aoff + m * 2048 + k * 1024); } while (0)
; #define PG8_LDB(dst, b, h) do { _Pragma("unroll") for (int n = 0; n < 2; ++n) _Pragma("unroll") for (int k = 0; k < 2; ++k) dst[n][k] = *(const LAS bf16x8*)(lds + PG8_SB(b, h) + boff + n * 2048 + k * 1024); } while (0)
; #define PG8_MMA(ai, bj, At, Bt) do { __builtin_amdgcn_s_setprio(1); _Pragma("unroll") for (int m = 0; m < 4; ++m) _Pragma("unroll") for (int n = 0; n < 2; ++n) _Pragma("unroll") for (int k = 0; k < 2; ++k) \
;         acc[ai][bj][m][n] = __builtin_amdgcn_mfma_f32_16x16x32_bf16(Bt[n][k], At[m][k], acc[ai][bj][m][n], 0, 0, 0); __builtin_amdgcn_s_setprio(0); } while (0)
; #define PG8_WAIT_V(n) asm volatile("s_waitcnt vmcnt(" #n ")" ::: "memory")
; #define PG8_WAIT_L(n) asm volatile("s_waitcnt lgkmcnt(" #n ")" ::: "memory")
; #define PG8_BAR __builtin_amdgcn_s_barrier()
; #define PG8_SCHED __builtin_amdgcn_sched_barrier(0)
; template <class Desc, class Epi>
; DI void gemm_phase(LAS unsigned char* lds, const Desc& D, const Epi& E, int wv) {
;     ...
;             PG8_WAIT_V(8); PG8_WAIT_L(0); PG8_BAR; PG8_MMA(1, 0, At, B0); PG8_MMA(1, 1, At, B1); PG8_BAR; PG8_SCHED;
;             PG8_LDB(B0, 1, 0); PG8_LDB(B1, 1, 1); PG8_SCHED; PG8_LDA(At, 1, 0); PG8_STAGE(PG8_SA(0, 1), a2 + hstepA, voffA);
;             PG8_WAIT_V(8); PG8_WAIT_L(0); PG8_BAR; PG8_MMA(0, 0, At, B0); PG8_MMA(0, 1, At, B1); PG8_BAR; PG8_SCHED;
	s_setprio 1
	v_mfma_f32_16x16x32_bf16 v[60:63], v[128:131], v[174:177], v[60:63]
	v_mfma_f32_16x16x32_bf16 v[56:59], v[150:153], v[174:177], v[56:59]
	v_mfma_f32_16x16x32_bf16 v[44:47], v[128:131], v[190:193], v[44:47]
	v_mfma_f32_16x16x32_bf16 v[40:43], v[150:153], v[190:193], v[40:43]
	v_mfma_f32_16x16x32_bf16 v[28:31], v[128:131], v[198:201], v[28:31]
	v_mfma_f32_16x16x32_bf16 v[24:27], v[150:153], v[198:201], v[24:27]
	v_mfma_f32_16x16x32_bf16 v[12:15], v[128:131], v[206:209], v[12:15]
	v_mfma_f32_16x16x32_bf16 v[8:11], v[150:153], v[206:209], v[8:11]
	v_mfma_f32_16x16x32_bf16 v[60:63], v[132:135], v[178:181], v[60:63]
	v_mfma_f32_16x16x32_bf16 v[56:59], v[154:157], v[178:181], v[56:59]
	v_mfma_f32_16x16x32_bf16 v[44:47], v[132:135], v[194:197], v[44:47]
	v_mfma_f32_16x16x32_bf16 v[40:43], v[154:157], v[194:197], v[40:43]
	v_mfma_f32_16x16x32_bf16 v[28:31], v[132:135], v[202:205], v[28:31]
	v_mfma_f32_16x16x32_bf16 v[24:27], v[154:157], v[202:205], v[24:27]
	v_mfma_f32_16x16x32_bf16 v[12:15], v[132:135], v[210:213], v[12:15]
	v_mfma_f32_16x16x32_bf16 v[8:11], v[154:157], v[210:213], v[8:11]
	v_mfma_f32_16x16x32_bf16 v[52:55], v[158:161], v[174:177], v[52:55]
	v_mfma_f32_16x16x32_bf16 v[48:51], v[166:169], v[174:177], v[48:51]
	v_mfma_f32_16x16x32_bf16 v[36:39], v[158:161], v[190:193], v[36:39]
	v_mfma_f32_16x16x32_bf16 v[32:35], v[166:169], v[190:193], v[32:35]
	v_mfma_f32_16x16x32_bf16 v[20:23], v[158:161], v[198:201], v[20:23]
	v_mfma_f32_16x16x32_bf16 v[16:19], v[166:169], v[198:201], v[16:19]
	v_mfma_f32_16x16x32_bf16 v[4:7], v[158:161], v[206:209], v[4:7]
	v_mfma_f32_16x16x32_bf16 v[0:3], v[166:169], v[206:209], v[0:3]
	v_mfma_f32_16x16x32_bf16 v[52:55], v[162:165], v[178:181], v[52:55]
	v_mfma_f32_16x16x32_bf16 v[48:51], v[170:173], v[178:181], v[48:51]
	v_mfma_f32_16x16x32_bf16 v[36:39], v[162:165], v[194:197], v[36:39]
	v_mfma_f32_16x16x32_bf16 v[32:35], v[170:173], v[194:197], v[32:35]
	v_mfma_f32_16x16x32_bf16 v[20:23], v[162:165], v[202:205], v[20:23]
	v_mfma_f32_16x16x32_bf16 v[16:19], v[170:173], v[202:205], v[16:19]
	v_mfma_f32_16x16x32_bf16 v[4:7], v[162:165], v[210:213], v[4:7]
	v_mfma_f32_16x16x32_bf16 v[0:3], v[170:173], v[210:213], v[0:3]
	s_setprio 0
	s_barrier
	s_add_i32 s49, 0, 0x18000
	v_add_u32_e32 v144, s49, v184
	s_add_i32 s61, 0, 0x1c000
	ds_read_b128 v[128:131], v144
	ds_read_b128 v[132:135], v144 offset:1024
	ds_read_b128 v[150:153], v144 offset:2048
	ds_read_b128 v[154:157], v144 offset:3072
	v_add_u32_e32 v144, s61, v184
	ds_read_b128 v[158:161], v144
	ds_read_b128 v[162:165], v144 offset:1024
	ds_read_b128 v[166:169], v144 offset:2048
	ds_read_b128 v[170:173], v144 offset:3072
	s_add_u32 s46, s46, 0x100000
	s_addc_u32 s47, s47, 0
	s_mov_b32 m0, s29
	v_lshl_add_u64 v[220:221], s[46:47], 0, v[142:143]
	ds_read_b128 v[174:177], v187 offset:32768
	ds_read_b128 v[178:181], v187 offset:33792
	ds_read_b128 v[190:193], v187 offset:34816
	ds_read_b128 v[194:197], v187 offset:35840
	ds_read_b128 v[198:201], v187 offset:36864
	ds_read_b128 v[202:205], v187 offset:37888
	ds_read_b128 v[206:209], v187 offset:38912
	ds_read_b128 v[210:213], v187 offset:39936
	global_load_lds_dwordx4 v[220:221], off
	s_mov_b32 m0, s30
	v_lshl_add_u64 v[220:221], s[46:47], 0, v[138:139]
	global_load_lds_dwordx4 v[220:221], off
	s_waitcnt vmcnt(8) lgkmcnt(0)
	s_barrier
	s_setprio 1
	v_mfma_f32_16x16x32_bf16 v[124:127], v[128:131], v[174:177], v[124:127]
	v_mfma_f32_16x16x32_bf16 v[120:123], v[150:153], v[174:177], v[120:123]
	v_mfma_f32_16x16x32_bf16 v[108:111], v[128:131], v[190:193], v[108:111]
	v_mfma_f32_16x16x32_bf16 v[104:107], v[150:153], v[190:193], v[104:107]
	v_mfma_f32_16x16x32_bf16 v[92:95], v[128:131], v[198:201], v[92:95]
	v_mfma_f32_16x16x32_bf16 v[88:91], v[150:153], v[198:201], v[88:91]
	v_mfma_f32_16x16x32_bf16 v[76:79], v[128:131], v[206:209], v[76:79]
	v_mfma_f32_16x16x32_bf16 v[72:75], v[150:153], v[206:209], v[72:75]
	v_mfma_f32_16x16x32_bf16 v[124:127], v[132:135], v[178:181], v[124:127]
	v_mfma_f32_16x16x32_bf16 v[120:123], v[154:157], v[178:181], v[120:123]
	v_mfma_f32_16x16x32_bf16 v[108:111], v[132:135], v[194:197], v[108:111]
	v_mfma_f32_16x16x32_bf16 v[104:107], v[154:157], v[194:197], v[104:107]
	v_mfma_f32_16x16x32_bf16 v[92:95], v[132:135], v[202:205], v[92:95]
	v_mfma_f32_16x16x32_bf16 v[88:91], v[154:157], v[202:205], v[88:91]
	v_mfma_f32_16x16x32_bf16 v[76:79], v[132:135], v[210:213], v[76:79]
	v_mfma_f32_16x16x32_bf16 v[72:75], v[154:157], v[210:213], v[72:75]
	v_mfma_f32_16x16x32_bf16 v[116:119], v[158:161], v[174:177], v[116:119]
	v_mfma_f32_16x16x32_bf16 v[112:115], v[166:169], v[174:177], v[112:115]
	v_mfma_f32_16x16x32_bf16 v[100:103], v[158:161], v[190:193], v[100:103]
	v_mfma_f32_16x16x32_bf16 v[96:99], v[166:169], v[190:193], v[96:99]
	v_mfma_f32_16x16x32_bf16 v[84:87], v[158:161], v[198:201], v[84:87]
	v_mfma_f32_16x16x32_bf16 v[80:83], v[166:169], v[198:201], v[80:83]
	v_mfma_f32_16x16x32_bf16 v[68:71], v[158:161], v[206:209], v[68:71]
	v_mfma_f32_16x16x32_bf16 v[64:67], v[166:169], v[206:209], v[64:67]
	v_mfma_f32_16x16x32_bf16 v[116:119], v[162:165], v[178:181], v[116:119]
	v_mfma_f32_16x16x32_bf16 v[112:115], v[170:173], v[178:181], v[112:115]
	v_mfma_f32_16x16x32_bf16 v[100:103], v[162:165], v[194:197], v[100:103]
	v_mfma_f32_16x16x32_bf16 v[96:99], v[170:173], v[194:197], v[96:99]
	v_mfma_f32_16x16x32_bf16 v[84:87], v[162:165], v[202:205], v[84:87]
	v_mfma_f32_16x16x32_bf16 v[80:83], v[170:173], v[202:205], v[80:83]
	v_mfma_f32_16x16x32_bf16 v[68:71], v[162:165], v[210:213], v[68:71]
	v_mfma_f32_16x16x32_bf16 v[64:67], v[170:173], v[210:213], v[64:67]
	s_setprio 0
	s_barrier
; #define PG8_STAGE(bufoff, gbase, voff) do { _Pragma("unroll") for (int _i = 0; _i < 2; ++_i) \
;         __builtin_amdgcn_global_load_lds((const unsigned*)((const char*)(gbase) + (voff)[_i]), (LAS unsigned*)(lds + (bufoff) + ldsw + _i * 8192), 16, 0, 0); } while (0)
; #define PG8_LDA(dst, b, h) do { _Pragma("unroll") for (int m = 0; m < 4; ++m) _Pragma("unroll") for (int k = 0; k < 2; ++k) dst[m][k] = *(const LAS bf16x8*)(lds + PG8_SA(b, h) + aoff + m * 2048 + k * 1024); } while (0)
; #define PG8_MMA(ai, bj, At, Bt) do { __builtin_amdgcn_s_setprio(1); _Pragma("unroll") for (int m = 0; m < 4; ++m) _Pragma("unroll") for (int n = 0; n < 2; ++n) _Pragma("unroll") for (int k = 0; k < 2; ++k) \
;         acc[ai][bj][m][n] = __builtin_amdgcn_mfma_f32_16x16x32_bf16(Bt[n][k], At[m][k], acc[ai][bj][m][n], 0, 0, 0); __builtin_amdgcn_s_setprio(0); } while (0)
; #define PG8_WAIT_V(n) asm volatile("s_waitcnt vmcnt(" #n ")" ::: "memory")
; #define PG8_WAIT_L(n) asm volatile("s_waitcnt lgkmcnt(" #n ")" ::: "memory")
; #define PG8_BAR __builtin_amdgcn_s_barrier()
; #define PG8_SCHED __builtin_amdgcn_sched_barrier(0)
; template <class Desc, class Epi>
; DI void gemm_phase(LAS unsigned char* lds, const Desc& D, const Epi& E, int wv) {
;     ...
;             PG8_LDA(At, 1, 1); PG8_STAGE(PG8_SB(1, 0), b3, voffB); PG8_STAGE(PG8_SB(1, 1), b3 + hstepB, voffB); PG8_STAGE(PG8_SA(1, 0), a3, voffA);
;             PG8_WAIT_V(8); PG8_WAIT_L(0); PG8_BAR; PG8_MMA(1, 0, At, B0); PG8_MMA(1, 1, At, B1); PG8_BAR; PG8_SCHED;
;         }
;         if (wr == 0) PG8_BAR;
	s_add_i32 s46, s49, s2
	v_lshl_add_u64 v[182:183], v[182:183], 0, s[12:13]
	s_mov_b32 m0, s46
	ds_read_b128 v[174:177], v187 offset:49152
	ds_read_b128 v[178:181], v187 offset:50176
	ds_read_b128 v[190:193], v187 offset:51200
	ds_read_b128 v[194:197], v187 offset:52224
	ds_read_b128 v[198:201], v187 offset:53248
	ds_read_b128 v[202:205], v187 offset:54272
	ds_read_b128 v[206:209], v187 offset:55296
	ds_read_b128 v[210:213], v187 offset:56320
	global_load_lds_dwordx4 v[182:183], off
	s_add_i32 m0, s46, 0x2000
	s_add_u32 s42, s42, 0x100080
	v_lshl_add_u64 v[182:183], v[214:215], 0, s[12:13]
	s_addc_u32 s43, s43, 0
	s_add_i32 s46, s61, s2
	global_load_lds_dwordx4 v[182:183], off
	s_mov_b32 m0, s46
	v_lshl_add_u64 v[182:183], s[42:43], 0, v[140:141]
	global_load_lds_dwordx4 v[182:183], off
	s_add_i32 m0, s46, 0x2000
	v_lshl_add_u64 v[182:183], s[42:43], 0, v[136:137]
	global_load_lds_dwordx4 v[182:183], off
	s_mov_b32 m0, s50
	v_lshl_add_u64 v[182:183], v[216:217], 0, s[12:13]
	global_load_lds_dwordx4 v[182:183], off
	s_mov_b32 m0, s51
	v_lshl_add_u64 v[182:183], v[218:219], 0, s[12:13]
	global_load_lds_dwordx4 v[182:183], off
	s_waitcnt vmcnt(8) lgkmcnt(0)
	s_barrier
	s_setprio 1
	v_mfma_f32_16x16x32_bf16 v[60:63], v[128:131], v[174:177], v[60:63]
	v_mfma_f32_16x16x32_bf16 v[56:59], v[150:153], v[174:177], v[56:59]
	v_mfma_f32_16x16x32_bf16 v[44:47], v[128:131], v[190:193], v[44:47]
	v_mfma_f32_16x16x32_bf16 v[40:43], v[150:153], v[190:193], v[40:43]
	v_mfma_f32_16x16x32_bf16 v[28:31], v[128:131], v[198:201], v[28:31]
	v_mfma_f32_16x16x32_bf16 v[24:27], v[150:153], v[198:201], v[24:27]
	v_mfma_f32_16x16x32_bf16 v[12:15], v[128:131], v[206:209], v[12:15]
	v_mfma_f32_16x16x32_bf16 v[8:11], v[150:153], v[206:209], v[8:11]
	v_mfma_f32_16x16x32_bf16 v[60:63], v[132:135], v[178:181], v[60:63]
	v_mfma_f32_16x16x32_bf16 v[56:59], v[154:157], v[178:181], v[56:59]
	v_mfma_f32_16x16x32_bf16 v[44:47], v[132:135], v[194:197], v[44:47]
	v_mfma_f32_16x16x32_bf16 v[40:43], v[154:157], v[194:197], v[40:43]
	v_mfma_f32_16x16x32_bf16 v[28:31], v[132:135], v[202:205], v[28:31]
	v_mfma_f32_16x16x32_bf16 v[24:27], v[154:157], v[202:205], v[24:27]
	v_mfma_f32_16x16x32_bf16 v[12:15], v[132:135], v[210:213], v[12:15]
	v_mfma_f32_16x16x32_bf16 v[8:11], v[154:157], v[210:213], v[8:11]
	v_mfma_f32_16x16x32_bf16 v[52:55], v[158:161], v[174:177], v[52:55]
	v_mfma_f32_16x16x32_bf16 v[48:51], v[166:169], v[174:177], v[48:51]
	v_mfma_f32_16x16x32_bf16 v[36:39], v[158:161], v[190:193], v[36:39]
	v_mfma_f32_16x16x32_bf16 v[32:35], v[166:169], v[190:193], v[32:35]
	v_mfma_f32_16x16x32_bf16 v[20:23], v[158:161], v[198:201], v[20:23]
	v_mfma_f32_16x16x32_bf16 v[16:19], v[166:169], v[198:201], v[16:19]
	v_mfma_f32_16x16x32_bf16 v[4:7], v[158:161], v[206:209], v[4:7]
	v_mfma_f32_16x16x32_bf16 v[0:3], v[166:169], v[206:209], v[0:3]
	v_mfma_f32_16x16x32_bf16 v[52:55], v[162:165], v[178:181], v[52:55]
	v_mfma_f32_16x16x32_bf16 v[48:51], v[170:173], v[178:181], v[48:51]
	v_mfma_f32_16x16x32_bf16 v[36:39], v[162:165], v[194:197], v[36:39]
	v_mfma_f32_16x16x32_bf16 v[32:35], v[170:173], v[194:197], v[32:35]
	v_mfma_f32_16x16x32_bf16 v[20:23], v[162:165], v[202:205], v[20:23]
	v_mfma_f32_16x16x32_bf16 v[16:19], v[170:173], v[202:205], v[16:19]
	v_mfma_f32_16x16x32_bf16 v[4:7], v[162:165], v[210:213], v[4:7]
	v_mfma_f32_16x16x32_bf16 v[0:3], v[170:173], v[210:213], v[0:3]
	s_setprio 0
	s_barrier
	s_add_i32 s48, s48, 2
	s_add_u32 s40, s40, 0x100
	s_addc_u32 s41, s41, 0
	s_add_u32 s5, s5, 0x100
	s_addc_u32 s23, s23, 0
	s_cmp_gt_u32 s48, 29
	s_cbranch_scc0 .LBB0_2480
	s_and_b64 vcc, exec, s[14:15]
	s_cbranch_vccz .LBB0_2483
	s_barrier

; #define PG8_STAGE(bufoff, gbase, voff) do { _Pragma("unroll") for (int _i = 0; _i < 2; ++_i) \
;         __builtin_amdgcn_global_load_lds((const unsigned*)((const char*)(gbase) + (voff)[_i]), (LAS unsigned*)(lds + (bufoff) + ldsw + _i * 8192), 16, 0, 0); } while (0)
; #define PG8_LDA(dst, b, h) do { _Pragma("unroll") for (int m = 0; m < 4; ++m) _Pragma("unroll") for (int k = 0; k < 2; ++k) dst[m][k] = *(const LAS bf16x8*)(lds + PG8_SA(b, h) + aoff + m * 2048 + k * 1024); } while (0)
; #define PG8_LDB(dst, b, h) do { _Pragma("unroll") for (int n = 0; n < 2; ++n) _Pragma("unroll") for (int k = 0; k < 2; ++k) dst[n][k] = *(const LAS bf16x8*)(lds + PG8_SB(b, h) + boff + n * 2048 + k * 1024); } while (0)
; #define PG8_MMA(ai, bj, At, Bt) do { __builtin_amdgcn_s_setprio(1); _Pragma("unroll") for (int m = 0; m < 4; ++m) _Pragma("unroll") for (int n = 0; n < 2; ++n) _Pragma("unroll") for (int k = 0; k < 2; ++k) \
;         acc[ai][bj][m][n] = __builtin_amdgcn_mfma_f32_16x16x32_bf16(Bt[n][k], At[m][k], acc[ai][bj][m][n], 0, 0, 0); __builtin_amdgcn_s_setprio(0); } while (0)
; #define PG8_WAIT_V(n) asm volatile("s_waitcnt vmcnt(" #n ")" ::: "memory")
; #define PG8_WAIT_L(n) asm volatile("s_waitcnt lgkmcnt(" #n ")" ::: "memory")
; #define PG8_BAR __builtin_amdgcn_s_barrier()
; #define PG8_SCHED __builtin_amdgcn_sched_barrier(0)
; template <class Desc, class Epi>
; DI void gemm_phase(LAS unsigned char* lds, const Desc& D, const Epi& E, int wv) {
;     ...
;         for (int t = 0; t < nt; t += 2) {
;             const bool last = (t == nt - 2);
;             const char* a1 = cA + (size_t)(t + 1) * kstep;
;             const char* a2 = last ? nA : cA + (size_t)(t + 2) * kstep; const char* b2 = last ? nB : cB + (size_t)(t + 2) * kstep;
;             const char* a3 = a2 + kstep; const char* b3 = b2 + kstep;
;             PG8_LDB(B0, 0, 0); PG8_LDB(B1, 0, 1); PG8_SCHED; PG8_LDA(At, 0, 0); PG8_STAGE(PG8_SA(1, 1), a1 + hstepA, voffA);
;             PG8_WAIT_V(8); PG8_WAIT_L(0); PG8_BAR; PG8_MMA(0, 0, At, B0); PG8_MMA(0, 1, At, B1); PG8_BAR; PG8_SCHED;
;             PG8_LDA(At, 0, 1); PG8_STAGE(PG8_SB(0, 0), b2, voffB); PG8_STAGE(PG8_SB(0, 1), b2 + hstepB, voffB); PG8_STAGE(PG8_SA(0, 0), a2, voffA);
;             PG8_WAIT_V(8); PG8_WAIT_L(0); PG8_BAR; PG8_MMA(1, 0, At, B0); PG8_MMA(1, 1, At, B1); PG8_BAR; PG8_SCHED;
.LBB0_2706:
	ds_read_b128 v[128:131], v205
	ds_read_b128 v[132:135], v205 offset:1024
	ds_read_b128 v[136:139], v205 offset:2048
	ds_read_b128 v[140:143], v205 offset:3072
	ds_read_b128 v[144:147], v206
	ds_read_b128 v[148:151], v206 offset:1024
	ds_read_b128 v[152:155], v206 offset:2048
	ds_read_b128 v[156:159], v206 offset:3072
	s_add_u32 s34, s24, 0xfff80080
	s_addc_u32 s35, s25, -1
	s_cmp_eq_u32 s66, 28
	s_cselect_b32 s41, s15, s35
	s_cselect_b32 s40, s14, s34
	s_cselect_b32 s35, s17, s21
	s_cselect_b32 s34, s16, s19
	v_lshl_add_u64 v[212:213], s[24:25], 0, v[192:193]
	s_add_i32 m0, s30, 0xc000
	ds_read_b128 v[160:163], v207
	ds_read_b128 v[164:167], v207 offset:1024
	ds_read_b128 v[168:171], v207 offset:2048
	ds_read_b128 v[172:175], v207 offset:3072
	ds_read_b128 v[176:179], v207 offset:4096
	ds_read_b128 v[180:183], v207 offset:5120
	ds_read_b128 v[200:203], v207 offset:6144
	ds_read_b128 v[208:211], v207 offset:7168
	global_load_lds_dwordx4 v[212:213], off
	s_add_i32 m0, s30, 0xe000
	v_lshl_add_u64 v[212:213], s[24:25], 0, v[194:195]
	global_load_lds_dwordx4 v[212:213], off
	s_waitcnt vmcnt(8) lgkmcnt(0)
	s_barrier
	s_setprio 1
	v_mfma_f32_16x16x32_bf16 v[124:127], v[128:131], v[160:163], v[124:127]
	v_mfma_f32_16x16x32_bf16 v[120:123], v[136:139], v[160:163], v[120:123]
	v_mfma_f32_16x16x32_bf16 v[112:115], v[128:131], v[168:171], v[112:115]
	v_mfma_f32_16x16x32_bf16 v[104:107], v[136:139], v[168:171], v[104:107]
	v_mfma_f32_16x16x32_bf16 v[96:99], v[128:131], v[176:179], v[96:99]
	v_mfma_f32_16x16x32_bf16 v[88:91], v[136:139], v[176:179], v[88:91]
	v_mfma_f32_16x16x32_bf16 v[80:83], v[128:131], v[200:203], v[80:83]
	v_mfma_f32_16x16x32_bf16 v[72:75], v[136:139], v[200:203], v[72:75]
	v_mfma_f32_16x16x32_bf16 v[124:127], v[132:135], v[164:167], v[124:127]
	v_mfma_f32_16x16x32_bf16 v[120:123], v[140:143], v[164:167], v[120:123]
	v_mfma_f32_16x16x32_bf16 v[112:115], v[132:135], v[172:175], v[112:115]
	v_mfma_f32_16x16x32_bf16 v[104:107], v[140:143], v[172:175], v[104:107]
	v_mfma_f32_16x16x32_bf16 v[96:99], v[132:135], v[180:183], v[96:99]
	v_mfma_f32_16x16x32_bf16 v[88:91], v[140:143], v[180:183], v[88:91]
	v_mfma_f32_16x16x32_bf16 v[80:83], v[132:135], v[208:211], v[80:83]
	v_mfma_f32_16x16x32_bf16 v[72:75], v[140:143], v[208:211], v[72:75]
	v_mfma_f32_16x16x32_bf16 v[116:119], v[144:147], v[160:163], v[116:119]
	v_mfma_f32_16x16x32_bf16 v[108:111], v[152:155], v[160:163], v[108:111]
	v_mfma_f32_16x16x32_bf16 v[100:103], v[144:147], v[168:171], v[100:103]
	v_mfma_f32_16x16x32_bf16 v[92:95], v[152:155], v[168:171], v[92:95]
	v_mfma_f32_16x16x32_bf16 v[84:87], v[144:147], v[176:179], v[84:87]
	v_mfma_f32_16x16x32_bf16 v[76:79], v[152:155], v[176:179], v[76:79]
	v_mfma_f32_16x16x32_bf16 v[68:71], v[144:147], v[200:203], v[68:71]
	v_mfma_f32_16x16x32_bf16 v[64:67], v[152:155], v[200:203], v[64:67]
	v_mfma_f32_16x16x32_bf16 v[116:119], v[148:151], v[164:167], v[116:119]
	v_mfma_f32_16x16x32_bf16 v[108:111], v[156:159], v[164:167], v[108:111]
	v_mfma_f32_16x16x32_bf16 v[100:103], v[148:151], v[172:175], v[100:103]
	v_mfma_f32_16x16x32_bf16 v[92:95], v[156:159], v[172:175], v[92:95]
	v_mfma_f32_16x16x32_bf16 v[84:87], v[148:151], v[180:183], v[84:87]
	v_mfma_f32_16x16x32_bf16 v[76:79], v[156:159], v[180:183], v[76:79]
	v_mfma_f32_16x16x32_bf16 v[68:71], v[148:151], v[208:211], v[68:71]
	v_mfma_f32_16x16x32_bf16 v[64:67], v[156:159], v[208:211], v[64:67]
	s_setprio 0
	s_barrier
	s_add_i32 s67, s52, s28
	v_lshl_add_u64 v[212:213], s[34:35], 0, v[188:189]
	s_mov_b32 m0, s67
	ds_read_b128 v[160:163], v207 offset:16384
	ds_read_b128 v[164:167], v207 offset:17408
	ds_read_b128 v[168:171], v207 offset:18432
	ds_read_b128 v[172:175], v207 offset:19456
	ds_read_b128 v[176:179], v207 offset:20480
	ds_read_b128 v[180:183], v207 offset:21504
	ds_read_b128 v[200:203], v207 offset:22528
	ds_read_b128 v[208:211], v207 offset:23552
	global_load_lds_dwordx4 v[212:213], off
	s_add_i32 m0, s67, 0x2000
	s_add_u32 s68, s34, 0x80000
	v_lshl_add_u64 v[214:215], s[34:35], 0, v[184:185]
	s_addc_u32 s69, s35, 0
	s_add_i32 s67, s53, s28
	global_load_lds_dwordx4 v[214:215], off
	v_lshl_add_u64 v[216:217], s[68:69], 0, v[188:189]
	s_mov_b32 m0, s67
	v_lshl_add_u64 v[218:219], s[40:41], 0, v[186:187]
	global_load_lds_dwordx4 v[216:217], off
	s_add_i32 m0, s67, 0x2000
	v_lshl_add_u64 v[216:217], s[68:69], 0, v[184:185]
	global_load_lds_dwordx4 v[216:217], off
	s_mov_b32 m0, s30
	v_lshl_add_u64 v[216:217], s[40:41], 0, v[190:191]
	global_load_lds_dwordx4 v[216:217], off
	s_mov_b32 m0, s31
	s_nop 0
	global_load_lds_dwordx4 v[218:219], off
	s_waitcnt vmcnt(8) lgkmcnt(0)
	s_barrier
; #define PG8_STAGE(bufoff, gbase, voff) do { _Pragma("unroll") for (int _i = 0; _i < 2; ++_i) \
;         __builtin_amdgcn_global_load_lds((const unsigned*)((const char*)(gbase) + (voff)[_i]), (LAS unsigned*)(lds + (bufoff) + ldsw + _i * 8192), 16, 0, 0); } while (0)
; #define PG8_LDA(dst, b, h) do { _Pragma("unroll") for (int m = 0; m < 4; ++m) _Pragma("unroll") for (int k = 0; k < 2; ++k) dst[m][k] = *(const LAS bf16x8*)(lds + PG8_SA(b, h) + aoff + m * 2048 + k * 1024); } while (0)
; #define PG8_LDB(dst, b, h) do { _Pragma("unroll") for (int n = 0; n < 2; ++n) _Pragma("unroll") for (int k = 0; k < 2; ++k) dst[n][k] = *(const LAS bf16x8*)(lds + PG8_SB(b, h) + boff + n * 2048 + k * 1024); } while (0)
; #define PG8_MMA(ai, bj, At, Bt) do { __builtin_amdgcn_s_setprio(1); _Pragma("unroll") for (int m = 0; m < 4; ++m) _Pragma("unroll") for (int n = 0; n < 2; ++n) _Pragma("unroll") for (int k = 0; k < 2; ++k) \
;         acc[ai][bj][m][n] = __builtin_amdgcn_mfma_f32_16x16x32_bf16(Bt[n][k], At[m][k], acc[ai][bj][m][n], 0, 0, 0); __builtin_amdgcn_s_setprio(0); } while (0)
; #define PG8_WAIT_V(n) asm volatile("s_waitcnt vmcnt(" #n ")" ::: "memory")
; #define PG8_WAIT_L(n) asm volatile("s_waitcnt lgkmcnt(" #n ")" ::: "memory")
; #define PG8_BAR __builtin_amdgcn_s_barrier()
; #define PG8_SCHED __builtin_amdgcn_sched_barrier(0)
; template <class Desc, class Epi>
; DI void gemm_phase(LAS unsigned char* lds, const Desc& D, const Epi& E, int wv) {
;     ...
;             PG8_WAIT_V(8); PG8_WAIT_L(0); PG8_BAR; PG8_MMA(1, 0, At, B0); PG8_MMA(1, 1, At, B1); PG8_BAR; PG8_SCHED;
;             PG8_LDB(B0, 1, 0); PG8_LDB(B1, 1, 1); PG8_SCHED; PG8_LDA(At, 1, 0); PG8_STAGE(PG8_SA(0, 1), a2 + hstepA, voffA);
;             PG8_WAIT_V(8); PG8_WAIT_L(0); PG8_BAR; PG8_MMA(0, 0, At, B0); PG8_MMA(0, 1, At, B1); PG8_BAR; PG8_SCHED;
	s_setprio 1
	v_mfma_f32_16x16x32_bf16 v[60:63], v[128:131], v[160:163], v[60:63]
	v_mfma_f32_16x16x32_bf16 v[56:59], v[136:139], v[160:163], v[56:59]
	v_mfma_f32_16x16x32_bf16 v[48:51], v[128:131], v[168:171], v[48:51]
	v_mfma_f32_16x16x32_bf16 v[40:43], v[136:139], v[168:171], v[40:43]
	v_mfma_f32_16x16x32_bf16 v[32:35], v[128:131], v[176:179], v[32:35]
	v_mfma_f32_16x16x32_bf16 v[24:27], v[136:139], v[176:179], v[24:27]
	v_mfma_f32_16x16x32_bf16 v[16:19], v[128:131], v[200:203], v[16:19]
	v_mfma_f32_16x16x32_bf16 v[8:11], v[136:139], v[200:203], v[8:11]
	v_mfma_f32_16x16x32_bf16 v[60:63], v[132:135], v[164:167], v[60:63]
	v_mfma_f32_16x16x32_bf16 v[56:59], v[140:143], v[164:167], v[56:59]
	v_mfma_f32_16x16x32_bf16 v[48:51], v[132:135], v[172:175], v[48:51]
	v_mfma_f32_16x16x32_bf16 v[40:43], v[140:143], v[172:175], v[40:43]
	v_mfma_f32_16x16x32_bf16 v[32:35], v[132:135], v[180:183], v[32:35]
	v_mfma_f32_16x16x32_bf16 v[24:27], v[140:143], v[180:183], v[24:27]
	v_mfma_f32_16x16x32_bf16 v[16:19], v[132:135], v[208:211], v[16:19]
	v_mfma_f32_16x16x32_bf16 v[8:11], v[140:143], v[208:211], v[8:11]
	v_mfma_f32_16x16x32_bf16 v[52:55], v[144:147], v[160:163], v[52:55]
	v_mfma_f32_16x16x32_bf16 v[44:47], v[152:155], v[160:163], v[44:47]
	v_mfma_f32_16x16x32_bf16 v[36:39], v[144:147], v[168:171], v[36:39]
	v_mfma_f32_16x16x32_bf16 v[28:31], v[152:155], v[168:171], v[28:31]
	v_mfma_f32_16x16x32_bf16 v[20:23], v[144:147], v[176:179], v[20:23]
	v_mfma_f32_16x16x32_bf16 v[12:15], v[152:155], v[176:179], v[12:15]
	v_mfma_f32_16x16x32_bf16 v[4:7], v[144:147], v[200:203], v[4:7]
	v_mfma_f32_16x16x32_bf16 v[0:3], v[152:155], v[200:203], v[0:3]
	v_mfma_f32_16x16x32_bf16 v[52:55], v[148:151], v[164:167], v[52:55]
	v_mfma_f32_16x16x32_bf16 v[44:47], v[156:159], v[164:167], v[44:47]
	v_mfma_f32_16x16x32_bf16 v[36:39], v[148:151], v[172:175], v[36:39]
	v_mfma_f32_16x16x32_bf16 v[28:31], v[156:159], v[172:175], v[28:31]
	v_mfma_f32_16x16x32_bf16 v[20:23], v[148:151], v[180:183], v[20:23]
	v_mfma_f32_16x16x32_bf16 v[12:15], v[156:159], v[180:183], v[12:15]
	v_mfma_f32_16x16x32_bf16 v[4:7], v[148:151], v[208:211], v[4:7]
	v_mfma_f32_16x16x32_bf16 v[0:3], v[156:159], v[208:211], v[0:3]
	s_setprio 0
	s_barrier
	s_add_i32 s67, 0, 0x18000
	s_add_i32 s68, 0, 0x1c000
	v_add_u32_e32 v140, s67, v204
	v_add_u32_e32 v156, s68, v204
	ds_read_b128 v[128:131], v140
	ds_read_b128 v[132:135], v140 offset:1024
	ds_read_b128 v[136:139], v140 offset:2048
	ds_read_b128 v[140:143], v140 offset:3072
	ds_read_b128 v[144:147], v156
	ds_read_b128 v[148:151], v156 offset:1024
	ds_read_b128 v[152:155], v156 offset:2048
	ds_read_b128 v[156:159], v156 offset:3072
	s_add_u32 s40, s40, 0x80000
	s_addc_u32 s41, s41, 0
	s_mov_b32 m0, s42
	v_lshl_add_u64 v[220:221], s[40:41], 0, v[190:191]
	ds_read_b128 v[160:163], v207 offset:32768
	ds_read_b128 v[164:167], v207 offset:33792
	ds_read_b128 v[168:171], v207 offset:34816
	ds_read_b128 v[172:175], v207 offset:35840
	ds_read_b128 v[176:179], v207 offset:36864
	ds_read_b128 v[180:183], v207 offset:37888
	ds_read_b128 v[200:203], v207 offset:38912
	ds_read_b128 v[208:211], v207 offset:39936
	global_load_lds_dwordx4 v[220:221], off
	s_mov_b32 m0, s43
	v_lshl_add_u64 v[220:221], s[40:41], 0, v[186:187]
	global_load_lds_dwordx4 v[220:221], off
	s_waitcnt vmcnt(8) lgkmcnt(0)
	s_barrier
	s_setprio 1
	v_mfma_f32_16x16x32_bf16 v[124:127], v[128:131], v[160:163], v[124:127]
	v_mfma_f32_16x16x32_bf16 v[120:123], v[136:139], v[160:163], v[120:123]
	v_mfma_f32_16x16x32_bf16 v[112:115], v[128:131], v[168:171], v[112:115]
	v_mfma_f32_16x16x32_bf16 v[104:107], v[136:139], v[168:171], v[104:107]
	v_mfma_f32_16x16x32_bf16 v[96:99], v[128:131], v[176:179], v[96:99]
	v_mfma_f32_16x16x32_bf16 v[88:91], v[136:139], v[176:179], v[88:91]
	v_mfma_f32_16x16x32_bf16 v[80:83], v[128:131], v[200:203], v[80:83]
	v_mfma_f32_16x16x32_bf16 v[72:75], v[136:139], v[200:203], v[72:75]
	v_mfma_f32_16x16x32_bf16 v[124:127], v[132:135], v[164:167], v[124:127]
	v_mfma_f32_16x16x32_bf16 v[120:123], v[140:143], v[164:167], v[120:123]
	v_mfma_f32_16x16x32_bf16 v[112:115], v[132:135], v[172:175], v[112:115]
	v_mfma_f32_16x16x32_bf16 v[104:107], v[140:143], v[172:175], v[104:107]
	v_mfma_f32_16x16x32_bf16 v[96:99], v[132:135], v[180:183], v[96:99]
	v_mfma_f32_16x16x32_bf16 v[88:91], v[140:143], v[180:183], v[88:91]
	v_mfma_f32_16x16x32_bf16 v[80:83], v[132:135], v[208:211], v[80:83]
	v_mfma_f32_16x16x32_bf16 v[72:75], v[140:143], v[208:211], v[72:75]
	v_mfma_f32_16x16x32_bf16 v[116:119], v[144:147], v[160:163], v[116:119]
	v_mfma_f32_16x16x32_bf16 v[108:111], v[152:155], v[160:163], v[108:111]
	v_mfma_f32_16x16x32_bf16 v[100:103], v[144:147], v[168:171], v[100:103]
	v_mfma_f32_16x16x32_bf16 v[92:95], v[152:155], v[168:171], v[92:95]
	v_mfma_f32_16x16x32_bf16 v[84:87], v[144:147], v[176:179], v[84:87]
	v_mfma_f32_16x16x32_bf16 v[76:79], v[152:155], v[176:179], v[76:79]
	v_mfma_f32_16x16x32_bf16 v[68:71], v[144:147], v[200:203], v[68:71]
	v_mfma_f32_16x16x32_bf16 v[64:67], v[152:155], v[200:203], v[64:67]
	v_mfma_f32_16x16x32_bf16 v[116:119], v[148:151], v[164:167], v[116:119]
	v_mfma_f32_16x16x32_bf16 v[108:111], v[156:159], v[164:167], v[108:111]
	v_mfma_f32_16x16x32_bf16 v[100:103], v[148:151], v[172:175], v[100:103]
	v_mfma_f32_16x16x32_bf16 v[92:95], v[156:159], v[172:175], v[92:95]
	v_mfma_f32_16x16x32_bf16 v[84:87], v[148:151], v[180:183], v[84:87]
	v_mfma_f32_16x16x32_bf16 v[76:79], v[156:159], v[180:183], v[76:79]
	v_mfma_f32_16x16x32_bf16 v[68:71], v[148:151], v[208:211], v[68:71]
	v_mfma_f32_16x16x32_bf16 v[64:67], v[156:159], v[208:211], v[64:67]
	s_setprio 0
	s_barrier
; #define PG8_STAGE(bufoff, gbase, voff) do { _Pragma("unroll") for (int _i = 0; _i < 2; ++_i) \
;         __builtin_amdgcn_global_load_lds((const unsigned*)((const char*)(gbase) + (voff)[_i]), (LAS unsigned*)(lds + (bufoff) + ldsw + _i * 8192), 16, 0, 0); } while (0)
; #define PG8_LDA(dst, b, h) do { _Pragma("unroll") for (int m = 0; m < 4; ++m) _Pragma("unroll") for (int k = 0; k < 2; ++k) dst[m][k] = *(const LAS bf16x8*)(lds + PG8_SA(b, h) + aoff + m * 2048 + k * 1024); } while (0)
; #define PG8_MMA(ai, bj, At, Bt) do { __builtin_amdgcn_s_setprio(1); _Pragma("unroll") for (int m = 0; m < 4; ++m) _Pragma("unroll") for (int n = 0; n < 2; ++n) _Pragma("unroll") for (int k = 0; k < 2; ++k) \
;         acc[ai][bj][m][n] = __builtin_amdgcn_mfma_f32_16x16x32_bf16(Bt[n][k], At[m][k], acc[ai][bj][m][n], 0, 0, 0); __builtin_amdgcn_s_setprio(0); } while (0)
; #define PG8_WAIT_V(n) asm volatile("s_waitcnt vmcnt(" #n ")" ::: "memory")
; #define PG8_WAIT_L(n) asm volatile("s_waitcnt lgkmcnt(" #n ")" ::: "memory")
; #define PG8_BAR __builtin_amdgcn_s_barrier()
; #define PG8_SCHED __builtin_amdgcn_sched_barrier(0)
; template <class Desc, class Epi>
; DI void gemm_phase(LAS unsigned char* lds, const Desc& D, const Epi& E, int wv) {
;     ...
;             PG8_LDA(At, 1, 1); PG8_STAGE(PG8_SB(1, 0), b3, voffB); PG8_STAGE(PG8_SB(1, 1), b3 + hstepB, voffB); PG8_STAGE(PG8_SA(1, 0), a3, voffA);
;             PG8_WAIT_V(8); PG8_WAIT_L(0); PG8_BAR; PG8_MMA(1, 0, At, B0); PG8_MMA(1, 1, At, B1); PG8_BAR; PG8_SCHED;
;         }
;         if (wr == 0) PG8_BAR;
	s_add_i32 s40, s67, s28
	v_lshl_add_u64 v[212:213], v[212:213], 0, s[6:7]
	s_mov_b32 m0, s40
	ds_read_b128 v[160:163], v207 offset:49152
	ds_read_b128 v[164:167], v207 offset:50176
	ds_read_b128 v[168:171], v207 offset:51200
	ds_read_b128 v[172:175], v207 offset:52224
	ds_read_b128 v[176:179], v207 offset:53248
	ds_read_b128 v[180:183], v207 offset:54272
	ds_read_b128 v[200:203], v207 offset:55296
	ds_read_b128 v[208:211], v207 offset:56320
	global_load_lds_dwordx4 v[212:213], off
	s_add_i32 m0, s40, 0x2000
	s_add_u32 s34, s34, 0x80080
	v_lshl_add_u64 v[212:213], v[214:215], 0, s[6:7]
	s_addc_u32 s35, s35, 0
	s_add_i32 s40, s68, s28
	global_load_lds_dwordx4 v[212:213], off
	s_mov_b32 m0, s40
	v_lshl_add_u64 v[212:213], s[34:35], 0, v[188:189]
	global_load_lds_dwordx4 v[212:213], off
	s_add_i32 m0, s40, 0x2000
	v_lshl_add_u64 v[212:213], s[34:35], 0, v[184:185]
	global_load_lds_dwordx4 v[212:213], off
	s_mov_b32 m0, s49
	v_lshl_add_u64 v[212:213], v[216:217], 0, s[6:7]
	global_load_lds_dwordx4 v[212:213], off
	s_mov_b32 m0, s50
	v_lshl_add_u64 v[212:213], v[218:219], 0, s[6:7]
	global_load_lds_dwordx4 v[212:213], off
	s_waitcnt vmcnt(8) lgkmcnt(0)
	s_barrier
	s_setprio 1
	v_mfma_f32_16x16x32_bf16 v[60:63], v[128:131], v[160:163], v[60:63]
	v_mfma_f32_16x16x32_bf16 v[56:59], v[136:139], v[160:163], v[56:59]
	v_mfma_f32_16x16x32_bf16 v[48:51], v[128:131], v[168:171], v[48:51]
	v_mfma_f32_16x16x32_bf16 v[40:43], v[136:139], v[168:171], v[40:43]
	v_mfma_f32_16x16x32_bf16 v[32:35], v[128:131], v[176:179], v[32:35]
	v_mfma_f32_16x16x32_bf16 v[24:27], v[136:139], v[176:179], v[24:27]
	v_mfma_f32_16x16x32_bf16 v[16:19], v[128:131], v[200:203], v[16:19]
	v_mfma_f32_16x16x32_bf16 v[8:11], v[136:139], v[200:203], v[8:11]
	v_mfma_f32_16x16x32_bf16 v[60:63], v[132:135], v[164:167], v[60:63]
	v_mfma_f32_16x16x32_bf16 v[56:59], v[140:143], v[164:167], v[56:59]
	v_mfma_f32_16x16x32_bf16 v[48:51], v[132:135], v[172:175], v[48:51]
	v_mfma_f32_16x16x32_bf16 v[40:43], v[140:143], v[172:175], v[40:43]
	v_mfma_f32_16x16x32_bf16 v[32:35], v[132:135], v[180:183], v[32:35]
	v_mfma_f32_16x16x32_bf16 v[24:27], v[140:143], v[180:183], v[24:27]
	v_mfma_f32_16x16x32_bf16 v[16:19], v[132:135], v[208:211], v[16:19]
	v_mfma_f32_16x16x32_bf16 v[8:11], v[140:143], v[208:211], v[8:11]
	v_mfma_f32_16x16x32_bf16 v[52:55], v[144:147], v[160:163], v[52:55]
	v_mfma_f32_16x16x32_bf16 v[44:47], v[152:155], v[160:163], v[44:47]
	v_mfma_f32_16x16x32_bf16 v[36:39], v[144:147], v[168:171], v[36:39]
	v_mfma_f32_16x16x32_bf16 v[28:31], v[152:155], v[168:171], v[28:31]
	v_mfma_f32_16x16x32_bf16 v[20:23], v[144:147], v[176:179], v[20:23]
	v_mfma_f32_16x16x32_bf16 v[12:15], v[152:155], v[176:179], v[12:15]
	v_mfma_f32_16x16x32_bf16 v[4:7], v[144:147], v[200:203], v[4:7]
	v_mfma_f32_16x16x32_bf16 v[0:3], v[152:155], v[200:203], v[0:3]
	v_mfma_f32_16x16x32_bf16 v[52:55], v[148:151], v[164:167], v[52:55]
	v_mfma_f32_16x16x32_bf16 v[44:47], v[156:159], v[164:167], v[44:47]
	v_mfma_f32_16x16x32_bf16 v[36:39], v[148:151], v[172:175], v[36:39]
	v_mfma_f32_16x16x32_bf16 v[28:31], v[156:159], v[172:175], v[28:31]
	v_mfma_f32_16x16x32_bf16 v[20:23], v[148:151], v[180:183], v[20:23]
	v_mfma_f32_16x16x32_bf16 v[12:15], v[156:159], v[180:183], v[12:15]
	v_mfma_f32_16x16x32_bf16 v[4:7], v[148:151], v[208:211], v[4:7]
	v_mfma_f32_16x16x32_bf16 v[0:3], v[156:159], v[208:211], v[0:3]
	s_setprio 0
	s_barrier
	s_add_i32 s66, s66, 2
	s_add_u32 s24, s24, 0x100
	s_addc_u32 s25, s25, 0
	s_add_u32 s19, s19, 0x100
	s_addc_u32 s21, s21, 0
	s_cmp_gt_u32 s66, 29
	s_cbranch_scc0 .LBB0_2706
	s_and_b64 vcc, exec, s[8:9]
	s_cbranch_vccz .LBB0_2709
	s_barrier
